# K-loop DMA confirmation moved one phase later (vmcnt 10/8 split, 4-phase lead) in all 12 GEMMs + 64-bit accumulator zeroing, on top of v69
# speedup vs baseline: 1.0029x; 1.0029x over previous
; #define PG8_STAGE(bufoff, gbase, voff) do { _Pragma("unroll") for (int _i = 0; _i < 2; ++_i) \
;     __builtin_amdgcn_global_load_lds((const unsigned*)((const char*)(gbase) + (voff)[_i]), (LAS unsigned*)(lds + (bufoff) + ldsw + _i * 8192), 16, 0, 0); } while (0)
; #define PG8_LDA(dst, b, h) do { _Pragma("unroll") for (int m = 0; m < 4; ++m) _Pragma("unroll") for (int k = 0; k < 2; ++k) dst[m][k] = *(const LAS bf16x8*)(lds + PG8_SA(b, h) + aoff + m * 2048 + k * 1024); } while (0)
; #define PG8_LDB(dst, b, h) do { _Pragma("unroll") for (int n = 0; n < 2; ++n) _Pragma("unroll") for (int k = 0; k < 2; ++k) dst[n][k] = *(const LAS bf16x8*)(lds + PG8_SB(b, h) + boff + n * 2048 + k * 1024); } while (0)
; #define PG8_MMA(ai, bj, At, Bt) do { __builtin_amdgcn_s_setprio(1); _Pragma("unroll") for (int m = 0; m < 4; ++m) _Pragma("unroll") for (int n = 0; n < 2; ++n) _Pragma("unroll") for (int k = 0; k < 2; ++k) \
;     acc[ai][bj][m][n] = __builtin_amdgcn_mfma_f32_16x16x32_bf16(Bt[n][k], At[m][k], acc[ai][bj][m][n], 0, 0, 0); __builtin_amdgcn_s_setprio(0); } while (0)
; template <class Epi, class Sched>
; __device__ __forceinline__ void gemm_phase(LAS unsigned char* lds, const Gemm g, const Sched& S, const Epi& E) {
;     ...
;     const bool has_next = S.next(ui + 1, nxt);
;     const char* nA = has_next ? (const char*)g.A + (size_t)nxt.pm * tstep : cA; const char* nB = has_next ? (const char*)g.Bt + (size_t)nxt.pn * tstep : cB;
;     for (int t = 0; t < nt; t += 2) {
;       const bool last = (t == nt - 2);
;       const char* a1 = cA + (size_t)(t + 1) * kstep;
;       const char* a2 = last ? nA : cA + (size_t)(t + 2) * kstep; const char* b2 = last ? nB : cB + (size_t)(t + 2) * kstep;
;       const char* a3 = a2 + kstep; const char* b3 = b2 + kstep;
;       if (last && has_next) S.a_ready(nxt);
;       PG8_LDB(B0, 0, 0); PG8_SCHED; PG8_LDA(At, 0, 0); PG8_STAGE(PG8_SA(1, 1), a1 + hstep, voffA);
;       PG8_WAIT_L(8); PG8_BAR; PG8_WAIT_L(0); PG8_MMA(0, 0, At, B0); PG8_BAR; PG8_SCHED;
;       PG8_LDB(B1, 0, 1); PG8_STAGE(PG8_SB(0, 0), b2, voffB);
;       PG8_BAR; PG8_WAIT_L(0); PG8_MMA(0, 1, At, B1); PG8_BAR;
;     ...
;     for (int a = 0; a < 2; ++a)
; #pragma unroll
;       for (int b = 0; b < 2; ++b)
; #pragma unroll
;         for (int m = 0; m < 4; ++m)
; #pragma unroll
;           for (int n = 0; n < 2; ++n) acc[a][b][m][n] = (f32x4){0.f, 0.f, 0.f, 0.f};
.LBB0_207:
	s_ashr_i32 s35, s34, 31
	v_cmp_lt_i64_e32 vcc, s[38:39], v[164:165]
	s_lshl_b64 s[38:39], s[34:35], 19
	s_add_u32 s38, s94, s38
	s_addc_u32 s39, s95, s39
	s_and_b64 s[40:41], vcc, exec
	s_cselect_b32 s35, s39, s43
	s_cselect_b32 s69, s38, s42
	s_ashr_i32 s23, s22, 31
	s_lshl_b64 s[40:41], s[22:23], 19
	v_readlane_b32 s60, v252, 0
	v_readlane_b32 s61, v252, 1
	s_add_u32 s40, s60, s40
	s_addc_u32 s41, s61, s41
	s_and_b64 s[70:71], vcc, exec
	s_cselect_b32 s23, s41, s45
	s_cselect_b32 s70, s40, s44
	s_add_u32 s42, s42, 0x40080
	s_addc_u32 s43, s43, 0
	s_add_u32 s71, s44, 0x100
	v_mov_b32_e32 v0, 0
	s_addc_u32 s52, s45, 0
	s_mov_b32 s72, -2
	v_mov_b32_e32 v1, v0
	v_mov_b64_e32 v[2:3], v[0:1]
	v_mov_b64_e32 v[4:5], v[0:1]
	v_mov_b64_e32 v[6:7], v[0:1]
	v_mov_b64_e32 v[8:9], v[0:1]
	v_mov_b64_e32 v[10:11], v[0:1]
	v_mov_b64_e32 v[12:13], v[0:1]
	v_mov_b64_e32 v[14:15], v[0:1]
	v_mov_b64_e32 v[16:17], v[0:1]
	v_mov_b64_e32 v[18:19], v[0:1]
	v_mov_b64_e32 v[20:21], v[0:1]
	v_mov_b64_e32 v[22:23], v[0:1]
	v_mov_b64_e32 v[24:25], v[0:1]
	v_mov_b64_e32 v[26:27], v[0:1]
	v_mov_b64_e32 v[28:29], v[0:1]
	v_mov_b64_e32 v[30:31], v[0:1]
	v_mov_b64_e32 v[32:33], v[0:1]
	v_mov_b64_e32 v[34:35], v[0:1]
	v_mov_b64_e32 v[36:37], v[0:1]
	v_mov_b64_e32 v[38:39], v[0:1]
	v_mov_b64_e32 v[40:41], v[0:1]
	v_mov_b64_e32 v[42:43], v[0:1]
	v_mov_b64_e32 v[44:45], v[0:1]
	v_mov_b64_e32 v[46:47], v[0:1]
	v_mov_b64_e32 v[48:49], v[0:1]
	v_mov_b64_e32 v[50:51], v[0:1]
	v_mov_b64_e32 v[52:53], v[0:1]
	v_mov_b64_e32 v[54:55], v[0:1]
	v_mov_b64_e32 v[56:57], v[0:1]
	v_mov_b64_e32 v[58:59], v[0:1]
	v_mov_b64_e32 v[60:61], v[0:1]
	v_mov_b64_e32 v[62:63], v[0:1]
	v_mov_b64_e32 v[64:65], v[0:1]
	v_mov_b64_e32 v[66:67], v[0:1]
	v_mov_b64_e32 v[68:69], v[0:1]
	v_mov_b64_e32 v[70:71], v[0:1]
	v_mov_b64_e32 v[72:73], v[0:1]
	v_mov_b64_e32 v[74:75], v[0:1]
	v_mov_b64_e32 v[76:77], v[0:1]
	v_mov_b64_e32 v[78:79], v[0:1]
	v_mov_b64_e32 v[80:81], v[0:1]
	v_mov_b64_e32 v[82:83], v[0:1]
	v_mov_b64_e32 v[84:85], v[0:1]
	v_mov_b64_e32 v[86:87], v[0:1]
	v_mov_b64_e32 v[88:89], v[0:1]
	v_mov_b64_e32 v[90:91], v[0:1]
	v_mov_b64_e32 v[92:93], v[0:1]
	v_mov_b64_e32 v[94:95], v[0:1]
	v_mov_b64_e32 v[96:97], v[0:1]
	v_mov_b64_e32 v[98:99], v[0:1]
	v_mov_b64_e32 v[100:101], v[0:1]
	v_mov_b64_e32 v[102:103], v[0:1]
	v_mov_b64_e32 v[104:105], v[0:1]
	v_mov_b64_e32 v[106:107], v[0:1]
	v_mov_b64_e32 v[108:109], v[0:1]
	v_mov_b64_e32 v[110:111], v[0:1]
	v_mov_b64_e32 v[112:113], v[0:1]
	v_mov_b64_e32 v[114:115], v[0:1]
	v_mov_b64_e32 v[116:117], v[0:1]
	v_mov_b64_e32 v[118:119], v[0:1]
	v_mov_b64_e32 v[120:121], v[0:1]
	v_mov_b64_e32 v[122:123], v[0:1]
	v_mov_b64_e32 v[124:125], v[0:1]
	v_mov_b64_e32 v[126:127], v[0:1]
	s_cmp_eq_u32 s100, 0
	s_cbranch_scc1 .Lxs_e0
	s_barrier
	s_mov_b32 s100, 0
.Lxs_e0:
.LBB0_208:
	s_add_u32 s44, s42, 0xfffc0080
	s_addc_u32 s45, s43, -1
	s_add_i32 s73, 0, 0x10000
	v_add_u32_e32 v151, s73, v141
	ds_read_b128 v[152:155], v151
	ds_read_b128 v[156:159], v151 offset:1024
	ds_read_b128 v[174:177], v151 offset:2048
	ds_read_b128 v[178:181], v151 offset:3072
	s_cmp_eq_u32 s72, 12
	s_cselect_b32 vcc_hi, s35, s45
	s_cselect_b32 vcc_lo, s69, s44
	s_cselect_b32 s45, s23, s52
	s_cselect_b32 s44, s70, s71
	s_add_i32 m0, s12, 0xc000
	ds_read_b128 v[182:185], v150
	ds_read_b128 v[186:189], v150 offset:1024
	ds_read_b128 v[190:193], v150 offset:2048
	ds_read_b128 v[194:197], v150 offset:3072
	ds_read_b128 v[198:201], v150 offset:4096
	ds_read_b128 v[202:205], v150 offset:5120
	ds_read_b128 v[206:209], v150 offset:6144
	ds_read_b128 v[210:213], v150 offset:7168
	global_load_lds_dwordx4 v136, s[42:43]
	s_add_i32 m0, s12, 0xe000
	s_nop 0
	global_load_lds_dwordx4 v138, s[42:43]
	s_waitcnt vmcnt(8)
	s_waitcnt lgkmcnt(8)
	s_barrier
	s_waitcnt lgkmcnt(0)
	s_waitcnt lgkmcnt(0)
	v_mfma_f32_16x16x32_bf16 v[124:127], v[152:155], v[182:185], v[124:127]
	v_mfma_f32_16x16x32_bf16 v[116:119], v[174:177], v[182:185], v[116:119]
	v_mfma_f32_16x16x32_bf16 v[108:111], v[152:155], v[190:193], v[108:111]
	v_mfma_f32_16x16x32_bf16 v[100:103], v[174:177], v[190:193], v[100:103]
	v_mfma_f32_16x16x32_bf16 v[92:95], v[152:155], v[198:201], v[92:95]
	v_mfma_f32_16x16x32_bf16 v[84:87], v[174:177], v[198:201], v[84:87]
	v_mfma_f32_16x16x32_bf16 v[76:79], v[152:155], v[206:209], v[76:79]
	v_mfma_f32_16x16x32_bf16 v[68:71], v[174:177], v[206:209], v[68:71]
	v_mfma_f32_16x16x32_bf16 v[124:127], v[156:159], v[186:189], v[124:127]
	v_mfma_f32_16x16x32_bf16 v[116:119], v[178:181], v[186:189], v[116:119]
	v_mfma_f32_16x16x32_bf16 v[108:111], v[156:159], v[194:197], v[108:111]
	v_mfma_f32_16x16x32_bf16 v[100:103], v[178:181], v[194:197], v[100:103]
	v_mfma_f32_16x16x32_bf16 v[92:95], v[156:159], v[202:205], v[92:95]
	v_mfma_f32_16x16x32_bf16 v[84:87], v[178:181], v[202:205], v[84:87]
	v_mfma_f32_16x16x32_bf16 v[76:79], v[156:159], v[210:213], v[76:79]
	v_mfma_f32_16x16x32_bf16 v[68:71], v[178:181], v[210:213], v[68:71]
	s_barrier
	s_add_i32 s76, 0, 0x14000
	s_add_i32 s73, s73, s7
	v_add_u32_e32 v151, s76, v141
	s_mov_b32 m0, s73
	ds_read_b128 v[226:229], v151
	ds_read_b128 v[232:235], v151 offset:1024
	ds_read_b128 v[236:239], v151 offset:2048
	ds_read_b128 v[240:243], v151 offset:3072
	global_load_lds_dwordx4 v132, s[44:45]
	s_add_i32 m0, s73, 0x2000
	s_nop 0
	global_load_lds_dwordx4 v128, s[44:45]
	s_barrier
; #define PG8_STAGE(bufoff, gbase, voff) do { _Pragma("unroll") for (int _i = 0; _i < 2; ++_i) \
;     __builtin_amdgcn_global_load_lds((const unsigned*)((const char*)(gbase) + (voff)[_i]), (LAS unsigned*)(lds + (bufoff) + ldsw + _i * 8192), 16, 0, 0); } while (0)
; #define PG8_LDA(dst, b, h) do { _Pragma("unroll") for (int m = 0; m < 4; ++m) _Pragma("unroll") for (int k = 0; k < 2; ++k) dst[m][k] = *(const LAS bf16x8*)(lds + PG8_SA(b, h) + aoff + m * 2048 + k * 1024); } while (0)
; #define PG8_LDB(dst, b, h) do { _Pragma("unroll") for (int n = 0; n < 2; ++n) _Pragma("unroll") for (int k = 0; k < 2; ++k) dst[n][k] = *(const LAS bf16x8*)(lds + PG8_SB(b, h) + boff + n * 2048 + k * 1024); } while (0)
; #define PG8_MMA(ai, bj, At, Bt) do { __builtin_amdgcn_s_setprio(1); _Pragma("unroll") for (int m = 0; m < 4; ++m) _Pragma("unroll") for (int n = 0; n < 2; ++n) _Pragma("unroll") for (int k = 0; k < 2; ++k) \
;     acc[ai][bj][m][n] = __builtin_amdgcn_mfma_f32_16x16x32_bf16(Bt[n][k], At[m][k], acc[ai][bj][m][n], 0, 0, 0); __builtin_amdgcn_s_setprio(0); } while (0)
; #define PG8_WAIT_V(n) asm volatile("s_waitcnt vmcnt(" #n ")" ::: "memory")
; #define PG8_WAIT_L(n) asm volatile("s_waitcnt lgkmcnt(" #n ")" ::: "memory")
; #define PG8_BAR __builtin_amdgcn_s_barrier()
; #define PG8_SCHED __builtin_amdgcn_sched_barrier(0)
; template <class Epi, class Sched>
; __device__ __forceinline__ void gemm_phase(LAS unsigned char* lds, const Gemm g, const Sched& S, const Epi& E) {
;     ...
;       PG8_BAR; PG8_WAIT_L(0); PG8_MMA(0, 1, At, B1); PG8_BAR;
;       PG8_LDA(At, 0, 1); PG8_STAGE(PG8_SA(0, 0), a2, voffA);
;       PG8_BAR; PG8_WAIT_L(0); PG8_MMA(1, 0, At, B0); PG8_BAR; PG8_SCHED;
;       PG8_STAGE(PG8_SB(0, 1), b2 + hstep, voffB);
;       PG8_WAIT_V(6); PG8_BAR; PG8_MMA(1, 1, At, B1); PG8_BAR;
;       PG8_LDB(B0, 1, 0); PG8_SCHED; PG8_LDA(At, 1, 0); PG8_STAGE(PG8_SA(0, 1), a2 + hstep, voffA);
;       PG8_WAIT_L(8); PG8_BAR; PG8_WAIT_L(0); PG8_MMA(0, 0, At, B0); PG8_BAR; PG8_SCHED;
	s_waitcnt lgkmcnt(0)
	s_waitcnt lgkmcnt(0)
	v_mfma_f32_16x16x32_bf16 v[120:123], v[226:229], v[182:185], v[120:123]
	v_mfma_f32_16x16x32_bf16 v[112:115], v[236:239], v[182:185], v[112:115]
	v_mfma_f32_16x16x32_bf16 v[104:107], v[226:229], v[190:193], v[104:107]
	v_mfma_f32_16x16x32_bf16 v[96:99], v[236:239], v[190:193], v[96:99]
	v_mfma_f32_16x16x32_bf16 v[88:91], v[226:229], v[198:201], v[88:91]
	v_mfma_f32_16x16x32_bf16 v[80:83], v[236:239], v[198:201], v[80:83]
	v_mfma_f32_16x16x32_bf16 v[72:75], v[226:229], v[206:209], v[72:75]
	v_mfma_f32_16x16x32_bf16 v[64:67], v[236:239], v[206:209], v[64:67]
	v_mfma_f32_16x16x32_bf16 v[120:123], v[232:235], v[186:189], v[120:123]
	v_mfma_f32_16x16x32_bf16 v[112:115], v[240:243], v[186:189], v[112:115]
	v_mfma_f32_16x16x32_bf16 v[104:107], v[232:235], v[194:197], v[104:107]
	v_mfma_f32_16x16x32_bf16 v[96:99], v[240:243], v[194:197], v[96:99]
	v_mfma_f32_16x16x32_bf16 v[88:91], v[232:235], v[202:205], v[88:91]
	v_mfma_f32_16x16x32_bf16 v[80:83], v[240:243], v[202:205], v[80:83]
	v_mfma_f32_16x16x32_bf16 v[72:75], v[232:235], v[210:213], v[72:75]
	v_mfma_f32_16x16x32_bf16 v[64:67], v[240:243], v[210:213], v[64:67]
	s_mov_b32 m0, s12
	s_barrier
	ds_read_b128 v[182:185], v150 offset:16384
	ds_read_b128 v[186:189], v150 offset:17408
	ds_read_b128 v[190:193], v150 offset:18432
	ds_read_b128 v[194:197], v150 offset:19456
	ds_read_b128 v[198:201], v150 offset:20480
	ds_read_b128 v[202:205], v150 offset:21504
	ds_read_b128 v[206:209], v150 offset:22528
	ds_read_b128 v[210:213], v150 offset:23552
	global_load_lds_dwordx4 v134, vcc
	s_mov_b32 m0, s13
	s_nop 0
	global_load_lds_dwordx4 v130, vcc
	s_barrier
	s_waitcnt lgkmcnt(0)
	s_waitcnt lgkmcnt(0)
	v_mfma_f32_16x16x32_bf16 v[60:63], v[152:155], v[182:185], v[60:63]
	v_mfma_f32_16x16x32_bf16 v[52:55], v[174:177], v[182:185], v[52:55]
	v_mfma_f32_16x16x32_bf16 v[44:47], v[152:155], v[190:193], v[44:47]
	v_mfma_f32_16x16x32_bf16 v[36:39], v[174:177], v[190:193], v[36:39]
	v_mfma_f32_16x16x32_bf16 v[28:31], v[152:155], v[198:201], v[28:31]
	v_mfma_f32_16x16x32_bf16 v[20:23], v[174:177], v[198:201], v[20:23]
	v_mfma_f32_16x16x32_bf16 v[12:15], v[152:155], v[206:209], v[12:15]
	v_mfma_f32_16x16x32_bf16 v[4:7], v[174:177], v[206:209], v[4:7]
	v_mfma_f32_16x16x32_bf16 v[60:63], v[156:159], v[186:189], v[60:63]
	v_mfma_f32_16x16x32_bf16 v[52:55], v[178:181], v[186:189], v[52:55]
	v_mfma_f32_16x16x32_bf16 v[44:47], v[156:159], v[194:197], v[44:47]
	v_mfma_f32_16x16x32_bf16 v[36:39], v[178:181], v[194:197], v[36:39]
	v_mfma_f32_16x16x32_bf16 v[28:31], v[156:159], v[202:205], v[28:31]
	v_mfma_f32_16x16x32_bf16 v[20:23], v[178:181], v[202:205], v[20:23]
	v_mfma_f32_16x16x32_bf16 v[12:15], v[156:159], v[210:213], v[12:15]
	v_mfma_f32_16x16x32_bf16 v[4:7], v[178:181], v[210:213], v[4:7]
	s_barrier
	s_add_u32 s74, s44, 0x40000
	s_addc_u32 s75, s45, 0
	s_add_i32 s73, s76, s7
	s_mov_b32 m0, s73
	s_nop 0
	global_load_lds_dwordx4 v132, s[74:75]
	s_add_i32 m0, s73, 0x2000
	s_nop 0
	global_load_lds_dwordx4 v128, s[74:75]
	s_waitcnt vmcnt(10)
	s_barrier
	v_mfma_f32_16x16x32_bf16 v[56:59], v[226:229], v[182:185], v[56:59]
	v_mfma_f32_16x16x32_bf16 v[48:51], v[236:239], v[182:185], v[48:51]
	v_mfma_f32_16x16x32_bf16 v[40:43], v[226:229], v[190:193], v[40:43]
	v_mfma_f32_16x16x32_bf16 v[32:35], v[236:239], v[190:193], v[32:35]
	v_mfma_f32_16x16x32_bf16 v[24:27], v[226:229], v[198:201], v[24:27]
	v_mfma_f32_16x16x32_bf16 v[16:19], v[236:239], v[198:201], v[16:19]
	v_mfma_f32_16x16x32_bf16 v[8:11], v[226:229], v[206:209], v[8:11]
	v_mfma_f32_16x16x32_bf16 v[0:3], v[236:239], v[206:209], v[0:3]
	v_mfma_f32_16x16x32_bf16 v[56:59], v[232:235], v[186:189], v[56:59]
	v_mfma_f32_16x16x32_bf16 v[48:51], v[240:243], v[186:189], v[48:51]
	v_mfma_f32_16x16x32_bf16 v[40:43], v[232:235], v[194:197], v[40:43]
	v_mfma_f32_16x16x32_bf16 v[32:35], v[240:243], v[194:197], v[32:35]
	v_mfma_f32_16x16x32_bf16 v[24:27], v[232:235], v[202:205], v[24:27]
	v_mfma_f32_16x16x32_bf16 v[16:19], v[240:243], v[202:205], v[16:19]
	v_mfma_f32_16x16x32_bf16 v[8:11], v[232:235], v[210:213], v[8:11]
	v_mfma_f32_16x16x32_bf16 v[0:3], v[240:243], v[210:213], v[0:3]
	s_add_i32 s73, 0, 0x18000
	v_add_u32_e32 v151, s73, v141
	s_barrier
	ds_read_b128 v[152:155], v151
	ds_read_b128 v[156:159], v151 offset:1024
	ds_read_b128 v[174:177], v151 offset:2048
	ds_read_b128 v[178:181], v151 offset:3072
	s_add_u32 s74, vcc_lo, 0x40000
	s_addc_u32 s75, vcc_hi, 0
	s_mov_b32 m0, s48
	ds_read_b128 v[182:185], v150 offset:32768
	ds_read_b128 v[186:189], v150 offset:33792
	ds_read_b128 v[190:193], v150 offset:34816
	ds_read_b128 v[194:197], v150 offset:35840
	ds_read_b128 v[198:201], v150 offset:36864
	ds_read_b128 v[202:205], v150 offset:37888
	ds_read_b128 v[206:209], v150 offset:38912
	ds_read_b128 v[210:213], v150 offset:39936
	global_load_lds_dwordx4 v134, s[74:75]
	s_mov_b32 m0, s49
	s_nop 0
	global_load_lds_dwordx4 v130, s[74:75]
	s_waitcnt vmcnt(8)
	s_waitcnt lgkmcnt(8)
	s_barrier
; #define PG8_STAGE(bufoff, gbase, voff) do { _Pragma("unroll") for (int _i = 0; _i < 2; ++_i) \
;     __builtin_amdgcn_global_load_lds((const unsigned*)((const char*)(gbase) + (voff)[_i]), (LAS unsigned*)(lds + (bufoff) + ldsw + _i * 8192), 16, 0, 0); } while (0)
; #define PG8_LDA(dst, b, h) do { _Pragma("unroll") for (int m = 0; m < 4; ++m) _Pragma("unroll") for (int k = 0; k < 2; ++k) dst[m][k] = *(const LAS bf16x8*)(lds + PG8_SA(b, h) + aoff + m * 2048 + k * 1024); } while (0)
; #define PG8_LDB(dst, b, h) do { _Pragma("unroll") for (int n = 0; n < 2; ++n) _Pragma("unroll") for (int k = 0; k < 2; ++k) dst[n][k] = *(const LAS bf16x8*)(lds + PG8_SB(b, h) + boff + n * 2048 + k * 1024); } while (0)
; #define PG8_MMA(ai, bj, At, Bt) do { __builtin_amdgcn_s_setprio(1); _Pragma("unroll") for (int m = 0; m < 4; ++m) _Pragma("unroll") for (int n = 0; n < 2; ++n) _Pragma("unroll") for (int k = 0; k < 2; ++k) \
;     acc[ai][bj][m][n] = __builtin_amdgcn_mfma_f32_16x16x32_bf16(Bt[n][k], At[m][k], acc[ai][bj][m][n], 0, 0, 0); __builtin_amdgcn_s_setprio(0); } while (0)
; #define PG8_WAIT_V(n) asm volatile("s_waitcnt vmcnt(" #n ")" ::: "memory")
; #define PG8_WAIT_L(n) asm volatile("s_waitcnt lgkmcnt(" #n ")" ::: "memory")
; #define PG8_BAR __builtin_amdgcn_s_barrier()
; #define PG8_SCHED __builtin_amdgcn_sched_barrier(0)
; template <class Epi, class Sched>
; __device__ __forceinline__ void gemm_phase(LAS unsigned char* lds, const Gemm g, const Sched& S, const Epi& E) {
;     ...
;       PG8_WAIT_L(8); PG8_BAR; PG8_WAIT_L(0); PG8_MMA(0, 0, At, B0); PG8_BAR; PG8_SCHED;
;       PG8_LDB(B1, 1, 1); PG8_STAGE(PG8_SB(1, 0), b3, voffB);
;       PG8_BAR; PG8_WAIT_L(0); PG8_MMA(0, 1, At, B1); PG8_BAR;
;       PG8_LDA(At, 1, 1); PG8_STAGE(PG8_SA(1, 0), a3, voffA);
;       PG8_BAR; PG8_WAIT_L(0); PG8_MMA(1, 0, At, B0); PG8_BAR; PG8_SCHED;
;       PG8_STAGE(PG8_SB(1, 1), b3 + hstep, voffB);
;       PG8_WAIT_V(6); PG8_BAR; PG8_MMA(1, 1, At, B1); PG8_BAR;
;     }
	s_waitcnt lgkmcnt(0)
	s_waitcnt lgkmcnt(0)
	v_mfma_f32_16x16x32_bf16 v[124:127], v[152:155], v[182:185], v[124:127]
	v_mfma_f32_16x16x32_bf16 v[116:119], v[174:177], v[182:185], v[116:119]
	v_mfma_f32_16x16x32_bf16 v[108:111], v[152:155], v[190:193], v[108:111]
	v_mfma_f32_16x16x32_bf16 v[100:103], v[174:177], v[190:193], v[100:103]
	v_mfma_f32_16x16x32_bf16 v[92:95], v[152:155], v[198:201], v[92:95]
	v_mfma_f32_16x16x32_bf16 v[84:87], v[174:177], v[198:201], v[84:87]
	v_mfma_f32_16x16x32_bf16 v[76:79], v[152:155], v[206:209], v[76:79]
	v_mfma_f32_16x16x32_bf16 v[68:71], v[174:177], v[206:209], v[68:71]
	v_mfma_f32_16x16x32_bf16 v[124:127], v[156:159], v[186:189], v[124:127]
	v_mfma_f32_16x16x32_bf16 v[116:119], v[178:181], v[186:189], v[116:119]
	v_mfma_f32_16x16x32_bf16 v[108:111], v[156:159], v[194:197], v[108:111]
	v_mfma_f32_16x16x32_bf16 v[100:103], v[178:181], v[194:197], v[100:103]
	v_mfma_f32_16x16x32_bf16 v[92:95], v[156:159], v[202:205], v[92:95]
	v_mfma_f32_16x16x32_bf16 v[84:87], v[178:181], v[202:205], v[84:87]
	v_mfma_f32_16x16x32_bf16 v[76:79], v[156:159], v[210:213], v[76:79]
	v_mfma_f32_16x16x32_bf16 v[68:71], v[178:181], v[210:213], v[68:71]
	s_barrier
	s_add_i32 s74, 0, 0x1c000
	s_add_i32 s73, s73, s7
	v_add_u32_e32 v151, s74, v141
	s_add_u32 s60, s44, s80
	s_addc_u32 s61, s45, s81
	s_mov_b32 m0, s73
	ds_read_b128 v[226:229], v151
	ds_read_b128 v[232:235], v151 offset:1024
	ds_read_b128 v[236:239], v151 offset:2048
	ds_read_b128 v[240:243], v151 offset:3072
	global_load_lds_dwordx4 v132, s[60:61]
	s_add_i32 m0, s73, 0x2000
	s_nop 0
	global_load_lds_dwordx4 v128, s[60:61]
	s_barrier
	s_waitcnt lgkmcnt(0)
	s_waitcnt lgkmcnt(0)
	v_mfma_f32_16x16x32_bf16 v[120:123], v[226:229], v[182:185], v[120:123]
	v_mfma_f32_16x16x32_bf16 v[112:115], v[236:239], v[182:185], v[112:115]
	v_mfma_f32_16x16x32_bf16 v[104:107], v[226:229], v[190:193], v[104:107]
	v_mfma_f32_16x16x32_bf16 v[96:99], v[236:239], v[190:193], v[96:99]
	v_mfma_f32_16x16x32_bf16 v[88:91], v[226:229], v[198:201], v[88:91]
	v_mfma_f32_16x16x32_bf16 v[80:83], v[236:239], v[198:201], v[80:83]
	v_mfma_f32_16x16x32_bf16 v[72:75], v[226:229], v[206:209], v[72:75]
	v_mfma_f32_16x16x32_bf16 v[64:67], v[236:239], v[206:209], v[64:67]
	v_mfma_f32_16x16x32_bf16 v[120:123], v[232:235], v[186:189], v[120:123]
	v_mfma_f32_16x16x32_bf16 v[112:115], v[240:243], v[186:189], v[112:115]
	v_mfma_f32_16x16x32_bf16 v[104:107], v[232:235], v[194:197], v[104:107]
	v_mfma_f32_16x16x32_bf16 v[96:99], v[240:243], v[194:197], v[96:99]
	v_mfma_f32_16x16x32_bf16 v[88:91], v[232:235], v[202:205], v[88:91]
	v_mfma_f32_16x16x32_bf16 v[80:83], v[240:243], v[202:205], v[80:83]
	v_mfma_f32_16x16x32_bf16 v[72:75], v[232:235], v[210:213], v[72:75]
	v_mfma_f32_16x16x32_bf16 v[64:67], v[240:243], v[210:213], v[64:67]
	s_mov_b32 m0, s51
	s_add_u32 s66, vcc_lo, s80
	s_addc_u32 s67, vcc_hi, s81
	s_barrier
	ds_read_b128 v[182:185], v150 offset:49152
	ds_read_b128 v[186:189], v150 offset:50176
	ds_read_b128 v[190:193], v150 offset:51200
	ds_read_b128 v[194:197], v150 offset:52224
	ds_read_b128 v[198:201], v150 offset:53248
	ds_read_b128 v[202:205], v150 offset:54272
	ds_read_b128 v[206:209], v150 offset:55296
	ds_read_b128 v[210:213], v150 offset:56320
	global_load_lds_dwordx4 v134, s[66:67]
	s_mov_b32 m0, s62
	s_nop 0
	global_load_lds_dwordx4 v130, s[66:67]
	s_barrier
	s_waitcnt lgkmcnt(0)
	s_waitcnt lgkmcnt(0)
	v_mfma_f32_16x16x32_bf16 v[60:63], v[152:155], v[182:185], v[60:63]
	v_mfma_f32_16x16x32_bf16 v[52:55], v[174:177], v[182:185], v[52:55]
	v_mfma_f32_16x16x32_bf16 v[44:47], v[152:155], v[190:193], v[44:47]
	v_mfma_f32_16x16x32_bf16 v[36:39], v[174:177], v[190:193], v[36:39]
	v_mfma_f32_16x16x32_bf16 v[28:31], v[152:155], v[198:201], v[28:31]
	v_mfma_f32_16x16x32_bf16 v[20:23], v[174:177], v[198:201], v[20:23]
	v_mfma_f32_16x16x32_bf16 v[12:15], v[152:155], v[206:209], v[12:15]
	v_mfma_f32_16x16x32_bf16 v[4:7], v[174:177], v[206:209], v[4:7]
	v_mfma_f32_16x16x32_bf16 v[60:63], v[156:159], v[186:189], v[60:63]
	v_mfma_f32_16x16x32_bf16 v[52:55], v[178:181], v[186:189], v[52:55]
	v_mfma_f32_16x16x32_bf16 v[44:47], v[156:159], v[194:197], v[44:47]
	v_mfma_f32_16x16x32_bf16 v[36:39], v[178:181], v[194:197], v[36:39]
	v_mfma_f32_16x16x32_bf16 v[28:31], v[156:159], v[202:205], v[28:31]
	v_mfma_f32_16x16x32_bf16 v[20:23], v[178:181], v[202:205], v[20:23]
	v_mfma_f32_16x16x32_bf16 v[12:15], v[156:159], v[210:213], v[12:15]
	v_mfma_f32_16x16x32_bf16 v[4:7], v[178:181], v[210:213], v[4:7]
	s_barrier
	s_add_u32 s44, s44, 0x40080
	s_addc_u32 s45, s45, 0
	s_add_i32 s73, s74, s7
	s_mov_b32 m0, s73
	s_nop 0
	global_load_lds_dwordx4 v132, s[44:45]
	s_add_i32 m0, s73, 0x2000
	s_nop 0
	global_load_lds_dwordx4 v128, s[44:45]
	s_waitcnt vmcnt(10)
	s_barrier
	v_mfma_f32_16x16x32_bf16 v[56:59], v[226:229], v[182:185], v[56:59]
	v_mfma_f32_16x16x32_bf16 v[48:51], v[236:239], v[182:185], v[48:51]
	v_mfma_f32_16x16x32_bf16 v[40:43], v[226:229], v[190:193], v[40:43]
	v_mfma_f32_16x16x32_bf16 v[32:35], v[236:239], v[190:193], v[32:35]
	v_mfma_f32_16x16x32_bf16 v[24:27], v[226:229], v[198:201], v[24:27]
	v_mfma_f32_16x16x32_bf16 v[16:19], v[236:239], v[198:201], v[16:19]
	v_mfma_f32_16x16x32_bf16 v[8:11], v[226:229], v[206:209], v[8:11]
	v_mfma_f32_16x16x32_bf16 v[0:3], v[236:239], v[206:209], v[0:3]
	v_mfma_f32_16x16x32_bf16 v[56:59], v[232:235], v[186:189], v[56:59]
	v_mfma_f32_16x16x32_bf16 v[48:51], v[240:243], v[186:189], v[48:51]
	v_mfma_f32_16x16x32_bf16 v[40:43], v[232:235], v[194:197], v[40:43]
	v_mfma_f32_16x16x32_bf16 v[32:35], v[240:243], v[194:197], v[32:35]
	v_mfma_f32_16x16x32_bf16 v[24:27], v[232:235], v[202:205], v[24:27]
	v_mfma_f32_16x16x32_bf16 v[16:19], v[240:243], v[202:205], v[16:19]
	v_mfma_f32_16x16x32_bf16 v[8:11], v[232:235], v[210:213], v[8:11]
	v_mfma_f32_16x16x32_bf16 v[0:3], v[240:243], v[210:213], v[0:3]
	s_add_i32 s72, s72, 2
	s_add_u32 s42, s42, 0x100
	s_addc_u32 s43, s43, 0
	s_add_u32 s71, s71, 0x100
	s_addc_u32 s52, s52, 0
	s_cmp_gt_u32 s72, 13
	s_barrier
	s_cbranch_scc0 .LBB0_208
	s_cmp_lt_u32 s101, 0x100
	s_cbranch_scc0 .Lxa_0
	s_barrier

; #define PG8_STAGE(bufoff, gbase, voff) do { _Pragma("unroll") for (int _i = 0; _i < 2; ++_i) \
;     __builtin_amdgcn_global_load_lds((const unsigned*)((const char*)(gbase) + (voff)[_i]), (LAS unsigned*)(lds + (bufoff) + ldsw + _i * 8192), 16, 0, 0); } while (0)
; #define PG8_LDA(dst, b, h) do { _Pragma("unroll") for (int m = 0; m < 4; ++m) _Pragma("unroll") for (int k = 0; k < 2; ++k) dst[m][k] = *(const LAS bf16x8*)(lds + PG8_SA(b, h) + aoff + m * 2048 + k * 1024); } while (0)
; #define PG8_LDB(dst, b, h) do { _Pragma("unroll") for (int n = 0; n < 2; ++n) _Pragma("unroll") for (int k = 0; k < 2; ++k) dst[n][k] = *(const LAS bf16x8*)(lds + PG8_SB(b, h) + boff + n * 2048 + k * 1024); } while (0)
; #define PG8_MMA(ai, bj, At, Bt) do { __builtin_amdgcn_s_setprio(1); _Pragma("unroll") for (int m = 0; m < 4; ++m) _Pragma("unroll") for (int n = 0; n < 2; ++n) _Pragma("unroll") for (int k = 0; k < 2; ++k) \
;     acc[ai][bj][m][n] = __builtin_amdgcn_mfma_f32_16x16x32_bf16(Bt[n][k], At[m][k], acc[ai][bj][m][n], 0, 0, 0); __builtin_amdgcn_s_setprio(0); } while (0)
; #define PG8_WAIT_L(n) asm volatile("s_waitcnt lgkmcnt(" #n ")" ::: "memory")
; #define PG8_BAR __builtin_amdgcn_s_barrier()
; #define PG8_SCHED __builtin_amdgcn_sched_barrier(0)
; template <class Epi, class Sched>
; __device__ __forceinline__ void gemm_phase(LAS unsigned char* lds, const Gemm g, const Sched& S, const Epi& E) {
;     ...
;       PG8_LDB(B0, 0, 0); PG8_SCHED; PG8_LDA(At, 0, 0); PG8_STAGE(PG8_SA(1, 1), a1 + hstep, voffA);
;       PG8_WAIT_L(8); PG8_BAR; PG8_WAIT_L(0); PG8_MMA(0, 0, At, B0); PG8_BAR; PG8_SCHED;
;       PG8_LDB(B1, 0, 1); PG8_STAGE(PG8_SB(0, 0), b2, voffB);
;       PG8_BAR; PG8_WAIT_L(0); PG8_MMA(0, 1, At, B1); PG8_BAR;
;     ...
;     for (int a = 0; a < 2; ++a)
; #pragma unroll
;       for (int b = 0; b < 2; ++b)
; #pragma unroll
;         for (int m = 0; m < 4; ++m)
; #pragma unroll
;           for (int n = 0; n < 2; ++n) acc[a][b][m][n] = (f32x4){0.f, 0.f, 0.f, 0.f};
.LBB0_280:
	s_add_u32 s48, s48, 0x100
	v_mov_b32_e32 v0, 0
	s_addc_u32 s49, s49, 0
	s_mov_b32 s52, -2
	s_waitcnt lgkmcnt(0)
	v_mov_b32_e32 v1, v0
	v_mov_b64_e32 v[2:3], v[0:1]
	v_mov_b64_e32 v[4:5], v[0:1]
	v_mov_b64_e32 v[6:7], v[0:1]
	v_mov_b64_e32 v[8:9], v[0:1]
	v_mov_b64_e32 v[10:11], v[0:1]
	v_mov_b64_e32 v[12:13], v[0:1]
	v_mov_b64_e32 v[14:15], v[0:1]
	v_mov_b64_e32 v[16:17], v[0:1]
	v_mov_b64_e32 v[18:19], v[0:1]
	v_mov_b64_e32 v[20:21], v[0:1]
	v_mov_b64_e32 v[22:23], v[0:1]
	v_mov_b64_e32 v[24:25], v[0:1]
	v_mov_b64_e32 v[26:27], v[0:1]
	v_mov_b64_e32 v[28:29], v[0:1]
	v_mov_b64_e32 v[30:31], v[0:1]
	v_mov_b64_e32 v[32:33], v[0:1]
	v_mov_b64_e32 v[34:35], v[0:1]
	v_mov_b64_e32 v[36:37], v[0:1]
	v_mov_b64_e32 v[38:39], v[0:1]
	v_mov_b64_e32 v[40:41], v[0:1]
	v_mov_b64_e32 v[42:43], v[0:1]
	v_mov_b64_e32 v[44:45], v[0:1]
	v_mov_b64_e32 v[46:47], v[0:1]
	v_mov_b64_e32 v[48:49], v[0:1]
	v_mov_b64_e32 v[50:51], v[0:1]
	v_mov_b64_e32 v[52:53], v[0:1]
	v_mov_b64_e32 v[54:55], v[0:1]
	v_mov_b64_e32 v[56:57], v[0:1]
	v_mov_b64_e32 v[58:59], v[0:1]
	v_mov_b64_e32 v[60:61], v[0:1]
	v_mov_b64_e32 v[62:63], v[0:1]
	v_mov_b64_e32 v[64:65], v[0:1]
	v_mov_b64_e32 v[66:67], v[0:1]
	v_mov_b64_e32 v[68:69], v[0:1]
	v_mov_b64_e32 v[70:71], v[0:1]
	v_mov_b64_e32 v[72:73], v[0:1]
	v_mov_b64_e32 v[74:75], v[0:1]
	v_mov_b64_e32 v[76:77], v[0:1]
	v_mov_b64_e32 v[78:79], v[0:1]
	v_mov_b64_e32 v[80:81], v[0:1]
	v_mov_b64_e32 v[82:83], v[0:1]
	v_mov_b64_e32 v[84:85], v[0:1]
	v_mov_b64_e32 v[86:87], v[0:1]
	v_mov_b64_e32 v[88:89], v[0:1]
	v_mov_b64_e32 v[90:91], v[0:1]
	v_mov_b64_e32 v[92:93], v[0:1]
	v_mov_b64_e32 v[94:95], v[0:1]
	v_mov_b64_e32 v[96:97], v[0:1]
	v_mov_b64_e32 v[98:99], v[0:1]
	v_mov_b64_e32 v[100:101], v[0:1]
	v_mov_b64_e32 v[102:103], v[0:1]
	v_mov_b64_e32 v[104:105], v[0:1]
	v_mov_b64_e32 v[106:107], v[0:1]
	v_mov_b64_e32 v[108:109], v[0:1]
	v_mov_b64_e32 v[110:111], v[0:1]
	v_mov_b64_e32 v[112:113], v[0:1]
	v_mov_b64_e32 v[114:115], v[0:1]
	v_mov_b64_e32 v[116:117], v[0:1]
	v_mov_b64_e32 v[118:119], v[0:1]
	v_mov_b64_e32 v[120:121], v[0:1]
	v_mov_b64_e32 v[122:123], v[0:1]
	v_mov_b64_e32 v[124:125], v[0:1]
	v_mov_b64_e32 v[126:127], v[0:1]
	s_cmp_eq_u32 s100, 0
	s_cbranch_scc1 .Lxs_e1
	s_barrier
	s_mov_b32 s100, 0
.Lxs_e1:
.LBB0_281:
	s_add_u32 s42, s34, 0x100
	s_addc_u32 s43, s35, 0
	s_add_i32 s72, 0, 0x10000
	v_add_u32_e32 v140, s72, v202
	ds_read_b128 v[128:131], v140
	ds_read_b128 v[132:135], v140 offset:1024
	ds_read_b128 v[136:139], v140 offset:2048
	ds_read_b128 v[140:143], v140 offset:3072
	s_cmp_eq_u32 s52, 40
	s_cselect_b32 vcc_hi, s23, s43
	s_cselect_b32 vcc_lo, s22, s42
	s_cselect_b32 s45, s37, s49
	s_cselect_b32 s44, s36, s48
	s_add_i32 m0, s51, 0xc000
	ds_read_b128 v[144:147], v203
	ds_read_b128 v[148:151], v203 offset:1024
	ds_read_b128 v[152:155], v203 offset:2048
	ds_read_b128 v[186:189], v203 offset:3072
	ds_read_b128 v[190:193], v203 offset:4096
	ds_read_b128 v[194:197], v203 offset:5120
	ds_read_b128 v[198:201], v203 offset:6144
	ds_read_b128 v[204:207], v203 offset:7168
	global_load_lds_dwordx4 v182, s[34:35]
	s_add_i32 m0, s51, 0xe000
	s_nop 0
	global_load_lds_dwordx4 v184, s[34:35]
	s_waitcnt vmcnt(8)
	s_waitcnt lgkmcnt(8)
	s_barrier
	s_waitcnt lgkmcnt(0)
	s_waitcnt lgkmcnt(0)
	v_mfma_f32_16x16x32_bf16 v[124:127], v[128:131], v[144:147], v[124:127]
	v_mfma_f32_16x16x32_bf16 v[120:123], v[136:139], v[144:147], v[120:123]
	v_mfma_f32_16x16x32_bf16 v[108:111], v[128:131], v[152:155], v[108:111]
	v_mfma_f32_16x16x32_bf16 v[104:107], v[136:139], v[152:155], v[104:107]
	v_mfma_f32_16x16x32_bf16 v[92:95], v[128:131], v[190:193], v[92:95]
	v_mfma_f32_16x16x32_bf16 v[88:91], v[136:139], v[190:193], v[88:91]
	v_mfma_f32_16x16x32_bf16 v[76:79], v[128:131], v[198:201], v[76:79]
	v_mfma_f32_16x16x32_bf16 v[72:75], v[136:139], v[198:201], v[72:75]
	v_mfma_f32_16x16x32_bf16 v[124:127], v[132:135], v[148:151], v[124:127]
	v_mfma_f32_16x16x32_bf16 v[120:123], v[140:143], v[148:151], v[120:123]
	v_mfma_f32_16x16x32_bf16 v[108:111], v[132:135], v[186:189], v[108:111]
	v_mfma_f32_16x16x32_bf16 v[104:107], v[140:143], v[186:189], v[104:107]
	v_mfma_f32_16x16x32_bf16 v[92:95], v[132:135], v[194:197], v[92:95]
	v_mfma_f32_16x16x32_bf16 v[88:91], v[140:143], v[194:197], v[88:91]
	v_mfma_f32_16x16x32_bf16 v[76:79], v[132:135], v[204:207], v[76:79]
	v_mfma_f32_16x16x32_bf16 v[72:75], v[140:143], v[204:207], v[72:75]
	s_barrier
	s_add_i32 s73, 0, 0x14000
	s_add_i32 s34, s72, s7
	v_add_u32_e32 v160, s73, v202
	s_mov_b32 m0, s34
	ds_read_b128 v[208:211], v160
	ds_read_b128 v[226:229], v160 offset:1024
	ds_read_b128 v[232:235], v160 offset:2048
	ds_read_b128 v[236:239], v160 offset:3072
	global_load_lds_dwordx4 v174, s[44:45]
	s_add_i32 m0, s34, 0x2000
	s_nop 0
	global_load_lds_dwordx4 v156, s[44:45]
	s_barrier
	s_waitcnt lgkmcnt(0)
	s_waitcnt lgkmcnt(0)
	v_mfma_f32_16x16x32_bf16 v[116:119], v[208:211], v[144:147], v[116:119]
	v_mfma_f32_16x16x32_bf16 v[112:115], v[232:235], v[144:147], v[112:115]
	v_mfma_f32_16x16x32_bf16 v[100:103], v[208:211], v[152:155], v[100:103]
	v_mfma_f32_16x16x32_bf16 v[96:99], v[232:235], v[152:155], v[96:99]
	v_mfma_f32_16x16x32_bf16 v[84:87], v[208:211], v[190:193], v[84:87]
	v_mfma_f32_16x16x32_bf16 v[80:83], v[232:235], v[190:193], v[80:83]
	v_mfma_f32_16x16x32_bf16 v[68:71], v[208:211], v[198:201], v[68:71]
	v_mfma_f32_16x16x32_bf16 v[64:67], v[232:235], v[198:201], v[64:67]
	v_mfma_f32_16x16x32_bf16 v[116:119], v[226:229], v[148:151], v[116:119]
	v_mfma_f32_16x16x32_bf16 v[112:115], v[236:239], v[148:151], v[112:115]
	v_mfma_f32_16x16x32_bf16 v[100:103], v[226:229], v[186:189], v[100:103]
	v_mfma_f32_16x16x32_bf16 v[96:99], v[236:239], v[186:189], v[96:99]
	v_mfma_f32_16x16x32_bf16 v[84:87], v[226:229], v[194:197], v[84:87]
	v_mfma_f32_16x16x32_bf16 v[80:83], v[236:239], v[194:197], v[80:83]
	v_mfma_f32_16x16x32_bf16 v[68:71], v[226:229], v[204:207], v[68:71]
	v_mfma_f32_16x16x32_bf16 v[64:67], v[236:239], v[204:207], v[64:67]
	s_mov_b32 m0, s51
	s_barrier
; #define PG8_STAGE(bufoff, gbase, voff) do { _Pragma("unroll") for (int _i = 0; _i < 2; ++_i) \
;     __builtin_amdgcn_global_load_lds((const unsigned*)((const char*)(gbase) + (voff)[_i]), (LAS unsigned*)(lds + (bufoff) + ldsw + _i * 8192), 16, 0, 0); } while (0)
; #define PG8_LDA(dst, b, h) do { _Pragma("unroll") for (int m = 0; m < 4; ++m) _Pragma("unroll") for (int k = 0; k < 2; ++k) dst[m][k] = *(const LAS bf16x8*)(lds + PG8_SA(b, h) + aoff + m * 2048 + k * 1024); } while (0)
; #define PG8_LDB(dst, b, h) do { _Pragma("unroll") for (int n = 0; n < 2; ++n) _Pragma("unroll") for (int k = 0; k < 2; ++k) dst[n][k] = *(const LAS bf16x8*)(lds + PG8_SB(b, h) + boff + n * 2048 + k * 1024); } while (0)
; #define PG8_MMA(ai, bj, At, Bt) do { __builtin_amdgcn_s_setprio(1); _Pragma("unroll") for (int m = 0; m < 4; ++m) _Pragma("unroll") for (int n = 0; n < 2; ++n) _Pragma("unroll") for (int k = 0; k < 2; ++k) \
;     acc[ai][bj][m][n] = __builtin_amdgcn_mfma_f32_16x16x32_bf16(Bt[n][k], At[m][k], acc[ai][bj][m][n], 0, 0, 0); __builtin_amdgcn_s_setprio(0); } while (0)
; #define PG8_WAIT_V(n) asm volatile("s_waitcnt vmcnt(" #n ")" ::: "memory")
; #define PG8_WAIT_L(n) asm volatile("s_waitcnt lgkmcnt(" #n ")" ::: "memory")
; #define PG8_BAR __builtin_amdgcn_s_barrier()
; #define PG8_SCHED __builtin_amdgcn_sched_barrier(0)
; template <class Epi, class Sched>
; __device__ __forceinline__ void gemm_phase(LAS unsigned char* lds, const Gemm g, const Sched& S, const Epi& E) {
;     ...
;       PG8_LDA(At, 0, 1); PG8_STAGE(PG8_SA(0, 0), a2, voffA);
;       PG8_BAR; PG8_WAIT_L(0); PG8_MMA(1, 0, At, B0); PG8_BAR; PG8_SCHED;
;       PG8_STAGE(PG8_SB(0, 1), b2 + hstep, voffB);
;       PG8_WAIT_V(6); PG8_BAR; PG8_MMA(1, 1, At, B1); PG8_BAR;
;       PG8_LDB(B0, 1, 0); PG8_SCHED; PG8_LDA(At, 1, 0); PG8_STAGE(PG8_SA(0, 1), a2 + hstep, voffA);
;       PG8_WAIT_L(8); PG8_BAR; PG8_WAIT_L(0); PG8_MMA(0, 0, At, B0); PG8_BAR; PG8_SCHED;
	ds_read_b128 v[144:147], v203 offset:16384
	ds_read_b128 v[148:151], v203 offset:17408
	ds_read_b128 v[152:155], v203 offset:18432
	ds_read_b128 v[186:189], v203 offset:19456
	ds_read_b128 v[190:193], v203 offset:20480
	ds_read_b128 v[194:197], v203 offset:21504
	ds_read_b128 v[198:201], v203 offset:22528
	ds_read_b128 v[204:207], v203 offset:23552
	global_load_lds_dwordx4 v176, vcc
	s_mov_b32 m0, s62
	s_nop 0
	global_load_lds_dwordx4 v158, vcc
	s_barrier
	s_waitcnt lgkmcnt(0)
	s_waitcnt lgkmcnt(0)
	v_mfma_f32_16x16x32_bf16 v[60:63], v[128:131], v[144:147], v[60:63]
	v_mfma_f32_16x16x32_bf16 v[56:59], v[136:139], v[144:147], v[56:59]
	v_mfma_f32_16x16x32_bf16 v[44:47], v[128:131], v[152:155], v[44:47]
	v_mfma_f32_16x16x32_bf16 v[40:43], v[136:139], v[152:155], v[40:43]
	v_mfma_f32_16x16x32_bf16 v[28:31], v[128:131], v[190:193], v[28:31]
	v_mfma_f32_16x16x32_bf16 v[24:27], v[136:139], v[190:193], v[24:27]
	v_mfma_f32_16x16x32_bf16 v[12:15], v[128:131], v[198:201], v[12:15]
	v_mfma_f32_16x16x32_bf16 v[8:11], v[136:139], v[198:201], v[8:11]
	v_mfma_f32_16x16x32_bf16 v[60:63], v[132:135], v[148:151], v[60:63]
	v_mfma_f32_16x16x32_bf16 v[56:59], v[140:143], v[148:151], v[56:59]
	v_mfma_f32_16x16x32_bf16 v[44:47], v[132:135], v[186:189], v[44:47]
	v_mfma_f32_16x16x32_bf16 v[40:43], v[140:143], v[186:189], v[40:43]
	v_mfma_f32_16x16x32_bf16 v[28:31], v[132:135], v[194:197], v[28:31]
	v_mfma_f32_16x16x32_bf16 v[24:27], v[140:143], v[194:197], v[24:27]
	v_mfma_f32_16x16x32_bf16 v[12:15], v[132:135], v[204:207], v[12:15]
	v_mfma_f32_16x16x32_bf16 v[8:11], v[140:143], v[204:207], v[8:11]
	s_barrier
	s_add_u32 s34, s44, 0xb0000
	s_addc_u32 s35, s45, 0
	s_add_i32 s72, s73, s7
	s_mov_b32 m0, s72
	s_nop 0
	global_load_lds_dwordx4 v174, s[34:35]
	s_add_i32 m0, s72, 0x2000
	s_nop 0
	global_load_lds_dwordx4 v156, s[34:35]
	s_waitcnt vmcnt(10)
	s_barrier
	v_mfma_f32_16x16x32_bf16 v[52:55], v[208:211], v[144:147], v[52:55]
	v_mfma_f32_16x16x32_bf16 v[48:51], v[232:235], v[144:147], v[48:51]
	v_mfma_f32_16x16x32_bf16 v[36:39], v[208:211], v[152:155], v[36:39]
	v_mfma_f32_16x16x32_bf16 v[32:35], v[232:235], v[152:155], v[32:35]
	v_mfma_f32_16x16x32_bf16 v[20:23], v[208:211], v[190:193], v[20:23]
	v_mfma_f32_16x16x32_bf16 v[16:19], v[232:235], v[190:193], v[16:19]
	v_mfma_f32_16x16x32_bf16 v[4:7], v[208:211], v[198:201], v[4:7]
	v_mfma_f32_16x16x32_bf16 v[0:3], v[232:235], v[198:201], v[0:3]
	v_mfma_f32_16x16x32_bf16 v[52:55], v[226:229], v[148:151], v[52:55]
	v_mfma_f32_16x16x32_bf16 v[48:51], v[236:239], v[148:151], v[48:51]
	v_mfma_f32_16x16x32_bf16 v[36:39], v[226:229], v[186:189], v[36:39]
	v_mfma_f32_16x16x32_bf16 v[32:35], v[236:239], v[186:189], v[32:35]
	v_mfma_f32_16x16x32_bf16 v[20:23], v[226:229], v[194:197], v[20:23]
	v_mfma_f32_16x16x32_bf16 v[16:19], v[236:239], v[194:197], v[16:19]
	v_mfma_f32_16x16x32_bf16 v[4:7], v[226:229], v[204:207], v[4:7]
	v_mfma_f32_16x16x32_bf16 v[0:3], v[236:239], v[204:207], v[0:3]
	s_add_i32 s72, 0, 0x18000
	v_add_u32_e32 v140, s72, v202
	s_barrier
	ds_read_b128 v[128:131], v140
	ds_read_b128 v[132:135], v140 offset:1024
	ds_read_b128 v[136:139], v140 offset:2048
	ds_read_b128 v[140:143], v140 offset:3072
	s_add_u32 s34, vcc_lo, 0xb0000
	s_addc_u32 s35, vcc_hi, 0
	s_mov_b32 m0, s63
	ds_read_b128 v[144:147], v203 offset:32768
	ds_read_b128 v[148:151], v203 offset:33792
	ds_read_b128 v[152:155], v203 offset:34816
	ds_read_b128 v[186:189], v203 offset:35840
	ds_read_b128 v[190:193], v203 offset:36864
	ds_read_b128 v[194:197], v203 offset:37888
	ds_read_b128 v[198:201], v203 offset:38912
	ds_read_b128 v[204:207], v203 offset:39936
	global_load_lds_dwordx4 v176, s[34:35]
	s_mov_b32 m0, s64
	s_nop 0
	global_load_lds_dwordx4 v158, s[34:35]
	s_waitcnt vmcnt(8)
	s_waitcnt lgkmcnt(8)
	s_barrier
	s_waitcnt lgkmcnt(0)
	s_waitcnt lgkmcnt(0)
	v_mfma_f32_16x16x32_bf16 v[124:127], v[128:131], v[144:147], v[124:127]
	v_mfma_f32_16x16x32_bf16 v[120:123], v[136:139], v[144:147], v[120:123]
	v_mfma_f32_16x16x32_bf16 v[108:111], v[128:131], v[152:155], v[108:111]
	v_mfma_f32_16x16x32_bf16 v[104:107], v[136:139], v[152:155], v[104:107]
	v_mfma_f32_16x16x32_bf16 v[92:95], v[128:131], v[190:193], v[92:95]
	v_mfma_f32_16x16x32_bf16 v[88:91], v[136:139], v[190:193], v[88:91]
	v_mfma_f32_16x16x32_bf16 v[76:79], v[128:131], v[198:201], v[76:79]
	v_mfma_f32_16x16x32_bf16 v[72:75], v[136:139], v[198:201], v[72:75]
	v_mfma_f32_16x16x32_bf16 v[124:127], v[132:135], v[148:151], v[124:127]
	v_mfma_f32_16x16x32_bf16 v[120:123], v[140:143], v[148:151], v[120:123]
	v_mfma_f32_16x16x32_bf16 v[108:111], v[132:135], v[186:189], v[108:111]
	v_mfma_f32_16x16x32_bf16 v[104:107], v[140:143], v[186:189], v[104:107]
	v_mfma_f32_16x16x32_bf16 v[92:95], v[132:135], v[194:197], v[92:95]
	v_mfma_f32_16x16x32_bf16 v[88:91], v[140:143], v[194:197], v[88:91]
	v_mfma_f32_16x16x32_bf16 v[76:79], v[132:135], v[204:207], v[76:79]
	v_mfma_f32_16x16x32_bf16 v[72:75], v[140:143], v[204:207], v[72:75]
	s_barrier
; #define PG8_STAGE(bufoff, gbase, voff) do { _Pragma("unroll") for (int _i = 0; _i < 2; ++_i) \
;     __builtin_amdgcn_global_load_lds((const unsigned*)((const char*)(gbase) + (voff)[_i]), (LAS unsigned*)(lds + (bufoff) + ldsw + _i * 8192), 16, 0, 0); } while (0)
; #define PG8_LDA(dst, b, h) do { _Pragma("unroll") for (int m = 0; m < 4; ++m) _Pragma("unroll") for (int k = 0; k < 2; ++k) dst[m][k] = *(const LAS bf16x8*)(lds + PG8_SA(b, h) + aoff + m * 2048 + k * 1024); } while (0)
; #define PG8_LDB(dst, b, h) do { _Pragma("unroll") for (int n = 0; n < 2; ++n) _Pragma("unroll") for (int k = 0; k < 2; ++k) dst[n][k] = *(const LAS bf16x8*)(lds + PG8_SB(b, h) + boff + n * 2048 + k * 1024); } while (0)
; #define PG8_MMA(ai, bj, At, Bt) do { __builtin_amdgcn_s_setprio(1); _Pragma("unroll") for (int m = 0; m < 4; ++m) _Pragma("unroll") for (int n = 0; n < 2; ++n) _Pragma("unroll") for (int k = 0; k < 2; ++k) \
;     acc[ai][bj][m][n] = __builtin_amdgcn_mfma_f32_16x16x32_bf16(Bt[n][k], At[m][k], acc[ai][bj][m][n], 0, 0, 0); __builtin_amdgcn_s_setprio(0); } while (0)
; #define PG8_WAIT_V(n) asm volatile("s_waitcnt vmcnt(" #n ")" ::: "memory")
; #define PG8_WAIT_L(n) asm volatile("s_waitcnt lgkmcnt(" #n ")" ::: "memory")
; #define PG8_BAR __builtin_amdgcn_s_barrier()
; #define PG8_SCHED __builtin_amdgcn_sched_barrier(0)
; template <class Epi, class Sched>
; __device__ __forceinline__ void gemm_phase(LAS unsigned char* lds, const Gemm g, const Sched& S, const Epi& E) {
;     ...
;       PG8_WAIT_L(8); PG8_BAR; PG8_WAIT_L(0); PG8_MMA(0, 0, At, B0); PG8_BAR; PG8_SCHED;
;       PG8_LDB(B1, 1, 1); PG8_STAGE(PG8_SB(1, 0), b3, voffB);
;       PG8_BAR; PG8_WAIT_L(0); PG8_MMA(0, 1, At, B1); PG8_BAR;
;       PG8_LDA(At, 1, 1); PG8_STAGE(PG8_SA(1, 0), a3, voffA);
;       PG8_BAR; PG8_WAIT_L(0); PG8_MMA(1, 0, At, B0); PG8_BAR; PG8_SCHED;
;       PG8_STAGE(PG8_SB(1, 1), b3 + hstep, voffB);
;       PG8_WAIT_V(6); PG8_BAR; PG8_MMA(1, 1, At, B1); PG8_BAR;
;     }
	s_add_i32 s73, 0, 0x1c000
	s_add_i32 s34, s72, s7
	v_add_u32_e32 v160, s73, v202
	s_add_u32 s66, s44, s80
	s_addc_u32 s67, s45, s81
	s_mov_b32 m0, s34
	ds_read_b128 v[208:211], v160
	ds_read_b128 v[226:229], v160 offset:1024
	ds_read_b128 v[232:235], v160 offset:2048
	ds_read_b128 v[236:239], v160 offset:3072
	global_load_lds_dwordx4 v174, s[66:67]
	s_add_i32 m0, s34, 0x2000
	s_nop 0
	global_load_lds_dwordx4 v156, s[66:67]
	s_barrier
	s_waitcnt lgkmcnt(0)
	s_waitcnt lgkmcnt(0)
	v_mfma_f32_16x16x32_bf16 v[116:119], v[208:211], v[144:147], v[116:119]
	v_mfma_f32_16x16x32_bf16 v[112:115], v[232:235], v[144:147], v[112:115]
	v_mfma_f32_16x16x32_bf16 v[100:103], v[208:211], v[152:155], v[100:103]
	v_mfma_f32_16x16x32_bf16 v[96:99], v[232:235], v[152:155], v[96:99]
	v_mfma_f32_16x16x32_bf16 v[84:87], v[208:211], v[190:193], v[84:87]
	v_mfma_f32_16x16x32_bf16 v[80:83], v[232:235], v[190:193], v[80:83]
	v_mfma_f32_16x16x32_bf16 v[68:71], v[208:211], v[198:201], v[68:71]
	v_mfma_f32_16x16x32_bf16 v[64:67], v[232:235], v[198:201], v[64:67]
	v_mfma_f32_16x16x32_bf16 v[116:119], v[226:229], v[148:151], v[116:119]
	v_mfma_f32_16x16x32_bf16 v[112:115], v[236:239], v[148:151], v[112:115]
	v_mfma_f32_16x16x32_bf16 v[100:103], v[226:229], v[186:189], v[100:103]
	v_mfma_f32_16x16x32_bf16 v[96:99], v[236:239], v[186:189], v[96:99]
	v_mfma_f32_16x16x32_bf16 v[84:87], v[226:229], v[194:197], v[84:87]
	v_mfma_f32_16x16x32_bf16 v[80:83], v[236:239], v[194:197], v[80:83]
	v_mfma_f32_16x16x32_bf16 v[68:71], v[226:229], v[204:207], v[68:71]
	v_mfma_f32_16x16x32_bf16 v[64:67], v[236:239], v[204:207], v[64:67]
	s_mov_b32 m0, s65
	s_add_u32 s74, vcc_lo, s80
	s_addc_u32 s75, vcc_hi, s81
	s_barrier
	ds_read_b128 v[144:147], v203 offset:49152
	ds_read_b128 v[148:151], v203 offset:50176
	ds_read_b128 v[152:155], v203 offset:51200
	ds_read_b128 v[186:189], v203 offset:52224
	ds_read_b128 v[190:193], v203 offset:53248
	ds_read_b128 v[194:197], v203 offset:54272
	ds_read_b128 v[198:201], v203 offset:55296
	ds_read_b128 v[204:207], v203 offset:56320
	global_load_lds_dwordx4 v176, s[74:75]
	s_mov_b32 m0, s70
	s_nop 0
	global_load_lds_dwordx4 v158, s[74:75]
	s_barrier
	s_waitcnt lgkmcnt(0)
	s_waitcnt lgkmcnt(0)
	v_mfma_f32_16x16x32_bf16 v[60:63], v[128:131], v[144:147], v[60:63]
	v_mfma_f32_16x16x32_bf16 v[56:59], v[136:139], v[144:147], v[56:59]
	v_mfma_f32_16x16x32_bf16 v[44:47], v[128:131], v[152:155], v[44:47]
	v_mfma_f32_16x16x32_bf16 v[40:43], v[136:139], v[152:155], v[40:43]
	v_mfma_f32_16x16x32_bf16 v[28:31], v[128:131], v[190:193], v[28:31]
	v_mfma_f32_16x16x32_bf16 v[24:27], v[136:139], v[190:193], v[24:27]
	v_mfma_f32_16x16x32_bf16 v[12:15], v[128:131], v[198:201], v[12:15]
	v_mfma_f32_16x16x32_bf16 v[8:11], v[136:139], v[198:201], v[8:11]
	v_mfma_f32_16x16x32_bf16 v[60:63], v[132:135], v[148:151], v[60:63]
	v_mfma_f32_16x16x32_bf16 v[56:59], v[140:143], v[148:151], v[56:59]
	v_mfma_f32_16x16x32_bf16 v[44:47], v[132:135], v[186:189], v[44:47]
	v_mfma_f32_16x16x32_bf16 v[40:43], v[140:143], v[186:189], v[40:43]
	v_mfma_f32_16x16x32_bf16 v[28:31], v[132:135], v[194:197], v[28:31]
	v_mfma_f32_16x16x32_bf16 v[24:27], v[140:143], v[194:197], v[24:27]
	v_mfma_f32_16x16x32_bf16 v[12:15], v[132:135], v[204:207], v[12:15]
	v_mfma_f32_16x16x32_bf16 v[8:11], v[140:143], v[204:207], v[8:11]
	s_barrier
	s_add_u32 s34, s44, 0xb0080
	s_addc_u32 s35, s45, 0
	s_add_i32 s44, s73, s7
	s_mov_b32 m0, s44
	s_nop 0
	global_load_lds_dwordx4 v174, s[34:35]
	s_add_i32 m0, s44, 0x2000
	s_nop 0
	global_load_lds_dwordx4 v156, s[34:35]
	s_waitcnt vmcnt(10)
	s_barrier
	v_mfma_f32_16x16x32_bf16 v[52:55], v[208:211], v[144:147], v[52:55]
	v_mfma_f32_16x16x32_bf16 v[48:51], v[232:235], v[144:147], v[48:51]
	v_mfma_f32_16x16x32_bf16 v[36:39], v[208:211], v[152:155], v[36:39]
	v_mfma_f32_16x16x32_bf16 v[32:35], v[232:235], v[152:155], v[32:35]
	v_mfma_f32_16x16x32_bf16 v[20:23], v[208:211], v[190:193], v[20:23]
	v_mfma_f32_16x16x32_bf16 v[16:19], v[232:235], v[190:193], v[16:19]
	v_mfma_f32_16x16x32_bf16 v[4:7], v[208:211], v[198:201], v[4:7]
	v_mfma_f32_16x16x32_bf16 v[0:3], v[232:235], v[198:201], v[0:3]
	v_mfma_f32_16x16x32_bf16 v[52:55], v[226:229], v[148:151], v[52:55]
	v_mfma_f32_16x16x32_bf16 v[48:51], v[236:239], v[148:151], v[48:51]
	v_mfma_f32_16x16x32_bf16 v[36:39], v[226:229], v[186:189], v[36:39]
	v_mfma_f32_16x16x32_bf16 v[32:35], v[236:239], v[186:189], v[32:35]
	v_mfma_f32_16x16x32_bf16 v[20:23], v[226:229], v[194:197], v[20:23]
	v_mfma_f32_16x16x32_bf16 v[16:19], v[236:239], v[194:197], v[16:19]
	v_mfma_f32_16x16x32_bf16 v[4:7], v[226:229], v[204:207], v[4:7]
	v_mfma_f32_16x16x32_bf16 v[0:3], v[236:239], v[204:207], v[0:3]
	s_add_i32 s52, s52, 2
	s_add_u32 s48, s48, 0x100
	s_addc_u32 s49, s49, 0
	s_cmp_gt_u32 s52, 41
	s_mov_b64 s[34:35], s[42:43]
	s_barrier
	s_cbranch_scc0 .LBB0_281
	s_cmp_lt_u32 s101, 0x100
	s_cbranch_scc0 .Lxa_1
	s_barrier

; #define PG8_STAGE(bufoff, gbase, voff) do { _Pragma("unroll") for (int _i = 0; _i < 2; ++_i) \
;     __builtin_amdgcn_global_load_lds((const unsigned*)((const char*)(gbase) + (voff)[_i]), (LAS unsigned*)(lds + (bufoff) + ldsw + _i * 8192), 16, 0, 0); } while (0)
; #define PG8_LDA(dst, b, h) do { _Pragma("unroll") for (int m = 0; m < 4; ++m) _Pragma("unroll") for (int k = 0; k < 2; ++k) dst[m][k] = *(const LAS bf16x8*)(lds + PG8_SA(b, h) + aoff + m * 2048 + k * 1024); } while (0)
; #define PG8_LDB(dst, b, h) do { _Pragma("unroll") for (int n = 0; n < 2; ++n) _Pragma("unroll") for (int k = 0; k < 2; ++k) dst[n][k] = *(const LAS bf16x8*)(lds + PG8_SB(b, h) + boff + n * 2048 + k * 1024); } while (0)
; #define PG8_MMA(ai, bj, At, Bt) do { __builtin_amdgcn_s_setprio(1); _Pragma("unroll") for (int m = 0; m < 4; ++m) _Pragma("unroll") for (int n = 0; n < 2; ++n) _Pragma("unroll") for (int k = 0; k < 2; ++k) \
;     acc[ai][bj][m][n] = __builtin_amdgcn_mfma_f32_16x16x32_bf16(Bt[n][k], At[m][k], acc[ai][bj][m][n], 0, 0, 0); __builtin_amdgcn_s_setprio(0); } while (0)
; template <class Epi, class Sched>
; __device__ __forceinline__ void gemm_phase(LAS unsigned char* lds, const Gemm g, const Sched& S, const Epi& E) {
;     ...
;     const bool has_next = S.next(ui + 1, nxt);
;     const char* nA = has_next ? (const char*)g.A + (size_t)nxt.pm * tstep : cA; const char* nB = has_next ? (const char*)g.Bt + (size_t)nxt.pn * tstep : cB;
;     for (int t = 0; t < nt; t += 2) {
;       const bool last = (t == nt - 2);
;       const char* a1 = cA + (size_t)(t + 1) * kstep;
;       const char* a2 = last ? nA : cA + (size_t)(t + 2) * kstep; const char* b2 = last ? nB : cB + (size_t)(t + 2) * kstep;
;       const char* a3 = a2 + kstep; const char* b3 = b2 + kstep;
;       if (last && has_next) S.a_ready(nxt);
;       PG8_LDB(B0, 0, 0); PG8_SCHED; PG8_LDA(At, 0, 0); PG8_STAGE(PG8_SA(1, 1), a1 + hstep, voffA);
;       PG8_WAIT_L(8); PG8_BAR; PG8_WAIT_L(0); PG8_MMA(0, 0, At, B0); PG8_BAR; PG8_SCHED;
;       PG8_LDB(B1, 0, 1); PG8_STAGE(PG8_SB(0, 0), b2, voffB);
;       PG8_BAR; PG8_WAIT_L(0); PG8_MMA(0, 1, At, B1); PG8_BAR;
;     ...
;     for (int a = 0; a < 2; ++a)
; #pragma unroll
;       for (int b = 0; b < 2; ++b)
; #pragma unroll
;         for (int m = 0; m < 4; ++m)
; #pragma unroll
;           for (int n = 0; n < 2; ++n) acc[a][b][m][n] = (f32x4){0.f, 0.f, 0.f, 0.f};
.LBB0_366:
	s_ashr_i32 s37, s36, 31
	v_cmp_lt_i64_e32 vcc, s[40:41], v[172:173]
	s_lshl_b64 s[40:41], s[36:37], 19
	s_add_u32 s40, s94, s40
	s_addc_u32 s41, s95, s41
	s_and_b64 s[42:43], vcc, exec
	s_cselect_b32 s37, s41, s35
	s_cselect_b32 s70, s40, s34
	s_ashr_i32 s23, s22, 31
	s_lshl_b64 s[42:43], s[22:23], 19
	v_readlane_b32 s60, v252, 19
	v_readlane_b32 s61, v252, 20
	s_add_u32 s42, s60, s42
	s_addc_u32 s43, s61, s43
	s_and_b64 s[72:73], vcc, exec
	s_cselect_b32 s23, s43, s45
	s_cselect_b32 s71, s42, s44
	s_add_u32 s34, s34, 0x40080
	s_addc_u32 s35, s35, 0
	s_add_u32 s6, s44, 0x100
	v_mov_b32_e32 v0, 0
	s_addc_u32 s52, s45, 0
	s_mov_b32 s72, -2
	v_mov_b32_e32 v1, v0
	v_mov_b64_e32 v[2:3], v[0:1]
	v_mov_b64_e32 v[4:5], v[0:1]
	v_mov_b64_e32 v[6:7], v[0:1]
	v_mov_b64_e32 v[8:9], v[0:1]
	v_mov_b64_e32 v[10:11], v[0:1]
	v_mov_b64_e32 v[12:13], v[0:1]
	v_mov_b64_e32 v[14:15], v[0:1]
	v_mov_b64_e32 v[16:17], v[0:1]
	v_mov_b64_e32 v[18:19], v[0:1]
	v_mov_b64_e32 v[20:21], v[0:1]
	v_mov_b64_e32 v[22:23], v[0:1]
	v_mov_b64_e32 v[24:25], v[0:1]
	v_mov_b64_e32 v[26:27], v[0:1]
	v_mov_b64_e32 v[28:29], v[0:1]
	v_mov_b64_e32 v[30:31], v[0:1]
	v_mov_b64_e32 v[32:33], v[0:1]
	v_mov_b64_e32 v[34:35], v[0:1]
	v_mov_b64_e32 v[36:37], v[0:1]
	v_mov_b64_e32 v[38:39], v[0:1]
	v_mov_b64_e32 v[40:41], v[0:1]
	v_mov_b64_e32 v[42:43], v[0:1]
	v_mov_b64_e32 v[44:45], v[0:1]
	v_mov_b64_e32 v[46:47], v[0:1]
	v_mov_b64_e32 v[48:49], v[0:1]
	v_mov_b64_e32 v[50:51], v[0:1]
	v_mov_b64_e32 v[52:53], v[0:1]
	v_mov_b64_e32 v[54:55], v[0:1]
	v_mov_b64_e32 v[56:57], v[0:1]
	v_mov_b64_e32 v[58:59], v[0:1]
	v_mov_b64_e32 v[60:61], v[0:1]
	v_mov_b64_e32 v[62:63], v[0:1]
	v_mov_b64_e32 v[64:65], v[0:1]
	v_mov_b64_e32 v[66:67], v[0:1]
	v_mov_b64_e32 v[68:69], v[0:1]
	v_mov_b64_e32 v[70:71], v[0:1]
	v_mov_b64_e32 v[72:73], v[0:1]
	v_mov_b64_e32 v[74:75], v[0:1]
	v_mov_b64_e32 v[76:77], v[0:1]
	v_mov_b64_e32 v[78:79], v[0:1]
	v_mov_b64_e32 v[80:81], v[0:1]
	v_mov_b64_e32 v[82:83], v[0:1]
	v_mov_b64_e32 v[84:85], v[0:1]
	v_mov_b64_e32 v[86:87], v[0:1]
	v_mov_b64_e32 v[88:89], v[0:1]
	v_mov_b64_e32 v[90:91], v[0:1]
	v_mov_b64_e32 v[92:93], v[0:1]
	v_mov_b64_e32 v[94:95], v[0:1]
	v_mov_b64_e32 v[96:97], v[0:1]
	v_mov_b64_e32 v[98:99], v[0:1]
	v_mov_b64_e32 v[100:101], v[0:1]
	v_mov_b64_e32 v[102:103], v[0:1]
	v_mov_b64_e32 v[104:105], v[0:1]
	v_mov_b64_e32 v[106:107], v[0:1]
	v_mov_b64_e32 v[108:109], v[0:1]
	v_mov_b64_e32 v[110:111], v[0:1]
	v_mov_b64_e32 v[112:113], v[0:1]
	v_mov_b64_e32 v[114:115], v[0:1]
	v_mov_b64_e32 v[116:117], v[0:1]
	v_mov_b64_e32 v[118:119], v[0:1]
	v_mov_b64_e32 v[120:121], v[0:1]
	v_mov_b64_e32 v[122:123], v[0:1]
	v_mov_b64_e32 v[124:125], v[0:1]
	v_mov_b64_e32 v[126:127], v[0:1]
	s_cmp_eq_u32 s100, 0
	s_cbranch_scc1 .Lxs_e2
	s_barrier
	s_mov_b32 s100, 0
.Lxs_e2:
.LBB0_367:
	s_add_u32 s44, s34, 0xfffc0080
	s_addc_u32 s45, s35, -1
	s_add_i32 s73, 0, 0x10000
	v_add_u32_e32 v140, s73, v183
	ds_read_b128 v[128:131], v140
	ds_read_b128 v[132:135], v140 offset:1024
	ds_read_b128 v[136:139], v140 offset:2048
	ds_read_b128 v[140:143], v140 offset:3072
	s_cmp_eq_u32 s72, 12
	s_cselect_b32 vcc_hi, s37, s45
	s_cselect_b32 vcc_lo, s70, s44
	s_cselect_b32 s45, s23, s52
	s_cselect_b32 s44, s71, s6
	s_add_i32 m0, s12, 0xc000
	ds_read_b128 v[174:177], v185
	ds_read_b128 v[178:181], v185 offset:1024
	ds_read_b128 v[186:189], v185 offset:2048
	ds_read_b128 v[190:193], v185 offset:3072
	ds_read_b128 v[194:197], v185 offset:4096
	ds_read_b128 v[198:201], v185 offset:5120
	ds_read_b128 v[202:205], v185 offset:6144
	ds_read_b128 v[206:209], v185 offset:7168
	global_load_lds_dwordx4 v154, s[34:35]
	s_add_i32 m0, s12, 0xe000
	s_nop 0
	global_load_lds_dwordx4 v156, s[34:35]
	s_waitcnt vmcnt(8)
	s_waitcnt lgkmcnt(8)
	s_barrier
	s_waitcnt lgkmcnt(0)
	s_waitcnt lgkmcnt(0)
	v_mfma_f32_16x16x32_bf16 v[124:127], v[128:131], v[174:177], v[124:127]
	v_mfma_f32_16x16x32_bf16 v[120:123], v[136:139], v[174:177], v[120:123]
	v_mfma_f32_16x16x32_bf16 v[116:119], v[128:131], v[186:189], v[116:119]
	v_mfma_f32_16x16x32_bf16 v[108:111], v[136:139], v[186:189], v[108:111]
	v_mfma_f32_16x16x32_bf16 v[96:99], v[128:131], v[194:197], v[96:99]
	v_mfma_f32_16x16x32_bf16 v[88:91], v[136:139], v[194:197], v[88:91]
	v_mfma_f32_16x16x32_bf16 v[84:87], v[128:131], v[202:205], v[84:87]
	v_mfma_f32_16x16x32_bf16 v[76:79], v[136:139], v[202:205], v[76:79]
	v_mfma_f32_16x16x32_bf16 v[124:127], v[132:135], v[178:181], v[124:127]
	v_mfma_f32_16x16x32_bf16 v[120:123], v[140:143], v[178:181], v[120:123]
	v_mfma_f32_16x16x32_bf16 v[116:119], v[132:135], v[190:193], v[116:119]
	v_mfma_f32_16x16x32_bf16 v[108:111], v[140:143], v[190:193], v[108:111]
	v_mfma_f32_16x16x32_bf16 v[96:99], v[132:135], v[198:201], v[96:99]
	v_mfma_f32_16x16x32_bf16 v[88:91], v[140:143], v[198:201], v[88:91]
	v_mfma_f32_16x16x32_bf16 v[84:87], v[132:135], v[206:209], v[84:87]
	v_mfma_f32_16x16x32_bf16 v[76:79], v[140:143], v[206:209], v[76:79]
	s_barrier
	s_add_i32 s76, 0, 0x14000
	s_add_i32 s73, s73, s7
	v_add_u32_e32 v159, s76, v183
	s_mov_b32 m0, s73
	ds_read_b128 v[210:213], v159
	ds_read_b128 v[226:229], v159 offset:1024
	ds_read_b128 v[232:235], v159 offset:2048
	ds_read_b128 v[236:239], v159 offset:3072
	global_load_lds_dwordx4 v148, s[44:45]
	s_add_i32 m0, s73, 0x2000
	s_nop 0
	global_load_lds_dwordx4 v144, s[44:45]
	s_barrier
; #define PG8_STAGE(bufoff, gbase, voff) do { _Pragma("unroll") for (int _i = 0; _i < 2; ++_i) \
;     __builtin_amdgcn_global_load_lds((const unsigned*)((const char*)(gbase) + (voff)[_i]), (LAS unsigned*)(lds + (bufoff) + ldsw + _i * 8192), 16, 0, 0); } while (0)
; #define PG8_LDA(dst, b, h) do { _Pragma("unroll") for (int m = 0; m < 4; ++m) _Pragma("unroll") for (int k = 0; k < 2; ++k) dst[m][k] = *(const LAS bf16x8*)(lds + PG8_SA(b, h) + aoff + m * 2048 + k * 1024); } while (0)
; #define PG8_LDB(dst, b, h) do { _Pragma("unroll") for (int n = 0; n < 2; ++n) _Pragma("unroll") for (int k = 0; k < 2; ++k) dst[n][k] = *(const LAS bf16x8*)(lds + PG8_SB(b, h) + boff + n * 2048 + k * 1024); } while (0)
; #define PG8_MMA(ai, bj, At, Bt) do { __builtin_amdgcn_s_setprio(1); _Pragma("unroll") for (int m = 0; m < 4; ++m) _Pragma("unroll") for (int n = 0; n < 2; ++n) _Pragma("unroll") for (int k = 0; k < 2; ++k) \
;     acc[ai][bj][m][n] = __builtin_amdgcn_mfma_f32_16x16x32_bf16(Bt[n][k], At[m][k], acc[ai][bj][m][n], 0, 0, 0); __builtin_amdgcn_s_setprio(0); } while (0)
; #define PG8_WAIT_V(n) asm volatile("s_waitcnt vmcnt(" #n ")" ::: "memory")
; #define PG8_WAIT_L(n) asm volatile("s_waitcnt lgkmcnt(" #n ")" ::: "memory")
; #define PG8_BAR __builtin_amdgcn_s_barrier()
; #define PG8_SCHED __builtin_amdgcn_sched_barrier(0)
; template <class Epi, class Sched>
; __device__ __forceinline__ void gemm_phase(LAS unsigned char* lds, const Gemm g, const Sched& S, const Epi& E) {
;     ...
;       PG8_BAR; PG8_WAIT_L(0); PG8_MMA(0, 1, At, B1); PG8_BAR;
;       PG8_LDA(At, 0, 1); PG8_STAGE(PG8_SA(0, 0), a2, voffA);
;       PG8_BAR; PG8_WAIT_L(0); PG8_MMA(1, 0, At, B0); PG8_BAR; PG8_SCHED;
;       PG8_STAGE(PG8_SB(0, 1), b2 + hstep, voffB);
;       PG8_WAIT_V(6); PG8_BAR; PG8_MMA(1, 1, At, B1); PG8_BAR;
;       PG8_LDB(B0, 1, 0); PG8_SCHED; PG8_LDA(At, 1, 0); PG8_STAGE(PG8_SA(0, 1), a2 + hstep, voffA);
;       PG8_WAIT_L(8); PG8_BAR; PG8_WAIT_L(0); PG8_MMA(0, 0, At, B0); PG8_BAR; PG8_SCHED;
	s_waitcnt lgkmcnt(0)
	s_waitcnt lgkmcnt(0)
	v_mfma_f32_16x16x32_bf16 v[112:115], v[210:213], v[174:177], v[112:115]
	v_mfma_f32_16x16x32_bf16 v[104:107], v[232:235], v[174:177], v[104:107]
	v_mfma_f32_16x16x32_bf16 v[100:103], v[210:213], v[186:189], v[100:103]
	v_mfma_f32_16x16x32_bf16 v[92:95], v[232:235], v[186:189], v[92:95]
	v_mfma_f32_16x16x32_bf16 v[80:83], v[210:213], v[194:197], v[80:83]
	v_mfma_f32_16x16x32_bf16 v[72:75], v[232:235], v[194:197], v[72:75]
	v_mfma_f32_16x16x32_bf16 v[68:71], v[210:213], v[202:205], v[68:71]
	v_mfma_f32_16x16x32_bf16 v[64:67], v[232:235], v[202:205], v[64:67]
	v_mfma_f32_16x16x32_bf16 v[112:115], v[226:229], v[178:181], v[112:115]
	v_mfma_f32_16x16x32_bf16 v[104:107], v[236:239], v[178:181], v[104:107]
	v_mfma_f32_16x16x32_bf16 v[100:103], v[226:229], v[190:193], v[100:103]
	v_mfma_f32_16x16x32_bf16 v[92:95], v[236:239], v[190:193], v[92:95]
	v_mfma_f32_16x16x32_bf16 v[80:83], v[226:229], v[198:201], v[80:83]
	v_mfma_f32_16x16x32_bf16 v[72:75], v[236:239], v[198:201], v[72:75]
	v_mfma_f32_16x16x32_bf16 v[68:71], v[226:229], v[206:209], v[68:71]
	v_mfma_f32_16x16x32_bf16 v[64:67], v[236:239], v[206:209], v[64:67]
	s_mov_b32 m0, s12
	s_barrier
	ds_read_b128 v[174:177], v185 offset:16384
	ds_read_b128 v[178:181], v185 offset:17408
	ds_read_b128 v[186:189], v185 offset:18432
	ds_read_b128 v[190:193], v185 offset:19456
	ds_read_b128 v[194:197], v185 offset:20480
	ds_read_b128 v[198:201], v185 offset:21504
	ds_read_b128 v[202:205], v185 offset:22528
	ds_read_b128 v[206:209], v185 offset:23552
	global_load_lds_dwordx4 v150, vcc
	s_mov_b32 m0, s13
	s_nop 0
	global_load_lds_dwordx4 v146, vcc
	s_barrier
	s_waitcnt lgkmcnt(0)
	s_waitcnt lgkmcnt(0)
	v_mfma_f32_16x16x32_bf16 v[60:63], v[128:131], v[174:177], v[60:63]
	v_mfma_f32_16x16x32_bf16 v[56:59], v[136:139], v[174:177], v[56:59]
	v_mfma_f32_16x16x32_bf16 v[52:55], v[128:131], v[186:189], v[52:55]
	v_mfma_f32_16x16x32_bf16 v[44:47], v[136:139], v[186:189], v[44:47]
	v_mfma_f32_16x16x32_bf16 v[32:35], v[128:131], v[194:197], v[32:35]
	v_mfma_f32_16x16x32_bf16 v[24:27], v[136:139], v[194:197], v[24:27]
	v_mfma_f32_16x16x32_bf16 v[20:23], v[128:131], v[202:205], v[20:23]
	v_mfma_f32_16x16x32_bf16 v[12:15], v[136:139], v[202:205], v[12:15]
	v_mfma_f32_16x16x32_bf16 v[60:63], v[132:135], v[178:181], v[60:63]
	v_mfma_f32_16x16x32_bf16 v[56:59], v[140:143], v[178:181], v[56:59]
	v_mfma_f32_16x16x32_bf16 v[52:55], v[132:135], v[190:193], v[52:55]
	v_mfma_f32_16x16x32_bf16 v[44:47], v[140:143], v[190:193], v[44:47]
	v_mfma_f32_16x16x32_bf16 v[32:35], v[132:135], v[198:201], v[32:35]
	v_mfma_f32_16x16x32_bf16 v[24:27], v[140:143], v[198:201], v[24:27]
	v_mfma_f32_16x16x32_bf16 v[20:23], v[132:135], v[206:209], v[20:23]
	v_mfma_f32_16x16x32_bf16 v[12:15], v[140:143], v[206:209], v[12:15]
	s_barrier
	s_add_u32 s74, s44, 0x40000
	s_addc_u32 s75, s45, 0
	s_add_i32 s73, s76, s7
	s_mov_b32 m0, s73
	s_nop 0
	global_load_lds_dwordx4 v148, s[74:75]
	s_add_i32 m0, s73, 0x2000
	s_nop 0
	global_load_lds_dwordx4 v144, s[74:75]
	s_waitcnt vmcnt(10)
	s_barrier
	v_mfma_f32_16x16x32_bf16 v[48:51], v[210:213], v[174:177], v[48:51]
	v_mfma_f32_16x16x32_bf16 v[40:43], v[232:235], v[174:177], v[40:43]
	v_mfma_f32_16x16x32_bf16 v[36:39], v[210:213], v[186:189], v[36:39]
	v_mfma_f32_16x16x32_bf16 v[28:31], v[232:235], v[186:189], v[28:31]
	v_mfma_f32_16x16x32_bf16 v[16:19], v[210:213], v[194:197], v[16:19]
	v_mfma_f32_16x16x32_bf16 v[8:11], v[232:235], v[194:197], v[8:11]
	v_mfma_f32_16x16x32_bf16 v[4:7], v[210:213], v[202:205], v[4:7]
	v_mfma_f32_16x16x32_bf16 v[0:3], v[232:235], v[202:205], v[0:3]
	v_mfma_f32_16x16x32_bf16 v[48:51], v[226:229], v[178:181], v[48:51]
	v_mfma_f32_16x16x32_bf16 v[40:43], v[236:239], v[178:181], v[40:43]
	v_mfma_f32_16x16x32_bf16 v[36:39], v[226:229], v[190:193], v[36:39]
	v_mfma_f32_16x16x32_bf16 v[28:31], v[236:239], v[190:193], v[28:31]
	v_mfma_f32_16x16x32_bf16 v[16:19], v[226:229], v[198:201], v[16:19]
	v_mfma_f32_16x16x32_bf16 v[8:11], v[236:239], v[198:201], v[8:11]
	v_mfma_f32_16x16x32_bf16 v[4:7], v[226:229], v[206:209], v[4:7]
	v_mfma_f32_16x16x32_bf16 v[0:3], v[236:239], v[206:209], v[0:3]
	s_add_i32 s73, 0, 0x18000
	v_add_u32_e32 v140, s73, v183
	s_barrier
	ds_read_b128 v[128:131], v140
	ds_read_b128 v[132:135], v140 offset:1024
	ds_read_b128 v[136:139], v140 offset:2048
	ds_read_b128 v[140:143], v140 offset:3072
	s_add_u32 s74, vcc_lo, 0x40000
	s_addc_u32 s75, vcc_hi, 0
	s_mov_b32 m0, s20
	ds_read_b128 v[174:177], v185 offset:32768
	ds_read_b128 v[178:181], v185 offset:33792
	ds_read_b128 v[186:189], v185 offset:34816
	ds_read_b128 v[190:193], v185 offset:35840
	ds_read_b128 v[194:197], v185 offset:36864
	ds_read_b128 v[198:201], v185 offset:37888
	ds_read_b128 v[202:205], v185 offset:38912
	ds_read_b128 v[206:209], v185 offset:39936
	global_load_lds_dwordx4 v150, s[74:75]
	s_mov_b32 m0, s48
	s_nop 0
	global_load_lds_dwordx4 v146, s[74:75]
	s_waitcnt vmcnt(8)
	s_waitcnt lgkmcnt(8)
	s_barrier
; #define PG8_STAGE(bufoff, gbase, voff) do { _Pragma("unroll") for (int _i = 0; _i < 2; ++_i) \
;     __builtin_amdgcn_global_load_lds((const unsigned*)((const char*)(gbase) + (voff)[_i]), (LAS unsigned*)(lds + (bufoff) + ldsw + _i * 8192), 16, 0, 0); } while (0)
; #define PG8_LDA(dst, b, h) do { _Pragma("unroll") for (int m = 0; m < 4; ++m) _Pragma("unroll") for (int k = 0; k < 2; ++k) dst[m][k] = *(const LAS bf16x8*)(lds + PG8_SA(b, h) + aoff + m * 2048 + k * 1024); } while (0)
; #define PG8_LDB(dst, b, h) do { _Pragma("unroll") for (int n = 0; n < 2; ++n) _Pragma("unroll") for (int k = 0; k < 2; ++k) dst[n][k] = *(const LAS bf16x8*)(lds + PG8_SB(b, h) + boff + n * 2048 + k * 1024); } while (0)
; #define PG8_MMA(ai, bj, At, Bt) do { __builtin_amdgcn_s_setprio(1); _Pragma("unroll") for (int m = 0; m < 4; ++m) _Pragma("unroll") for (int n = 0; n < 2; ++n) _Pragma("unroll") for (int k = 0; k < 2; ++k) \
;     acc[ai][bj][m][n] = __builtin_amdgcn_mfma_f32_16x16x32_bf16(Bt[n][k], At[m][k], acc[ai][bj][m][n], 0, 0, 0); __builtin_amdgcn_s_setprio(0); } while (0)
; #define PG8_WAIT_V(n) asm volatile("s_waitcnt vmcnt(" #n ")" ::: "memory")
; #define PG8_WAIT_L(n) asm volatile("s_waitcnt lgkmcnt(" #n ")" ::: "memory")
; #define PG8_BAR __builtin_amdgcn_s_barrier()
; #define PG8_SCHED __builtin_amdgcn_sched_barrier(0)
; template <class Epi, class Sched>
; __device__ __forceinline__ void gemm_phase(LAS unsigned char* lds, const Gemm g, const Sched& S, const Epi& E) {
;     ...
;       PG8_WAIT_L(8); PG8_BAR; PG8_WAIT_L(0); PG8_MMA(0, 0, At, B0); PG8_BAR; PG8_SCHED;
;       PG8_LDB(B1, 1, 1); PG8_STAGE(PG8_SB(1, 0), b3, voffB);
;       PG8_BAR; PG8_WAIT_L(0); PG8_MMA(0, 1, At, B1); PG8_BAR;
;       PG8_LDA(At, 1, 1); PG8_STAGE(PG8_SA(1, 0), a3, voffA);
;       PG8_BAR; PG8_WAIT_L(0); PG8_MMA(1, 0, At, B0); PG8_BAR; PG8_SCHED;
;       PG8_STAGE(PG8_SB(1, 1), b3 + hstep, voffB);
;       PG8_WAIT_V(6); PG8_BAR; PG8_MMA(1, 1, At, B1); PG8_BAR;
;     }
	s_waitcnt lgkmcnt(0)
	s_waitcnt lgkmcnt(0)
	v_mfma_f32_16x16x32_bf16 v[124:127], v[128:131], v[174:177], v[124:127]
	v_mfma_f32_16x16x32_bf16 v[120:123], v[136:139], v[174:177], v[120:123]
	v_mfma_f32_16x16x32_bf16 v[116:119], v[128:131], v[186:189], v[116:119]
	v_mfma_f32_16x16x32_bf16 v[108:111], v[136:139], v[186:189], v[108:111]
	v_mfma_f32_16x16x32_bf16 v[96:99], v[128:131], v[194:197], v[96:99]
	v_mfma_f32_16x16x32_bf16 v[88:91], v[136:139], v[194:197], v[88:91]
	v_mfma_f32_16x16x32_bf16 v[84:87], v[128:131], v[202:205], v[84:87]
	v_mfma_f32_16x16x32_bf16 v[76:79], v[136:139], v[202:205], v[76:79]
	v_mfma_f32_16x16x32_bf16 v[124:127], v[132:135], v[178:181], v[124:127]
	v_mfma_f32_16x16x32_bf16 v[120:123], v[140:143], v[178:181], v[120:123]
	v_mfma_f32_16x16x32_bf16 v[116:119], v[132:135], v[190:193], v[116:119]
	v_mfma_f32_16x16x32_bf16 v[108:111], v[140:143], v[190:193], v[108:111]
	v_mfma_f32_16x16x32_bf16 v[96:99], v[132:135], v[198:201], v[96:99]
	v_mfma_f32_16x16x32_bf16 v[88:91], v[140:143], v[198:201], v[88:91]
	v_mfma_f32_16x16x32_bf16 v[84:87], v[132:135], v[206:209], v[84:87]
	v_mfma_f32_16x16x32_bf16 v[76:79], v[140:143], v[206:209], v[76:79]
	s_barrier
	s_add_i32 s74, 0, 0x1c000
	s_add_i32 s73, s73, s7
	v_add_u32_e32 v159, s74, v183
	s_add_u32 s60, s44, s80
	s_addc_u32 s61, s45, s81
	s_mov_b32 m0, s73
	ds_read_b128 v[210:213], v159
	ds_read_b128 v[226:229], v159 offset:1024
	ds_read_b128 v[232:235], v159 offset:2048
	ds_read_b128 v[236:239], v159 offset:3072
	global_load_lds_dwordx4 v148, s[60:61]
	s_add_i32 m0, s73, 0x2000
	s_nop 0
	global_load_lds_dwordx4 v144, s[60:61]
	s_barrier
	s_waitcnt lgkmcnt(0)
	s_waitcnt lgkmcnt(0)
	v_mfma_f32_16x16x32_bf16 v[112:115], v[210:213], v[174:177], v[112:115]
	v_mfma_f32_16x16x32_bf16 v[104:107], v[232:235], v[174:177], v[104:107]
	v_mfma_f32_16x16x32_bf16 v[100:103], v[210:213], v[186:189], v[100:103]
	v_mfma_f32_16x16x32_bf16 v[92:95], v[232:235], v[186:189], v[92:95]
	v_mfma_f32_16x16x32_bf16 v[80:83], v[210:213], v[194:197], v[80:83]
	v_mfma_f32_16x16x32_bf16 v[72:75], v[232:235], v[194:197], v[72:75]
	v_mfma_f32_16x16x32_bf16 v[68:71], v[210:213], v[202:205], v[68:71]
	v_mfma_f32_16x16x32_bf16 v[64:67], v[232:235], v[202:205], v[64:67]
	v_mfma_f32_16x16x32_bf16 v[112:115], v[226:229], v[178:181], v[112:115]
	v_mfma_f32_16x16x32_bf16 v[104:107], v[236:239], v[178:181], v[104:107]
	v_mfma_f32_16x16x32_bf16 v[100:103], v[226:229], v[190:193], v[100:103]
	v_mfma_f32_16x16x32_bf16 v[92:95], v[236:239], v[190:193], v[92:95]
	v_mfma_f32_16x16x32_bf16 v[80:83], v[226:229], v[198:201], v[80:83]
	v_mfma_f32_16x16x32_bf16 v[72:75], v[236:239], v[198:201], v[72:75]
	v_mfma_f32_16x16x32_bf16 v[68:71], v[226:229], v[206:209], v[68:71]
	v_mfma_f32_16x16x32_bf16 v[64:67], v[236:239], v[206:209], v[64:67]
	s_mov_b32 m0, s49
	s_add_u32 s98, vcc_lo, s80
	s_addc_u32 s99, vcc_hi, s81
	s_barrier
	ds_read_b128 v[174:177], v185 offset:49152
	ds_read_b128 v[178:181], v185 offset:50176
	ds_read_b128 v[186:189], v185 offset:51200
	ds_read_b128 v[190:193], v185 offset:52224
	ds_read_b128 v[194:197], v185 offset:53248
	ds_read_b128 v[198:201], v185 offset:54272
	ds_read_b128 v[202:205], v185 offset:55296
	ds_read_b128 v[206:209], v185 offset:56320
	global_load_lds_dwordx4 v150, s[98:99]
	s_mov_b32 m0, s51
	s_nop 0
	global_load_lds_dwordx4 v146, s[98:99]
	s_barrier
	s_waitcnt lgkmcnt(0)
	s_waitcnt lgkmcnt(0)
	v_mfma_f32_16x16x32_bf16 v[60:63], v[128:131], v[174:177], v[60:63]
	v_mfma_f32_16x16x32_bf16 v[56:59], v[136:139], v[174:177], v[56:59]
	v_mfma_f32_16x16x32_bf16 v[52:55], v[128:131], v[186:189], v[52:55]
	v_mfma_f32_16x16x32_bf16 v[44:47], v[136:139], v[186:189], v[44:47]
	v_mfma_f32_16x16x32_bf16 v[32:35], v[128:131], v[194:197], v[32:35]
	v_mfma_f32_16x16x32_bf16 v[24:27], v[136:139], v[194:197], v[24:27]
	v_mfma_f32_16x16x32_bf16 v[20:23], v[128:131], v[202:205], v[20:23]
	v_mfma_f32_16x16x32_bf16 v[12:15], v[136:139], v[202:205], v[12:15]
	v_mfma_f32_16x16x32_bf16 v[60:63], v[132:135], v[178:181], v[60:63]
	v_mfma_f32_16x16x32_bf16 v[56:59], v[140:143], v[178:181], v[56:59]
	v_mfma_f32_16x16x32_bf16 v[52:55], v[132:135], v[190:193], v[52:55]
	v_mfma_f32_16x16x32_bf16 v[44:47], v[140:143], v[190:193], v[44:47]
	v_mfma_f32_16x16x32_bf16 v[32:35], v[132:135], v[198:201], v[32:35]
	v_mfma_f32_16x16x32_bf16 v[24:27], v[140:143], v[198:201], v[24:27]
	v_mfma_f32_16x16x32_bf16 v[20:23], v[132:135], v[206:209], v[20:23]
	v_mfma_f32_16x16x32_bf16 v[12:15], v[140:143], v[206:209], v[12:15]
	s_barrier
	s_add_u32 s44, s44, 0x40080
	s_addc_u32 s45, s45, 0
	s_add_i32 s73, s74, s7
	s_mov_b32 m0, s73
	s_nop 0
	global_load_lds_dwordx4 v148, s[44:45]
	s_add_i32 m0, s73, 0x2000
	s_nop 0
	global_load_lds_dwordx4 v144, s[44:45]
	s_waitcnt vmcnt(10)
	s_barrier
	v_mfma_f32_16x16x32_bf16 v[48:51], v[210:213], v[174:177], v[48:51]
	v_mfma_f32_16x16x32_bf16 v[40:43], v[232:235], v[174:177], v[40:43]
	v_mfma_f32_16x16x32_bf16 v[36:39], v[210:213], v[186:189], v[36:39]
	v_mfma_f32_16x16x32_bf16 v[28:31], v[232:235], v[186:189], v[28:31]
	v_mfma_f32_16x16x32_bf16 v[16:19], v[210:213], v[194:197], v[16:19]
	v_mfma_f32_16x16x32_bf16 v[8:11], v[232:235], v[194:197], v[8:11]
	v_mfma_f32_16x16x32_bf16 v[4:7], v[210:213], v[202:205], v[4:7]
	v_mfma_f32_16x16x32_bf16 v[0:3], v[232:235], v[202:205], v[0:3]
	v_mfma_f32_16x16x32_bf16 v[48:51], v[226:229], v[178:181], v[48:51]
	v_mfma_f32_16x16x32_bf16 v[40:43], v[236:239], v[178:181], v[40:43]
	v_mfma_f32_16x16x32_bf16 v[36:39], v[226:229], v[190:193], v[36:39]
	v_mfma_f32_16x16x32_bf16 v[28:31], v[236:239], v[190:193], v[28:31]
	v_mfma_f32_16x16x32_bf16 v[16:19], v[226:229], v[198:201], v[16:19]
	v_mfma_f32_16x16x32_bf16 v[8:11], v[236:239], v[198:201], v[8:11]
	v_mfma_f32_16x16x32_bf16 v[4:7], v[226:229], v[206:209], v[4:7]
	v_mfma_f32_16x16x32_bf16 v[0:3], v[236:239], v[206:209], v[0:3]
	s_add_i32 s72, s72, 2
	s_add_u32 s34, s34, 0x100
	s_addc_u32 s35, s35, 0
	s_add_u32 s6, s6, 0x100
	s_addc_u32 s52, s52, 0
	s_cmp_gt_u32 s72, 13
	s_barrier
	s_cbranch_scc0 .LBB0_367
	s_cmp_lt_u32 s101, 0x100
	s_cbranch_scc0 .Lxa_2
	s_barrier

; #define PG8_STAGE(bufoff, gbase, voff) do { _Pragma("unroll") for (int _i = 0; _i < 2; ++_i) \
;     __builtin_amdgcn_global_load_lds((const unsigned*)((const char*)(gbase) + (voff)[_i]), (LAS unsigned*)(lds + (bufoff) + ldsw + _i * 8192), 16, 0, 0); } while (0)
; #define PG8_LDA(dst, b, h) do { _Pragma("unroll") for (int m = 0; m < 4; ++m) _Pragma("unroll") for (int k = 0; k < 2; ++k) dst[m][k] = *(const LAS bf16x8*)(lds + PG8_SA(b, h) + aoff + m * 2048 + k * 1024); } while (0)
; #define PG8_LDB(dst, b, h) do { _Pragma("unroll") for (int n = 0; n < 2; ++n) _Pragma("unroll") for (int k = 0; k < 2; ++k) dst[n][k] = *(const LAS bf16x8*)(lds + PG8_SB(b, h) + boff + n * 2048 + k * 1024); } while (0)
; #define PG8_MMA(ai, bj, At, Bt) do { __builtin_amdgcn_s_setprio(1); _Pragma("unroll") for (int m = 0; m < 4; ++m) _Pragma("unroll") for (int n = 0; n < 2; ++n) _Pragma("unroll") for (int k = 0; k < 2; ++k) \
;     acc[ai][bj][m][n] = __builtin_amdgcn_mfma_f32_16x16x32_bf16(Bt[n][k], At[m][k], acc[ai][bj][m][n], 0, 0, 0); __builtin_amdgcn_s_setprio(0); } while (0)
; #define PG8_WAIT_V(n) asm volatile("s_waitcnt vmcnt(" #n ")" ::: "memory")
; #define PG8_WAIT_L(n) asm volatile("s_waitcnt lgkmcnt(" #n ")" ::: "memory")
; #define PG8_BAR __builtin_amdgcn_s_barrier()
; #define PG8_SCHED __builtin_amdgcn_sched_barrier(0)
; template <class Epi, class Sched>
; __device__ __forceinline__ void gemm_phase(LAS unsigned char* lds, const Gemm g, const Sched& S, const Epi& E) {
;     ...
;       PG8_LDB(B0, 0, 0); PG8_SCHED; PG8_LDA(At, 0, 0); PG8_STAGE(PG8_SA(1, 1), a1 + hstep, voffA);
;       PG8_WAIT_L(8); PG8_BAR; PG8_WAIT_L(0); PG8_MMA(0, 0, At, B0); PG8_BAR; PG8_SCHED;
;       PG8_LDB(B1, 0, 1); PG8_STAGE(PG8_SB(0, 0), b2, voffB);
;       PG8_BAR; PG8_WAIT_L(0); PG8_MMA(0, 1, At, B1); PG8_BAR;
;       PG8_LDA(At, 0, 1); PG8_STAGE(PG8_SA(0, 0), a2, voffA);
;       PG8_BAR; PG8_WAIT_L(0); PG8_MMA(1, 0, At, B0); PG8_BAR; PG8_SCHED;
;       PG8_STAGE(PG8_SB(0, 1), b2 + hstep, voffB);
;       PG8_WAIT_V(6); PG8_BAR; PG8_MMA(1, 1, At, B1); PG8_BAR;
.Lxs_e3:
.LBB0_707:
	s_add_u32 s48, s34, 0xfffc0080
	s_addc_u32 s49, s35, -1
	s_add_i32 s73, 0, 0x10000
	v_add_u32_e32 v140, s73, v201
	ds_read_b128 v[120:123], v140
	ds_read_b128 v[124:127], v140 offset:1024
	ds_read_b128 v[136:139], v140 offset:2048
	ds_read_b128 v[140:143], v140 offset:3072
	s_cmp_eq_u32 s72, 12
	s_cselect_b32 s49, s20, s49
	s_cselect_b32 s48, s45, s48
	s_cselect_b32 vcc_hi, s43, s52
	s_cselect_b32 vcc_lo, s68, s69
	s_add_i32 m0, s65, 0xc000
	ds_read_b128 v[144:147], v203
	ds_read_b128 v[148:151], v203 offset:1024
	ds_read_b128 v[152:155], v203 offset:2048
	ds_read_b128 v[186:189], v203 offset:3072
	ds_read_b128 v[190:193], v203 offset:4096
	ds_read_b128 v[194:197], v203 offset:5120
	ds_read_b128 v[204:207], v203 offset:6144
	ds_read_b128 v[208:211], v203 offset:7168
	global_load_lds_dwordx4 v182, s[34:35]
	s_add_i32 m0, s65, 0xe000
	s_nop 0
	global_load_lds_dwordx4 v184, s[34:35]
	s_waitcnt vmcnt(8)
	s_waitcnt lgkmcnt(8)
	s_barrier
	s_waitcnt lgkmcnt(0)
	s_waitcnt lgkmcnt(0)
	v_mfma_f32_16x16x32_bf16 v[132:135], v[120:123], v[144:147], v[132:135]
	v_mfma_f32_16x16x32_bf16 v[128:131], v[136:139], v[144:147], v[128:131]
	v_mfma_f32_16x16x32_bf16 v[108:111], v[120:123], v[152:155], v[108:111]
	v_mfma_f32_16x16x32_bf16 v[104:107], v[136:139], v[152:155], v[104:107]
	v_mfma_f32_16x16x32_bf16 v[92:95], v[120:123], v[190:193], v[92:95]
	v_mfma_f32_16x16x32_bf16 v[88:91], v[136:139], v[190:193], v[88:91]
	v_mfma_f32_16x16x32_bf16 v[76:79], v[120:123], v[204:207], v[76:79]
	v_mfma_f32_16x16x32_bf16 v[72:75], v[136:139], v[204:207], v[72:75]
	v_mfma_f32_16x16x32_bf16 v[132:135], v[124:127], v[148:151], v[132:135]
	v_mfma_f32_16x16x32_bf16 v[128:131], v[140:143], v[148:151], v[128:131]
	v_mfma_f32_16x16x32_bf16 v[108:111], v[124:127], v[186:189], v[108:111]
	v_mfma_f32_16x16x32_bf16 v[104:107], v[140:143], v[186:189], v[104:107]
	v_mfma_f32_16x16x32_bf16 v[92:95], v[124:127], v[194:197], v[92:95]
	v_mfma_f32_16x16x32_bf16 v[88:91], v[140:143], v[194:197], v[88:91]
	v_mfma_f32_16x16x32_bf16 v[76:79], v[124:127], v[208:211], v[76:79]
	v_mfma_f32_16x16x32_bf16 v[72:75], v[140:143], v[208:211], v[72:75]
	s_barrier
	s_add_i32 s76, 0, 0x14000
	s_add_i32 s73, s73, s64
	v_add_u32_e32 v160, s76, v201
	s_mov_b32 m0, s73
	ds_read_b128 v[226:229], v160
	ds_read_b128 v[232:235], v160 offset:1024
	ds_read_b128 v[236:239], v160 offset:2048
	ds_read_b128 v[240:243], v160 offset:3072
	global_load_lds_dwordx4 v174, vcc
	s_add_i32 m0, s73, 0x2000
	s_nop 0
	global_load_lds_dwordx4 v156, vcc
	s_barrier
	s_waitcnt lgkmcnt(0)
	s_waitcnt lgkmcnt(0)
	v_mfma_f32_16x16x32_bf16 v[116:119], v[226:229], v[144:147], v[116:119]
	v_mfma_f32_16x16x32_bf16 v[112:115], v[236:239], v[144:147], v[112:115]
	v_mfma_f32_16x16x32_bf16 v[100:103], v[226:229], v[152:155], v[100:103]
	v_mfma_f32_16x16x32_bf16 v[96:99], v[236:239], v[152:155], v[96:99]
	v_mfma_f32_16x16x32_bf16 v[84:87], v[226:229], v[190:193], v[84:87]
	v_mfma_f32_16x16x32_bf16 v[80:83], v[236:239], v[190:193], v[80:83]
	v_mfma_f32_16x16x32_bf16 v[68:71], v[226:229], v[204:207], v[68:71]
	v_mfma_f32_16x16x32_bf16 v[64:67], v[236:239], v[204:207], v[64:67]
	v_mfma_f32_16x16x32_bf16 v[116:119], v[232:235], v[148:151], v[116:119]
	v_mfma_f32_16x16x32_bf16 v[112:115], v[240:243], v[148:151], v[112:115]
	v_mfma_f32_16x16x32_bf16 v[100:103], v[232:235], v[186:189], v[100:103]
	v_mfma_f32_16x16x32_bf16 v[96:99], v[240:243], v[186:189], v[96:99]
	v_mfma_f32_16x16x32_bf16 v[84:87], v[232:235], v[194:197], v[84:87]
	v_mfma_f32_16x16x32_bf16 v[80:83], v[240:243], v[194:197], v[80:83]
	v_mfma_f32_16x16x32_bf16 v[68:71], v[232:235], v[208:211], v[68:71]
	v_mfma_f32_16x16x32_bf16 v[64:67], v[240:243], v[208:211], v[64:67]
	s_mov_b32 m0, s65
	v_lshl_add_u64 v[222:223], s[48:49], 0, v[176:177]
	s_barrier
	ds_read_b128 v[144:147], v203 offset:16384
	ds_read_b128 v[148:151], v203 offset:17408
	ds_read_b128 v[152:155], v203 offset:18432
	ds_read_b128 v[186:189], v203 offset:19456
	ds_read_b128 v[190:193], v203 offset:20480
	ds_read_b128 v[194:197], v203 offset:21504
	ds_read_b128 v[204:207], v203 offset:22528
	ds_read_b128 v[208:211], v203 offset:23552
	global_load_lds_dwordx4 v176, s[48:49]
	v_lshl_add_u64 v[244:245], s[48:49], 0, v[158:159]
	s_mov_b32 m0, s51
	s_nop 0
	global_load_lds_dwordx4 v158, s[48:49]
	s_barrier
	s_waitcnt lgkmcnt(0)
	s_waitcnt lgkmcnt(0)
	v_mfma_f32_16x16x32_bf16 v[60:63], v[120:123], v[144:147], v[60:63]
	v_mfma_f32_16x16x32_bf16 v[56:59], v[136:139], v[144:147], v[56:59]
	v_mfma_f32_16x16x32_bf16 v[44:47], v[120:123], v[152:155], v[44:47]
	v_mfma_f32_16x16x32_bf16 v[40:43], v[136:139], v[152:155], v[40:43]
	v_mfma_f32_16x16x32_bf16 v[28:31], v[120:123], v[190:193], v[28:31]
	v_mfma_f32_16x16x32_bf16 v[24:27], v[136:139], v[190:193], v[24:27]
	v_mfma_f32_16x16x32_bf16 v[12:15], v[120:123], v[204:207], v[12:15]
	v_mfma_f32_16x16x32_bf16 v[8:11], v[136:139], v[204:207], v[8:11]
	v_mfma_f32_16x16x32_bf16 v[60:63], v[124:127], v[148:151], v[60:63]
	v_mfma_f32_16x16x32_bf16 v[56:59], v[140:143], v[148:151], v[56:59]
	v_mfma_f32_16x16x32_bf16 v[44:47], v[124:127], v[186:189], v[44:47]
	v_mfma_f32_16x16x32_bf16 v[40:43], v[140:143], v[186:189], v[40:43]
	v_mfma_f32_16x16x32_bf16 v[28:31], v[124:127], v[194:197], v[28:31]
	v_mfma_f32_16x16x32_bf16 v[24:27], v[140:143], v[194:197], v[24:27]
	v_mfma_f32_16x16x32_bf16 v[12:15], v[124:127], v[208:211], v[12:15]
	v_mfma_f32_16x16x32_bf16 v[8:11], v[140:143], v[208:211], v[8:11]
	s_barrier
	s_add_u32 s74, vcc_lo, 0x40000
	s_addc_u32 s75, vcc_hi, 0
	s_add_i32 s73, s76, s64
	s_mov_b32 m0, s73
	s_nop 0
	global_load_lds_dwordx4 v174, s[74:75]
	s_add_i32 m0, s73, 0x2000
	s_nop 0
	global_load_lds_dwordx4 v156, s[74:75]
	s_waitcnt vmcnt(10)
	s_barrier
; #define PG8_STAGE(bufoff, gbase, voff) do { _Pragma("unroll") for (int _i = 0; _i < 2; ++_i) \
;     __builtin_amdgcn_global_load_lds((const unsigned*)((const char*)(gbase) + (voff)[_i]), (LAS unsigned*)(lds + (bufoff) + ldsw + _i * 8192), 16, 0, 0); } while (0)
; #define PG8_LDA(dst, b, h) do { _Pragma("unroll") for (int m = 0; m < 4; ++m) _Pragma("unroll") for (int k = 0; k < 2; ++k) dst[m][k] = *(const LAS bf16x8*)(lds + PG8_SA(b, h) + aoff + m * 2048 + k * 1024); } while (0)
; #define PG8_LDB(dst, b, h) do { _Pragma("unroll") for (int n = 0; n < 2; ++n) _Pragma("unroll") for (int k = 0; k < 2; ++k) dst[n][k] = *(const LAS bf16x8*)(lds + PG8_SB(b, h) + boff + n * 2048 + k * 1024); } while (0)
; #define PG8_MMA(ai, bj, At, Bt) do { __builtin_amdgcn_s_setprio(1); _Pragma("unroll") for (int m = 0; m < 4; ++m) _Pragma("unroll") for (int n = 0; n < 2; ++n) _Pragma("unroll") for (int k = 0; k < 2; ++k) \
;     acc[ai][bj][m][n] = __builtin_amdgcn_mfma_f32_16x16x32_bf16(Bt[n][k], At[m][k], acc[ai][bj][m][n], 0, 0, 0); __builtin_amdgcn_s_setprio(0); } while (0)
; #define PG8_WAIT_V(n) asm volatile("s_waitcnt vmcnt(" #n ")" ::: "memory")
; #define PG8_WAIT_L(n) asm volatile("s_waitcnt lgkmcnt(" #n ")" ::: "memory")
; #define PG8_BAR __builtin_amdgcn_s_barrier()
; #define PG8_SCHED __builtin_amdgcn_sched_barrier(0)
; template <class Epi, class Sched>
; __device__ __forceinline__ void gemm_phase(LAS unsigned char* lds, const Gemm g, const Sched& S, const Epi& E) {
;     ...
;       PG8_WAIT_V(6); PG8_BAR; PG8_MMA(1, 1, At, B1); PG8_BAR;
;       PG8_LDB(B0, 1, 0); PG8_SCHED; PG8_LDA(At, 1, 0); PG8_STAGE(PG8_SA(0, 1), a2 + hstep, voffA);
;       PG8_WAIT_L(8); PG8_BAR; PG8_WAIT_L(0); PG8_MMA(0, 0, At, B0); PG8_BAR; PG8_SCHED;
;       PG8_LDB(B1, 1, 1); PG8_STAGE(PG8_SB(1, 0), b3, voffB);
	v_mfma_f32_16x16x32_bf16 v[52:55], v[226:229], v[144:147], v[52:55]
	v_mfma_f32_16x16x32_bf16 v[48:51], v[236:239], v[144:147], v[48:51]
	v_mfma_f32_16x16x32_bf16 v[36:39], v[226:229], v[152:155], v[36:39]
	v_mfma_f32_16x16x32_bf16 v[32:35], v[236:239], v[152:155], v[32:35]
	v_mfma_f32_16x16x32_bf16 v[20:23], v[226:229], v[190:193], v[20:23]
	v_mfma_f32_16x16x32_bf16 v[16:19], v[236:239], v[190:193], v[16:19]
	v_mfma_f32_16x16x32_bf16 v[4:7], v[226:229], v[204:207], v[4:7]
	v_mfma_f32_16x16x32_bf16 v[0:3], v[236:239], v[204:207], v[0:3]
	v_mfma_f32_16x16x32_bf16 v[52:55], v[232:235], v[148:151], v[52:55]
	v_mfma_f32_16x16x32_bf16 v[48:51], v[240:243], v[148:151], v[48:51]
	v_mfma_f32_16x16x32_bf16 v[36:39], v[232:235], v[186:189], v[36:39]
	v_mfma_f32_16x16x32_bf16 v[32:35], v[240:243], v[186:189], v[32:35]
	v_mfma_f32_16x16x32_bf16 v[20:23], v[232:235], v[194:197], v[20:23]
	v_mfma_f32_16x16x32_bf16 v[16:19], v[240:243], v[194:197], v[16:19]
	v_mfma_f32_16x16x32_bf16 v[4:7], v[232:235], v[208:211], v[4:7]
	v_mfma_f32_16x16x32_bf16 v[0:3], v[240:243], v[208:211], v[0:3]
	s_add_i32 s73, 0, 0x18000
	v_add_u32_e32 v140, s73, v201
	s_barrier
	ds_read_b128 v[120:123], v140
	ds_read_b128 v[124:127], v140 offset:1024
	ds_read_b128 v[136:139], v140 offset:2048
	ds_read_b128 v[140:143], v140 offset:3072
	s_add_u32 s48, s48, 0x40000
	s_addc_u32 s49, s49, 0
	s_mov_b32 m0, s62
	ds_read_b128 v[144:147], v203 offset:32768
	ds_read_b128 v[148:151], v203 offset:33792
	ds_read_b128 v[152:155], v203 offset:34816
	ds_read_b128 v[186:189], v203 offset:35840
	ds_read_b128 v[190:193], v203 offset:36864
	ds_read_b128 v[194:197], v203 offset:37888
	ds_read_b128 v[204:207], v203 offset:38912
	ds_read_b128 v[208:211], v203 offset:39936
	global_load_lds_dwordx4 v176, s[48:49]
	s_mov_b32 m0, s63
	s_nop 0
	global_load_lds_dwordx4 v158, s[48:49]
	s_waitcnt vmcnt(8)
	s_waitcnt lgkmcnt(8)
	s_barrier
	s_waitcnt lgkmcnt(0)
	s_waitcnt lgkmcnt(0)
	v_mfma_f32_16x16x32_bf16 v[132:135], v[120:123], v[144:147], v[132:135]
	v_mfma_f32_16x16x32_bf16 v[128:131], v[136:139], v[144:147], v[128:131]
	v_mfma_f32_16x16x32_bf16 v[108:111], v[120:123], v[152:155], v[108:111]
	v_mfma_f32_16x16x32_bf16 v[104:107], v[136:139], v[152:155], v[104:107]
	v_mfma_f32_16x16x32_bf16 v[92:95], v[120:123], v[190:193], v[92:95]
	v_mfma_f32_16x16x32_bf16 v[88:91], v[136:139], v[190:193], v[88:91]
	v_mfma_f32_16x16x32_bf16 v[76:79], v[120:123], v[204:207], v[76:79]
	v_mfma_f32_16x16x32_bf16 v[72:75], v[136:139], v[204:207], v[72:75]
	v_mfma_f32_16x16x32_bf16 v[132:135], v[124:127], v[148:151], v[132:135]
	v_mfma_f32_16x16x32_bf16 v[128:131], v[140:143], v[148:151], v[128:131]
	v_mfma_f32_16x16x32_bf16 v[108:111], v[124:127], v[186:189], v[108:111]
	v_mfma_f32_16x16x32_bf16 v[104:107], v[140:143], v[186:189], v[104:107]
	v_mfma_f32_16x16x32_bf16 v[92:95], v[124:127], v[194:197], v[92:95]
	v_mfma_f32_16x16x32_bf16 v[88:91], v[140:143], v[194:197], v[88:91]
	v_mfma_f32_16x16x32_bf16 v[76:79], v[124:127], v[208:211], v[76:79]
	v_mfma_f32_16x16x32_bf16 v[72:75], v[140:143], v[208:211], v[72:75]
	s_barrier
	s_add_i32 s74, 0, 0x1c000
	s_add_i32 s48, s73, s64
	v_add_u32_e32 v160, s74, v201
	s_add_u32 s98, vcc_lo, s80
	s_addc_u32 s99, vcc_hi, s81
	s_mov_b32 m0, s48
	ds_read_b128 v[226:229], v160
	ds_read_b128 v[232:235], v160 offset:1024
	ds_read_b128 v[236:239], v160 offset:2048
	ds_read_b128 v[240:243], v160 offset:3072
	global_load_lds_dwordx4 v174, s[98:99]
	v_lshl_add_u64 v[198:199], v[212:213], 0, s[80:81]
	s_add_i32 m0, s48, 0x2000
	s_nop 0
	global_load_lds_dwordx4 v156, s[98:99]
	s_barrier
; #define PG8_STAGE(bufoff, gbase, voff) do { _Pragma("unroll") for (int _i = 0; _i < 2; ++_i) \
;     __builtin_amdgcn_global_load_lds((const unsigned*)((const char*)(gbase) + (voff)[_i]), (LAS unsigned*)(lds + (bufoff) + ldsw + _i * 8192), 16, 0, 0); } while (0)
; #define PG8_LDA(dst, b, h) do { _Pragma("unroll") for (int m = 0; m < 4; ++m) _Pragma("unroll") for (int k = 0; k < 2; ++k) dst[m][k] = *(const LAS bf16x8*)(lds + PG8_SA(b, h) + aoff + m * 2048 + k * 1024); } while (0)
; #define PG8_MMA(ai, bj, At, Bt) do { __builtin_amdgcn_s_setprio(1); _Pragma("unroll") for (int m = 0; m < 4; ++m) _Pragma("unroll") for (int n = 0; n < 2; ++n) _Pragma("unroll") for (int k = 0; k < 2; ++k) \
;     acc[ai][bj][m][n] = __builtin_amdgcn_mfma_f32_16x16x32_bf16(Bt[n][k], At[m][k], acc[ai][bj][m][n], 0, 0, 0); __builtin_amdgcn_s_setprio(0); } while (0)
; #define PG8_WAIT_V(n) asm volatile("s_waitcnt vmcnt(" #n ")" ::: "memory")
; #define PG8_WAIT_L(n) asm volatile("s_waitcnt lgkmcnt(" #n ")" ::: "memory")
; #define PG8_BAR __builtin_amdgcn_s_barrier()
; #define PG8_SCHED __builtin_amdgcn_sched_barrier(0)
; template <class Epi, class Sched>
; __device__ __forceinline__ void gemm_phase(LAS unsigned char* lds, const Gemm g, const Sched& S, const Epi& E) {
;     ...
;       PG8_BAR; PG8_WAIT_L(0); PG8_MMA(0, 1, At, B1); PG8_BAR;
;       PG8_LDA(At, 1, 1); PG8_STAGE(PG8_SA(1, 0), a3, voffA);
;       PG8_BAR; PG8_WAIT_L(0); PG8_MMA(1, 0, At, B0); PG8_BAR; PG8_SCHED;
;       PG8_STAGE(PG8_SB(1, 1), b3 + hstep, voffB);
;       PG8_WAIT_V(6); PG8_BAR; PG8_MMA(1, 1, At, B1); PG8_BAR;
;     }
	s_waitcnt lgkmcnt(0)
	s_waitcnt lgkmcnt(0)
	v_mfma_f32_16x16x32_bf16 v[116:119], v[226:229], v[144:147], v[116:119]
	v_mfma_f32_16x16x32_bf16 v[112:115], v[236:239], v[144:147], v[112:115]
	v_mfma_f32_16x16x32_bf16 v[100:103], v[226:229], v[152:155], v[100:103]
	v_mfma_f32_16x16x32_bf16 v[96:99], v[236:239], v[152:155], v[96:99]
	v_mfma_f32_16x16x32_bf16 v[84:87], v[226:229], v[190:193], v[84:87]
	v_mfma_f32_16x16x32_bf16 v[80:83], v[236:239], v[190:193], v[80:83]
	v_mfma_f32_16x16x32_bf16 v[68:71], v[226:229], v[204:207], v[68:71]
	v_mfma_f32_16x16x32_bf16 v[64:67], v[236:239], v[204:207], v[64:67]
	v_mfma_f32_16x16x32_bf16 v[116:119], v[232:235], v[148:151], v[116:119]
	v_mfma_f32_16x16x32_bf16 v[112:115], v[240:243], v[148:151], v[112:115]
	v_mfma_f32_16x16x32_bf16 v[100:103], v[232:235], v[186:189], v[100:103]
	v_mfma_f32_16x16x32_bf16 v[96:99], v[240:243], v[186:189], v[96:99]
	v_mfma_f32_16x16x32_bf16 v[84:87], v[232:235], v[194:197], v[84:87]
	v_mfma_f32_16x16x32_bf16 v[80:83], v[240:243], v[194:197], v[80:83]
	v_mfma_f32_16x16x32_bf16 v[68:71], v[232:235], v[208:211], v[68:71]
	v_mfma_f32_16x16x32_bf16 v[64:67], v[240:243], v[208:211], v[64:67]
	s_mov_b32 m0, s70
	v_lshl_add_u64 v[198:199], v[222:223], 0, s[80:81]
	s_barrier
	ds_read_b128 v[144:147], v203 offset:49152
	ds_read_b128 v[148:151], v203 offset:50176
	ds_read_b128 v[152:155], v203 offset:51200
	ds_read_b128 v[186:189], v203 offset:52224
	ds_read_b128 v[190:193], v203 offset:53248
	ds_read_b128 v[194:197], v203 offset:54272
	ds_read_b128 v[204:207], v203 offset:55296
	ds_read_b128 v[208:211], v203 offset:56320
	global_load_lds_dwordx4 v[198:199], off
	v_lshl_add_u64 v[198:199], v[244:245], 0, s[80:81]
	s_mov_b32 m0, s71
	s_nop 0
	global_load_lds_dwordx4 v[198:199], off
	s_barrier
	s_waitcnt lgkmcnt(0)
	s_waitcnt lgkmcnt(0)
	v_mfma_f32_16x16x32_bf16 v[60:63], v[120:123], v[144:147], v[60:63]
	v_mfma_f32_16x16x32_bf16 v[56:59], v[136:139], v[144:147], v[56:59]
	v_mfma_f32_16x16x32_bf16 v[44:47], v[120:123], v[152:155], v[44:47]
	v_mfma_f32_16x16x32_bf16 v[40:43], v[136:139], v[152:155], v[40:43]
	v_mfma_f32_16x16x32_bf16 v[28:31], v[120:123], v[190:193], v[28:31]
	v_mfma_f32_16x16x32_bf16 v[24:27], v[136:139], v[190:193], v[24:27]
	v_mfma_f32_16x16x32_bf16 v[12:15], v[120:123], v[204:207], v[12:15]
	v_mfma_f32_16x16x32_bf16 v[8:11], v[136:139], v[204:207], v[8:11]
	v_mfma_f32_16x16x32_bf16 v[60:63], v[124:127], v[148:151], v[60:63]
	v_mfma_f32_16x16x32_bf16 v[56:59], v[140:143], v[148:151], v[56:59]
	v_mfma_f32_16x16x32_bf16 v[44:47], v[124:127], v[186:189], v[44:47]
	v_mfma_f32_16x16x32_bf16 v[40:43], v[140:143], v[186:189], v[40:43]
	v_mfma_f32_16x16x32_bf16 v[28:31], v[124:127], v[194:197], v[28:31]
	v_mfma_f32_16x16x32_bf16 v[24:27], v[140:143], v[194:197], v[24:27]
	v_mfma_f32_16x16x32_bf16 v[12:15], v[124:127], v[208:211], v[12:15]
	v_mfma_f32_16x16x32_bf16 v[8:11], v[140:143], v[208:211], v[8:11]
	s_barrier
	s_add_u32 s48, vcc_lo, 0x40080
	s_addc_u32 s49, vcc_hi, 0
	s_add_i32 s73, s74, s64
	s_mov_b32 m0, s73
	s_nop 0
	global_load_lds_dwordx4 v174, s[48:49]
	s_add_i32 m0, s73, 0x2000
	s_nop 0
	global_load_lds_dwordx4 v156, s[48:49]
	s_waitcnt vmcnt(10)
	s_barrier
	v_mfma_f32_16x16x32_bf16 v[52:55], v[226:229], v[144:147], v[52:55]
	v_mfma_f32_16x16x32_bf16 v[48:51], v[236:239], v[144:147], v[48:51]
	v_mfma_f32_16x16x32_bf16 v[36:39], v[226:229], v[152:155], v[36:39]
	v_mfma_f32_16x16x32_bf16 v[32:35], v[236:239], v[152:155], v[32:35]
	v_mfma_f32_16x16x32_bf16 v[20:23], v[226:229], v[190:193], v[20:23]
	v_mfma_f32_16x16x32_bf16 v[16:19], v[236:239], v[190:193], v[16:19]
	v_mfma_f32_16x16x32_bf16 v[4:7], v[226:229], v[204:207], v[4:7]
	v_mfma_f32_16x16x32_bf16 v[0:3], v[236:239], v[204:207], v[0:3]
	v_mfma_f32_16x16x32_bf16 v[52:55], v[232:235], v[148:151], v[52:55]
	v_mfma_f32_16x16x32_bf16 v[48:51], v[240:243], v[148:151], v[48:51]
	v_mfma_f32_16x16x32_bf16 v[36:39], v[232:235], v[186:189], v[36:39]
	v_mfma_f32_16x16x32_bf16 v[32:35], v[240:243], v[186:189], v[32:35]
	v_mfma_f32_16x16x32_bf16 v[20:23], v[232:235], v[194:197], v[20:23]
	v_mfma_f32_16x16x32_bf16 v[16:19], v[240:243], v[194:197], v[16:19]
	v_mfma_f32_16x16x32_bf16 v[4:7], v[232:235], v[208:211], v[4:7]
	v_mfma_f32_16x16x32_bf16 v[0:3], v[240:243], v[208:211], v[0:3]
	s_add_i32 s72, s72, 2
	s_add_u32 s34, s34, 0x100
	s_addc_u32 s35, s35, 0
	s_add_u32 s69, s69, 0x100
	s_addc_u32 s52, s52, 0
	s_cmp_gt_u32 s72, 13
	s_barrier
	s_cbranch_scc0 .LBB0_707
	s_cmp_lt_u32 s101, 0x100
	s_cbranch_scc0 .Lxa_3
	s_barrier

; #define PG8_STAGE(bufoff, gbase, voff) do { _Pragma("unroll") for (int _i = 0; _i < 2; ++_i) \
;     __builtin_amdgcn_global_load_lds((const unsigned*)((const char*)(gbase) + (voff)[_i]), (LAS unsigned*)(lds + (bufoff) + ldsw + _i * 8192), 16, 0, 0); } while (0)
; #define PG8_LDA(dst, b, h) do { _Pragma("unroll") for (int m = 0; m < 4; ++m) _Pragma("unroll") for (int k = 0; k < 2; ++k) dst[m][k] = *(const LAS bf16x8*)(lds + PG8_SA(b, h) + aoff + m * 2048 + k * 1024); } while (0)
; #define PG8_LDB(dst, b, h) do { _Pragma("unroll") for (int n = 0; n < 2; ++n) _Pragma("unroll") for (int k = 0; k < 2; ++k) dst[n][k] = *(const LAS bf16x8*)(lds + PG8_SB(b, h) + boff + n * 2048 + k * 1024); } while (0)
; #define PG8_MMA(ai, bj, At, Bt) do { __builtin_amdgcn_s_setprio(1); _Pragma("unroll") for (int m = 0; m < 4; ++m) _Pragma("unroll") for (int n = 0; n < 2; ++n) _Pragma("unroll") for (int k = 0; k < 2; ++k) \
;     acc[ai][bj][m][n] = __builtin_amdgcn_mfma_f32_16x16x32_bf16(Bt[n][k], At[m][k], acc[ai][bj][m][n], 0, 0, 0); __builtin_amdgcn_s_setprio(0); } while (0)
; template <class Epi, class Sched>
; __device__ __forceinline__ void gemm_phase(LAS unsigned char* lds, const Gemm g, const Sched& S, const Epi& E) {
;     ...
;     const bool has_next = S.next(ui + 1, nxt);
;     const char* nA = has_next ? (const char*)g.A + (size_t)nxt.pm * tstep : cA; const char* nB = has_next ? (const char*)g.Bt + (size_t)nxt.pn * tstep : cB;
;     for (int t = 0; t < nt; t += 2) {
;       const bool last = (t == nt - 2);
;       const char* a1 = cA + (size_t)(t + 1) * kstep;
;       const char* a2 = last ? nA : cA + (size_t)(t + 2) * kstep; const char* b2 = last ? nB : cB + (size_t)(t + 2) * kstep;
;       const char* a3 = a2 + kstep; const char* b3 = b2 + kstep;
;       if (last && has_next) S.a_ready(nxt);
;       PG8_LDB(B0, 0, 0); PG8_SCHED; PG8_LDA(At, 0, 0); PG8_STAGE(PG8_SA(1, 1), a1 + hstep, voffA);
;       PG8_WAIT_L(8); PG8_BAR; PG8_WAIT_L(0); PG8_MMA(0, 0, At, B0); PG8_BAR; PG8_SCHED;
;       PG8_LDB(B1, 0, 1); PG8_STAGE(PG8_SB(0, 0), b2, voffB);
;       PG8_BAR; PG8_WAIT_L(0); PG8_MMA(0, 1, At, B1); PG8_BAR;
;     ...
;     for (int a = 0; a < 2; ++a)
; #pragma unroll
;       for (int b = 0; b < 2; ++b)
; #pragma unroll
;         for (int m = 0; m < 4; ++m)
; #pragma unroll
;           for (int n = 0; n < 2; ++n) acc[a][b][m][n] = (f32x4){0.f, 0.f, 0.f, 0.f};
.LBB0_777:
	s_ashr_i32 s37, s36, 31
	v_cmp_lt_i64_e32 vcc, s[40:41], v[166:167]
	s_lshl_b64 s[40:41], s[36:37], 18
	v_readlane_b32 s42, v253, 3
	v_readlane_b32 s43, v253, 4
	s_add_u32 s40, s42, s40
	s_addc_u32 s41, s43, s41
	s_and_b64 s[42:43], vcc, exec
	s_cselect_b32 s37, s41, s35
	s_cselect_b32 s69, s40, s34
	s_ashr_i32 s23, s22, 31
	s_lshl_b64 s[42:43], s[22:23], 18
	v_readlane_b32 s48, v253, 1
	v_readlane_b32 s49, v253, 2
	s_add_u32 s42, s48, s42
	s_addc_u32 s43, s49, s43
	s_and_b64 s[48:49], vcc, exec
	s_cselect_b32 s23, s43, s45
	s_cselect_b32 s70, s42, s44
	s_add_u32 s34, s34, 0x20080
	s_addc_u32 s35, s35, 0
	s_add_u32 s71, s44, 0x100
	v_mov_b32_e32 v0, 0
	s_addc_u32 s52, s45, 0
	s_mov_b32 s72, -2
	v_mov_b32_e32 v1, v0
	v_mov_b64_e32 v[2:3], v[0:1]
	v_mov_b64_e32 v[4:5], v[0:1]
	v_mov_b64_e32 v[6:7], v[0:1]
	v_mov_b64_e32 v[8:9], v[0:1]
	v_mov_b64_e32 v[10:11], v[0:1]
	v_mov_b64_e32 v[12:13], v[0:1]
	v_mov_b64_e32 v[14:15], v[0:1]
	v_mov_b64_e32 v[16:17], v[0:1]
	v_mov_b64_e32 v[18:19], v[0:1]
	v_mov_b64_e32 v[20:21], v[0:1]
	v_mov_b64_e32 v[22:23], v[0:1]
	v_mov_b64_e32 v[24:25], v[0:1]
	v_mov_b64_e32 v[26:27], v[0:1]
	v_mov_b64_e32 v[28:29], v[0:1]
	v_mov_b64_e32 v[30:31], v[0:1]
	v_mov_b64_e32 v[32:33], v[0:1]
	v_mov_b64_e32 v[34:35], v[0:1]
	v_mov_b64_e32 v[36:37], v[0:1]
	v_mov_b64_e32 v[38:39], v[0:1]
	v_mov_b64_e32 v[40:41], v[0:1]
	v_mov_b64_e32 v[42:43], v[0:1]
	v_mov_b64_e32 v[44:45], v[0:1]
	v_mov_b64_e32 v[46:47], v[0:1]
	v_mov_b64_e32 v[48:49], v[0:1]
	v_mov_b64_e32 v[50:51], v[0:1]
	v_mov_b64_e32 v[52:53], v[0:1]
	v_mov_b64_e32 v[54:55], v[0:1]
	v_mov_b64_e32 v[56:57], v[0:1]
	v_mov_b64_e32 v[58:59], v[0:1]
	v_mov_b64_e32 v[60:61], v[0:1]
	v_mov_b64_e32 v[62:63], v[0:1]
	v_mov_b64_e32 v[64:65], v[0:1]
	v_mov_b64_e32 v[66:67], v[0:1]
	v_mov_b64_e32 v[68:69], v[0:1]
	v_mov_b64_e32 v[70:71], v[0:1]
	v_mov_b64_e32 v[72:73], v[0:1]
	v_mov_b64_e32 v[74:75], v[0:1]
	v_mov_b64_e32 v[76:77], v[0:1]
	v_mov_b64_e32 v[78:79], v[0:1]
	v_mov_b64_e32 v[80:81], v[0:1]
	v_mov_b64_e32 v[82:83], v[0:1]
	v_mov_b64_e32 v[84:85], v[0:1]
	v_mov_b64_e32 v[86:87], v[0:1]
	v_mov_b64_e32 v[88:89], v[0:1]
	v_mov_b64_e32 v[90:91], v[0:1]
	v_mov_b64_e32 v[92:93], v[0:1]
	v_mov_b64_e32 v[94:95], v[0:1]
	v_mov_b64_e32 v[96:97], v[0:1]
	v_mov_b64_e32 v[98:99], v[0:1]
	v_mov_b64_e32 v[100:101], v[0:1]
	v_mov_b64_e32 v[102:103], v[0:1]
	v_mov_b64_e32 v[104:105], v[0:1]
	v_mov_b64_e32 v[106:107], v[0:1]
	v_mov_b64_e32 v[108:109], v[0:1]
	v_mov_b64_e32 v[110:111], v[0:1]
	v_mov_b64_e32 v[112:113], v[0:1]
	v_mov_b64_e32 v[114:115], v[0:1]
	v_mov_b64_e32 v[116:117], v[0:1]
	v_mov_b64_e32 v[118:119], v[0:1]
	v_mov_b64_e32 v[120:121], v[0:1]
	v_mov_b64_e32 v[122:123], v[0:1]
	v_mov_b64_e32 v[124:125], v[0:1]
	v_mov_b64_e32 v[126:127], v[0:1]
	s_cmp_eq_u32 s100, 0
	s_cbranch_scc1 .Lxs_e4
	s_barrier
	s_mov_b32 s100, 0
.Lxs_e4:
.LBB0_778:
	s_add_u32 s44, s34, 0xfffe0080
	s_addc_u32 s45, s35, -1
	s_add_i32 s73, 0, 0x10000
	v_add_u32_e32 v150, s73, v177
	ds_read_b128 v[138:141], v150
	ds_read_b128 v[142:145], v150 offset:1024
	ds_read_b128 v[146:149], v150 offset:2048
	ds_read_b128 v[150:153], v150 offset:3072
	s_cmp_eq_u32 s72, 4
	s_cselect_b32 s49, s37, s45
	s_cselect_b32 s48, s69, s44
	s_cselect_b32 s45, s23, s52
	s_cselect_b32 s44, s70, s71
	s_add_i32 m0, s12, 0xc000
	ds_read_b128 v[154:157], v179
	ds_read_b128 v[180:183], v179 offset:1024
	ds_read_b128 v[184:187], v179 offset:2048
	ds_read_b128 v[188:191], v179 offset:3072
	ds_read_b128 v[192:195], v179 offset:4096
	ds_read_b128 v[196:199], v179 offset:5120
	ds_read_b128 v[200:203], v179 offset:6144
	ds_read_b128 v[204:207], v179 offset:7168
	global_load_lds_dwordx4 v134, s[34:35]
	s_add_i32 m0, s12, 0xe000
	s_nop 0
	global_load_lds_dwordx4 v136, s[34:35]
	s_waitcnt vmcnt(8)
	s_waitcnt lgkmcnt(8)
	s_barrier
	s_waitcnt lgkmcnt(0)
	s_waitcnt lgkmcnt(0)
	v_mfma_f32_16x16x32_bf16 v[124:127], v[138:141], v[154:157], v[124:127]
	v_mfma_f32_16x16x32_bf16 v[120:123], v[146:149], v[154:157], v[120:123]
	v_mfma_f32_16x16x32_bf16 v[108:111], v[138:141], v[184:187], v[108:111]
	v_mfma_f32_16x16x32_bf16 v[104:107], v[146:149], v[184:187], v[104:107]
	v_mfma_f32_16x16x32_bf16 v[92:95], v[138:141], v[192:195], v[92:95]
	v_mfma_f32_16x16x32_bf16 v[88:91], v[146:149], v[192:195], v[88:91]
	v_mfma_f32_16x16x32_bf16 v[76:79], v[138:141], v[200:203], v[76:79]
	v_mfma_f32_16x16x32_bf16 v[72:75], v[146:149], v[200:203], v[72:75]
	v_mfma_f32_16x16x32_bf16 v[124:127], v[142:145], v[180:183], v[124:127]
	v_mfma_f32_16x16x32_bf16 v[120:123], v[150:153], v[180:183], v[120:123]
	v_mfma_f32_16x16x32_bf16 v[108:111], v[142:145], v[188:191], v[108:111]
	v_mfma_f32_16x16x32_bf16 v[104:107], v[150:153], v[188:191], v[104:107]
	v_mfma_f32_16x16x32_bf16 v[92:95], v[142:145], v[196:199], v[92:95]
	v_mfma_f32_16x16x32_bf16 v[88:91], v[150:153], v[196:199], v[88:91]
	v_mfma_f32_16x16x32_bf16 v[76:79], v[142:145], v[204:207], v[76:79]
	v_mfma_f32_16x16x32_bf16 v[72:75], v[150:153], v[204:207], v[72:75]
	s_barrier
	s_add_i32 s76, 0, 0x14000
	v_add_u32_e32 v158, s76, v177
	s_add_i32 s73, s73, s7
	ds_read_b128 v[208:211], v158
	ds_read_b128 v[226:229], v158 offset:1024
	ds_read_b128 v[232:235], v158 offset:2048
	ds_read_b128 v[236:239], v158 offset:3072
	v_lshl_add_u64 v[158:159], s[44:45], 0, v[160:161]
	s_mov_b32 m0, s73
	v_lshl_add_u64 v[174:175], s[44:45], 0, v[128:129]
	global_load_lds_dwordx4 v[158:159], off
	s_add_i32 m0, s73, 0x2000
	s_nop 0
	global_load_lds_dwordx4 v[174:175], off
	s_barrier
; #define PG8_STAGE(bufoff, gbase, voff) do { _Pragma("unroll") for (int _i = 0; _i < 2; ++_i) \
;     __builtin_amdgcn_global_load_lds((const unsigned*)((const char*)(gbase) + (voff)[_i]), (LAS unsigned*)(lds + (bufoff) + ldsw + _i * 8192), 16, 0, 0); } while (0)
; #define PG8_LDA(dst, b, h) do { _Pragma("unroll") for (int m = 0; m < 4; ++m) _Pragma("unroll") for (int k = 0; k < 2; ++k) dst[m][k] = *(const LAS bf16x8*)(lds + PG8_SA(b, h) + aoff + m * 2048 + k * 1024); } while (0)
; #define PG8_LDB(dst, b, h) do { _Pragma("unroll") for (int n = 0; n < 2; ++n) _Pragma("unroll") for (int k = 0; k < 2; ++k) dst[n][k] = *(const LAS bf16x8*)(lds + PG8_SB(b, h) + boff + n * 2048 + k * 1024); } while (0)
; #define PG8_MMA(ai, bj, At, Bt) do { __builtin_amdgcn_s_setprio(1); _Pragma("unroll") for (int m = 0; m < 4; ++m) _Pragma("unroll") for (int n = 0; n < 2; ++n) _Pragma("unroll") for (int k = 0; k < 2; ++k) \
;     acc[ai][bj][m][n] = __builtin_amdgcn_mfma_f32_16x16x32_bf16(Bt[n][k], At[m][k], acc[ai][bj][m][n], 0, 0, 0); __builtin_amdgcn_s_setprio(0); } while (0)
; #define PG8_WAIT_V(n) asm volatile("s_waitcnt vmcnt(" #n ")" ::: "memory")
; #define PG8_WAIT_L(n) asm volatile("s_waitcnt lgkmcnt(" #n ")" ::: "memory")
; #define PG8_BAR __builtin_amdgcn_s_barrier()
; #define PG8_SCHED __builtin_amdgcn_sched_barrier(0)
; template <class Epi, class Sched>
; __device__ __forceinline__ void gemm_phase(LAS unsigned char* lds, const Gemm g, const Sched& S, const Epi& E) {
;     ...
;       PG8_BAR; PG8_WAIT_L(0); PG8_MMA(0, 1, At, B1); PG8_BAR;
;       PG8_LDA(At, 0, 1); PG8_STAGE(PG8_SA(0, 0), a2, voffA);
;       PG8_BAR; PG8_WAIT_L(0); PG8_MMA(1, 0, At, B0); PG8_BAR; PG8_SCHED;
;       PG8_STAGE(PG8_SB(0, 1), b2 + hstep, voffB);
;       PG8_WAIT_V(6); PG8_BAR; PG8_MMA(1, 1, At, B1); PG8_BAR;
;       PG8_LDB(B0, 1, 0); PG8_SCHED; PG8_LDA(At, 1, 0); PG8_STAGE(PG8_SA(0, 1), a2 + hstep, voffA);
;       PG8_WAIT_L(8); PG8_BAR; PG8_WAIT_L(0); PG8_MMA(0, 0, At, B0); PG8_BAR; PG8_SCHED;
	s_waitcnt lgkmcnt(0)
	s_waitcnt lgkmcnt(0)
	v_mfma_f32_16x16x32_bf16 v[116:119], v[208:211], v[154:157], v[116:119]
	v_mfma_f32_16x16x32_bf16 v[112:115], v[232:235], v[154:157], v[112:115]
	v_mfma_f32_16x16x32_bf16 v[100:103], v[208:211], v[184:187], v[100:103]
	v_mfma_f32_16x16x32_bf16 v[96:99], v[232:235], v[184:187], v[96:99]
	v_mfma_f32_16x16x32_bf16 v[84:87], v[208:211], v[192:195], v[84:87]
	v_mfma_f32_16x16x32_bf16 v[80:83], v[232:235], v[192:195], v[80:83]
	v_mfma_f32_16x16x32_bf16 v[68:71], v[208:211], v[200:203], v[68:71]
	v_mfma_f32_16x16x32_bf16 v[64:67], v[232:235], v[200:203], v[64:67]
	v_mfma_f32_16x16x32_bf16 v[116:119], v[226:229], v[180:183], v[116:119]
	v_mfma_f32_16x16x32_bf16 v[112:115], v[236:239], v[180:183], v[112:115]
	v_mfma_f32_16x16x32_bf16 v[100:103], v[226:229], v[188:191], v[100:103]
	v_mfma_f32_16x16x32_bf16 v[96:99], v[236:239], v[188:191], v[96:99]
	v_mfma_f32_16x16x32_bf16 v[84:87], v[226:229], v[196:199], v[84:87]
	v_mfma_f32_16x16x32_bf16 v[80:83], v[236:239], v[196:199], v[80:83]
	v_mfma_f32_16x16x32_bf16 v[68:71], v[226:229], v[204:207], v[68:71]
	v_mfma_f32_16x16x32_bf16 v[64:67], v[236:239], v[204:207], v[64:67]
	s_mov_b32 m0, s12
	v_lshl_add_u64 v[212:213], s[48:49], 0, v[132:133]
	s_barrier
	ds_read_b128 v[154:157], v179 offset:16384
	ds_read_b128 v[180:183], v179 offset:17408
	ds_read_b128 v[184:187], v179 offset:18432
	ds_read_b128 v[188:191], v179 offset:19456
	ds_read_b128 v[192:195], v179 offset:20480
	ds_read_b128 v[196:199], v179 offset:21504
	ds_read_b128 v[200:203], v179 offset:22528
	ds_read_b128 v[204:207], v179 offset:23552
	global_load_lds_dwordx4 v132, s[48:49]
	v_lshl_add_u64 v[222:223], s[48:49], 0, v[130:131]
	s_mov_b32 m0, s13
	s_nop 0
	global_load_lds_dwordx4 v130, s[48:49]
	s_barrier
	s_waitcnt lgkmcnt(0)
	s_waitcnt lgkmcnt(0)
	v_mfma_f32_16x16x32_bf16 v[60:63], v[138:141], v[154:157], v[60:63]
	v_mfma_f32_16x16x32_bf16 v[56:59], v[146:149], v[154:157], v[56:59]
	v_mfma_f32_16x16x32_bf16 v[44:47], v[138:141], v[184:187], v[44:47]
	v_mfma_f32_16x16x32_bf16 v[40:43], v[146:149], v[184:187], v[40:43]
	v_mfma_f32_16x16x32_bf16 v[28:31], v[138:141], v[192:195], v[28:31]
	v_mfma_f32_16x16x32_bf16 v[24:27], v[146:149], v[192:195], v[24:27]
	v_mfma_f32_16x16x32_bf16 v[12:15], v[138:141], v[200:203], v[12:15]
	v_mfma_f32_16x16x32_bf16 v[8:11], v[146:149], v[200:203], v[8:11]
	v_mfma_f32_16x16x32_bf16 v[60:63], v[142:145], v[180:183], v[60:63]
	v_mfma_f32_16x16x32_bf16 v[56:59], v[150:153], v[180:183], v[56:59]
	v_mfma_f32_16x16x32_bf16 v[44:47], v[142:145], v[188:191], v[44:47]
	v_mfma_f32_16x16x32_bf16 v[40:43], v[150:153], v[188:191], v[40:43]
	v_mfma_f32_16x16x32_bf16 v[28:31], v[142:145], v[196:199], v[28:31]
	v_mfma_f32_16x16x32_bf16 v[24:27], v[150:153], v[196:199], v[24:27]
	v_mfma_f32_16x16x32_bf16 v[12:15], v[142:145], v[204:207], v[12:15]
	v_mfma_f32_16x16x32_bf16 v[8:11], v[150:153], v[204:207], v[8:11]
	s_barrier
	s_add_u32 s74, s44, 0x20000
	s_addc_u32 s75, s45, 0
	s_add_i32 s73, s76, s7
	s_mov_b32 m0, s73
	s_nop 0
	global_load_lds_dwordx4 v160, s[74:75]
	s_add_i32 m0, s73, 0x2000
	s_nop 0
	global_load_lds_dwordx4 v128, s[74:75]
	s_waitcnt vmcnt(10)
	s_barrier
	v_mfma_f32_16x16x32_bf16 v[52:55], v[208:211], v[154:157], v[52:55]
	v_mfma_f32_16x16x32_bf16 v[48:51], v[232:235], v[154:157], v[48:51]
	v_mfma_f32_16x16x32_bf16 v[36:39], v[208:211], v[184:187], v[36:39]
	v_mfma_f32_16x16x32_bf16 v[32:35], v[232:235], v[184:187], v[32:35]
	v_mfma_f32_16x16x32_bf16 v[20:23], v[208:211], v[192:195], v[20:23]
	v_mfma_f32_16x16x32_bf16 v[16:19], v[232:235], v[192:195], v[16:19]
	v_mfma_f32_16x16x32_bf16 v[4:7], v[208:211], v[200:203], v[4:7]
	v_mfma_f32_16x16x32_bf16 v[0:3], v[232:235], v[200:203], v[0:3]
	v_mfma_f32_16x16x32_bf16 v[52:55], v[226:229], v[180:183], v[52:55]
	v_mfma_f32_16x16x32_bf16 v[48:51], v[236:239], v[180:183], v[48:51]
	v_mfma_f32_16x16x32_bf16 v[36:39], v[226:229], v[188:191], v[36:39]
	v_mfma_f32_16x16x32_bf16 v[32:35], v[236:239], v[188:191], v[32:35]
	v_mfma_f32_16x16x32_bf16 v[20:23], v[226:229], v[196:199], v[20:23]
	v_mfma_f32_16x16x32_bf16 v[16:19], v[236:239], v[196:199], v[16:19]
	v_mfma_f32_16x16x32_bf16 v[4:7], v[226:229], v[204:207], v[4:7]
	v_mfma_f32_16x16x32_bf16 v[0:3], v[236:239], v[204:207], v[0:3]
	s_add_i32 s73, 0, 0x18000
	v_add_u32_e32 v150, s73, v177
	s_barrier
	ds_read_b128 v[138:141], v150
	ds_read_b128 v[142:145], v150 offset:1024
	ds_read_b128 v[146:149], v150 offset:2048
	ds_read_b128 v[150:153], v150 offset:3072
	s_add_u32 s48, s48, 0x20000
	s_addc_u32 s49, s49, 0
	s_mov_b32 m0, s20
	ds_read_b128 v[154:157], v179 offset:32768
	ds_read_b128 v[180:183], v179 offset:33792
	ds_read_b128 v[184:187], v179 offset:34816
	ds_read_b128 v[188:191], v179 offset:35840
	ds_read_b128 v[192:195], v179 offset:36864
	ds_read_b128 v[196:199], v179 offset:37888
	ds_read_b128 v[200:203], v179 offset:38912
	ds_read_b128 v[204:207], v179 offset:39936
	global_load_lds_dwordx4 v132, s[48:49]
	s_mov_b32 m0, s51
	s_nop 0
	global_load_lds_dwordx4 v130, s[48:49]
	s_waitcnt vmcnt(8)
	s_waitcnt lgkmcnt(8)
	s_barrier
; #define PG8_STAGE(bufoff, gbase, voff) do { _Pragma("unroll") for (int _i = 0; _i < 2; ++_i) \
;     __builtin_amdgcn_global_load_lds((const unsigned*)((const char*)(gbase) + (voff)[_i]), (LAS unsigned*)(lds + (bufoff) + ldsw + _i * 8192), 16, 0, 0); } while (0)
; #define PG8_LDA(dst, b, h) do { _Pragma("unroll") for (int m = 0; m < 4; ++m) _Pragma("unroll") for (int k = 0; k < 2; ++k) dst[m][k] = *(const LAS bf16x8*)(lds + PG8_SA(b, h) + aoff + m * 2048 + k * 1024); } while (0)
; #define PG8_LDB(dst, b, h) do { _Pragma("unroll") for (int n = 0; n < 2; ++n) _Pragma("unroll") for (int k = 0; k < 2; ++k) dst[n][k] = *(const LAS bf16x8*)(lds + PG8_SB(b, h) + boff + n * 2048 + k * 1024); } while (0)
; #define PG8_MMA(ai, bj, At, Bt) do { __builtin_amdgcn_s_setprio(1); _Pragma("unroll") for (int m = 0; m < 4; ++m) _Pragma("unroll") for (int n = 0; n < 2; ++n) _Pragma("unroll") for (int k = 0; k < 2; ++k) \
;     acc[ai][bj][m][n] = __builtin_amdgcn_mfma_f32_16x16x32_bf16(Bt[n][k], At[m][k], acc[ai][bj][m][n], 0, 0, 0); __builtin_amdgcn_s_setprio(0); } while (0)
; #define PG8_WAIT_V(n) asm volatile("s_waitcnt vmcnt(" #n ")" ::: "memory")
; #define PG8_WAIT_L(n) asm volatile("s_waitcnt lgkmcnt(" #n ")" ::: "memory")
; #define PG8_BAR __builtin_amdgcn_s_barrier()
; #define PG8_SCHED __builtin_amdgcn_sched_barrier(0)
; template <class Epi, class Sched>
; __device__ __forceinline__ void gemm_phase(LAS unsigned char* lds, const Gemm g, const Sched& S, const Epi& E) {
;     ...
;       PG8_WAIT_L(8); PG8_BAR; PG8_WAIT_L(0); PG8_MMA(0, 0, At, B0); PG8_BAR; PG8_SCHED;
;       PG8_LDB(B1, 1, 1); PG8_STAGE(PG8_SB(1, 0), b3, voffB);
;       PG8_BAR; PG8_WAIT_L(0); PG8_MMA(0, 1, At, B1); PG8_BAR;
;       PG8_LDA(At, 1, 1); PG8_STAGE(PG8_SA(1, 0), a3, voffA);
;       PG8_BAR; PG8_WAIT_L(0); PG8_MMA(1, 0, At, B0); PG8_BAR; PG8_SCHED;
;       PG8_STAGE(PG8_SB(1, 1), b3 + hstep, voffB);
;       PG8_WAIT_V(6); PG8_BAR; PG8_MMA(1, 1, At, B1); PG8_BAR;
;     }
	s_waitcnt lgkmcnt(0)
	s_waitcnt lgkmcnt(0)
	v_mfma_f32_16x16x32_bf16 v[124:127], v[138:141], v[154:157], v[124:127]
	v_mfma_f32_16x16x32_bf16 v[120:123], v[146:149], v[154:157], v[120:123]
	v_mfma_f32_16x16x32_bf16 v[108:111], v[138:141], v[184:187], v[108:111]
	v_mfma_f32_16x16x32_bf16 v[104:107], v[146:149], v[184:187], v[104:107]
	v_mfma_f32_16x16x32_bf16 v[92:95], v[138:141], v[192:195], v[92:95]
	v_mfma_f32_16x16x32_bf16 v[88:91], v[146:149], v[192:195], v[88:91]
	v_mfma_f32_16x16x32_bf16 v[76:79], v[138:141], v[200:203], v[76:79]
	v_mfma_f32_16x16x32_bf16 v[72:75], v[146:149], v[200:203], v[72:75]
	v_mfma_f32_16x16x32_bf16 v[124:127], v[142:145], v[180:183], v[124:127]
	v_mfma_f32_16x16x32_bf16 v[120:123], v[150:153], v[180:183], v[120:123]
	v_mfma_f32_16x16x32_bf16 v[108:111], v[142:145], v[188:191], v[108:111]
	v_mfma_f32_16x16x32_bf16 v[104:107], v[150:153], v[188:191], v[104:107]
	v_mfma_f32_16x16x32_bf16 v[92:95], v[142:145], v[196:199], v[92:95]
	v_mfma_f32_16x16x32_bf16 v[88:91], v[150:153], v[196:199], v[88:91]
	v_mfma_f32_16x16x32_bf16 v[76:79], v[142:145], v[204:207], v[76:79]
	v_mfma_f32_16x16x32_bf16 v[72:75], v[150:153], v[204:207], v[72:75]
	s_barrier
	s_add_i32 s48, 0, 0x1c000
	s_add_i32 s49, s73, s7
	v_add_u32_e32 v225, s48, v177
	s_add_u32 s98, s44, s80
	s_addc_u32 s99, s45, s81
	s_mov_b32 m0, s49
	ds_read_b128 v[208:211], v225
	ds_read_b128 v[226:229], v225 offset:1024
	ds_read_b128 v[232:235], v225 offset:2048
	ds_read_b128 v[236:239], v225 offset:3072
	global_load_lds_dwordx4 v160, s[98:99]
	v_lshl_add_u64 v[158:159], v[174:175], 0, s[80:81]
	s_add_i32 m0, s49, 0x2000
	s_nop 0
	global_load_lds_dwordx4 v128, s[98:99]
	s_barrier
	s_waitcnt lgkmcnt(0)
	s_waitcnt lgkmcnt(0)
	v_mfma_f32_16x16x32_bf16 v[116:119], v[208:211], v[154:157], v[116:119]
	v_mfma_f32_16x16x32_bf16 v[112:115], v[232:235], v[154:157], v[112:115]
	v_mfma_f32_16x16x32_bf16 v[100:103], v[208:211], v[184:187], v[100:103]
	v_mfma_f32_16x16x32_bf16 v[96:99], v[232:235], v[184:187], v[96:99]
	v_mfma_f32_16x16x32_bf16 v[84:87], v[208:211], v[192:195], v[84:87]
	v_mfma_f32_16x16x32_bf16 v[80:83], v[232:235], v[192:195], v[80:83]
	v_mfma_f32_16x16x32_bf16 v[68:71], v[208:211], v[200:203], v[68:71]
	v_mfma_f32_16x16x32_bf16 v[64:67], v[232:235], v[200:203], v[64:67]
	v_mfma_f32_16x16x32_bf16 v[116:119], v[226:229], v[180:183], v[116:119]
	v_mfma_f32_16x16x32_bf16 v[112:115], v[236:239], v[180:183], v[112:115]
	v_mfma_f32_16x16x32_bf16 v[100:103], v[226:229], v[188:191], v[100:103]
	v_mfma_f32_16x16x32_bf16 v[96:99], v[236:239], v[188:191], v[96:99]
	v_mfma_f32_16x16x32_bf16 v[84:87], v[226:229], v[196:199], v[84:87]
	v_mfma_f32_16x16x32_bf16 v[80:83], v[236:239], v[196:199], v[80:83]
	v_mfma_f32_16x16x32_bf16 v[68:71], v[226:229], v[204:207], v[68:71]
	v_mfma_f32_16x16x32_bf16 v[64:67], v[236:239], v[204:207], v[64:67]
	s_mov_b32 m0, s62
	v_lshl_add_u64 v[158:159], v[212:213], 0, s[80:81]
	s_barrier
	ds_read_b128 v[154:157], v179 offset:49152
	ds_read_b128 v[180:183], v179 offset:50176
	ds_read_b128 v[184:187], v179 offset:51200
	ds_read_b128 v[188:191], v179 offset:52224
	ds_read_b128 v[192:195], v179 offset:53248
	ds_read_b128 v[196:199], v179 offset:54272
	ds_read_b128 v[200:203], v179 offset:55296
	ds_read_b128 v[204:207], v179 offset:56320
	global_load_lds_dwordx4 v[158:159], off
	v_lshl_add_u64 v[158:159], v[222:223], 0, s[80:81]
	s_mov_b32 m0, s63
	s_nop 0
	global_load_lds_dwordx4 v[158:159], off
	s_barrier
	s_waitcnt lgkmcnt(0)
	s_waitcnt lgkmcnt(0)
	v_mfma_f32_16x16x32_bf16 v[60:63], v[138:141], v[154:157], v[60:63]
	v_mfma_f32_16x16x32_bf16 v[56:59], v[146:149], v[154:157], v[56:59]
	v_mfma_f32_16x16x32_bf16 v[44:47], v[138:141], v[184:187], v[44:47]
	v_mfma_f32_16x16x32_bf16 v[40:43], v[146:149], v[184:187], v[40:43]
	v_mfma_f32_16x16x32_bf16 v[28:31], v[138:141], v[192:195], v[28:31]
	v_mfma_f32_16x16x32_bf16 v[24:27], v[146:149], v[192:195], v[24:27]
	v_mfma_f32_16x16x32_bf16 v[12:15], v[138:141], v[200:203], v[12:15]
	v_mfma_f32_16x16x32_bf16 v[8:11], v[146:149], v[200:203], v[8:11]
	v_mfma_f32_16x16x32_bf16 v[60:63], v[142:145], v[180:183], v[60:63]
	v_mfma_f32_16x16x32_bf16 v[56:59], v[150:153], v[180:183], v[56:59]
	v_mfma_f32_16x16x32_bf16 v[44:47], v[142:145], v[188:191], v[44:47]
	v_mfma_f32_16x16x32_bf16 v[40:43], v[150:153], v[188:191], v[40:43]
	v_mfma_f32_16x16x32_bf16 v[28:31], v[142:145], v[196:199], v[28:31]
	v_mfma_f32_16x16x32_bf16 v[24:27], v[150:153], v[196:199], v[24:27]
	v_mfma_f32_16x16x32_bf16 v[12:15], v[142:145], v[204:207], v[12:15]
	v_mfma_f32_16x16x32_bf16 v[8:11], v[150:153], v[204:207], v[8:11]
	s_barrier
	s_add_u32 s44, s44, 0x20080
	s_addc_u32 s45, s45, 0
	s_add_i32 s48, s48, s7
	s_mov_b32 m0, s48
	s_nop 0
	global_load_lds_dwordx4 v160, s[44:45]
	s_add_i32 m0, s48, 0x2000
	s_nop 0
	global_load_lds_dwordx4 v128, s[44:45]
	s_waitcnt vmcnt(10)
	s_barrier
	v_mfma_f32_16x16x32_bf16 v[52:55], v[208:211], v[154:157], v[52:55]
	v_mfma_f32_16x16x32_bf16 v[48:51], v[232:235], v[154:157], v[48:51]
	v_mfma_f32_16x16x32_bf16 v[36:39], v[208:211], v[184:187], v[36:39]
	v_mfma_f32_16x16x32_bf16 v[32:35], v[232:235], v[184:187], v[32:35]
	v_mfma_f32_16x16x32_bf16 v[20:23], v[208:211], v[192:195], v[20:23]
	v_mfma_f32_16x16x32_bf16 v[16:19], v[232:235], v[192:195], v[16:19]
	v_mfma_f32_16x16x32_bf16 v[4:7], v[208:211], v[200:203], v[4:7]
	v_mfma_f32_16x16x32_bf16 v[0:3], v[232:235], v[200:203], v[0:3]
	v_mfma_f32_16x16x32_bf16 v[52:55], v[226:229], v[180:183], v[52:55]
	v_mfma_f32_16x16x32_bf16 v[48:51], v[236:239], v[180:183], v[48:51]
	v_mfma_f32_16x16x32_bf16 v[36:39], v[226:229], v[188:191], v[36:39]
	v_mfma_f32_16x16x32_bf16 v[32:35], v[236:239], v[188:191], v[32:35]
	v_mfma_f32_16x16x32_bf16 v[20:23], v[226:229], v[196:199], v[20:23]
	v_mfma_f32_16x16x32_bf16 v[16:19], v[236:239], v[196:199], v[16:19]
	v_mfma_f32_16x16x32_bf16 v[4:7], v[226:229], v[204:207], v[4:7]
	v_mfma_f32_16x16x32_bf16 v[0:3], v[236:239], v[204:207], v[0:3]
	s_add_i32 s72, s72, 2
	s_add_u32 s34, s34, 0x100
	s_addc_u32 s35, s35, 0
	s_add_u32 s71, s71, 0x100
	s_addc_u32 s52, s52, 0
	s_cmp_gt_u32 s72, 5
	s_barrier
	s_cbranch_scc0 .LBB0_778
	s_cmp_lt_u32 s101, 0x100
	s_cbranch_scc0 .Lxa_4
	s_barrier

; #define PG8_STAGE(bufoff, gbase, voff) do { _Pragma("unroll") for (int _i = 0; _i < 2; ++_i) \
;     __builtin_amdgcn_global_load_lds((const unsigned*)((const char*)(gbase) + (voff)[_i]), (LAS unsigned*)(lds + (bufoff) + ldsw + _i * 8192), 16, 0, 0); } while (0)
; #define PG8_LDA(dst, b, h) do { _Pragma("unroll") for (int m = 0; m < 4; ++m) _Pragma("unroll") for (int k = 0; k < 2; ++k) dst[m][k] = *(const LAS bf16x8*)(lds + PG8_SA(b, h) + aoff + m * 2048 + k * 1024); } while (0)
; #define PG8_LDB(dst, b, h) do { _Pragma("unroll") for (int n = 0; n < 2; ++n) _Pragma("unroll") for (int k = 0; k < 2; ++k) dst[n][k] = *(const LAS bf16x8*)(lds + PG8_SB(b, h) + boff + n * 2048 + k * 1024); } while (0)
; #define PG8_MMA(ai, bj, At, Bt) do { __builtin_amdgcn_s_setprio(1); _Pragma("unroll") for (int m = 0; m < 4; ++m) _Pragma("unroll") for (int n = 0; n < 2; ++n) _Pragma("unroll") for (int k = 0; k < 2; ++k) \
;     acc[ai][bj][m][n] = __builtin_amdgcn_mfma_f32_16x16x32_bf16(Bt[n][k], At[m][k], acc[ai][bj][m][n], 0, 0, 0); __builtin_amdgcn_s_setprio(0); } while (0)
; template <class Epi, class Sched>
; __device__ __forceinline__ void gemm_phase(LAS unsigned char* lds, const Gemm g, const Sched& S, const Epi& E) {
;     ...
;     const bool has_next = S.next(ui + 1, nxt);
;     const char* nA = has_next ? (const char*)g.A + (size_t)nxt.pm * tstep : cA; const char* nB = has_next ? (const char*)g.Bt + (size_t)nxt.pn * tstep : cB;
;     for (int t = 0; t < nt; t += 2) {
;       const bool last = (t == nt - 2);
;       const char* a1 = cA + (size_t)(t + 1) * kstep;
;       const char* a2 = last ? nA : cA + (size_t)(t + 2) * kstep; const char* b2 = last ? nB : cB + (size_t)(t + 2) * kstep;
;       const char* a3 = a2 + kstep; const char* b3 = b2 + kstep;
;       if (last && has_next) S.a_ready(nxt);
;       PG8_LDB(B0, 0, 0); PG8_SCHED; PG8_LDA(At, 0, 0); PG8_STAGE(PG8_SA(1, 1), a1 + hstep, voffA);
;       PG8_WAIT_L(8); PG8_BAR; PG8_WAIT_L(0); PG8_MMA(0, 0, At, B0); PG8_BAR; PG8_SCHED;
;       PG8_LDB(B1, 0, 1); PG8_STAGE(PG8_SB(0, 0), b2, voffB);
;       PG8_BAR; PG8_WAIT_L(0); PG8_MMA(0, 1, At, B1); PG8_BAR;
;     ...
;     for (int a = 0; a < 2; ++a)
; #pragma unroll
;       for (int b = 0; b < 2; ++b)
; #pragma unroll
;         for (int m = 0; m < 4; ++m)
; #pragma unroll
;           for (int n = 0; n < 2; ++n) acc[a][b][m][n] = (f32x4){0.f, 0.f, 0.f, 0.f};
.LBB0_793:
	s_ashr_i32 s37, s36, 31
	v_cmp_lt_i64_e32 vcc, s[40:41], v[166:167]
	s_lshl_b64 s[40:41], s[36:37], 19
	s_add_u32 s40, s14, s40
	s_addc_u32 s41, s15, s41
	s_and_b64 s[42:43], vcc, exec
	s_cselect_b32 s37, s41, s35
	s_cselect_b32 s69, s40, s34
	s_ashr_i32 s23, s22, 31
	s_lshl_b64 s[42:43], s[22:23], 19
	v_readlane_b32 s48, v253, 15
	v_readlane_b32 s49, v253, 16
	s_add_u32 s42, s48, s42
	s_addc_u32 s43, s49, s43
	s_and_b64 s[48:49], vcc, exec
	s_cselect_b32 s23, s43, s45
	s_cselect_b32 s70, s42, s44
	s_add_u32 s34, s34, 0x40080
	s_addc_u32 s35, s35, 0
	s_add_u32 s71, s44, 0x100
	v_mov_b32_e32 v0, 0
	s_addc_u32 s52, s45, 0
	s_mov_b32 s72, -2
	v_mov_b32_e32 v1, v0
	v_mov_b64_e32 v[2:3], v[0:1]
	v_mov_b64_e32 v[4:5], v[0:1]
	v_mov_b64_e32 v[6:7], v[0:1]
	v_mov_b64_e32 v[8:9], v[0:1]
	v_mov_b64_e32 v[10:11], v[0:1]
	v_mov_b64_e32 v[12:13], v[0:1]
	v_mov_b64_e32 v[14:15], v[0:1]
	v_mov_b64_e32 v[16:17], v[0:1]
	v_mov_b64_e32 v[18:19], v[0:1]
	v_mov_b64_e32 v[20:21], v[0:1]
	v_mov_b64_e32 v[22:23], v[0:1]
	v_mov_b64_e32 v[24:25], v[0:1]
	v_mov_b64_e32 v[26:27], v[0:1]
	v_mov_b64_e32 v[28:29], v[0:1]
	v_mov_b64_e32 v[30:31], v[0:1]
	v_mov_b64_e32 v[32:33], v[0:1]
	v_mov_b64_e32 v[34:35], v[0:1]
	v_mov_b64_e32 v[36:37], v[0:1]
	v_mov_b64_e32 v[38:39], v[0:1]
	v_mov_b64_e32 v[40:41], v[0:1]
	v_mov_b64_e32 v[42:43], v[0:1]
	v_mov_b64_e32 v[44:45], v[0:1]
	v_mov_b64_e32 v[46:47], v[0:1]
	v_mov_b64_e32 v[48:49], v[0:1]
	v_mov_b64_e32 v[50:51], v[0:1]
	v_mov_b64_e32 v[52:53], v[0:1]
	v_mov_b64_e32 v[54:55], v[0:1]
	v_mov_b64_e32 v[56:57], v[0:1]
	v_mov_b64_e32 v[58:59], v[0:1]
	v_mov_b64_e32 v[60:61], v[0:1]
	v_mov_b64_e32 v[62:63], v[0:1]
	v_mov_b64_e32 v[64:65], v[0:1]
	v_mov_b64_e32 v[66:67], v[0:1]
	v_mov_b64_e32 v[68:69], v[0:1]
	v_mov_b64_e32 v[70:71], v[0:1]
	v_mov_b64_e32 v[72:73], v[0:1]
	v_mov_b64_e32 v[74:75], v[0:1]
	v_mov_b64_e32 v[76:77], v[0:1]
	v_mov_b64_e32 v[78:79], v[0:1]
	v_mov_b64_e32 v[80:81], v[0:1]
	v_mov_b64_e32 v[82:83], v[0:1]
	v_mov_b64_e32 v[84:85], v[0:1]
	v_mov_b64_e32 v[86:87], v[0:1]
	v_mov_b64_e32 v[88:89], v[0:1]
	v_mov_b64_e32 v[90:91], v[0:1]
	v_mov_b64_e32 v[92:93], v[0:1]
	v_mov_b64_e32 v[94:95], v[0:1]
	v_mov_b64_e32 v[96:97], v[0:1]
	v_mov_b64_e32 v[98:99], v[0:1]
	v_mov_b64_e32 v[100:101], v[0:1]
	v_mov_b64_e32 v[102:103], v[0:1]
	v_mov_b64_e32 v[104:105], v[0:1]
	v_mov_b64_e32 v[106:107], v[0:1]
	v_mov_b64_e32 v[108:109], v[0:1]
	v_mov_b64_e32 v[110:111], v[0:1]
	v_mov_b64_e32 v[112:113], v[0:1]
	v_mov_b64_e32 v[114:115], v[0:1]
	v_mov_b64_e32 v[116:117], v[0:1]
	v_mov_b64_e32 v[118:119], v[0:1]
	v_mov_b64_e32 v[120:121], v[0:1]
	v_mov_b64_e32 v[122:123], v[0:1]
	v_mov_b64_e32 v[124:125], v[0:1]
	v_mov_b64_e32 v[126:127], v[0:1]
	s_cmp_eq_u32 s100, 0
	s_cbranch_scc1 .Lxs_e5
	s_barrier
	s_mov_b32 s100, 0
.Lxs_e5:
.LBB0_794:
	s_add_u32 s44, s34, 0xfffc0080
	s_addc_u32 s45, s35, -1
	s_add_i32 s73, 0, 0x10000
	v_add_u32_e32 v140, s73, v226
	ds_read_b128 v[128:131], v140
	ds_read_b128 v[132:135], v140 offset:1024
	ds_read_b128 v[136:139], v140 offset:2048
	ds_read_b128 v[140:143], v140 offset:3072
	s_cmp_eq_u32 s72, 12
	s_cselect_b32 s49, s37, s45
	s_cselect_b32 s48, s69, s44
	s_cselect_b32 s45, s23, s52
	s_cselect_b32 s44, s70, s71
	s_add_i32 m0, s12, 0xc000
	ds_read_b128 v[144:147], v228
	ds_read_b128 v[148:151], v228 offset:1024
	ds_read_b128 v[152:155], v228 offset:2048
	ds_read_b128 v[156:159], v228 offset:3072
	ds_read_b128 v[184:187], v228 offset:4096
	ds_read_b128 v[188:191], v228 offset:5120
	ds_read_b128 v[192:195], v228 offset:6144
	ds_read_b128 v[196:199], v228 offset:7168
	global_load_lds_dwordx4 v180, s[34:35]
	s_add_i32 m0, s12, 0xe000
	s_nop 0
	global_load_lds_dwordx4 v182, s[34:35]
	s_waitcnt vmcnt(8)
	s_waitcnt lgkmcnt(8)
	s_barrier
	s_waitcnt lgkmcnt(0)
	s_waitcnt lgkmcnt(0)
	v_mfma_f32_16x16x32_bf16 v[124:127], v[128:131], v[144:147], v[124:127]
	v_mfma_f32_16x16x32_bf16 v[120:123], v[136:139], v[144:147], v[120:123]
	v_mfma_f32_16x16x32_bf16 v[108:111], v[128:131], v[152:155], v[108:111]
	v_mfma_f32_16x16x32_bf16 v[104:107], v[136:139], v[152:155], v[104:107]
	v_mfma_f32_16x16x32_bf16 v[92:95], v[128:131], v[184:187], v[92:95]
	v_mfma_f32_16x16x32_bf16 v[88:91], v[136:139], v[184:187], v[88:91]
	v_mfma_f32_16x16x32_bf16 v[76:79], v[128:131], v[192:195], v[76:79]
	v_mfma_f32_16x16x32_bf16 v[72:75], v[136:139], v[192:195], v[72:75]
	v_mfma_f32_16x16x32_bf16 v[124:127], v[132:135], v[148:151], v[124:127]
	v_mfma_f32_16x16x32_bf16 v[120:123], v[140:143], v[148:151], v[120:123]
	v_mfma_f32_16x16x32_bf16 v[108:111], v[132:135], v[156:159], v[108:111]
	v_mfma_f32_16x16x32_bf16 v[104:107], v[140:143], v[156:159], v[104:107]
	v_mfma_f32_16x16x32_bf16 v[92:95], v[132:135], v[188:191], v[92:95]
	v_mfma_f32_16x16x32_bf16 v[88:91], v[140:143], v[188:191], v[88:91]
	v_mfma_f32_16x16x32_bf16 v[76:79], v[132:135], v[196:199], v[76:79]
	v_mfma_f32_16x16x32_bf16 v[72:75], v[140:143], v[196:199], v[72:75]
	s_barrier
	s_add_i32 s76, 0, 0x14000
	v_add_u32_e32 v212, s76, v226
	s_add_i32 s73, s73, s7
	ds_read_b128 v[200:203], v212
	ds_read_b128 v[204:207], v212 offset:1024
	ds_read_b128 v[208:211], v212 offset:2048
	ds_read_b128 v[232:235], v212 offset:3072
	v_lshl_add_u64 v[212:213], s[44:45], 0, v[160:161]
	s_mov_b32 m0, s73
	v_lshl_add_u64 v[222:223], s[44:45], 0, v[174:175]
	global_load_lds_dwordx4 v[212:213], off
	s_add_i32 m0, s73, 0x2000
	s_nop 0
	global_load_lds_dwordx4 v[222:223], off
	s_barrier
; #define PG8_STAGE(bufoff, gbase, voff) do { _Pragma("unroll") for (int _i = 0; _i < 2; ++_i) \
;     __builtin_amdgcn_global_load_lds((const unsigned*)((const char*)(gbase) + (voff)[_i]), (LAS unsigned*)(lds + (bufoff) + ldsw + _i * 8192), 16, 0, 0); } while (0)
; #define PG8_LDA(dst, b, h) do { _Pragma("unroll") for (int m = 0; m < 4; ++m) _Pragma("unroll") for (int k = 0; k < 2; ++k) dst[m][k] = *(const LAS bf16x8*)(lds + PG8_SA(b, h) + aoff + m * 2048 + k * 1024); } while (0)
; #define PG8_LDB(dst, b, h) do { _Pragma("unroll") for (int n = 0; n < 2; ++n) _Pragma("unroll") for (int k = 0; k < 2; ++k) dst[n][k] = *(const LAS bf16x8*)(lds + PG8_SB(b, h) + boff + n * 2048 + k * 1024); } while (0)
; #define PG8_MMA(ai, bj, At, Bt) do { __builtin_amdgcn_s_setprio(1); _Pragma("unroll") for (int m = 0; m < 4; ++m) _Pragma("unroll") for (int n = 0; n < 2; ++n) _Pragma("unroll") for (int k = 0; k < 2; ++k) \
;     acc[ai][bj][m][n] = __builtin_amdgcn_mfma_f32_16x16x32_bf16(Bt[n][k], At[m][k], acc[ai][bj][m][n], 0, 0, 0); __builtin_amdgcn_s_setprio(0); } while (0)
; #define PG8_WAIT_V(n) asm volatile("s_waitcnt vmcnt(" #n ")" ::: "memory")
; #define PG8_WAIT_L(n) asm volatile("s_waitcnt lgkmcnt(" #n ")" ::: "memory")
; #define PG8_BAR __builtin_amdgcn_s_barrier()
; #define PG8_SCHED __builtin_amdgcn_sched_barrier(0)
; template <class Epi, class Sched>
; __device__ __forceinline__ void gemm_phase(LAS unsigned char* lds, const Gemm g, const Sched& S, const Epi& E) {
;     ...
;       PG8_BAR; PG8_WAIT_L(0); PG8_MMA(0, 1, At, B1); PG8_BAR;
;       PG8_LDA(At, 0, 1); PG8_STAGE(PG8_SA(0, 0), a2, voffA);
;       PG8_BAR; PG8_WAIT_L(0); PG8_MMA(1, 0, At, B0); PG8_BAR; PG8_SCHED;
;       PG8_STAGE(PG8_SB(0, 1), b2 + hstep, voffB);
;       PG8_WAIT_V(6); PG8_BAR; PG8_MMA(1, 1, At, B1); PG8_BAR;
;       PG8_LDB(B0, 1, 0); PG8_SCHED; PG8_LDA(At, 1, 0); PG8_STAGE(PG8_SA(0, 1), a2 + hstep, voffA);
;       PG8_WAIT_L(8); PG8_BAR; PG8_WAIT_L(0); PG8_MMA(0, 0, At, B0); PG8_BAR; PG8_SCHED;
	s_waitcnt lgkmcnt(0)
	s_waitcnt lgkmcnt(0)
	v_mfma_f32_16x16x32_bf16 v[116:119], v[200:203], v[144:147], v[116:119]
	v_mfma_f32_16x16x32_bf16 v[112:115], v[208:211], v[144:147], v[112:115]
	v_mfma_f32_16x16x32_bf16 v[100:103], v[200:203], v[152:155], v[100:103]
	v_mfma_f32_16x16x32_bf16 v[96:99], v[208:211], v[152:155], v[96:99]
	v_mfma_f32_16x16x32_bf16 v[84:87], v[200:203], v[184:187], v[84:87]
	v_mfma_f32_16x16x32_bf16 v[80:83], v[208:211], v[184:187], v[80:83]
	v_mfma_f32_16x16x32_bf16 v[68:71], v[200:203], v[192:195], v[68:71]
	v_mfma_f32_16x16x32_bf16 v[64:67], v[208:211], v[192:195], v[64:67]
	v_mfma_f32_16x16x32_bf16 v[116:119], v[204:207], v[148:151], v[116:119]
	v_mfma_f32_16x16x32_bf16 v[112:115], v[232:235], v[148:151], v[112:115]
	v_mfma_f32_16x16x32_bf16 v[100:103], v[204:207], v[156:159], v[100:103]
	v_mfma_f32_16x16x32_bf16 v[96:99], v[232:235], v[156:159], v[96:99]
	v_mfma_f32_16x16x32_bf16 v[84:87], v[204:207], v[188:191], v[84:87]
	v_mfma_f32_16x16x32_bf16 v[80:83], v[232:235], v[188:191], v[80:83]
	v_mfma_f32_16x16x32_bf16 v[68:71], v[204:207], v[196:199], v[68:71]
	v_mfma_f32_16x16x32_bf16 v[64:67], v[232:235], v[196:199], v[64:67]
	s_mov_b32 m0, s12
	v_lshl_add_u64 v[236:237], s[48:49], 0, v[178:179]
	s_barrier
	ds_read_b128 v[144:147], v228 offset:16384
	ds_read_b128 v[148:151], v228 offset:17408
	ds_read_b128 v[152:155], v228 offset:18432
	ds_read_b128 v[156:159], v228 offset:19456
	ds_read_b128 v[184:187], v228 offset:20480
	ds_read_b128 v[188:191], v228 offset:21504
	ds_read_b128 v[192:195], v228 offset:22528
	ds_read_b128 v[196:199], v228 offset:23552
	global_load_lds_dwordx4 v178, s[48:49]
	v_lshl_add_u64 v[238:239], s[48:49], 0, v[176:177]
	s_mov_b32 m0, s13
	s_nop 0
	global_load_lds_dwordx4 v176, s[48:49]
	s_barrier
	s_waitcnt lgkmcnt(0)
	s_waitcnt lgkmcnt(0)
	v_mfma_f32_16x16x32_bf16 v[60:63], v[128:131], v[144:147], v[60:63]
	v_mfma_f32_16x16x32_bf16 v[56:59], v[136:139], v[144:147], v[56:59]
	v_mfma_f32_16x16x32_bf16 v[44:47], v[128:131], v[152:155], v[44:47]
	v_mfma_f32_16x16x32_bf16 v[40:43], v[136:139], v[152:155], v[40:43]
	v_mfma_f32_16x16x32_bf16 v[28:31], v[128:131], v[184:187], v[28:31]
	v_mfma_f32_16x16x32_bf16 v[24:27], v[136:139], v[184:187], v[24:27]
	v_mfma_f32_16x16x32_bf16 v[12:15], v[128:131], v[192:195], v[12:15]
	v_mfma_f32_16x16x32_bf16 v[8:11], v[136:139], v[192:195], v[8:11]
	v_mfma_f32_16x16x32_bf16 v[60:63], v[132:135], v[148:151], v[60:63]
	v_mfma_f32_16x16x32_bf16 v[56:59], v[140:143], v[148:151], v[56:59]
	v_mfma_f32_16x16x32_bf16 v[44:47], v[132:135], v[156:159], v[44:47]
	v_mfma_f32_16x16x32_bf16 v[40:43], v[140:143], v[156:159], v[40:43]
	v_mfma_f32_16x16x32_bf16 v[28:31], v[132:135], v[188:191], v[28:31]
	v_mfma_f32_16x16x32_bf16 v[24:27], v[140:143], v[188:191], v[24:27]
	v_mfma_f32_16x16x32_bf16 v[12:15], v[132:135], v[196:199], v[12:15]
	v_mfma_f32_16x16x32_bf16 v[8:11], v[140:143], v[196:199], v[8:11]
	s_barrier
	s_add_u32 s74, s44, 0x40000
	s_addc_u32 s75, s45, 0
	s_add_i32 s73, s76, s7
	s_mov_b32 m0, s73
	s_nop 0
	global_load_lds_dwordx4 v160, s[74:75]
	s_add_i32 m0, s73, 0x2000
	s_nop 0
	global_load_lds_dwordx4 v174, s[74:75]
	s_waitcnt vmcnt(10)
	s_barrier
	v_mfma_f32_16x16x32_bf16 v[52:55], v[200:203], v[144:147], v[52:55]
	v_mfma_f32_16x16x32_bf16 v[48:51], v[208:211], v[144:147], v[48:51]
	v_mfma_f32_16x16x32_bf16 v[36:39], v[200:203], v[152:155], v[36:39]
	v_mfma_f32_16x16x32_bf16 v[32:35], v[208:211], v[152:155], v[32:35]
	v_mfma_f32_16x16x32_bf16 v[20:23], v[200:203], v[184:187], v[20:23]
	v_mfma_f32_16x16x32_bf16 v[16:19], v[208:211], v[184:187], v[16:19]
	v_mfma_f32_16x16x32_bf16 v[4:7], v[200:203], v[192:195], v[4:7]
	v_mfma_f32_16x16x32_bf16 v[0:3], v[208:211], v[192:195], v[0:3]
	v_mfma_f32_16x16x32_bf16 v[52:55], v[204:207], v[148:151], v[52:55]
	v_mfma_f32_16x16x32_bf16 v[48:51], v[232:235], v[148:151], v[48:51]
	v_mfma_f32_16x16x32_bf16 v[36:39], v[204:207], v[156:159], v[36:39]
	v_mfma_f32_16x16x32_bf16 v[32:35], v[232:235], v[156:159], v[32:35]
	v_mfma_f32_16x16x32_bf16 v[20:23], v[204:207], v[188:191], v[20:23]
	v_mfma_f32_16x16x32_bf16 v[16:19], v[232:235], v[188:191], v[16:19]
	v_mfma_f32_16x16x32_bf16 v[4:7], v[204:207], v[196:199], v[4:7]
	v_mfma_f32_16x16x32_bf16 v[0:3], v[232:235], v[196:199], v[0:3]
	s_add_i32 s73, 0, 0x18000
	v_add_u32_e32 v140, s73, v226
	s_barrier
	ds_read_b128 v[128:131], v140
	ds_read_b128 v[132:135], v140 offset:1024
	ds_read_b128 v[136:139], v140 offset:2048
	ds_read_b128 v[140:143], v140 offset:3072
	s_add_u32 s48, s48, 0x40000
	s_addc_u32 s49, s49, 0
	s_mov_b32 m0, s20
	ds_read_b128 v[144:147], v228 offset:32768
	ds_read_b128 v[148:151], v228 offset:33792
	ds_read_b128 v[152:155], v228 offset:34816
	ds_read_b128 v[156:159], v228 offset:35840
	ds_read_b128 v[184:187], v228 offset:36864
	ds_read_b128 v[188:191], v228 offset:37888
	ds_read_b128 v[192:195], v228 offset:38912
	ds_read_b128 v[196:199], v228 offset:39936
	global_load_lds_dwordx4 v178, s[48:49]
	s_mov_b32 m0, s51
	s_nop 0
	global_load_lds_dwordx4 v176, s[48:49]
	s_waitcnt vmcnt(8)
	s_waitcnt lgkmcnt(8)
	s_barrier
; #define PG8_STAGE(bufoff, gbase, voff) do { _Pragma("unroll") for (int _i = 0; _i < 2; ++_i) \
;     __builtin_amdgcn_global_load_lds((const unsigned*)((const char*)(gbase) + (voff)[_i]), (LAS unsigned*)(lds + (bufoff) + ldsw + _i * 8192), 16, 0, 0); } while (0)
; #define PG8_LDA(dst, b, h) do { _Pragma("unroll") for (int m = 0; m < 4; ++m) _Pragma("unroll") for (int k = 0; k < 2; ++k) dst[m][k] = *(const LAS bf16x8*)(lds + PG8_SA(b, h) + aoff + m * 2048 + k * 1024); } while (0)
; #define PG8_LDB(dst, b, h) do { _Pragma("unroll") for (int n = 0; n < 2; ++n) _Pragma("unroll") for (int k = 0; k < 2; ++k) dst[n][k] = *(const LAS bf16x8*)(lds + PG8_SB(b, h) + boff + n * 2048 + k * 1024); } while (0)
; #define PG8_MMA(ai, bj, At, Bt) do { __builtin_amdgcn_s_setprio(1); _Pragma("unroll") for (int m = 0; m < 4; ++m) _Pragma("unroll") for (int n = 0; n < 2; ++n) _Pragma("unroll") for (int k = 0; k < 2; ++k) \
;     acc[ai][bj][m][n] = __builtin_amdgcn_mfma_f32_16x16x32_bf16(Bt[n][k], At[m][k], acc[ai][bj][m][n], 0, 0, 0); __builtin_amdgcn_s_setprio(0); } while (0)
; #define PG8_WAIT_V(n) asm volatile("s_waitcnt vmcnt(" #n ")" ::: "memory")
; #define PG8_WAIT_L(n) asm volatile("s_waitcnt lgkmcnt(" #n ")" ::: "memory")
; #define PG8_BAR __builtin_amdgcn_s_barrier()
; #define PG8_SCHED __builtin_amdgcn_sched_barrier(0)
; template <class Epi, class Sched>
; __device__ __forceinline__ void gemm_phase(LAS unsigned char* lds, const Gemm g, const Sched& S, const Epi& E) {
;     ...
;       PG8_WAIT_L(8); PG8_BAR; PG8_WAIT_L(0); PG8_MMA(0, 0, At, B0); PG8_BAR; PG8_SCHED;
;       PG8_LDB(B1, 1, 1); PG8_STAGE(PG8_SB(1, 0), b3, voffB);
;       PG8_BAR; PG8_WAIT_L(0); PG8_MMA(0, 1, At, B1); PG8_BAR;
;       PG8_LDA(At, 1, 1); PG8_STAGE(PG8_SA(1, 0), a3, voffA);
;       PG8_BAR; PG8_WAIT_L(0); PG8_MMA(1, 0, At, B0); PG8_BAR; PG8_SCHED;
;       PG8_STAGE(PG8_SB(1, 1), b3 + hstep, voffB);
;       PG8_WAIT_V(6); PG8_BAR; PG8_MMA(1, 1, At, B1); PG8_BAR;
;     }
	s_waitcnt lgkmcnt(0)
	s_waitcnt lgkmcnt(0)
	v_mfma_f32_16x16x32_bf16 v[124:127], v[128:131], v[144:147], v[124:127]
	v_mfma_f32_16x16x32_bf16 v[120:123], v[136:139], v[144:147], v[120:123]
	v_mfma_f32_16x16x32_bf16 v[108:111], v[128:131], v[152:155], v[108:111]
	v_mfma_f32_16x16x32_bf16 v[104:107], v[136:139], v[152:155], v[104:107]
	v_mfma_f32_16x16x32_bf16 v[92:95], v[128:131], v[184:187], v[92:95]
	v_mfma_f32_16x16x32_bf16 v[88:91], v[136:139], v[184:187], v[88:91]
	v_mfma_f32_16x16x32_bf16 v[76:79], v[128:131], v[192:195], v[76:79]
	v_mfma_f32_16x16x32_bf16 v[72:75], v[136:139], v[192:195], v[72:75]
	v_mfma_f32_16x16x32_bf16 v[124:127], v[132:135], v[148:151], v[124:127]
	v_mfma_f32_16x16x32_bf16 v[120:123], v[140:143], v[148:151], v[120:123]
	v_mfma_f32_16x16x32_bf16 v[108:111], v[132:135], v[156:159], v[108:111]
	v_mfma_f32_16x16x32_bf16 v[104:107], v[140:143], v[156:159], v[104:107]
	v_mfma_f32_16x16x32_bf16 v[92:95], v[132:135], v[188:191], v[92:95]
	v_mfma_f32_16x16x32_bf16 v[88:91], v[140:143], v[188:191], v[88:91]
	v_mfma_f32_16x16x32_bf16 v[76:79], v[132:135], v[196:199], v[76:79]
	v_mfma_f32_16x16x32_bf16 v[72:75], v[140:143], v[196:199], v[72:75]
	s_barrier
	s_add_i32 s48, 0, 0x1c000
	s_add_i32 s49, s73, s7
	v_add_u32_e32 v229, s48, v226
	s_add_u32 s98, s44, s80
	s_addc_u32 s99, s45, s81
	s_mov_b32 m0, s49
	ds_read_b128 v[200:203], v229
	ds_read_b128 v[204:207], v229 offset:1024
	ds_read_b128 v[208:211], v229 offset:2048
	ds_read_b128 v[232:235], v229 offset:3072
	global_load_lds_dwordx4 v160, s[98:99]
	v_lshl_add_u64 v[212:213], v[222:223], 0, s[80:81]
	s_add_i32 m0, s49, 0x2000
	s_nop 0
	global_load_lds_dwordx4 v174, s[98:99]
	s_barrier
	s_waitcnt lgkmcnt(0)
	s_waitcnt lgkmcnt(0)
	v_mfma_f32_16x16x32_bf16 v[116:119], v[200:203], v[144:147], v[116:119]
	v_mfma_f32_16x16x32_bf16 v[112:115], v[208:211], v[144:147], v[112:115]
	v_mfma_f32_16x16x32_bf16 v[100:103], v[200:203], v[152:155], v[100:103]
	v_mfma_f32_16x16x32_bf16 v[96:99], v[208:211], v[152:155], v[96:99]
	v_mfma_f32_16x16x32_bf16 v[84:87], v[200:203], v[184:187], v[84:87]
	v_mfma_f32_16x16x32_bf16 v[80:83], v[208:211], v[184:187], v[80:83]
	v_mfma_f32_16x16x32_bf16 v[68:71], v[200:203], v[192:195], v[68:71]
	v_mfma_f32_16x16x32_bf16 v[64:67], v[208:211], v[192:195], v[64:67]
	v_mfma_f32_16x16x32_bf16 v[116:119], v[204:207], v[148:151], v[116:119]
	v_mfma_f32_16x16x32_bf16 v[112:115], v[232:235], v[148:151], v[112:115]
	v_mfma_f32_16x16x32_bf16 v[100:103], v[204:207], v[156:159], v[100:103]
	v_mfma_f32_16x16x32_bf16 v[96:99], v[232:235], v[156:159], v[96:99]
	v_mfma_f32_16x16x32_bf16 v[84:87], v[204:207], v[188:191], v[84:87]
	v_mfma_f32_16x16x32_bf16 v[80:83], v[232:235], v[188:191], v[80:83]
	v_mfma_f32_16x16x32_bf16 v[68:71], v[204:207], v[196:199], v[68:71]
	v_mfma_f32_16x16x32_bf16 v[64:67], v[232:235], v[196:199], v[64:67]
	s_mov_b32 m0, s62
	v_lshl_add_u64 v[212:213], v[236:237], 0, s[80:81]
	s_barrier
	ds_read_b128 v[144:147], v228 offset:49152
	ds_read_b128 v[148:151], v228 offset:50176
	ds_read_b128 v[152:155], v228 offset:51200
	ds_read_b128 v[156:159], v228 offset:52224
	ds_read_b128 v[184:187], v228 offset:53248
	ds_read_b128 v[188:191], v228 offset:54272
	ds_read_b128 v[192:195], v228 offset:55296
	ds_read_b128 v[196:199], v228 offset:56320
	global_load_lds_dwordx4 v[212:213], off
	v_lshl_add_u64 v[212:213], v[238:239], 0, s[80:81]
	s_mov_b32 m0, s63
	s_nop 0
	global_load_lds_dwordx4 v[212:213], off
	s_barrier
	s_waitcnt lgkmcnt(0)
	s_waitcnt lgkmcnt(0)
	v_mfma_f32_16x16x32_bf16 v[60:63], v[128:131], v[144:147], v[60:63]
	v_mfma_f32_16x16x32_bf16 v[56:59], v[136:139], v[144:147], v[56:59]
	v_mfma_f32_16x16x32_bf16 v[44:47], v[128:131], v[152:155], v[44:47]
	v_mfma_f32_16x16x32_bf16 v[40:43], v[136:139], v[152:155], v[40:43]
	v_mfma_f32_16x16x32_bf16 v[28:31], v[128:131], v[184:187], v[28:31]
	v_mfma_f32_16x16x32_bf16 v[24:27], v[136:139], v[184:187], v[24:27]
	v_mfma_f32_16x16x32_bf16 v[12:15], v[128:131], v[192:195], v[12:15]
	v_mfma_f32_16x16x32_bf16 v[8:11], v[136:139], v[192:195], v[8:11]
	v_mfma_f32_16x16x32_bf16 v[60:63], v[132:135], v[148:151], v[60:63]
	v_mfma_f32_16x16x32_bf16 v[56:59], v[140:143], v[148:151], v[56:59]
	v_mfma_f32_16x16x32_bf16 v[44:47], v[132:135], v[156:159], v[44:47]
	v_mfma_f32_16x16x32_bf16 v[40:43], v[140:143], v[156:159], v[40:43]
	v_mfma_f32_16x16x32_bf16 v[28:31], v[132:135], v[188:191], v[28:31]
	v_mfma_f32_16x16x32_bf16 v[24:27], v[140:143], v[188:191], v[24:27]
	v_mfma_f32_16x16x32_bf16 v[12:15], v[132:135], v[196:199], v[12:15]
	v_mfma_f32_16x16x32_bf16 v[8:11], v[140:143], v[196:199], v[8:11]
	s_barrier
	s_add_u32 s44, s44, 0x40080
	s_addc_u32 s45, s45, 0
	s_add_i32 s48, s48, s7
	s_mov_b32 m0, s48
	s_nop 0
	global_load_lds_dwordx4 v160, s[44:45]
	s_add_i32 m0, s48, 0x2000
	s_nop 0
	global_load_lds_dwordx4 v174, s[44:45]
	s_waitcnt vmcnt(10)
	s_barrier
	v_mfma_f32_16x16x32_bf16 v[52:55], v[200:203], v[144:147], v[52:55]
	v_mfma_f32_16x16x32_bf16 v[48:51], v[208:211], v[144:147], v[48:51]
	v_mfma_f32_16x16x32_bf16 v[36:39], v[200:203], v[152:155], v[36:39]
	v_mfma_f32_16x16x32_bf16 v[32:35], v[208:211], v[152:155], v[32:35]
	v_mfma_f32_16x16x32_bf16 v[20:23], v[200:203], v[184:187], v[20:23]
	v_mfma_f32_16x16x32_bf16 v[16:19], v[208:211], v[184:187], v[16:19]
	v_mfma_f32_16x16x32_bf16 v[4:7], v[200:203], v[192:195], v[4:7]
	v_mfma_f32_16x16x32_bf16 v[0:3], v[208:211], v[192:195], v[0:3]
	v_mfma_f32_16x16x32_bf16 v[52:55], v[204:207], v[148:151], v[52:55]
	v_mfma_f32_16x16x32_bf16 v[48:51], v[232:235], v[148:151], v[48:51]
	v_mfma_f32_16x16x32_bf16 v[36:39], v[204:207], v[156:159], v[36:39]
	v_mfma_f32_16x16x32_bf16 v[32:35], v[232:235], v[156:159], v[32:35]
	v_mfma_f32_16x16x32_bf16 v[20:23], v[204:207], v[188:191], v[20:23]
	v_mfma_f32_16x16x32_bf16 v[16:19], v[232:235], v[188:191], v[16:19]
	v_mfma_f32_16x16x32_bf16 v[4:7], v[204:207], v[196:199], v[4:7]
	v_mfma_f32_16x16x32_bf16 v[0:3], v[232:235], v[196:199], v[0:3]
	s_add_i32 s72, s72, 2
	s_add_u32 s34, s34, 0x100
	s_addc_u32 s35, s35, 0
	s_add_u32 s71, s71, 0x100
	s_addc_u32 s52, s52, 0
	s_cmp_gt_u32 s72, 13
	s_barrier
	s_cbranch_scc0 .LBB0_794
	s_cmp_lt_u32 s101, 0x100
	s_cbranch_scc0 .Lxa_5
	s_barrier

; #define PG8_STAGE(bufoff, gbase, voff) do { _Pragma("unroll") for (int _i = 0; _i < 2; ++_i) \
;     __builtin_amdgcn_global_load_lds((const unsigned*)((const char*)(gbase) + (voff)[_i]), (LAS unsigned*)(lds + (bufoff) + ldsw + _i * 8192), 16, 0, 0); } while (0)
; #define PG8_LDA(dst, b, h) do { _Pragma("unroll") for (int m = 0; m < 4; ++m) _Pragma("unroll") for (int k = 0; k < 2; ++k) dst[m][k] = *(const LAS bf16x8*)(lds + PG8_SA(b, h) + aoff + m * 2048 + k * 1024); } while (0)
; #define PG8_LDB(dst, b, h) do { _Pragma("unroll") for (int n = 0; n < 2; ++n) _Pragma("unroll") for (int k = 0; k < 2; ++k) dst[n][k] = *(const LAS bf16x8*)(lds + PG8_SB(b, h) + boff + n * 2048 + k * 1024); } while (0)
; #define PG8_MMA(ai, bj, At, Bt) do { __builtin_amdgcn_s_setprio(1); _Pragma("unroll") for (int m = 0; m < 4; ++m) _Pragma("unroll") for (int n = 0; n < 2; ++n) _Pragma("unroll") for (int k = 0; k < 2; ++k) \
;     acc[ai][bj][m][n] = __builtin_amdgcn_mfma_f32_16x16x32_bf16(Bt[n][k], At[m][k], acc[ai][bj][m][n], 0, 0, 0); __builtin_amdgcn_s_setprio(0); } while (0)
; template <class Epi, class Sched>
; __device__ __forceinline__ void gemm_phase(LAS unsigned char* lds, const Gemm g, const Sched& S, const Epi& E) {
;     ...
;     const bool has_next = S.next(ui + 1, nxt);
;     const char* nA = has_next ? (const char*)g.A + (size_t)nxt.pm * tstep : cA; const char* nB = has_next ? (const char*)g.Bt + (size_t)nxt.pn * tstep : cB;
;     for (int t = 0; t < nt; t += 2) {
;       const bool last = (t == nt - 2);
;       const char* a1 = cA + (size_t)(t + 1) * kstep;
;       const char* a2 = last ? nA : cA + (size_t)(t + 2) * kstep; const char* b2 = last ? nB : cB + (size_t)(t + 2) * kstep;
;       const char* a3 = a2 + kstep; const char* b3 = b2 + kstep;
;       if (last && has_next) S.a_ready(nxt);
;       PG8_LDB(B0, 0, 0); PG8_SCHED; PG8_LDA(At, 0, 0); PG8_STAGE(PG8_SA(1, 1), a1 + hstep, voffA);
;       PG8_WAIT_L(8); PG8_BAR; PG8_WAIT_L(0); PG8_MMA(0, 0, At, B0); PG8_BAR; PG8_SCHED;
;       PG8_LDB(B1, 0, 1); PG8_STAGE(PG8_SB(0, 0), b2, voffB);
;       PG8_BAR; PG8_WAIT_L(0); PG8_MMA(0, 1, At, B1); PG8_BAR;
;     ...
;     for (int a = 0; a < 2; ++a)
; #pragma unroll
;       for (int b = 0; b < 2; ++b)
; #pragma unroll
;         for (int m = 0; m < 4; ++m)
; #pragma unroll
;           for (int n = 0; n < 2; ++n) acc[a][b][m][n] = (f32x4){0.f, 0.f, 0.f, 0.f};
.LBB0_862:
	s_ashr_i32 s37, s36, 31
	v_cmp_lt_i64_e32 vcc, s[42:43], v[166:167]
	s_lshl_b64 s[42:43], s[36:37], 19
	s_add_u32 s42, s8, s42
	s_addc_u32 s43, s9, s43
	s_and_b64 s[44:45], vcc, exec
	s_cselect_b32 s37, s43, s35
	s_cselect_b32 s68, s42, s34
	s_ashr_i32 s23, s22, 31
	s_lshl_b64 s[44:45], s[22:23], 19
	v_readlane_b32 s72, v253, 54
	v_readlane_b32 s73, v253, 55
	s_add_u32 s44, s72, s44
	s_addc_u32 s45, s73, s45
	s_and_b64 s[72:73], vcc, exec
	s_cselect_b32 s23, s45, s49
	s_cselect_b32 s69, s44, s48
	s_add_u32 s34, s34, 0x40080
	s_addc_u32 s35, s35, 0
	s_add_u32 s52, s48, 0x100
	v_mov_b32_e32 v0, 0
	s_addc_u32 s72, s49, 0
	s_mov_b32 s73, -2
	s_waitcnt lgkmcnt(0)
	v_mov_b32_e32 v1, v0
	v_mov_b64_e32 v[2:3], v[0:1]
	v_mov_b64_e32 v[4:5], v[0:1]
	v_mov_b64_e32 v[6:7], v[0:1]
	v_mov_b64_e32 v[8:9], v[0:1]
	v_mov_b64_e32 v[10:11], v[0:1]
	v_mov_b64_e32 v[12:13], v[0:1]
	v_mov_b64_e32 v[14:15], v[0:1]
	v_mov_b64_e32 v[16:17], v[0:1]
	v_mov_b64_e32 v[18:19], v[0:1]
	v_mov_b64_e32 v[20:21], v[0:1]
	v_mov_b64_e32 v[22:23], v[0:1]
	v_mov_b64_e32 v[24:25], v[0:1]
	v_mov_b64_e32 v[26:27], v[0:1]
	v_mov_b64_e32 v[28:29], v[0:1]
	v_mov_b64_e32 v[30:31], v[0:1]
	v_mov_b64_e32 v[32:33], v[0:1]
	v_mov_b64_e32 v[34:35], v[0:1]
	v_mov_b64_e32 v[36:37], v[0:1]
	v_mov_b64_e32 v[38:39], v[0:1]
	v_mov_b64_e32 v[40:41], v[0:1]
	v_mov_b64_e32 v[42:43], v[0:1]
	v_mov_b64_e32 v[44:45], v[0:1]
	v_mov_b64_e32 v[46:47], v[0:1]
	v_mov_b64_e32 v[48:49], v[0:1]
	v_mov_b64_e32 v[50:51], v[0:1]
	v_mov_b64_e32 v[52:53], v[0:1]
	v_mov_b64_e32 v[54:55], v[0:1]
	v_mov_b64_e32 v[56:57], v[0:1]
	v_mov_b64_e32 v[58:59], v[0:1]
	v_mov_b64_e32 v[60:61], v[0:1]
	v_mov_b64_e32 v[62:63], v[0:1]
	v_mov_b64_e32 v[64:65], v[0:1]
	v_mov_b64_e32 v[66:67], v[0:1]
	v_mov_b64_e32 v[68:69], v[0:1]
	v_mov_b64_e32 v[70:71], v[0:1]
	v_mov_b64_e32 v[72:73], v[0:1]
	v_mov_b64_e32 v[74:75], v[0:1]
	v_mov_b64_e32 v[76:77], v[0:1]
	v_mov_b64_e32 v[78:79], v[0:1]
	v_mov_b64_e32 v[80:81], v[0:1]
	v_mov_b64_e32 v[82:83], v[0:1]
	v_mov_b64_e32 v[84:85], v[0:1]
	v_mov_b64_e32 v[86:87], v[0:1]
	v_mov_b64_e32 v[88:89], v[0:1]
	v_mov_b64_e32 v[90:91], v[0:1]
	v_mov_b64_e32 v[92:93], v[0:1]
	v_mov_b64_e32 v[94:95], v[0:1]
	v_mov_b64_e32 v[96:97], v[0:1]
	v_mov_b64_e32 v[98:99], v[0:1]
	v_mov_b64_e32 v[100:101], v[0:1]
	v_mov_b64_e32 v[102:103], v[0:1]
	v_mov_b64_e32 v[104:105], v[0:1]
	v_mov_b64_e32 v[106:107], v[0:1]
	v_mov_b64_e32 v[108:109], v[0:1]
	v_mov_b64_e32 v[110:111], v[0:1]
	v_mov_b64_e32 v[112:113], v[0:1]
	v_mov_b64_e32 v[114:115], v[0:1]
	v_mov_b64_e32 v[116:117], v[0:1]
	v_mov_b64_e32 v[118:119], v[0:1]
	v_mov_b64_e32 v[120:121], v[0:1]
	v_mov_b64_e32 v[122:123], v[0:1]
	v_mov_b64_e32 v[124:125], v[0:1]
	v_mov_b64_e32 v[126:127], v[0:1]
	s_cmp_eq_u32 s100, 0
	s_cbranch_scc1 .Lxs_e6
	s_barrier
	s_mov_b32 s100, 0
.Lxs_e6:
.LBB0_863:
	s_add_u32 s48, s34, 0xfffc0080
	s_addc_u32 s49, s35, -1
	s_add_i32 s74, 0, 0x10000
	v_add_u32_e32 v140, s74, v202
	ds_read_b128 v[128:131], v140
	ds_read_b128 v[132:135], v140 offset:1024
	ds_read_b128 v[136:139], v140 offset:2048
	ds_read_b128 v[140:143], v140 offset:3072
	s_cmp_eq_u32 s73, 12
	s_cselect_b32 s49, s37, s49
	s_cselect_b32 s48, s68, s48
	s_cselect_b32 vcc_hi, s23, s72
	s_cselect_b32 vcc_lo, s69, s52
	s_add_i32 m0, s51, 0xc000
	ds_read_b128 v[144:147], v203
	ds_read_b128 v[148:151], v203 offset:1024
	ds_read_b128 v[152:155], v203 offset:2048
	ds_read_b128 v[186:189], v203 offset:3072
	ds_read_b128 v[190:193], v203 offset:4096
	ds_read_b128 v[194:197], v203 offset:5120
	ds_read_b128 v[198:201], v203 offset:6144
	ds_read_b128 v[204:207], v203 offset:7168
	global_load_lds_dwordx4 v182, s[34:35]
	s_add_i32 m0, s51, 0xe000
	s_nop 0
	global_load_lds_dwordx4 v184, s[34:35]
	s_waitcnt vmcnt(8)
	s_waitcnt lgkmcnt(8)
	s_barrier
	s_waitcnt lgkmcnt(0)
	s_waitcnt lgkmcnt(0)
	v_mfma_f32_16x16x32_bf16 v[124:127], v[128:131], v[144:147], v[124:127]
	v_mfma_f32_16x16x32_bf16 v[120:123], v[136:139], v[144:147], v[120:123]
	v_mfma_f32_16x16x32_bf16 v[108:111], v[128:131], v[152:155], v[108:111]
	v_mfma_f32_16x16x32_bf16 v[104:107], v[136:139], v[152:155], v[104:107]
	v_mfma_f32_16x16x32_bf16 v[92:95], v[128:131], v[190:193], v[92:95]
	v_mfma_f32_16x16x32_bf16 v[88:91], v[136:139], v[190:193], v[88:91]
	v_mfma_f32_16x16x32_bf16 v[76:79], v[128:131], v[198:201], v[76:79]
	v_mfma_f32_16x16x32_bf16 v[72:75], v[136:139], v[198:201], v[72:75]
	v_mfma_f32_16x16x32_bf16 v[124:127], v[132:135], v[148:151], v[124:127]
	v_mfma_f32_16x16x32_bf16 v[120:123], v[140:143], v[148:151], v[120:123]
	v_mfma_f32_16x16x32_bf16 v[108:111], v[132:135], v[186:189], v[108:111]
	v_mfma_f32_16x16x32_bf16 v[104:107], v[140:143], v[186:189], v[104:107]
	v_mfma_f32_16x16x32_bf16 v[92:95], v[132:135], v[194:197], v[92:95]
	v_mfma_f32_16x16x32_bf16 v[88:91], v[140:143], v[194:197], v[88:91]
	v_mfma_f32_16x16x32_bf16 v[76:79], v[132:135], v[204:207], v[76:79]
	v_mfma_f32_16x16x32_bf16 v[72:75], v[140:143], v[204:207], v[72:75]
	s_barrier
	s_add_i32 s76, 0, 0x14000
	s_add_i32 s74, s74, s7
	v_add_u32_e32 v160, s76, v202
	s_mov_b32 m0, s74
	ds_read_b128 v[208:211], v160
	ds_read_b128 v[226:229], v160 offset:1024
	ds_read_b128 v[232:235], v160 offset:2048
	ds_read_b128 v[236:239], v160 offset:3072
	global_load_lds_dwordx4 v174, vcc
	s_add_i32 m0, s74, 0x2000
	s_nop 0
	global_load_lds_dwordx4 v156, vcc
	s_barrier
; #define PG8_STAGE(bufoff, gbase, voff) do { _Pragma("unroll") for (int _i = 0; _i < 2; ++_i) \
;     __builtin_amdgcn_global_load_lds((const unsigned*)((const char*)(gbase) + (voff)[_i]), (LAS unsigned*)(lds + (bufoff) + ldsw + _i * 8192), 16, 0, 0); } while (0)
; #define PG8_LDA(dst, b, h) do { _Pragma("unroll") for (int m = 0; m < 4; ++m) _Pragma("unroll") for (int k = 0; k < 2; ++k) dst[m][k] = *(const LAS bf16x8*)(lds + PG8_SA(b, h) + aoff + m * 2048 + k * 1024); } while (0)
; #define PG8_LDB(dst, b, h) do { _Pragma("unroll") for (int n = 0; n < 2; ++n) _Pragma("unroll") for (int k = 0; k < 2; ++k) dst[n][k] = *(const LAS bf16x8*)(lds + PG8_SB(b, h) + boff + n * 2048 + k * 1024); } while (0)
; #define PG8_MMA(ai, bj, At, Bt) do { __builtin_amdgcn_s_setprio(1); _Pragma("unroll") for (int m = 0; m < 4; ++m) _Pragma("unroll") for (int n = 0; n < 2; ++n) _Pragma("unroll") for (int k = 0; k < 2; ++k) \
;     acc[ai][bj][m][n] = __builtin_amdgcn_mfma_f32_16x16x32_bf16(Bt[n][k], At[m][k], acc[ai][bj][m][n], 0, 0, 0); __builtin_amdgcn_s_setprio(0); } while (0)
; #define PG8_WAIT_V(n) asm volatile("s_waitcnt vmcnt(" #n ")" ::: "memory")
; #define PG8_WAIT_L(n) asm volatile("s_waitcnt lgkmcnt(" #n ")" ::: "memory")
; #define PG8_BAR __builtin_amdgcn_s_barrier()
; #define PG8_SCHED __builtin_amdgcn_sched_barrier(0)
; template <class Epi, class Sched>
; __device__ __forceinline__ void gemm_phase(LAS unsigned char* lds, const Gemm g, const Sched& S, const Epi& E) {
;     ...
;       PG8_WAIT_L(8); PG8_BAR; PG8_WAIT_L(0); PG8_MMA(0, 0, At, B0); PG8_BAR; PG8_SCHED;
;       PG8_LDB(B1, 0, 1); PG8_STAGE(PG8_SB(0, 0), b2, voffB);
;       PG8_BAR; PG8_WAIT_L(0); PG8_MMA(0, 1, At, B1); PG8_BAR;
;       PG8_LDA(At, 0, 1); PG8_STAGE(PG8_SA(0, 0), a2, voffA);
;       PG8_BAR; PG8_WAIT_L(0); PG8_MMA(1, 0, At, B0); PG8_BAR; PG8_SCHED;
;       PG8_STAGE(PG8_SB(0, 1), b2 + hstep, voffB);
;       PG8_WAIT_V(6); PG8_BAR; PG8_MMA(1, 1, At, B1); PG8_BAR;
;       PG8_LDB(B0, 1, 0); PG8_SCHED; PG8_LDA(At, 1, 0); PG8_STAGE(PG8_SA(0, 1), a2 + hstep, voffA);
;       PG8_WAIT_L(8); PG8_BAR; PG8_WAIT_L(0); PG8_MMA(0, 0, At, B0); PG8_BAR; PG8_SCHED;
	s_waitcnt lgkmcnt(0)
	s_waitcnt lgkmcnt(0)
	v_mfma_f32_16x16x32_bf16 v[116:119], v[208:211], v[144:147], v[116:119]
	v_mfma_f32_16x16x32_bf16 v[112:115], v[232:235], v[144:147], v[112:115]
	v_mfma_f32_16x16x32_bf16 v[100:103], v[208:211], v[152:155], v[100:103]
	v_mfma_f32_16x16x32_bf16 v[96:99], v[232:235], v[152:155], v[96:99]
	v_mfma_f32_16x16x32_bf16 v[84:87], v[208:211], v[190:193], v[84:87]
	v_mfma_f32_16x16x32_bf16 v[80:83], v[232:235], v[190:193], v[80:83]
	v_mfma_f32_16x16x32_bf16 v[68:71], v[208:211], v[198:201], v[68:71]
	v_mfma_f32_16x16x32_bf16 v[64:67], v[232:235], v[198:201], v[64:67]
	v_mfma_f32_16x16x32_bf16 v[116:119], v[226:229], v[148:151], v[116:119]
	v_mfma_f32_16x16x32_bf16 v[112:115], v[236:239], v[148:151], v[112:115]
	v_mfma_f32_16x16x32_bf16 v[100:103], v[226:229], v[186:189], v[100:103]
	v_mfma_f32_16x16x32_bf16 v[96:99], v[236:239], v[186:189], v[96:99]
	v_mfma_f32_16x16x32_bf16 v[84:87], v[226:229], v[194:197], v[84:87]
	v_mfma_f32_16x16x32_bf16 v[80:83], v[236:239], v[194:197], v[80:83]
	v_mfma_f32_16x16x32_bf16 v[68:71], v[226:229], v[204:207], v[68:71]
	v_mfma_f32_16x16x32_bf16 v[64:67], v[236:239], v[204:207], v[64:67]
	s_mov_b32 m0, s51
	v_lshl_add_u64 v[240:241], s[48:49], 0, v[176:177]
	s_barrier
	ds_read_b128 v[144:147], v203 offset:16384
	ds_read_b128 v[148:151], v203 offset:17408
	ds_read_b128 v[152:155], v203 offset:18432
	ds_read_b128 v[186:189], v203 offset:19456
	ds_read_b128 v[190:193], v203 offset:20480
	ds_read_b128 v[194:197], v203 offset:21504
	ds_read_b128 v[198:201], v203 offset:22528
	ds_read_b128 v[204:207], v203 offset:23552
	global_load_lds_dwordx4 v176, s[48:49]
	v_lshl_add_u64 v[242:243], s[48:49], 0, v[158:159]
	s_mov_b32 m0, s62
	s_nop 0
	global_load_lds_dwordx4 v158, s[48:49]
	s_barrier
	s_waitcnt lgkmcnt(0)
	s_waitcnt lgkmcnt(0)
	v_mfma_f32_16x16x32_bf16 v[60:63], v[128:131], v[144:147], v[60:63]
	v_mfma_f32_16x16x32_bf16 v[56:59], v[136:139], v[144:147], v[56:59]
	v_mfma_f32_16x16x32_bf16 v[44:47], v[128:131], v[152:155], v[44:47]
	v_mfma_f32_16x16x32_bf16 v[40:43], v[136:139], v[152:155], v[40:43]
	v_mfma_f32_16x16x32_bf16 v[28:31], v[128:131], v[190:193], v[28:31]
	v_mfma_f32_16x16x32_bf16 v[24:27], v[136:139], v[190:193], v[24:27]
	v_mfma_f32_16x16x32_bf16 v[12:15], v[128:131], v[198:201], v[12:15]
	v_mfma_f32_16x16x32_bf16 v[8:11], v[136:139], v[198:201], v[8:11]
	v_mfma_f32_16x16x32_bf16 v[60:63], v[132:135], v[148:151], v[60:63]
	v_mfma_f32_16x16x32_bf16 v[56:59], v[140:143], v[148:151], v[56:59]
	v_mfma_f32_16x16x32_bf16 v[44:47], v[132:135], v[186:189], v[44:47]
	v_mfma_f32_16x16x32_bf16 v[40:43], v[140:143], v[186:189], v[40:43]
	v_mfma_f32_16x16x32_bf16 v[28:31], v[132:135], v[194:197], v[28:31]
	v_mfma_f32_16x16x32_bf16 v[24:27], v[140:143], v[194:197], v[24:27]
	v_mfma_f32_16x16x32_bf16 v[12:15], v[132:135], v[204:207], v[12:15]
	v_mfma_f32_16x16x32_bf16 v[8:11], v[140:143], v[204:207], v[8:11]
	s_barrier
	s_add_u32 s74, vcc_lo, 0x40000
	s_addc_u32 s75, vcc_hi, 0
	s_add_i32 s76, s76, s7
	s_mov_b32 m0, s76
	s_nop 0
	global_load_lds_dwordx4 v174, s[74:75]
	s_add_i32 m0, s76, 0x2000
	s_nop 0
	global_load_lds_dwordx4 v156, s[74:75]
	s_waitcnt vmcnt(10)
	s_barrier
	v_mfma_f32_16x16x32_bf16 v[52:55], v[208:211], v[144:147], v[52:55]
	v_mfma_f32_16x16x32_bf16 v[48:51], v[232:235], v[144:147], v[48:51]
	v_mfma_f32_16x16x32_bf16 v[36:39], v[208:211], v[152:155], v[36:39]
	v_mfma_f32_16x16x32_bf16 v[32:35], v[232:235], v[152:155], v[32:35]
	v_mfma_f32_16x16x32_bf16 v[20:23], v[208:211], v[190:193], v[20:23]
	v_mfma_f32_16x16x32_bf16 v[16:19], v[232:235], v[190:193], v[16:19]
	v_mfma_f32_16x16x32_bf16 v[4:7], v[208:211], v[198:201], v[4:7]
	v_mfma_f32_16x16x32_bf16 v[0:3], v[232:235], v[198:201], v[0:3]
	v_mfma_f32_16x16x32_bf16 v[52:55], v[226:229], v[148:151], v[52:55]
	v_mfma_f32_16x16x32_bf16 v[48:51], v[236:239], v[148:151], v[48:51]
	v_mfma_f32_16x16x32_bf16 v[36:39], v[226:229], v[186:189], v[36:39]
	v_mfma_f32_16x16x32_bf16 v[32:35], v[236:239], v[186:189], v[32:35]
	v_mfma_f32_16x16x32_bf16 v[20:23], v[226:229], v[194:197], v[20:23]
	v_mfma_f32_16x16x32_bf16 v[16:19], v[236:239], v[194:197], v[16:19]
	v_mfma_f32_16x16x32_bf16 v[4:7], v[226:229], v[204:207], v[4:7]
	v_mfma_f32_16x16x32_bf16 v[0:3], v[236:239], v[204:207], v[0:3]
	s_add_i32 s74, 0, 0x18000
	v_add_u32_e32 v140, s74, v202
	s_barrier
	ds_read_b128 v[128:131], v140
	ds_read_b128 v[132:135], v140 offset:1024
	ds_read_b128 v[136:139], v140 offset:2048
	ds_read_b128 v[140:143], v140 offset:3072
	s_add_u32 s48, s48, 0x40000
	s_addc_u32 s49, s49, 0
	s_mov_b32 m0, s63
	ds_read_b128 v[144:147], v203 offset:32768
	ds_read_b128 v[148:151], v203 offset:33792
	ds_read_b128 v[152:155], v203 offset:34816
	ds_read_b128 v[186:189], v203 offset:35840
	ds_read_b128 v[190:193], v203 offset:36864
	ds_read_b128 v[194:197], v203 offset:37888
	ds_read_b128 v[198:201], v203 offset:38912
	ds_read_b128 v[204:207], v203 offset:39936
	global_load_lds_dwordx4 v176, s[48:49]
	s_mov_b32 m0, s64
	s_nop 0
	global_load_lds_dwordx4 v158, s[48:49]
	s_waitcnt vmcnt(8)
	s_waitcnt lgkmcnt(8)
	s_barrier
; #define PG8_STAGE(bufoff, gbase, voff) do { _Pragma("unroll") for (int _i = 0; _i < 2; ++_i) \
;     __builtin_amdgcn_global_load_lds((const unsigned*)((const char*)(gbase) + (voff)[_i]), (LAS unsigned*)(lds + (bufoff) + ldsw + _i * 8192), 16, 0, 0); } while (0)
; #define PG8_LDA(dst, b, h) do { _Pragma("unroll") for (int m = 0; m < 4; ++m) _Pragma("unroll") for (int k = 0; k < 2; ++k) dst[m][k] = *(const LAS bf16x8*)(lds + PG8_SA(b, h) + aoff + m * 2048 + k * 1024); } while (0)
; #define PG8_LDB(dst, b, h) do { _Pragma("unroll") for (int n = 0; n < 2; ++n) _Pragma("unroll") for (int k = 0; k < 2; ++k) dst[n][k] = *(const LAS bf16x8*)(lds + PG8_SB(b, h) + boff + n * 2048 + k * 1024); } while (0)
; #define PG8_MMA(ai, bj, At, Bt) do { __builtin_amdgcn_s_setprio(1); _Pragma("unroll") for (int m = 0; m < 4; ++m) _Pragma("unroll") for (int n = 0; n < 2; ++n) _Pragma("unroll") for (int k = 0; k < 2; ++k) \
;     acc[ai][bj][m][n] = __builtin_amdgcn_mfma_f32_16x16x32_bf16(Bt[n][k], At[m][k], acc[ai][bj][m][n], 0, 0, 0); __builtin_amdgcn_s_setprio(0); } while (0)
; #define PG8_WAIT_V(n) asm volatile("s_waitcnt vmcnt(" #n ")" ::: "memory")
; #define PG8_WAIT_L(n) asm volatile("s_waitcnt lgkmcnt(" #n ")" ::: "memory")
; #define PG8_BAR __builtin_amdgcn_s_barrier()
; #define PG8_SCHED __builtin_amdgcn_sched_barrier(0)
; template <class Epi, class Sched>
; __device__ __forceinline__ void gemm_phase(LAS unsigned char* lds, const Gemm g, const Sched& S, const Epi& E) {
;     ...
;       PG8_WAIT_L(8); PG8_BAR; PG8_WAIT_L(0); PG8_MMA(0, 0, At, B0); PG8_BAR; PG8_SCHED;
;       PG8_LDB(B1, 1, 1); PG8_STAGE(PG8_SB(1, 0), b3, voffB);
;       PG8_BAR; PG8_WAIT_L(0); PG8_MMA(0, 1, At, B1); PG8_BAR;
;       PG8_LDA(At, 1, 1); PG8_STAGE(PG8_SA(1, 0), a3, voffA);
;       PG8_BAR; PG8_WAIT_L(0); PG8_MMA(1, 0, At, B0); PG8_BAR; PG8_SCHED;
;       PG8_STAGE(PG8_SB(1, 1), b3 + hstep, voffB);
;       PG8_WAIT_V(6); PG8_BAR; PG8_MMA(1, 1, At, B1); PG8_BAR;
;     }
	s_waitcnt lgkmcnt(0)
	s_waitcnt lgkmcnt(0)
	v_mfma_f32_16x16x32_bf16 v[124:127], v[128:131], v[144:147], v[124:127]
	v_mfma_f32_16x16x32_bf16 v[120:123], v[136:139], v[144:147], v[120:123]
	v_mfma_f32_16x16x32_bf16 v[108:111], v[128:131], v[152:155], v[108:111]
	v_mfma_f32_16x16x32_bf16 v[104:107], v[136:139], v[152:155], v[104:107]
	v_mfma_f32_16x16x32_bf16 v[92:95], v[128:131], v[190:193], v[92:95]
	v_mfma_f32_16x16x32_bf16 v[88:91], v[136:139], v[190:193], v[88:91]
	v_mfma_f32_16x16x32_bf16 v[76:79], v[128:131], v[198:201], v[76:79]
	v_mfma_f32_16x16x32_bf16 v[72:75], v[136:139], v[198:201], v[72:75]
	v_mfma_f32_16x16x32_bf16 v[124:127], v[132:135], v[148:151], v[124:127]
	v_mfma_f32_16x16x32_bf16 v[120:123], v[140:143], v[148:151], v[120:123]
	v_mfma_f32_16x16x32_bf16 v[108:111], v[132:135], v[186:189], v[108:111]
	v_mfma_f32_16x16x32_bf16 v[104:107], v[140:143], v[186:189], v[104:107]
	v_mfma_f32_16x16x32_bf16 v[92:95], v[132:135], v[194:197], v[92:95]
	v_mfma_f32_16x16x32_bf16 v[88:91], v[140:143], v[194:197], v[88:91]
	v_mfma_f32_16x16x32_bf16 v[76:79], v[132:135], v[204:207], v[76:79]
	v_mfma_f32_16x16x32_bf16 v[72:75], v[140:143], v[204:207], v[72:75]
	s_barrier
	s_add_i32 s75, 0, 0x1c000
	s_add_i32 s48, s74, s7
	v_add_u32_e32 v160, s75, v202
	s_add_u32 s98, vcc_lo, s80
	s_addc_u32 s99, vcc_hi, s81
	s_mov_b32 m0, s48
	ds_read_b128 v[208:211], v160
	ds_read_b128 v[226:229], v160 offset:1024
	ds_read_b128 v[232:235], v160 offset:2048
	ds_read_b128 v[236:239], v160 offset:3072
	global_load_lds_dwordx4 v174, s[98:99]
	v_lshl_add_u64 v[212:213], v[222:223], 0, s[80:81]
	s_add_i32 m0, s48, 0x2000
	s_nop 0
	global_load_lds_dwordx4 v156, s[98:99]
	s_barrier
	s_waitcnt lgkmcnt(0)
	s_waitcnt lgkmcnt(0)
	v_mfma_f32_16x16x32_bf16 v[116:119], v[208:211], v[144:147], v[116:119]
	v_mfma_f32_16x16x32_bf16 v[112:115], v[232:235], v[144:147], v[112:115]
	v_mfma_f32_16x16x32_bf16 v[100:103], v[208:211], v[152:155], v[100:103]
	v_mfma_f32_16x16x32_bf16 v[96:99], v[232:235], v[152:155], v[96:99]
	v_mfma_f32_16x16x32_bf16 v[84:87], v[208:211], v[190:193], v[84:87]
	v_mfma_f32_16x16x32_bf16 v[80:83], v[232:235], v[190:193], v[80:83]
	v_mfma_f32_16x16x32_bf16 v[68:71], v[208:211], v[198:201], v[68:71]
	v_mfma_f32_16x16x32_bf16 v[64:67], v[232:235], v[198:201], v[64:67]
	v_mfma_f32_16x16x32_bf16 v[116:119], v[226:229], v[148:151], v[116:119]
	v_mfma_f32_16x16x32_bf16 v[112:115], v[236:239], v[148:151], v[112:115]
	v_mfma_f32_16x16x32_bf16 v[100:103], v[226:229], v[186:189], v[100:103]
	v_mfma_f32_16x16x32_bf16 v[96:99], v[236:239], v[186:189], v[96:99]
	v_mfma_f32_16x16x32_bf16 v[84:87], v[226:229], v[194:197], v[84:87]
	v_mfma_f32_16x16x32_bf16 v[80:83], v[236:239], v[194:197], v[80:83]
	v_mfma_f32_16x16x32_bf16 v[68:71], v[226:229], v[204:207], v[68:71]
	v_mfma_f32_16x16x32_bf16 v[64:67], v[236:239], v[204:207], v[64:67]
	s_mov_b32 m0, s65
	v_lshl_add_u64 v[212:213], v[240:241], 0, s[80:81]
	s_barrier
	ds_read_b128 v[144:147], v203 offset:49152
	ds_read_b128 v[148:151], v203 offset:50176
	ds_read_b128 v[152:155], v203 offset:51200
	ds_read_b128 v[186:189], v203 offset:52224
	ds_read_b128 v[190:193], v203 offset:53248
	ds_read_b128 v[194:197], v203 offset:54272
	ds_read_b128 v[198:201], v203 offset:55296
	ds_read_b128 v[204:207], v203 offset:56320
	global_load_lds_dwordx4 v[212:213], off
	v_lshl_add_u64 v[212:213], v[242:243], 0, s[80:81]
	s_mov_b32 m0, s70
	s_nop 0
	global_load_lds_dwordx4 v[212:213], off
	s_barrier
	s_waitcnt lgkmcnt(0)
	s_waitcnt lgkmcnt(0)
	v_mfma_f32_16x16x32_bf16 v[60:63], v[128:131], v[144:147], v[60:63]
	v_mfma_f32_16x16x32_bf16 v[56:59], v[136:139], v[144:147], v[56:59]
	v_mfma_f32_16x16x32_bf16 v[44:47], v[128:131], v[152:155], v[44:47]
	v_mfma_f32_16x16x32_bf16 v[40:43], v[136:139], v[152:155], v[40:43]
	v_mfma_f32_16x16x32_bf16 v[28:31], v[128:131], v[190:193], v[28:31]
	v_mfma_f32_16x16x32_bf16 v[24:27], v[136:139], v[190:193], v[24:27]
	v_mfma_f32_16x16x32_bf16 v[12:15], v[128:131], v[198:201], v[12:15]
	v_mfma_f32_16x16x32_bf16 v[8:11], v[136:139], v[198:201], v[8:11]
	v_mfma_f32_16x16x32_bf16 v[60:63], v[132:135], v[148:151], v[60:63]
	v_mfma_f32_16x16x32_bf16 v[56:59], v[140:143], v[148:151], v[56:59]
	v_mfma_f32_16x16x32_bf16 v[44:47], v[132:135], v[186:189], v[44:47]
	v_mfma_f32_16x16x32_bf16 v[40:43], v[140:143], v[186:189], v[40:43]
	v_mfma_f32_16x16x32_bf16 v[28:31], v[132:135], v[194:197], v[28:31]
	v_mfma_f32_16x16x32_bf16 v[24:27], v[140:143], v[194:197], v[24:27]
	v_mfma_f32_16x16x32_bf16 v[12:15], v[132:135], v[204:207], v[12:15]
	v_mfma_f32_16x16x32_bf16 v[8:11], v[140:143], v[204:207], v[8:11]
	s_barrier
	s_add_u32 s48, vcc_lo, 0x40080
	s_addc_u32 s49, vcc_hi, 0
	s_add_i32 s74, s75, s7
	s_mov_b32 m0, s74
	s_nop 0
	global_load_lds_dwordx4 v174, s[48:49]
	s_add_i32 m0, s74, 0x2000
	s_nop 0
	global_load_lds_dwordx4 v156, s[48:49]
	s_waitcnt vmcnt(10)
	s_barrier
	v_mfma_f32_16x16x32_bf16 v[52:55], v[208:211], v[144:147], v[52:55]
	v_mfma_f32_16x16x32_bf16 v[48:51], v[232:235], v[144:147], v[48:51]
	v_mfma_f32_16x16x32_bf16 v[36:39], v[208:211], v[152:155], v[36:39]
	v_mfma_f32_16x16x32_bf16 v[32:35], v[232:235], v[152:155], v[32:35]
	v_mfma_f32_16x16x32_bf16 v[20:23], v[208:211], v[190:193], v[20:23]
	v_mfma_f32_16x16x32_bf16 v[16:19], v[232:235], v[190:193], v[16:19]
	v_mfma_f32_16x16x32_bf16 v[4:7], v[208:211], v[198:201], v[4:7]
	v_mfma_f32_16x16x32_bf16 v[0:3], v[232:235], v[198:201], v[0:3]
	v_mfma_f32_16x16x32_bf16 v[52:55], v[226:229], v[148:151], v[52:55]
	v_mfma_f32_16x16x32_bf16 v[48:51], v[236:239], v[148:151], v[48:51]
	v_mfma_f32_16x16x32_bf16 v[36:39], v[226:229], v[186:189], v[36:39]
	v_mfma_f32_16x16x32_bf16 v[32:35], v[236:239], v[186:189], v[32:35]
	v_mfma_f32_16x16x32_bf16 v[20:23], v[226:229], v[194:197], v[20:23]
	v_mfma_f32_16x16x32_bf16 v[16:19], v[236:239], v[194:197], v[16:19]
	v_mfma_f32_16x16x32_bf16 v[4:7], v[226:229], v[204:207], v[4:7]
	v_mfma_f32_16x16x32_bf16 v[0:3], v[236:239], v[204:207], v[0:3]
	s_add_i32 s73, s73, 2
	s_add_u32 s34, s34, 0x100
	s_addc_u32 s35, s35, 0
	s_add_u32 s52, s52, 0x100
	s_addc_u32 s72, s72, 0
	s_cmp_gt_u32 s73, 13
	s_barrier
	s_cbranch_scc0 .LBB0_863
	s_cmp_lt_u32 s101, 0x100
	s_cbranch_scc0 .Lxa_6
	s_barrier

; #define PG8_STAGE(bufoff, gbase, voff) do { _Pragma("unroll") for (int _i = 0; _i < 2; ++_i) \
;     __builtin_amdgcn_global_load_lds((const unsigned*)((const char*)(gbase) + (voff)[_i]), (LAS unsigned*)(lds + (bufoff) + ldsw + _i * 8192), 16, 0, 0); } while (0)
; #define PG8_LDA(dst, b, h) do { _Pragma("unroll") for (int m = 0; m < 4; ++m) _Pragma("unroll") for (int k = 0; k < 2; ++k) dst[m][k] = *(const LAS bf16x8*)(lds + PG8_SA(b, h) + aoff + m * 2048 + k * 1024); } while (0)
; #define PG8_LDB(dst, b, h) do { _Pragma("unroll") for (int n = 0; n < 2; ++n) _Pragma("unroll") for (int k = 0; k < 2; ++k) dst[n][k] = *(const LAS bf16x8*)(lds + PG8_SB(b, h) + boff + n * 2048 + k * 1024); } while (0)
; #define PG8_MMA(ai, bj, At, Bt) do { __builtin_amdgcn_s_setprio(1); _Pragma("unroll") for (int m = 0; m < 4; ++m) _Pragma("unroll") for (int n = 0; n < 2; ++n) _Pragma("unroll") for (int k = 0; k < 2; ++k) \
;     acc[ai][bj][m][n] = __builtin_amdgcn_mfma_f32_16x16x32_bf16(Bt[n][k], At[m][k], acc[ai][bj][m][n], 0, 0, 0); __builtin_amdgcn_s_setprio(0); } while (0)
; #define PG8_WAIT_L(n) asm volatile("s_waitcnt lgkmcnt(" #n ")" ::: "memory")
; template <class Epi, class Sched>
; __device__ __forceinline__ void gemm_phase(LAS unsigned char* lds, const Gemm g, const Sched& S, const Epi& E) {
;     ...
;     const bool has_next = S.next(ui + 1, nxt);
;     const char* nA = has_next ? (const char*)g.A + (size_t)nxt.pm * tstep : cA; const char* nB = has_next ? (const char*)g.Bt + (size_t)nxt.pn * tstep : cB;
;     for (int t = 0; t < nt; t += 2) {
;       const bool last = (t == nt - 2);
;       const char* a1 = cA + (size_t)(t + 1) * kstep;
;       const char* a2 = last ? nA : cA + (size_t)(t + 2) * kstep; const char* b2 = last ? nB : cB + (size_t)(t + 2) * kstep;
;       const char* a3 = a2 + kstep; const char* b3 = b2 + kstep;
;       if (last && has_next) S.a_ready(nxt);
;       PG8_LDB(B0, 0, 0); PG8_SCHED; PG8_LDA(At, 0, 0); PG8_STAGE(PG8_SA(1, 1), a1 + hstep, voffA);
;       PG8_WAIT_L(8); PG8_BAR; PG8_WAIT_L(0); PG8_MMA(0, 0, At, B0); PG8_BAR; PG8_SCHED;
;     ...
; #pragma unroll
;     for (int a = 0; a < 2; ++a)
; #pragma unroll
;       for (int b = 0; b < 2; ++b)
; #pragma unroll
;         for (int m = 0; m < 4; ++m)
; #pragma unroll
;           for (int n = 0; n < 2; ++n) acc[a][b][m][n] = (f32x4){0.f, 0.f, 0.f, 0.f};
;     cur = nxt; cA = nA; cB = nB; ++ui;
.LBB0_889:
	v_mov_b64_e32 v[0:1], 0x48
	s_ashr_i32 s35, s34, 31
	v_cmp_lt_i64_e32 vcc, s[36:37], v[0:1]
	s_lshl_b64 s[36:37], s[34:35], 19
	s_add_u32 s36, s60, s36
	s_addc_u32 s37, s61, s37
	s_and_b64 s[40:41], vcc, exec
	s_cselect_b32 s35, s37, s43
	s_cselect_b32 s70, s36, s42
	s_ashr_i32 s23, s22, 31
	s_lshl_b64 s[40:41], s[22:23], 19
	v_readlane_b32 s48, v254, 51
	v_readlane_b32 s49, v254, 52
	s_add_u32 s40, s48, s40
	s_addc_u32 s41, s49, s41
	s_and_b64 s[48:49], vcc, exec
	s_cselect_b32 s23, s41, s45
	s_cselect_b32 s71, s40, s44
	s_add_u32 s42, s42, 0x40080
	s_addc_u32 s43, s43, 0
	s_add_u32 s52, s44, 0x100
	v_mov_b32_e32 v0, 0
	s_addc_u32 s72, s45, 0
	s_mov_b32 s73, -2
	v_mov_b32_e32 v1, v0
	v_mov_b64_e32 v[2:3], v[0:1]
	v_mov_b64_e32 v[4:5], v[0:1]
	v_mov_b64_e32 v[6:7], v[0:1]
	v_mov_b64_e32 v[8:9], v[0:1]
	v_mov_b64_e32 v[10:11], v[0:1]
	v_mov_b64_e32 v[12:13], v[0:1]
	v_mov_b64_e32 v[14:15], v[0:1]
	v_mov_b64_e32 v[16:17], v[0:1]
	v_mov_b64_e32 v[18:19], v[0:1]
	v_mov_b64_e32 v[20:21], v[0:1]
	v_mov_b64_e32 v[22:23], v[0:1]
	v_mov_b64_e32 v[24:25], v[0:1]
	v_mov_b64_e32 v[26:27], v[0:1]
	v_mov_b64_e32 v[28:29], v[0:1]
	v_mov_b64_e32 v[30:31], v[0:1]
	v_mov_b64_e32 v[32:33], v[0:1]
	v_mov_b64_e32 v[34:35], v[0:1]
	v_mov_b64_e32 v[36:37], v[0:1]
	v_mov_b64_e32 v[38:39], v[0:1]
	v_mov_b64_e32 v[40:41], v[0:1]
	v_mov_b64_e32 v[42:43], v[0:1]
	v_mov_b64_e32 v[44:45], v[0:1]
	v_mov_b64_e32 v[46:47], v[0:1]
	v_mov_b64_e32 v[48:49], v[0:1]
	v_mov_b64_e32 v[50:51], v[0:1]
	v_mov_b64_e32 v[52:53], v[0:1]
	v_mov_b64_e32 v[54:55], v[0:1]
	v_mov_b64_e32 v[56:57], v[0:1]
	v_mov_b64_e32 v[58:59], v[0:1]
	v_mov_b64_e32 v[60:61], v[0:1]
	v_mov_b64_e32 v[62:63], v[0:1]
	v_mov_b64_e32 v[64:65], v[0:1]
	v_mov_b64_e32 v[66:67], v[0:1]
	v_mov_b64_e32 v[68:69], v[0:1]
	v_mov_b64_e32 v[70:71], v[0:1]
	v_mov_b64_e32 v[72:73], v[0:1]
	v_mov_b64_e32 v[74:75], v[0:1]
	v_mov_b64_e32 v[76:77], v[0:1]
	v_mov_b64_e32 v[78:79], v[0:1]
	v_mov_b64_e32 v[80:81], v[0:1]
	v_mov_b64_e32 v[82:83], v[0:1]
	v_mov_b64_e32 v[84:85], v[0:1]
	v_mov_b64_e32 v[86:87], v[0:1]
	v_mov_b64_e32 v[88:89], v[0:1]
	v_mov_b64_e32 v[90:91], v[0:1]
	v_mov_b64_e32 v[92:93], v[0:1]
	v_mov_b64_e32 v[94:95], v[0:1]
	v_mov_b64_e32 v[96:97], v[0:1]
	v_mov_b64_e32 v[98:99], v[0:1]
	v_mov_b64_e32 v[100:101], v[0:1]
	v_mov_b64_e32 v[102:103], v[0:1]
	v_mov_b64_e32 v[104:105], v[0:1]
	v_mov_b64_e32 v[106:107], v[0:1]
	v_mov_b64_e32 v[108:109], v[0:1]
	v_mov_b64_e32 v[110:111], v[0:1]
	v_mov_b64_e32 v[112:113], v[0:1]
	v_mov_b64_e32 v[114:115], v[0:1]
	v_mov_b64_e32 v[116:117], v[0:1]
	v_mov_b64_e32 v[118:119], v[0:1]
	v_mov_b64_e32 v[120:121], v[0:1]
	v_mov_b64_e32 v[122:123], v[0:1]
	v_mov_b64_e32 v[124:125], v[0:1]
	v_mov_b64_e32 v[126:127], v[0:1]
	s_cmp_eq_u32 s100, 0
	s_cbranch_scc1 .Lxs_e7
	s_barrier
	s_mov_b32 s100, 0
.Lxs_e7:
.LBB0_890:
	s_add_u32 s44, s42, 0xfffc0080
	s_addc_u32 s45, s43, -1
	s_add_i32 s74, 0, 0x10000
	v_add_u32_e32 v143, s74, v141
	ds_read_b128 v[144:147], v143
	ds_read_b128 v[148:151], v143 offset:1024
	ds_read_b128 v[152:155], v143 offset:2048
	ds_read_b128 v[156:159], v143 offset:3072
	s_cmp_eq_u32 s73, 12
	s_cselect_b32 s49, s35, s45
	s_cselect_b32 s48, s70, s44
	s_cselect_b32 s45, s23, s72
	s_cselect_b32 s44, s71, s52
	s_add_i32 m0, s12, 0xc000
	ds_read_b128 v[174:177], v142
	ds_read_b128 v[178:181], v142 offset:1024
	ds_read_b128 v[182:185], v142 offset:2048
	ds_read_b128 v[186:189], v142 offset:3072
	ds_read_b128 v[190:193], v142 offset:4096
	ds_read_b128 v[194:197], v142 offset:5120
	ds_read_b128 v[198:201], v142 offset:6144
	ds_read_b128 v[202:205], v142 offset:7168
	global_load_lds_dwordx4 v136, s[42:43]
	s_add_i32 m0, s12, 0xe000
	s_nop 0
	global_load_lds_dwordx4 v138, s[42:43]
	s_waitcnt vmcnt(8)
	s_waitcnt lgkmcnt(8)
	s_barrier
	s_waitcnt lgkmcnt(0)
	s_waitcnt lgkmcnt(0)
	v_mfma_f32_16x16x32_bf16 v[124:127], v[144:147], v[174:177], v[124:127]
	v_mfma_f32_16x16x32_bf16 v[120:123], v[152:155], v[174:177], v[120:123]
	v_mfma_f32_16x16x32_bf16 v[116:119], v[144:147], v[182:185], v[116:119]
	v_mfma_f32_16x16x32_bf16 v[112:115], v[152:155], v[182:185], v[112:115]
	v_mfma_f32_16x16x32_bf16 v[100:103], v[144:147], v[190:193], v[100:103]
	v_mfma_f32_16x16x32_bf16 v[96:99], v[152:155], v[190:193], v[96:99]
	v_mfma_f32_16x16x32_bf16 v[84:87], v[144:147], v[198:201], v[84:87]
	v_mfma_f32_16x16x32_bf16 v[80:83], v[152:155], v[198:201], v[80:83]
	v_mfma_f32_16x16x32_bf16 v[124:127], v[148:151], v[178:181], v[124:127]
	v_mfma_f32_16x16x32_bf16 v[120:123], v[156:159], v[178:181], v[120:123]
	v_mfma_f32_16x16x32_bf16 v[116:119], v[148:151], v[186:189], v[116:119]
	v_mfma_f32_16x16x32_bf16 v[112:115], v[156:159], v[186:189], v[112:115]
	v_mfma_f32_16x16x32_bf16 v[100:103], v[148:151], v[194:197], v[100:103]
	v_mfma_f32_16x16x32_bf16 v[96:99], v[156:159], v[194:197], v[96:99]
	v_mfma_f32_16x16x32_bf16 v[84:87], v[148:151], v[202:205], v[84:87]
	v_mfma_f32_16x16x32_bf16 v[80:83], v[156:159], v[202:205], v[80:83]
	s_barrier
	s_add_i32 s76, 0, 0x14000
	s_add_i32 s74, s74, s7
	v_add_u32_e32 v143, s76, v141
	s_mov_b32 m0, s74
	ds_read_b128 v[206:209], v143
	ds_read_b128 v[210:213], v143 offset:1024
	ds_read_b128 v[226:229], v143 offset:2048
	ds_read_b128 v[232:235], v143 offset:3072
	global_load_lds_dwordx4 v132, s[44:45]
	s_add_i32 m0, s74, 0x2000
	s_nop 0
	global_load_lds_dwordx4 v128, s[44:45]
	s_barrier
; #define PG8_STAGE(bufoff, gbase, voff) do { _Pragma("unroll") for (int _i = 0; _i < 2; ++_i) \
;     __builtin_amdgcn_global_load_lds((const unsigned*)((const char*)(gbase) + (voff)[_i]), (LAS unsigned*)(lds + (bufoff) + ldsw + _i * 8192), 16, 0, 0); } while (0)
; #define PG8_LDA(dst, b, h) do { _Pragma("unroll") for (int m = 0; m < 4; ++m) _Pragma("unroll") for (int k = 0; k < 2; ++k) dst[m][k] = *(const LAS bf16x8*)(lds + PG8_SA(b, h) + aoff + m * 2048 + k * 1024); } while (0)
; #define PG8_LDB(dst, b, h) do { _Pragma("unroll") for (int n = 0; n < 2; ++n) _Pragma("unroll") for (int k = 0; k < 2; ++k) dst[n][k] = *(const LAS bf16x8*)(lds + PG8_SB(b, h) + boff + n * 2048 + k * 1024); } while (0)
; #define PG8_MMA(ai, bj, At, Bt) do { __builtin_amdgcn_s_setprio(1); _Pragma("unroll") for (int m = 0; m < 4; ++m) _Pragma("unroll") for (int n = 0; n < 2; ++n) _Pragma("unroll") for (int k = 0; k < 2; ++k) \
;     acc[ai][bj][m][n] = __builtin_amdgcn_mfma_f32_16x16x32_bf16(Bt[n][k], At[m][k], acc[ai][bj][m][n], 0, 0, 0); __builtin_amdgcn_s_setprio(0); } while (0)
; #define PG8_WAIT_V(n) asm volatile("s_waitcnt vmcnt(" #n ")" ::: "memory")
; #define PG8_WAIT_L(n) asm volatile("s_waitcnt lgkmcnt(" #n ")" ::: "memory")
; #define PG8_BAR __builtin_amdgcn_s_barrier()
; #define PG8_SCHED __builtin_amdgcn_sched_barrier(0)
; template <class Epi, class Sched>
; __device__ __forceinline__ void gemm_phase(LAS unsigned char* lds, const Gemm g, const Sched& S, const Epi& E) {
;     ...
;       PG8_LDB(B1, 0, 1); PG8_STAGE(PG8_SB(0, 0), b2, voffB);
;       PG8_BAR; PG8_WAIT_L(0); PG8_MMA(0, 1, At, B1); PG8_BAR;
;       PG8_LDA(At, 0, 1); PG8_STAGE(PG8_SA(0, 0), a2, voffA);
;       PG8_BAR; PG8_WAIT_L(0); PG8_MMA(1, 0, At, B0); PG8_BAR; PG8_SCHED;
;       PG8_STAGE(PG8_SB(0, 1), b2 + hstep, voffB);
;       PG8_WAIT_V(6); PG8_BAR; PG8_MMA(1, 1, At, B1); PG8_BAR;
;       PG8_LDB(B0, 1, 0); PG8_SCHED; PG8_LDA(At, 1, 0); PG8_STAGE(PG8_SA(0, 1), a2 + hstep, voffA);
;       PG8_WAIT_L(8); PG8_BAR; PG8_WAIT_L(0); PG8_MMA(0, 0, At, B0); PG8_BAR; PG8_SCHED;
	s_waitcnt lgkmcnt(0)
	s_waitcnt lgkmcnt(0)
	v_mfma_f32_16x16x32_bf16 v[108:111], v[206:209], v[174:177], v[108:111]
	v_mfma_f32_16x16x32_bf16 v[104:107], v[226:229], v[174:177], v[104:107]
	v_mfma_f32_16x16x32_bf16 v[92:95], v[206:209], v[182:185], v[92:95]
	v_mfma_f32_16x16x32_bf16 v[88:91], v[226:229], v[182:185], v[88:91]
	v_mfma_f32_16x16x32_bf16 v[76:79], v[206:209], v[190:193], v[76:79]
	v_mfma_f32_16x16x32_bf16 v[72:75], v[226:229], v[190:193], v[72:75]
	v_mfma_f32_16x16x32_bf16 v[68:71], v[206:209], v[198:201], v[68:71]
	v_mfma_f32_16x16x32_bf16 v[64:67], v[226:229], v[198:201], v[64:67]
	v_mfma_f32_16x16x32_bf16 v[108:111], v[210:213], v[178:181], v[108:111]
	v_mfma_f32_16x16x32_bf16 v[104:107], v[232:235], v[178:181], v[104:107]
	v_mfma_f32_16x16x32_bf16 v[92:95], v[210:213], v[186:189], v[92:95]
	v_mfma_f32_16x16x32_bf16 v[88:91], v[232:235], v[186:189], v[88:91]
	v_mfma_f32_16x16x32_bf16 v[76:79], v[210:213], v[194:197], v[76:79]
	v_mfma_f32_16x16x32_bf16 v[72:75], v[232:235], v[194:197], v[72:75]
	v_mfma_f32_16x16x32_bf16 v[68:71], v[210:213], v[202:205], v[68:71]
	v_mfma_f32_16x16x32_bf16 v[64:67], v[232:235], v[202:205], v[64:67]
	s_mov_b32 m0, s12
	v_lshl_add_u64 v[238:239], s[48:49], 0, v[134:135]
	s_barrier
	ds_read_b128 v[174:177], v142 offset:16384
	ds_read_b128 v[178:181], v142 offset:17408
	ds_read_b128 v[182:185], v142 offset:18432
	ds_read_b128 v[186:189], v142 offset:19456
	ds_read_b128 v[190:193], v142 offset:20480
	ds_read_b128 v[194:197], v142 offset:21504
	ds_read_b128 v[198:201], v142 offset:22528
	ds_read_b128 v[202:205], v142 offset:23552
	global_load_lds_dwordx4 v134, s[48:49]
	v_lshl_add_u64 v[240:241], s[48:49], 0, v[130:131]
	s_mov_b32 m0, s13
	s_nop 0
	global_load_lds_dwordx4 v130, s[48:49]
	s_barrier
	s_waitcnt lgkmcnt(0)
	s_waitcnt lgkmcnt(0)
	v_mfma_f32_16x16x32_bf16 v[60:63], v[144:147], v[174:177], v[60:63]
	v_mfma_f32_16x16x32_bf16 v[56:59], v[152:155], v[174:177], v[56:59]
	v_mfma_f32_16x16x32_bf16 v[52:55], v[144:147], v[182:185], v[52:55]
	v_mfma_f32_16x16x32_bf16 v[48:51], v[152:155], v[182:185], v[48:51]
	v_mfma_f32_16x16x32_bf16 v[36:39], v[144:147], v[190:193], v[36:39]
	v_mfma_f32_16x16x32_bf16 v[32:35], v[152:155], v[190:193], v[32:35]
	v_mfma_f32_16x16x32_bf16 v[20:23], v[144:147], v[198:201], v[20:23]
	v_mfma_f32_16x16x32_bf16 v[16:19], v[152:155], v[198:201], v[16:19]
	v_mfma_f32_16x16x32_bf16 v[60:63], v[148:151], v[178:181], v[60:63]
	v_mfma_f32_16x16x32_bf16 v[56:59], v[156:159], v[178:181], v[56:59]
	v_mfma_f32_16x16x32_bf16 v[52:55], v[148:151], v[186:189], v[52:55]
	v_mfma_f32_16x16x32_bf16 v[48:51], v[156:159], v[186:189], v[48:51]
	v_mfma_f32_16x16x32_bf16 v[36:39], v[148:151], v[194:197], v[36:39]
	v_mfma_f32_16x16x32_bf16 v[32:35], v[156:159], v[194:197], v[32:35]
	v_mfma_f32_16x16x32_bf16 v[20:23], v[148:151], v[202:205], v[20:23]
	v_mfma_f32_16x16x32_bf16 v[16:19], v[156:159], v[202:205], v[16:19]
	s_barrier
	s_add_u32 s74, s44, 0x40000
	s_addc_u32 s75, s45, 0
	s_add_i32 s76, s76, s7
	s_mov_b32 m0, s76
	s_nop 0
	global_load_lds_dwordx4 v132, s[74:75]
	s_add_i32 m0, s76, 0x2000
	s_nop 0
	global_load_lds_dwordx4 v128, s[74:75]
	s_waitcnt vmcnt(10)
	s_barrier
	v_mfma_f32_16x16x32_bf16 v[44:47], v[206:209], v[174:177], v[44:47]
	v_mfma_f32_16x16x32_bf16 v[40:43], v[226:229], v[174:177], v[40:43]
	v_mfma_f32_16x16x32_bf16 v[28:31], v[206:209], v[182:185], v[28:31]
	v_mfma_f32_16x16x32_bf16 v[24:27], v[226:229], v[182:185], v[24:27]
	v_mfma_f32_16x16x32_bf16 v[12:15], v[206:209], v[190:193], v[12:15]
	v_mfma_f32_16x16x32_bf16 v[8:11], v[226:229], v[190:193], v[8:11]
	v_mfma_f32_16x16x32_bf16 v[4:7], v[206:209], v[198:201], v[4:7]
	v_mfma_f32_16x16x32_bf16 v[0:3], v[226:229], v[198:201], v[0:3]
	v_mfma_f32_16x16x32_bf16 v[44:47], v[210:213], v[178:181], v[44:47]
	v_mfma_f32_16x16x32_bf16 v[40:43], v[232:235], v[178:181], v[40:43]
	v_mfma_f32_16x16x32_bf16 v[28:31], v[210:213], v[186:189], v[28:31]
	v_mfma_f32_16x16x32_bf16 v[24:27], v[232:235], v[186:189], v[24:27]
	v_mfma_f32_16x16x32_bf16 v[12:15], v[210:213], v[194:197], v[12:15]
	v_mfma_f32_16x16x32_bf16 v[8:11], v[232:235], v[194:197], v[8:11]
	v_mfma_f32_16x16x32_bf16 v[4:7], v[210:213], v[202:205], v[4:7]
	v_mfma_f32_16x16x32_bf16 v[0:3], v[232:235], v[202:205], v[0:3]
	s_add_i32 s74, 0, 0x18000
	v_add_u32_e32 v143, s74, v141
	s_barrier
	ds_read_b128 v[144:147], v143
	ds_read_b128 v[148:151], v143 offset:1024
	ds_read_b128 v[152:155], v143 offset:2048
	ds_read_b128 v[156:159], v143 offset:3072
	s_add_u32 s48, s48, 0x40000
	s_addc_u32 s49, s49, 0
	s_mov_b32 m0, s51
	ds_read_b128 v[174:177], v142 offset:32768
	ds_read_b128 v[178:181], v142 offset:33792
	ds_read_b128 v[182:185], v142 offset:34816
	ds_read_b128 v[186:189], v142 offset:35840
	ds_read_b128 v[190:193], v142 offset:36864
	ds_read_b128 v[194:197], v142 offset:37888
	ds_read_b128 v[198:201], v142 offset:38912
	ds_read_b128 v[202:205], v142 offset:39936
	global_load_lds_dwordx4 v134, s[48:49]
	s_mov_b32 m0, s62
	s_nop 0
	global_load_lds_dwordx4 v130, s[48:49]
	s_waitcnt vmcnt(8)
	s_waitcnt lgkmcnt(8)
	s_barrier
; #define PG8_STAGE(bufoff, gbase, voff) do { _Pragma("unroll") for (int _i = 0; _i < 2; ++_i) \
;     __builtin_amdgcn_global_load_lds((const unsigned*)((const char*)(gbase) + (voff)[_i]), (LAS unsigned*)(lds + (bufoff) + ldsw + _i * 8192), 16, 0, 0); } while (0)
; #define PG8_LDA(dst, b, h) do { _Pragma("unroll") for (int m = 0; m < 4; ++m) _Pragma("unroll") for (int k = 0; k < 2; ++k) dst[m][k] = *(const LAS bf16x8*)(lds + PG8_SA(b, h) + aoff + m * 2048 + k * 1024); } while (0)
; #define PG8_LDB(dst, b, h) do { _Pragma("unroll") for (int n = 0; n < 2; ++n) _Pragma("unroll") for (int k = 0; k < 2; ++k) dst[n][k] = *(const LAS bf16x8*)(lds + PG8_SB(b, h) + boff + n * 2048 + k * 1024); } while (0)
; #define PG8_MMA(ai, bj, At, Bt) do { __builtin_amdgcn_s_setprio(1); _Pragma("unroll") for (int m = 0; m < 4; ++m) _Pragma("unroll") for (int n = 0; n < 2; ++n) _Pragma("unroll") for (int k = 0; k < 2; ++k) \
;     acc[ai][bj][m][n] = __builtin_amdgcn_mfma_f32_16x16x32_bf16(Bt[n][k], At[m][k], acc[ai][bj][m][n], 0, 0, 0); __builtin_amdgcn_s_setprio(0); } while (0)
; #define PG8_WAIT_V(n) asm volatile("s_waitcnt vmcnt(" #n ")" ::: "memory")
; #define PG8_WAIT_L(n) asm volatile("s_waitcnt lgkmcnt(" #n ")" ::: "memory")
; #define PG8_BAR __builtin_amdgcn_s_barrier()
; #define PG8_SCHED __builtin_amdgcn_sched_barrier(0)
; template <class Epi, class Sched>
; __device__ __forceinline__ void gemm_phase(LAS unsigned char* lds, const Gemm g, const Sched& S, const Epi& E) {
;     ...
;       PG8_WAIT_L(8); PG8_BAR; PG8_WAIT_L(0); PG8_MMA(0, 0, At, B0); PG8_BAR; PG8_SCHED;
;       PG8_LDB(B1, 1, 1); PG8_STAGE(PG8_SB(1, 0), b3, voffB);
;       PG8_BAR; PG8_WAIT_L(0); PG8_MMA(0, 1, At, B1); PG8_BAR;
;       PG8_LDA(At, 1, 1); PG8_STAGE(PG8_SA(1, 0), a3, voffA);
;       PG8_BAR; PG8_WAIT_L(0); PG8_MMA(1, 0, At, B0); PG8_BAR; PG8_SCHED;
;       PG8_STAGE(PG8_SB(1, 1), b3 + hstep, voffB);
;       PG8_WAIT_V(6); PG8_BAR; PG8_MMA(1, 1, At, B1); PG8_BAR;
;     }
	s_waitcnt lgkmcnt(0)
	s_waitcnt lgkmcnt(0)
	v_mfma_f32_16x16x32_bf16 v[124:127], v[144:147], v[174:177], v[124:127]
	v_mfma_f32_16x16x32_bf16 v[120:123], v[152:155], v[174:177], v[120:123]
	v_mfma_f32_16x16x32_bf16 v[116:119], v[144:147], v[182:185], v[116:119]
	v_mfma_f32_16x16x32_bf16 v[112:115], v[152:155], v[182:185], v[112:115]
	v_mfma_f32_16x16x32_bf16 v[100:103], v[144:147], v[190:193], v[100:103]
	v_mfma_f32_16x16x32_bf16 v[96:99], v[152:155], v[190:193], v[96:99]
	v_mfma_f32_16x16x32_bf16 v[84:87], v[144:147], v[198:201], v[84:87]
	v_mfma_f32_16x16x32_bf16 v[80:83], v[152:155], v[198:201], v[80:83]
	v_mfma_f32_16x16x32_bf16 v[124:127], v[148:151], v[178:181], v[124:127]
	v_mfma_f32_16x16x32_bf16 v[120:123], v[156:159], v[178:181], v[120:123]
	v_mfma_f32_16x16x32_bf16 v[116:119], v[148:151], v[186:189], v[116:119]
	v_mfma_f32_16x16x32_bf16 v[112:115], v[156:159], v[186:189], v[112:115]
	v_mfma_f32_16x16x32_bf16 v[100:103], v[148:151], v[194:197], v[100:103]
	v_mfma_f32_16x16x32_bf16 v[96:99], v[156:159], v[194:197], v[96:99]
	v_mfma_f32_16x16x32_bf16 v[84:87], v[148:151], v[202:205], v[84:87]
	v_mfma_f32_16x16x32_bf16 v[80:83], v[156:159], v[202:205], v[80:83]
	s_barrier
	s_add_i32 s48, 0, 0x1c000
	s_add_i32 s49, s74, s7
	v_add_u32_e32 v143, s48, v141
	s_add_u32 s98, s44, s80
	s_addc_u32 s99, s45, s81
	s_mov_b32 m0, s49
	ds_read_b128 v[206:209], v143
	ds_read_b128 v[210:213], v143 offset:1024
	ds_read_b128 v[226:229], v143 offset:2048
	ds_read_b128 v[232:235], v143 offset:3072
	global_load_lds_dwordx4 v132, s[98:99]
	v_lshl_add_u64 v[222:223], v[236:237], 0, s[80:81]
	s_add_i32 m0, s49, 0x2000
	s_nop 0
	global_load_lds_dwordx4 v128, s[98:99]
	s_barrier
	s_waitcnt lgkmcnt(0)
	s_waitcnt lgkmcnt(0)
	v_mfma_f32_16x16x32_bf16 v[108:111], v[206:209], v[174:177], v[108:111]
	v_mfma_f32_16x16x32_bf16 v[104:107], v[226:229], v[174:177], v[104:107]
	v_mfma_f32_16x16x32_bf16 v[92:95], v[206:209], v[182:185], v[92:95]
	v_mfma_f32_16x16x32_bf16 v[88:91], v[226:229], v[182:185], v[88:91]
	v_mfma_f32_16x16x32_bf16 v[76:79], v[206:209], v[190:193], v[76:79]
	v_mfma_f32_16x16x32_bf16 v[72:75], v[226:229], v[190:193], v[72:75]
	v_mfma_f32_16x16x32_bf16 v[68:71], v[206:209], v[198:201], v[68:71]
	v_mfma_f32_16x16x32_bf16 v[64:67], v[226:229], v[198:201], v[64:67]
	v_mfma_f32_16x16x32_bf16 v[108:111], v[210:213], v[178:181], v[108:111]
	v_mfma_f32_16x16x32_bf16 v[104:107], v[232:235], v[178:181], v[104:107]
	v_mfma_f32_16x16x32_bf16 v[92:95], v[210:213], v[186:189], v[92:95]
	v_mfma_f32_16x16x32_bf16 v[88:91], v[232:235], v[186:189], v[88:91]
	v_mfma_f32_16x16x32_bf16 v[76:79], v[210:213], v[194:197], v[76:79]
	v_mfma_f32_16x16x32_bf16 v[72:75], v[232:235], v[194:197], v[72:75]
	v_mfma_f32_16x16x32_bf16 v[68:71], v[210:213], v[202:205], v[68:71]
	v_mfma_f32_16x16x32_bf16 v[64:67], v[232:235], v[202:205], v[64:67]
	s_mov_b32 m0, s63
	v_lshl_add_u64 v[222:223], v[238:239], 0, s[80:81]
	s_barrier
	ds_read_b128 v[174:177], v142 offset:49152
	ds_read_b128 v[178:181], v142 offset:50176
	ds_read_b128 v[182:185], v142 offset:51200
	ds_read_b128 v[186:189], v142 offset:52224
	ds_read_b128 v[190:193], v142 offset:53248
	ds_read_b128 v[194:197], v142 offset:54272
	ds_read_b128 v[198:201], v142 offset:55296
	ds_read_b128 v[202:205], v142 offset:56320
	global_load_lds_dwordx4 v[222:223], off
	v_lshl_add_u64 v[222:223], v[240:241], 0, s[80:81]
	s_mov_b32 m0, s64
	s_nop 0
	global_load_lds_dwordx4 v[222:223], off
	s_barrier
	s_waitcnt lgkmcnt(0)
	s_waitcnt lgkmcnt(0)
	v_mfma_f32_16x16x32_bf16 v[60:63], v[144:147], v[174:177], v[60:63]
	v_mfma_f32_16x16x32_bf16 v[56:59], v[152:155], v[174:177], v[56:59]
	v_mfma_f32_16x16x32_bf16 v[52:55], v[144:147], v[182:185], v[52:55]
	v_mfma_f32_16x16x32_bf16 v[48:51], v[152:155], v[182:185], v[48:51]
	v_mfma_f32_16x16x32_bf16 v[36:39], v[144:147], v[190:193], v[36:39]
	v_mfma_f32_16x16x32_bf16 v[32:35], v[152:155], v[190:193], v[32:35]
	v_mfma_f32_16x16x32_bf16 v[20:23], v[144:147], v[198:201], v[20:23]
	v_mfma_f32_16x16x32_bf16 v[16:19], v[152:155], v[198:201], v[16:19]
	v_mfma_f32_16x16x32_bf16 v[60:63], v[148:151], v[178:181], v[60:63]
	v_mfma_f32_16x16x32_bf16 v[56:59], v[156:159], v[178:181], v[56:59]
	v_mfma_f32_16x16x32_bf16 v[52:55], v[148:151], v[186:189], v[52:55]
	v_mfma_f32_16x16x32_bf16 v[48:51], v[156:159], v[186:189], v[48:51]
	v_mfma_f32_16x16x32_bf16 v[36:39], v[148:151], v[194:197], v[36:39]
	v_mfma_f32_16x16x32_bf16 v[32:35], v[156:159], v[194:197], v[32:35]
	v_mfma_f32_16x16x32_bf16 v[20:23], v[148:151], v[202:205], v[20:23]
	v_mfma_f32_16x16x32_bf16 v[16:19], v[156:159], v[202:205], v[16:19]
	s_barrier
	s_add_u32 s44, s44, 0x40080
	s_addc_u32 s45, s45, 0
	s_add_i32 s48, s48, s7
	s_mov_b32 m0, s48
	s_nop 0
	global_load_lds_dwordx4 v132, s[44:45]
	s_add_i32 m0, s48, 0x2000
	s_nop 0
	global_load_lds_dwordx4 v128, s[44:45]
	s_waitcnt vmcnt(10)
	s_barrier
	v_mfma_f32_16x16x32_bf16 v[44:47], v[206:209], v[174:177], v[44:47]
	v_mfma_f32_16x16x32_bf16 v[40:43], v[226:229], v[174:177], v[40:43]
	v_mfma_f32_16x16x32_bf16 v[28:31], v[206:209], v[182:185], v[28:31]
	v_mfma_f32_16x16x32_bf16 v[24:27], v[226:229], v[182:185], v[24:27]
	v_mfma_f32_16x16x32_bf16 v[12:15], v[206:209], v[190:193], v[12:15]
	v_mfma_f32_16x16x32_bf16 v[8:11], v[226:229], v[190:193], v[8:11]
	v_mfma_f32_16x16x32_bf16 v[4:7], v[206:209], v[198:201], v[4:7]
	v_mfma_f32_16x16x32_bf16 v[0:3], v[226:229], v[198:201], v[0:3]
	v_mfma_f32_16x16x32_bf16 v[44:47], v[210:213], v[178:181], v[44:47]
	v_mfma_f32_16x16x32_bf16 v[40:43], v[232:235], v[178:181], v[40:43]
	v_mfma_f32_16x16x32_bf16 v[28:31], v[210:213], v[186:189], v[28:31]
	v_mfma_f32_16x16x32_bf16 v[24:27], v[232:235], v[186:189], v[24:27]
	v_mfma_f32_16x16x32_bf16 v[12:15], v[210:213], v[194:197], v[12:15]
	v_mfma_f32_16x16x32_bf16 v[8:11], v[232:235], v[194:197], v[8:11]
	v_mfma_f32_16x16x32_bf16 v[4:7], v[210:213], v[202:205], v[4:7]
	v_mfma_f32_16x16x32_bf16 v[0:3], v[232:235], v[202:205], v[0:3]
	s_add_i32 s73, s73, 2
	s_add_u32 s42, s42, 0x100
	s_addc_u32 s43, s43, 0
	s_add_u32 s52, s52, 0x100
	s_addc_u32 s72, s72, 0
	s_cmp_gt_u32 s73, 13
	s_barrier
	s_cbranch_scc0 .LBB0_890
	s_cmp_lt_u32 s101, 0x100
	s_cbranch_scc0 .Lxa_7
	s_barrier

; #define PG8_STAGE(bufoff, gbase, voff) do { _Pragma("unroll") for (int _i = 0; _i < 2; ++_i) \
;     __builtin_amdgcn_global_load_lds((const unsigned*)((const char*)(gbase) + (voff)[_i]), (LAS unsigned*)(lds + (bufoff) + ldsw + _i * 8192), 16, 0, 0); } while (0)
; #define PG8_LDA(dst, b, h) do { _Pragma("unroll") for (int m = 0; m < 4; ++m) _Pragma("unroll") for (int k = 0; k < 2; ++k) dst[m][k] = *(const LAS bf16x8*)(lds + PG8_SA(b, h) + aoff + m * 2048 + k * 1024); } while (0)
; #define PG8_LDB(dst, b, h) do { _Pragma("unroll") for (int n = 0; n < 2; ++n) _Pragma("unroll") for (int k = 0; k < 2; ++k) dst[n][k] = *(const LAS bf16x8*)(lds + PG8_SB(b, h) + boff + n * 2048 + k * 1024); } while (0)
; #define PG8_MMA(ai, bj, At, Bt) do { __builtin_amdgcn_s_setprio(1); _Pragma("unroll") for (int m = 0; m < 4; ++m) _Pragma("unroll") for (int n = 0; n < 2; ++n) _Pragma("unroll") for (int k = 0; k < 2; ++k) \
;     acc[ai][bj][m][n] = __builtin_amdgcn_mfma_f32_16x16x32_bf16(Bt[n][k], At[m][k], acc[ai][bj][m][n], 0, 0, 0); __builtin_amdgcn_s_setprio(0); } while (0)
; #define PG8_WAIT_L(n) asm volatile("s_waitcnt lgkmcnt(" #n ")" ::: "memory")
; template <class Epi, class Sched>
; __device__ __forceinline__ void gemm_phase(LAS unsigned char* lds, const Gemm g, const Sched& S, const Epi& E) {
;     ...
;     const bool has_next = S.next(ui + 1, nxt);
;     const char* nA = has_next ? (const char*)g.A + (size_t)nxt.pm * tstep : cA; const char* nB = has_next ? (const char*)g.Bt + (size_t)nxt.pn * tstep : cB;
;     for (int t = 0; t < nt; t += 2) {
;       const bool last = (t == nt - 2);
;       const char* a1 = cA + (size_t)(t + 1) * kstep;
;       const char* a2 = last ? nA : cA + (size_t)(t + 2) * kstep; const char* b2 = last ? nB : cB + (size_t)(t + 2) * kstep;
;       const char* a3 = a2 + kstep; const char* b3 = b2 + kstep;
;       if (last && has_next) S.a_ready(nxt);
;       PG8_LDB(B0, 0, 0); PG8_SCHED; PG8_LDA(At, 0, 0); PG8_STAGE(PG8_SA(1, 1), a1 + hstep, voffA);
;       PG8_WAIT_L(8); PG8_BAR; PG8_WAIT_L(0); PG8_MMA(0, 0, At, B0); PG8_BAR; PG8_SCHED;
;     ...
; #pragma unroll
;     for (int a = 0; a < 2; ++a)
; #pragma unroll
;       for (int b = 0; b < 2; ++b)
; #pragma unroll
;         for (int m = 0; m < 4; ++m)
; #pragma unroll
;           for (int n = 0; n < 2; ++n) acc[a][b][m][n] = (f32x4){0.f, 0.f, 0.f, 0.f};
;     cur = nxt; cA = nA; cB = nB; ++ui;
.LBB0_967:
	s_ashr_i32 s35, s34, 31
	v_cmp_lt_i64_e32 vcc, s[36:37], v[166:167]
	s_lshl_b64 s[36:37], s[34:35], 19
	s_add_u32 s36, s94, s36
	s_addc_u32 s37, s95, s37
	s_and_b64 s[40:41], vcc, exec
	s_cselect_b32 s35, s37, s43
	s_cselect_b32 s71, s36, s42
	s_ashr_i32 s23, s22, 31
	s_lshl_b64 s[40:41], s[22:23], 19
	v_readlane_b32 s48, v253, 27
	v_readlane_b32 s49, v253, 28
	s_add_u32 s40, s48, s40
	s_addc_u32 s41, s49, s41
	s_and_b64 s[48:49], vcc, exec
	s_cselect_b32 s23, s41, s45
	s_cselect_b32 vcc_lo, s40, s44
	s_add_u32 s42, s42, 0x40080
	s_addc_u32 s43, s43, 0
	s_add_u32 s52, s44, 0x100
	v_mov_b32_e32 v0, 0
	s_addc_u32 s72, s45, 0
	s_mov_b32 s73, -2
	v_mov_b32_e32 v1, v0
	v_mov_b64_e32 v[2:3], v[0:1]
	v_mov_b64_e32 v[4:5], v[0:1]
	v_mov_b64_e32 v[6:7], v[0:1]
	v_mov_b64_e32 v[8:9], v[0:1]
	v_mov_b64_e32 v[10:11], v[0:1]
	v_mov_b64_e32 v[12:13], v[0:1]
	v_mov_b64_e32 v[14:15], v[0:1]
	v_mov_b64_e32 v[16:17], v[0:1]
	v_mov_b64_e32 v[18:19], v[0:1]
	v_mov_b64_e32 v[20:21], v[0:1]
	v_mov_b64_e32 v[22:23], v[0:1]
	v_mov_b64_e32 v[24:25], v[0:1]
	v_mov_b64_e32 v[26:27], v[0:1]
	v_mov_b64_e32 v[28:29], v[0:1]
	v_mov_b64_e32 v[30:31], v[0:1]
	v_mov_b64_e32 v[32:33], v[0:1]
	v_mov_b64_e32 v[34:35], v[0:1]
	v_mov_b64_e32 v[36:37], v[0:1]
	v_mov_b64_e32 v[38:39], v[0:1]
	v_mov_b64_e32 v[40:41], v[0:1]
	v_mov_b64_e32 v[42:43], v[0:1]
	v_mov_b64_e32 v[44:45], v[0:1]
	v_mov_b64_e32 v[46:47], v[0:1]
	v_mov_b64_e32 v[48:49], v[0:1]
	v_mov_b64_e32 v[50:51], v[0:1]
	v_mov_b64_e32 v[52:53], v[0:1]
	v_mov_b64_e32 v[54:55], v[0:1]
	v_mov_b64_e32 v[56:57], v[0:1]
	v_mov_b64_e32 v[58:59], v[0:1]
	v_mov_b64_e32 v[60:61], v[0:1]
	v_mov_b64_e32 v[62:63], v[0:1]
	v_mov_b64_e32 v[64:65], v[0:1]
	v_mov_b64_e32 v[66:67], v[0:1]
	v_mov_b64_e32 v[68:69], v[0:1]
	v_mov_b64_e32 v[70:71], v[0:1]
	v_mov_b64_e32 v[72:73], v[0:1]
	v_mov_b64_e32 v[74:75], v[0:1]
	v_mov_b64_e32 v[76:77], v[0:1]
	v_mov_b64_e32 v[78:79], v[0:1]
	v_mov_b64_e32 v[80:81], v[0:1]
	v_mov_b64_e32 v[82:83], v[0:1]
	v_mov_b64_e32 v[84:85], v[0:1]
	v_mov_b64_e32 v[86:87], v[0:1]
	v_mov_b64_e32 v[88:89], v[0:1]
	v_mov_b64_e32 v[90:91], v[0:1]
	v_mov_b64_e32 v[92:93], v[0:1]
	v_mov_b64_e32 v[94:95], v[0:1]
	v_mov_b64_e32 v[96:97], v[0:1]
	v_mov_b64_e32 v[98:99], v[0:1]
	v_mov_b64_e32 v[100:101], v[0:1]
	v_mov_b64_e32 v[102:103], v[0:1]
	v_mov_b64_e32 v[104:105], v[0:1]
	v_mov_b64_e32 v[106:107], v[0:1]
	v_mov_b64_e32 v[108:109], v[0:1]
	v_mov_b64_e32 v[110:111], v[0:1]
	v_mov_b64_e32 v[112:113], v[0:1]
	v_mov_b64_e32 v[114:115], v[0:1]
	v_mov_b64_e32 v[116:117], v[0:1]
	v_mov_b64_e32 v[118:119], v[0:1]
	v_mov_b64_e32 v[120:121], v[0:1]
	v_mov_b64_e32 v[122:123], v[0:1]
	v_mov_b64_e32 v[124:125], v[0:1]
	v_mov_b64_e32 v[126:127], v[0:1]
	s_cmp_eq_u32 s100, 0
	s_cbranch_scc1 .Lxs_e8
	s_barrier
	s_mov_b32 s100, 0
.Lxs_e8:
.LBB0_968:
	s_add_u32 s44, s42, 0xfffc0080
	s_addc_u32 s45, s43, -1
	s_add_i32 s74, 0, 0x10000
	v_add_u32_e32 v140, s74, v143
	ds_read_b128 v[146:149], v140
	ds_read_b128 v[150:153], v140 offset:1024
	ds_read_b128 v[154:157], v140 offset:2048
	ds_read_b128 v[174:177], v140 offset:3072
	s_cmp_eq_u32 s73, 12
	s_cselect_b32 s49, s35, s45
	s_cselect_b32 s48, s71, s44
	s_cselect_b32 s45, s23, s72
	s_cselect_b32 s44, vcc_lo, s52
	s_add_i32 m0, s12, 0xc000
	ds_read_b128 v[178:181], v145
	ds_read_b128 v[182:185], v145 offset:1024
	ds_read_b128 v[186:189], v145 offset:2048
	ds_read_b128 v[190:193], v145 offset:3072
	ds_read_b128 v[194:197], v145 offset:4096
	ds_read_b128 v[198:201], v145 offset:5120
	ds_read_b128 v[202:205], v145 offset:6144
	ds_read_b128 v[206:209], v145 offset:7168
	global_load_lds_dwordx4 v136, s[42:43]
	s_add_i32 m0, s12, 0xe000
	s_nop 0
	global_load_lds_dwordx4 v138, s[42:43]
	s_waitcnt vmcnt(8)
	s_waitcnt lgkmcnt(8)
	s_barrier
	s_waitcnt lgkmcnt(0)
	s_waitcnt lgkmcnt(0)
	v_mfma_f32_16x16x32_bf16 v[124:127], v[146:149], v[178:181], v[124:127]
	v_mfma_f32_16x16x32_bf16 v[120:123], v[154:157], v[178:181], v[120:123]
	v_mfma_f32_16x16x32_bf16 v[116:119], v[146:149], v[186:189], v[116:119]
	v_mfma_f32_16x16x32_bf16 v[108:111], v[154:157], v[186:189], v[108:111]
	v_mfma_f32_16x16x32_bf16 v[96:99], v[146:149], v[194:197], v[96:99]
	v_mfma_f32_16x16x32_bf16 v[88:91], v[154:157], v[194:197], v[88:91]
	v_mfma_f32_16x16x32_bf16 v[84:87], v[146:149], v[202:205], v[84:87]
	v_mfma_f32_16x16x32_bf16 v[76:79], v[154:157], v[202:205], v[76:79]
	v_mfma_f32_16x16x32_bf16 v[124:127], v[150:153], v[182:185], v[124:127]
	v_mfma_f32_16x16x32_bf16 v[120:123], v[174:177], v[182:185], v[120:123]
	v_mfma_f32_16x16x32_bf16 v[116:119], v[150:153], v[190:193], v[116:119]
	v_mfma_f32_16x16x32_bf16 v[108:111], v[174:177], v[190:193], v[108:111]
	v_mfma_f32_16x16x32_bf16 v[96:99], v[150:153], v[198:201], v[96:99]
	v_mfma_f32_16x16x32_bf16 v[88:91], v[174:177], v[198:201], v[88:91]
	v_mfma_f32_16x16x32_bf16 v[84:87], v[150:153], v[206:209], v[84:87]
	v_mfma_f32_16x16x32_bf16 v[76:79], v[174:177], v[206:209], v[76:79]
	s_barrier
	s_add_i32 s76, 0, 0x14000
	v_add_u32_e32 v140, s76, v143
	s_add_i32 s74, s74, s7
	ds_read_b128 v[210:213], v140
	ds_read_b128 v[226:229], v140 offset:1024
	ds_read_b128 v[232:235], v140 offset:2048
	ds_read_b128 v[236:239], v140 offset:3072
	v_lshl_add_u64 v[140:141], s[44:45], 0, v[132:133]
	s_mov_b32 m0, s74
	v_lshl_add_u64 v[158:159], s[44:45], 0, v[128:129]
	global_load_lds_dwordx4 v[140:141], off
	s_add_i32 m0, s74, 0x2000
	s_nop 0
	global_load_lds_dwordx4 v[158:159], off
	s_barrier
; #define PG8_STAGE(bufoff, gbase, voff) do { _Pragma("unroll") for (int _i = 0; _i < 2; ++_i) \
;     __builtin_amdgcn_global_load_lds((const unsigned*)((const char*)(gbase) + (voff)[_i]), (LAS unsigned*)(lds + (bufoff) + ldsw + _i * 8192), 16, 0, 0); } while (0)
; #define PG8_LDA(dst, b, h) do { _Pragma("unroll") for (int m = 0; m < 4; ++m) _Pragma("unroll") for (int k = 0; k < 2; ++k) dst[m][k] = *(const LAS bf16x8*)(lds + PG8_SA(b, h) + aoff + m * 2048 + k * 1024); } while (0)
; #define PG8_LDB(dst, b, h) do { _Pragma("unroll") for (int n = 0; n < 2; ++n) _Pragma("unroll") for (int k = 0; k < 2; ++k) dst[n][k] = *(const LAS bf16x8*)(lds + PG8_SB(b, h) + boff + n * 2048 + k * 1024); } while (0)
; #define PG8_MMA(ai, bj, At, Bt) do { __builtin_amdgcn_s_setprio(1); _Pragma("unroll") for (int m = 0; m < 4; ++m) _Pragma("unroll") for (int n = 0; n < 2; ++n) _Pragma("unroll") for (int k = 0; k < 2; ++k) \
;     acc[ai][bj][m][n] = __builtin_amdgcn_mfma_f32_16x16x32_bf16(Bt[n][k], At[m][k], acc[ai][bj][m][n], 0, 0, 0); __builtin_amdgcn_s_setprio(0); } while (0)
; #define PG8_WAIT_V(n) asm volatile("s_waitcnt vmcnt(" #n ")" ::: "memory")
; #define PG8_WAIT_L(n) asm volatile("s_waitcnt lgkmcnt(" #n ")" ::: "memory")
; #define PG8_BAR __builtin_amdgcn_s_barrier()
; #define PG8_SCHED __builtin_amdgcn_sched_barrier(0)
; template <class Epi, class Sched>
; __device__ __forceinline__ void gemm_phase(LAS unsigned char* lds, const Gemm g, const Sched& S, const Epi& E) {
;     ...
;       PG8_LDB(B1, 0, 1); PG8_STAGE(PG8_SB(0, 0), b2, voffB);
;       PG8_BAR; PG8_WAIT_L(0); PG8_MMA(0, 1, At, B1); PG8_BAR;
;       PG8_LDA(At, 0, 1); PG8_STAGE(PG8_SA(0, 0), a2, voffA);
;       PG8_BAR; PG8_WAIT_L(0); PG8_MMA(1, 0, At, B0); PG8_BAR; PG8_SCHED;
;       PG8_STAGE(PG8_SB(0, 1), b2 + hstep, voffB);
;       PG8_WAIT_V(6); PG8_BAR; PG8_MMA(1, 1, At, B1); PG8_BAR;
;       PG8_LDB(B0, 1, 0); PG8_SCHED; PG8_LDA(At, 1, 0); PG8_STAGE(PG8_SA(0, 1), a2 + hstep, voffA);
;       PG8_WAIT_L(8); PG8_BAR; PG8_WAIT_L(0); PG8_MMA(0, 0, At, B0); PG8_BAR; PG8_SCHED;
	s_waitcnt lgkmcnt(0)
	s_waitcnt lgkmcnt(0)
	v_mfma_f32_16x16x32_bf16 v[112:115], v[210:213], v[178:181], v[112:115]
	v_mfma_f32_16x16x32_bf16 v[104:107], v[232:235], v[178:181], v[104:107]
	v_mfma_f32_16x16x32_bf16 v[100:103], v[210:213], v[186:189], v[100:103]
	v_mfma_f32_16x16x32_bf16 v[92:95], v[232:235], v[186:189], v[92:95]
	v_mfma_f32_16x16x32_bf16 v[80:83], v[210:213], v[194:197], v[80:83]
	v_mfma_f32_16x16x32_bf16 v[72:75], v[232:235], v[194:197], v[72:75]
	v_mfma_f32_16x16x32_bf16 v[68:71], v[210:213], v[202:205], v[68:71]
	v_mfma_f32_16x16x32_bf16 v[64:67], v[232:235], v[202:205], v[64:67]
	v_mfma_f32_16x16x32_bf16 v[112:115], v[226:229], v[182:185], v[112:115]
	v_mfma_f32_16x16x32_bf16 v[104:107], v[236:239], v[182:185], v[104:107]
	v_mfma_f32_16x16x32_bf16 v[100:103], v[226:229], v[190:193], v[100:103]
	v_mfma_f32_16x16x32_bf16 v[92:95], v[236:239], v[190:193], v[92:95]
	v_mfma_f32_16x16x32_bf16 v[80:83], v[226:229], v[198:201], v[80:83]
	v_mfma_f32_16x16x32_bf16 v[72:75], v[236:239], v[198:201], v[72:75]
	v_mfma_f32_16x16x32_bf16 v[68:71], v[226:229], v[206:209], v[68:71]
	v_mfma_f32_16x16x32_bf16 v[64:67], v[236:239], v[206:209], v[64:67]
	s_mov_b32 m0, s12
	v_lshl_add_u64 v[222:223], s[48:49], 0, v[134:135]
	s_barrier
	ds_read_b128 v[178:181], v145 offset:16384
	ds_read_b128 v[182:185], v145 offset:17408
	ds_read_b128 v[186:189], v145 offset:18432
	ds_read_b128 v[190:193], v145 offset:19456
	ds_read_b128 v[194:197], v145 offset:20480
	ds_read_b128 v[198:201], v145 offset:21504
	ds_read_b128 v[202:205], v145 offset:22528
	ds_read_b128 v[206:209], v145 offset:23552
	global_load_lds_dwordx4 v134, s[48:49]
	v_lshl_add_u64 v[240:241], s[48:49], 0, v[130:131]
	s_mov_b32 m0, s13
	s_nop 0
	global_load_lds_dwordx4 v130, s[48:49]
	s_barrier
	s_waitcnt lgkmcnt(0)
	s_waitcnt lgkmcnt(0)
	v_mfma_f32_16x16x32_bf16 v[60:63], v[146:149], v[178:181], v[60:63]
	v_mfma_f32_16x16x32_bf16 v[56:59], v[154:157], v[178:181], v[56:59]
	v_mfma_f32_16x16x32_bf16 v[52:55], v[146:149], v[186:189], v[52:55]
	v_mfma_f32_16x16x32_bf16 v[44:47], v[154:157], v[186:189], v[44:47]
	v_mfma_f32_16x16x32_bf16 v[32:35], v[146:149], v[194:197], v[32:35]
	v_mfma_f32_16x16x32_bf16 v[24:27], v[154:157], v[194:197], v[24:27]
	v_mfma_f32_16x16x32_bf16 v[20:23], v[146:149], v[202:205], v[20:23]
	v_mfma_f32_16x16x32_bf16 v[12:15], v[154:157], v[202:205], v[12:15]
	v_mfma_f32_16x16x32_bf16 v[60:63], v[150:153], v[182:185], v[60:63]
	v_mfma_f32_16x16x32_bf16 v[56:59], v[174:177], v[182:185], v[56:59]
	v_mfma_f32_16x16x32_bf16 v[52:55], v[150:153], v[190:193], v[52:55]
	v_mfma_f32_16x16x32_bf16 v[44:47], v[174:177], v[190:193], v[44:47]
	v_mfma_f32_16x16x32_bf16 v[32:35], v[150:153], v[198:201], v[32:35]
	v_mfma_f32_16x16x32_bf16 v[24:27], v[174:177], v[198:201], v[24:27]
	v_mfma_f32_16x16x32_bf16 v[20:23], v[150:153], v[206:209], v[20:23]
	v_mfma_f32_16x16x32_bf16 v[12:15], v[174:177], v[206:209], v[12:15]
	s_barrier
	s_add_u32 s74, s44, 0x40000
	s_addc_u32 s75, s45, 0
	s_add_i32 s76, s76, s7
	s_mov_b32 m0, s76
	s_nop 0
	global_load_lds_dwordx4 v132, s[74:75]
	s_add_i32 m0, s76, 0x2000
	s_nop 0
	global_load_lds_dwordx4 v128, s[74:75]
	s_waitcnt vmcnt(10)
	s_barrier
	v_mfma_f32_16x16x32_bf16 v[48:51], v[210:213], v[178:181], v[48:51]
	v_mfma_f32_16x16x32_bf16 v[40:43], v[232:235], v[178:181], v[40:43]
	v_mfma_f32_16x16x32_bf16 v[36:39], v[210:213], v[186:189], v[36:39]
	v_mfma_f32_16x16x32_bf16 v[28:31], v[232:235], v[186:189], v[28:31]
	v_mfma_f32_16x16x32_bf16 v[16:19], v[210:213], v[194:197], v[16:19]
	v_mfma_f32_16x16x32_bf16 v[8:11], v[232:235], v[194:197], v[8:11]
	v_mfma_f32_16x16x32_bf16 v[4:7], v[210:213], v[202:205], v[4:7]
	v_mfma_f32_16x16x32_bf16 v[0:3], v[232:235], v[202:205], v[0:3]
	v_mfma_f32_16x16x32_bf16 v[48:51], v[226:229], v[182:185], v[48:51]
	v_mfma_f32_16x16x32_bf16 v[40:43], v[236:239], v[182:185], v[40:43]
	v_mfma_f32_16x16x32_bf16 v[36:39], v[226:229], v[190:193], v[36:39]
	v_mfma_f32_16x16x32_bf16 v[28:31], v[236:239], v[190:193], v[28:31]
	v_mfma_f32_16x16x32_bf16 v[16:19], v[226:229], v[198:201], v[16:19]
	v_mfma_f32_16x16x32_bf16 v[8:11], v[236:239], v[198:201], v[8:11]
	v_mfma_f32_16x16x32_bf16 v[4:7], v[226:229], v[206:209], v[4:7]
	v_mfma_f32_16x16x32_bf16 v[0:3], v[236:239], v[206:209], v[0:3]
	s_add_i32 s74, 0, 0x18000
	v_add_u32_e32 v174, s74, v143
	s_barrier
	ds_read_b128 v[146:149], v174
	ds_read_b128 v[150:153], v174 offset:1024
	ds_read_b128 v[154:157], v174 offset:2048
	ds_read_b128 v[174:177], v174 offset:3072
	s_add_u32 s48, s48, 0x40000
	s_addc_u32 s49, s49, 0
	s_mov_b32 m0, s51
	ds_read_b128 v[178:181], v145 offset:32768
	ds_read_b128 v[182:185], v145 offset:33792
	ds_read_b128 v[186:189], v145 offset:34816
	ds_read_b128 v[190:193], v145 offset:35840
	ds_read_b128 v[194:197], v145 offset:36864
	ds_read_b128 v[198:201], v145 offset:37888
	ds_read_b128 v[202:205], v145 offset:38912
	ds_read_b128 v[206:209], v145 offset:39936
	global_load_lds_dwordx4 v134, s[48:49]
	s_mov_b32 m0, s62
	s_nop 0
	global_load_lds_dwordx4 v130, s[48:49]
	s_waitcnt vmcnt(8)
	s_waitcnt lgkmcnt(8)
	s_barrier
; #define PG8_STAGE(bufoff, gbase, voff) do { _Pragma("unroll") for (int _i = 0; _i < 2; ++_i) \
;     __builtin_amdgcn_global_load_lds((const unsigned*)((const char*)(gbase) + (voff)[_i]), (LAS unsigned*)(lds + (bufoff) + ldsw + _i * 8192), 16, 0, 0); } while (0)
; #define PG8_LDA(dst, b, h) do { _Pragma("unroll") for (int m = 0; m < 4; ++m) _Pragma("unroll") for (int k = 0; k < 2; ++k) dst[m][k] = *(const LAS bf16x8*)(lds + PG8_SA(b, h) + aoff + m * 2048 + k * 1024); } while (0)
; #define PG8_LDB(dst, b, h) do { _Pragma("unroll") for (int n = 0; n < 2; ++n) _Pragma("unroll") for (int k = 0; k < 2; ++k) dst[n][k] = *(const LAS bf16x8*)(lds + PG8_SB(b, h) + boff + n * 2048 + k * 1024); } while (0)
; #define PG8_MMA(ai, bj, At, Bt) do { __builtin_amdgcn_s_setprio(1); _Pragma("unroll") for (int m = 0; m < 4; ++m) _Pragma("unroll") for (int n = 0; n < 2; ++n) _Pragma("unroll") for (int k = 0; k < 2; ++k) \
;     acc[ai][bj][m][n] = __builtin_amdgcn_mfma_f32_16x16x32_bf16(Bt[n][k], At[m][k], acc[ai][bj][m][n], 0, 0, 0); __builtin_amdgcn_s_setprio(0); } while (0)
; #define PG8_WAIT_V(n) asm volatile("s_waitcnt vmcnt(" #n ")" ::: "memory")
; #define PG8_WAIT_L(n) asm volatile("s_waitcnt lgkmcnt(" #n ")" ::: "memory")
; #define PG8_BAR __builtin_amdgcn_s_barrier()
; #define PG8_SCHED __builtin_amdgcn_sched_barrier(0)
; template <class Epi, class Sched>
; __device__ __forceinline__ void gemm_phase(LAS unsigned char* lds, const Gemm g, const Sched& S, const Epi& E) {
;     ...
;       PG8_WAIT_L(8); PG8_BAR; PG8_WAIT_L(0); PG8_MMA(0, 0, At, B0); PG8_BAR; PG8_SCHED;
;       PG8_LDB(B1, 1, 1); PG8_STAGE(PG8_SB(1, 0), b3, voffB);
;       PG8_BAR; PG8_WAIT_L(0); PG8_MMA(0, 1, At, B1); PG8_BAR;
;       PG8_LDA(At, 1, 1); PG8_STAGE(PG8_SA(1, 0), a3, voffA);
;       PG8_BAR; PG8_WAIT_L(0); PG8_MMA(1, 0, At, B0); PG8_BAR; PG8_SCHED;
;       PG8_STAGE(PG8_SB(1, 1), b3 + hstep, voffB);
;       PG8_WAIT_V(6); PG8_BAR; PG8_MMA(1, 1, At, B1); PG8_BAR;
;     }
	s_waitcnt lgkmcnt(0)
	s_waitcnt lgkmcnt(0)
	v_mfma_f32_16x16x32_bf16 v[124:127], v[146:149], v[178:181], v[124:127]
	v_mfma_f32_16x16x32_bf16 v[120:123], v[154:157], v[178:181], v[120:123]
	v_mfma_f32_16x16x32_bf16 v[116:119], v[146:149], v[186:189], v[116:119]
	v_mfma_f32_16x16x32_bf16 v[108:111], v[154:157], v[186:189], v[108:111]
	v_mfma_f32_16x16x32_bf16 v[96:99], v[146:149], v[194:197], v[96:99]
	v_mfma_f32_16x16x32_bf16 v[88:91], v[154:157], v[194:197], v[88:91]
	v_mfma_f32_16x16x32_bf16 v[84:87], v[146:149], v[202:205], v[84:87]
	v_mfma_f32_16x16x32_bf16 v[76:79], v[154:157], v[202:205], v[76:79]
	v_mfma_f32_16x16x32_bf16 v[124:127], v[150:153], v[182:185], v[124:127]
	v_mfma_f32_16x16x32_bf16 v[120:123], v[174:177], v[182:185], v[120:123]
	v_mfma_f32_16x16x32_bf16 v[116:119], v[150:153], v[190:193], v[116:119]
	v_mfma_f32_16x16x32_bf16 v[108:111], v[174:177], v[190:193], v[108:111]
	v_mfma_f32_16x16x32_bf16 v[96:99], v[150:153], v[198:201], v[96:99]
	v_mfma_f32_16x16x32_bf16 v[88:91], v[174:177], v[198:201], v[88:91]
	v_mfma_f32_16x16x32_bf16 v[84:87], v[150:153], v[206:209], v[84:87]
	v_mfma_f32_16x16x32_bf16 v[76:79], v[174:177], v[206:209], v[76:79]
	s_barrier
	s_add_i32 s48, 0, 0x1c000
	s_add_i32 s49, s74, s7
	v_add_u32_e32 v225, s48, v143
	s_add_u32 s60, s44, s80
	s_addc_u32 s61, s45, s81
	s_mov_b32 m0, s49
	ds_read_b128 v[210:213], v225
	ds_read_b128 v[226:229], v225 offset:1024
	ds_read_b128 v[232:235], v225 offset:2048
	ds_read_b128 v[236:239], v225 offset:3072
	global_load_lds_dwordx4 v132, s[60:61]
	v_lshl_add_u64 v[140:141], v[158:159], 0, s[80:81]
	s_add_i32 m0, s49, 0x2000
	s_nop 0
	global_load_lds_dwordx4 v128, s[60:61]
	s_barrier
	s_waitcnt lgkmcnt(0)
	s_waitcnt lgkmcnt(0)
	v_mfma_f32_16x16x32_bf16 v[112:115], v[210:213], v[178:181], v[112:115]
	v_mfma_f32_16x16x32_bf16 v[104:107], v[232:235], v[178:181], v[104:107]
	v_mfma_f32_16x16x32_bf16 v[100:103], v[210:213], v[186:189], v[100:103]
	v_mfma_f32_16x16x32_bf16 v[92:95], v[232:235], v[186:189], v[92:95]
	v_mfma_f32_16x16x32_bf16 v[80:83], v[210:213], v[194:197], v[80:83]
	v_mfma_f32_16x16x32_bf16 v[72:75], v[232:235], v[194:197], v[72:75]
	v_mfma_f32_16x16x32_bf16 v[68:71], v[210:213], v[202:205], v[68:71]
	v_mfma_f32_16x16x32_bf16 v[64:67], v[232:235], v[202:205], v[64:67]
	v_mfma_f32_16x16x32_bf16 v[112:115], v[226:229], v[182:185], v[112:115]
	v_mfma_f32_16x16x32_bf16 v[104:107], v[236:239], v[182:185], v[104:107]
	v_mfma_f32_16x16x32_bf16 v[100:103], v[226:229], v[190:193], v[100:103]
	v_mfma_f32_16x16x32_bf16 v[92:95], v[236:239], v[190:193], v[92:95]
	v_mfma_f32_16x16x32_bf16 v[80:83], v[226:229], v[198:201], v[80:83]
	v_mfma_f32_16x16x32_bf16 v[72:75], v[236:239], v[198:201], v[72:75]
	v_mfma_f32_16x16x32_bf16 v[68:71], v[226:229], v[206:209], v[68:71]
	v_mfma_f32_16x16x32_bf16 v[64:67], v[236:239], v[206:209], v[64:67]
	s_mov_b32 m0, s63
	v_lshl_add_u64 v[140:141], v[222:223], 0, s[80:81]
	s_barrier
	ds_read_b128 v[178:181], v145 offset:49152
	ds_read_b128 v[182:185], v145 offset:50176
	ds_read_b128 v[186:189], v145 offset:51200
	ds_read_b128 v[190:193], v145 offset:52224
	ds_read_b128 v[194:197], v145 offset:53248
	ds_read_b128 v[198:201], v145 offset:54272
	ds_read_b128 v[202:205], v145 offset:55296
	ds_read_b128 v[206:209], v145 offset:56320
	global_load_lds_dwordx4 v[140:141], off
	v_lshl_add_u64 v[140:141], v[240:241], 0, s[80:81]
	s_mov_b32 m0, s64
	s_nop 0
	global_load_lds_dwordx4 v[140:141], off
	s_barrier
	s_waitcnt lgkmcnt(0)
	s_waitcnt lgkmcnt(0)
	v_mfma_f32_16x16x32_bf16 v[60:63], v[146:149], v[178:181], v[60:63]
	v_mfma_f32_16x16x32_bf16 v[56:59], v[154:157], v[178:181], v[56:59]
	v_mfma_f32_16x16x32_bf16 v[52:55], v[146:149], v[186:189], v[52:55]
	v_mfma_f32_16x16x32_bf16 v[44:47], v[154:157], v[186:189], v[44:47]
	v_mfma_f32_16x16x32_bf16 v[32:35], v[146:149], v[194:197], v[32:35]
	v_mfma_f32_16x16x32_bf16 v[24:27], v[154:157], v[194:197], v[24:27]
	v_mfma_f32_16x16x32_bf16 v[20:23], v[146:149], v[202:205], v[20:23]
	v_mfma_f32_16x16x32_bf16 v[12:15], v[154:157], v[202:205], v[12:15]
	v_mfma_f32_16x16x32_bf16 v[60:63], v[150:153], v[182:185], v[60:63]
	v_mfma_f32_16x16x32_bf16 v[56:59], v[174:177], v[182:185], v[56:59]
	v_mfma_f32_16x16x32_bf16 v[52:55], v[150:153], v[190:193], v[52:55]
	v_mfma_f32_16x16x32_bf16 v[44:47], v[174:177], v[190:193], v[44:47]
	v_mfma_f32_16x16x32_bf16 v[32:35], v[150:153], v[198:201], v[32:35]
	v_mfma_f32_16x16x32_bf16 v[24:27], v[174:177], v[198:201], v[24:27]
	v_mfma_f32_16x16x32_bf16 v[20:23], v[150:153], v[206:209], v[20:23]
	v_mfma_f32_16x16x32_bf16 v[12:15], v[174:177], v[206:209], v[12:15]
	s_barrier
	s_add_u32 s44, s44, 0x40080
	s_addc_u32 s45, s45, 0
	s_add_i32 s48, s48, s7
	s_mov_b32 m0, s48
	s_nop 0
	global_load_lds_dwordx4 v132, s[44:45]
	s_add_i32 m0, s48, 0x2000
	s_nop 0
	global_load_lds_dwordx4 v128, s[44:45]
	s_waitcnt vmcnt(10)
	s_barrier
	v_mfma_f32_16x16x32_bf16 v[48:51], v[210:213], v[178:181], v[48:51]
	v_mfma_f32_16x16x32_bf16 v[40:43], v[232:235], v[178:181], v[40:43]
	v_mfma_f32_16x16x32_bf16 v[36:39], v[210:213], v[186:189], v[36:39]
	v_mfma_f32_16x16x32_bf16 v[28:31], v[232:235], v[186:189], v[28:31]
	v_mfma_f32_16x16x32_bf16 v[16:19], v[210:213], v[194:197], v[16:19]
	v_mfma_f32_16x16x32_bf16 v[8:11], v[232:235], v[194:197], v[8:11]
	v_mfma_f32_16x16x32_bf16 v[4:7], v[210:213], v[202:205], v[4:7]
	v_mfma_f32_16x16x32_bf16 v[0:3], v[232:235], v[202:205], v[0:3]
	v_mfma_f32_16x16x32_bf16 v[48:51], v[226:229], v[182:185], v[48:51]
	v_mfma_f32_16x16x32_bf16 v[40:43], v[236:239], v[182:185], v[40:43]
	v_mfma_f32_16x16x32_bf16 v[36:39], v[226:229], v[190:193], v[36:39]
	v_mfma_f32_16x16x32_bf16 v[28:31], v[236:239], v[190:193], v[28:31]
	v_mfma_f32_16x16x32_bf16 v[16:19], v[226:229], v[198:201], v[16:19]
	v_mfma_f32_16x16x32_bf16 v[8:11], v[236:239], v[198:201], v[8:11]
	v_mfma_f32_16x16x32_bf16 v[4:7], v[226:229], v[206:209], v[4:7]
	v_mfma_f32_16x16x32_bf16 v[0:3], v[236:239], v[206:209], v[0:3]
	s_add_i32 s73, s73, 2
	s_add_u32 s42, s42, 0x100
	s_addc_u32 s43, s43, 0
	s_add_u32 s52, s52, 0x100
	s_addc_u32 s72, s72, 0
	s_cmp_gt_u32 s73, 13
	s_barrier
	s_cbranch_scc0 .LBB0_968
	s_cmp_lt_u32 s101, 0x100
	s_cbranch_scc0 .Lxa_8
	s_barrier

; #define PG8_STAGE(bufoff, gbase, voff) do { _Pragma("unroll") for (int _i = 0; _i < 2; ++_i) \
;     __builtin_amdgcn_global_load_lds((const unsigned*)((const char*)(gbase) + (voff)[_i]), (LAS unsigned*)(lds + (bufoff) + ldsw + _i * 8192), 16, 0, 0); } while (0)
; #define PG8_LDA(dst, b, h) do { _Pragma("unroll") for (int m = 0; m < 4; ++m) _Pragma("unroll") for (int k = 0; k < 2; ++k) dst[m][k] = *(const LAS bf16x8*)(lds + PG8_SA(b, h) + aoff + m * 2048 + k * 1024); } while (0)
; #define PG8_LDB(dst, b, h) do { _Pragma("unroll") for (int n = 0; n < 2; ++n) _Pragma("unroll") for (int k = 0; k < 2; ++k) dst[n][k] = *(const LAS bf16x8*)(lds + PG8_SB(b, h) + boff + n * 2048 + k * 1024); } while (0)
; #define PG8_MMA(ai, bj, At, Bt) do { __builtin_amdgcn_s_setprio(1); _Pragma("unroll") for (int m = 0; m < 4; ++m) _Pragma("unroll") for (int n = 0; n < 2; ++n) _Pragma("unroll") for (int k = 0; k < 2; ++k) \
;     acc[ai][bj][m][n] = __builtin_amdgcn_mfma_f32_16x16x32_bf16(Bt[n][k], At[m][k], acc[ai][bj][m][n], 0, 0, 0); __builtin_amdgcn_s_setprio(0); } while (0)
; #define PG8_WAIT_L(n) asm volatile("s_waitcnt lgkmcnt(" #n ")" ::: "memory")
; template <class Epi, class Sched>
; __device__ __forceinline__ void gemm_phase(LAS unsigned char* lds, const Gemm g, const Sched& S, const Epi& E) {
;     ...
;     const bool has_next = S.next(ui + 1, nxt);
;     const char* nA = has_next ? (const char*)g.A + (size_t)nxt.pm * tstep : cA; const char* nB = has_next ? (const char*)g.Bt + (size_t)nxt.pn * tstep : cB;
;     for (int t = 0; t < nt; t += 2) {
;       const bool last = (t == nt - 2);
;       const char* a1 = cA + (size_t)(t + 1) * kstep;
;       const char* a2 = last ? nA : cA + (size_t)(t + 2) * kstep; const char* b2 = last ? nB : cB + (size_t)(t + 2) * kstep;
;       const char* a3 = a2 + kstep; const char* b3 = b2 + kstep;
;       if (last && has_next) S.a_ready(nxt);
;       PG8_LDB(B0, 0, 0); PG8_SCHED; PG8_LDA(At, 0, 0); PG8_STAGE(PG8_SA(1, 1), a1 + hstep, voffA);
;       PG8_WAIT_L(8); PG8_BAR; PG8_WAIT_L(0); PG8_MMA(0, 0, At, B0); PG8_BAR; PG8_SCHED;
;     ...
; #pragma unroll
;     for (int a = 0; a < 2; ++a)
; #pragma unroll
;       for (int b = 0; b < 2; ++b)
; #pragma unroll
;         for (int m = 0; m < 4; ++m)
; #pragma unroll
;           for (int n = 0; n < 2; ++n) acc[a][b][m][n] = (f32x4){0.f, 0.f, 0.f, 0.f};
;     cur = nxt; cA = nA; cB = nB; ++ui;
.LBB0_1056:
	s_ashr_i32 s37, s36, 31
	v_cmp_lt_i64_e32 vcc, s[42:43], v[166:167]
	s_lshl_b64 s[42:43], s[36:37], 19
	s_add_u32 s42, s10, s42
	s_addc_u32 s43, s11, s43
	s_and_b64 s[44:45], vcc, exec
	s_cselect_b32 s37, s43, s35
	s_cselect_b32 s68, s42, s34
	s_ashr_i32 s23, s22, 31
	s_lshl_b64 s[44:45], s[22:23], 19
	v_readlane_b32 s72, v254, 2
	v_readlane_b32 s73, v254, 3
	s_add_u32 s44, s72, s44
	s_addc_u32 s45, s73, s45
	s_and_b64 s[72:73], vcc, exec
	s_cselect_b32 s23, s45, s49
	s_cselect_b32 s69, s44, s48
	s_add_u32 s34, s34, 0x40080
	s_addc_u32 s35, s35, 0
	s_add_u32 s52, s48, 0x100
	v_mov_b32_e32 v0, 0
	s_addc_u32 s72, s49, 0
	s_mov_b32 s73, -2
	s_waitcnt lgkmcnt(0)
	v_mov_b32_e32 v1, v0
	v_mov_b64_e32 v[2:3], v[0:1]
	v_mov_b64_e32 v[4:5], v[0:1]
	v_mov_b64_e32 v[6:7], v[0:1]
	v_mov_b64_e32 v[8:9], v[0:1]
	v_mov_b64_e32 v[10:11], v[0:1]
	v_mov_b64_e32 v[12:13], v[0:1]
	v_mov_b64_e32 v[14:15], v[0:1]
	v_mov_b64_e32 v[16:17], v[0:1]
	v_mov_b64_e32 v[18:19], v[0:1]
	v_mov_b64_e32 v[20:21], v[0:1]
	v_mov_b64_e32 v[22:23], v[0:1]
	v_mov_b64_e32 v[24:25], v[0:1]
	v_mov_b64_e32 v[26:27], v[0:1]
	v_mov_b64_e32 v[28:29], v[0:1]
	v_mov_b64_e32 v[30:31], v[0:1]
	v_mov_b64_e32 v[32:33], v[0:1]
	v_mov_b64_e32 v[34:35], v[0:1]
	v_mov_b64_e32 v[36:37], v[0:1]
	v_mov_b64_e32 v[38:39], v[0:1]
	v_mov_b64_e32 v[40:41], v[0:1]
	v_mov_b64_e32 v[42:43], v[0:1]
	v_mov_b64_e32 v[44:45], v[0:1]
	v_mov_b64_e32 v[46:47], v[0:1]
	v_mov_b64_e32 v[48:49], v[0:1]
	v_mov_b64_e32 v[50:51], v[0:1]
	v_mov_b64_e32 v[52:53], v[0:1]
	v_mov_b64_e32 v[54:55], v[0:1]
	v_mov_b64_e32 v[56:57], v[0:1]
	v_mov_b64_e32 v[58:59], v[0:1]
	v_mov_b64_e32 v[60:61], v[0:1]
	v_mov_b64_e32 v[62:63], v[0:1]
	v_mov_b64_e32 v[64:65], v[0:1]
	v_mov_b64_e32 v[66:67], v[0:1]
	v_mov_b64_e32 v[68:69], v[0:1]
	v_mov_b64_e32 v[70:71], v[0:1]
	v_mov_b64_e32 v[72:73], v[0:1]
	v_mov_b64_e32 v[74:75], v[0:1]
	v_mov_b64_e32 v[76:77], v[0:1]
	v_mov_b64_e32 v[78:79], v[0:1]
	v_mov_b64_e32 v[80:81], v[0:1]
	v_mov_b64_e32 v[82:83], v[0:1]
	v_mov_b64_e32 v[84:85], v[0:1]
	v_mov_b64_e32 v[86:87], v[0:1]
	v_mov_b64_e32 v[88:89], v[0:1]
	v_mov_b64_e32 v[90:91], v[0:1]
	v_mov_b64_e32 v[92:93], v[0:1]
	v_mov_b64_e32 v[94:95], v[0:1]
	v_mov_b64_e32 v[96:97], v[0:1]
	v_mov_b64_e32 v[98:99], v[0:1]
	v_mov_b64_e32 v[100:101], v[0:1]
	v_mov_b64_e32 v[102:103], v[0:1]
	v_mov_b64_e32 v[104:105], v[0:1]
	v_mov_b64_e32 v[106:107], v[0:1]
	v_mov_b64_e32 v[108:109], v[0:1]
	v_mov_b64_e32 v[110:111], v[0:1]
	v_mov_b64_e32 v[112:113], v[0:1]
	v_mov_b64_e32 v[114:115], v[0:1]
	v_mov_b64_e32 v[116:117], v[0:1]
	v_mov_b64_e32 v[118:119], v[0:1]
	v_mov_b64_e32 v[120:121], v[0:1]
	v_mov_b64_e32 v[122:123], v[0:1]
	v_mov_b64_e32 v[124:125], v[0:1]
	v_mov_b64_e32 v[126:127], v[0:1]
	s_cmp_eq_u32 s100, 0
	s_cbranch_scc1 .Lxs_e9
	s_barrier
	s_mov_b32 s100, 0
.Lxs_e9:
.LBB0_1057:
	s_add_u32 s48, s34, 0xfffc0080
	s_addc_u32 s49, s35, -1
	s_add_i32 s74, 0, 0x10000
	v_add_u32_e32 v140, s74, v202
	ds_read_b128 v[128:131], v140
	ds_read_b128 v[132:135], v140 offset:1024
	ds_read_b128 v[136:139], v140 offset:2048
	ds_read_b128 v[140:143], v140 offset:3072
	s_cmp_eq_u32 s73, 12
	s_cselect_b32 s49, s37, s49
	s_cselect_b32 s48, s68, s48
	s_cselect_b32 vcc_hi, s23, s72
	s_cselect_b32 vcc_lo, s69, s52
	s_add_i32 m0, s51, 0xc000
	ds_read_b128 v[144:147], v203
	ds_read_b128 v[148:151], v203 offset:1024
	ds_read_b128 v[152:155], v203 offset:2048
	ds_read_b128 v[186:189], v203 offset:3072
	ds_read_b128 v[190:193], v203 offset:4096
	ds_read_b128 v[194:197], v203 offset:5120
	ds_read_b128 v[198:201], v203 offset:6144
	ds_read_b128 v[204:207], v203 offset:7168
	global_load_lds_dwordx4 v182, s[34:35]
	s_add_i32 m0, s51, 0xe000
	s_nop 0
	global_load_lds_dwordx4 v184, s[34:35]
	s_waitcnt vmcnt(8)
	s_waitcnt lgkmcnt(8)
	s_barrier
	s_waitcnt lgkmcnt(0)
	s_waitcnt lgkmcnt(0)
	v_mfma_f32_16x16x32_bf16 v[124:127], v[128:131], v[144:147], v[124:127]
	v_mfma_f32_16x16x32_bf16 v[120:123], v[136:139], v[144:147], v[120:123]
	v_mfma_f32_16x16x32_bf16 v[108:111], v[128:131], v[152:155], v[108:111]
	v_mfma_f32_16x16x32_bf16 v[104:107], v[136:139], v[152:155], v[104:107]
	v_mfma_f32_16x16x32_bf16 v[92:95], v[128:131], v[190:193], v[92:95]
	v_mfma_f32_16x16x32_bf16 v[88:91], v[136:139], v[190:193], v[88:91]
	v_mfma_f32_16x16x32_bf16 v[76:79], v[128:131], v[198:201], v[76:79]
	v_mfma_f32_16x16x32_bf16 v[72:75], v[136:139], v[198:201], v[72:75]
	v_mfma_f32_16x16x32_bf16 v[124:127], v[132:135], v[148:151], v[124:127]
	v_mfma_f32_16x16x32_bf16 v[120:123], v[140:143], v[148:151], v[120:123]
	v_mfma_f32_16x16x32_bf16 v[108:111], v[132:135], v[186:189], v[108:111]
	v_mfma_f32_16x16x32_bf16 v[104:107], v[140:143], v[186:189], v[104:107]
	v_mfma_f32_16x16x32_bf16 v[92:95], v[132:135], v[194:197], v[92:95]
	v_mfma_f32_16x16x32_bf16 v[88:91], v[140:143], v[194:197], v[88:91]
	v_mfma_f32_16x16x32_bf16 v[76:79], v[132:135], v[204:207], v[76:79]
	v_mfma_f32_16x16x32_bf16 v[72:75], v[140:143], v[204:207], v[72:75]
	s_barrier
	s_add_i32 s76, 0, 0x14000
	s_add_i32 s74, s74, s7
	v_add_u32_e32 v160, s76, v202
	s_mov_b32 m0, s74
	ds_read_b128 v[208:211], v160
	ds_read_b128 v[226:229], v160 offset:1024
	ds_read_b128 v[232:235], v160 offset:2048
	ds_read_b128 v[236:239], v160 offset:3072
	global_load_lds_dwordx4 v174, vcc
	s_add_i32 m0, s74, 0x2000
	s_nop 0
	global_load_lds_dwordx4 v156, vcc
	s_barrier
; #define PG8_STAGE(bufoff, gbase, voff) do { _Pragma("unroll") for (int _i = 0; _i < 2; ++_i) \
;     __builtin_amdgcn_global_load_lds((const unsigned*)((const char*)(gbase) + (voff)[_i]), (LAS unsigned*)(lds + (bufoff) + ldsw + _i * 8192), 16, 0, 0); } while (0)
; #define PG8_LDA(dst, b, h) do { _Pragma("unroll") for (int m = 0; m < 4; ++m) _Pragma("unroll") for (int k = 0; k < 2; ++k) dst[m][k] = *(const LAS bf16x8*)(lds + PG8_SA(b, h) + aoff + m * 2048 + k * 1024); } while (0)
; #define PG8_LDB(dst, b, h) do { _Pragma("unroll") for (int n = 0; n < 2; ++n) _Pragma("unroll") for (int k = 0; k < 2; ++k) dst[n][k] = *(const LAS bf16x8*)(lds + PG8_SB(b, h) + boff + n * 2048 + k * 1024); } while (0)
; #define PG8_MMA(ai, bj, At, Bt) do { __builtin_amdgcn_s_setprio(1); _Pragma("unroll") for (int m = 0; m < 4; ++m) _Pragma("unroll") for (int n = 0; n < 2; ++n) _Pragma("unroll") for (int k = 0; k < 2; ++k) \
;     acc[ai][bj][m][n] = __builtin_amdgcn_mfma_f32_16x16x32_bf16(Bt[n][k], At[m][k], acc[ai][bj][m][n], 0, 0, 0); __builtin_amdgcn_s_setprio(0); } while (0)
; #define PG8_WAIT_V(n) asm volatile("s_waitcnt vmcnt(" #n ")" ::: "memory")
; #define PG8_WAIT_L(n) asm volatile("s_waitcnt lgkmcnt(" #n ")" ::: "memory")
; #define PG8_BAR __builtin_amdgcn_s_barrier()
; #define PG8_SCHED __builtin_amdgcn_sched_barrier(0)
; template <class Epi, class Sched>
; __device__ __forceinline__ void gemm_phase(LAS unsigned char* lds, const Gemm g, const Sched& S, const Epi& E) {
;     ...
;       PG8_LDB(B1, 0, 1); PG8_STAGE(PG8_SB(0, 0), b2, voffB);
;       PG8_BAR; PG8_WAIT_L(0); PG8_MMA(0, 1, At, B1); PG8_BAR;
;       PG8_LDA(At, 0, 1); PG8_STAGE(PG8_SA(0, 0), a2, voffA);
;       PG8_BAR; PG8_WAIT_L(0); PG8_MMA(1, 0, At, B0); PG8_BAR; PG8_SCHED;
;       PG8_STAGE(PG8_SB(0, 1), b2 + hstep, voffB);
;       PG8_WAIT_V(6); PG8_BAR; PG8_MMA(1, 1, At, B1); PG8_BAR;
;       PG8_LDB(B0, 1, 0); PG8_SCHED; PG8_LDA(At, 1, 0); PG8_STAGE(PG8_SA(0, 1), a2 + hstep, voffA);
;       PG8_WAIT_L(8); PG8_BAR; PG8_WAIT_L(0); PG8_MMA(0, 0, At, B0); PG8_BAR; PG8_SCHED;
	s_waitcnt lgkmcnt(0)
	s_waitcnt lgkmcnt(0)
	v_mfma_f32_16x16x32_bf16 v[116:119], v[208:211], v[144:147], v[116:119]
	v_mfma_f32_16x16x32_bf16 v[112:115], v[232:235], v[144:147], v[112:115]
	v_mfma_f32_16x16x32_bf16 v[100:103], v[208:211], v[152:155], v[100:103]
	v_mfma_f32_16x16x32_bf16 v[96:99], v[232:235], v[152:155], v[96:99]
	v_mfma_f32_16x16x32_bf16 v[84:87], v[208:211], v[190:193], v[84:87]
	v_mfma_f32_16x16x32_bf16 v[80:83], v[232:235], v[190:193], v[80:83]
	v_mfma_f32_16x16x32_bf16 v[68:71], v[208:211], v[198:201], v[68:71]
	v_mfma_f32_16x16x32_bf16 v[64:67], v[232:235], v[198:201], v[64:67]
	v_mfma_f32_16x16x32_bf16 v[116:119], v[226:229], v[148:151], v[116:119]
	v_mfma_f32_16x16x32_bf16 v[112:115], v[236:239], v[148:151], v[112:115]
	v_mfma_f32_16x16x32_bf16 v[100:103], v[226:229], v[186:189], v[100:103]
	v_mfma_f32_16x16x32_bf16 v[96:99], v[236:239], v[186:189], v[96:99]
	v_mfma_f32_16x16x32_bf16 v[84:87], v[226:229], v[194:197], v[84:87]
	v_mfma_f32_16x16x32_bf16 v[80:83], v[236:239], v[194:197], v[80:83]
	v_mfma_f32_16x16x32_bf16 v[68:71], v[226:229], v[204:207], v[68:71]
	v_mfma_f32_16x16x32_bf16 v[64:67], v[236:239], v[204:207], v[64:67]
	s_mov_b32 m0, s51
	v_lshl_add_u64 v[240:241], s[48:49], 0, v[176:177]
	s_barrier
	ds_read_b128 v[144:147], v203 offset:16384
	ds_read_b128 v[148:151], v203 offset:17408
	ds_read_b128 v[152:155], v203 offset:18432
	ds_read_b128 v[186:189], v203 offset:19456
	ds_read_b128 v[190:193], v203 offset:20480
	ds_read_b128 v[194:197], v203 offset:21504
	ds_read_b128 v[198:201], v203 offset:22528
	ds_read_b128 v[204:207], v203 offset:23552
	global_load_lds_dwordx4 v176, s[48:49]
	v_lshl_add_u64 v[242:243], s[48:49], 0, v[158:159]
	s_mov_b32 m0, s62
	s_nop 0
	global_load_lds_dwordx4 v158, s[48:49]
	s_barrier
	s_waitcnt lgkmcnt(0)
	s_waitcnt lgkmcnt(0)
	v_mfma_f32_16x16x32_bf16 v[60:63], v[128:131], v[144:147], v[60:63]
	v_mfma_f32_16x16x32_bf16 v[56:59], v[136:139], v[144:147], v[56:59]
	v_mfma_f32_16x16x32_bf16 v[44:47], v[128:131], v[152:155], v[44:47]
	v_mfma_f32_16x16x32_bf16 v[40:43], v[136:139], v[152:155], v[40:43]
	v_mfma_f32_16x16x32_bf16 v[28:31], v[128:131], v[190:193], v[28:31]
	v_mfma_f32_16x16x32_bf16 v[24:27], v[136:139], v[190:193], v[24:27]
	v_mfma_f32_16x16x32_bf16 v[12:15], v[128:131], v[198:201], v[12:15]
	v_mfma_f32_16x16x32_bf16 v[8:11], v[136:139], v[198:201], v[8:11]
	v_mfma_f32_16x16x32_bf16 v[60:63], v[132:135], v[148:151], v[60:63]
	v_mfma_f32_16x16x32_bf16 v[56:59], v[140:143], v[148:151], v[56:59]
	v_mfma_f32_16x16x32_bf16 v[44:47], v[132:135], v[186:189], v[44:47]
	v_mfma_f32_16x16x32_bf16 v[40:43], v[140:143], v[186:189], v[40:43]
	v_mfma_f32_16x16x32_bf16 v[28:31], v[132:135], v[194:197], v[28:31]
	v_mfma_f32_16x16x32_bf16 v[24:27], v[140:143], v[194:197], v[24:27]
	v_mfma_f32_16x16x32_bf16 v[12:15], v[132:135], v[204:207], v[12:15]
	v_mfma_f32_16x16x32_bf16 v[8:11], v[140:143], v[204:207], v[8:11]
	s_barrier
	s_add_u32 s74, vcc_lo, 0x40000
	s_addc_u32 s75, vcc_hi, 0
	s_add_i32 s76, s76, s7
	s_mov_b32 m0, s76
	s_nop 0
	global_load_lds_dwordx4 v174, s[74:75]
	s_add_i32 m0, s76, 0x2000
	s_nop 0
	global_load_lds_dwordx4 v156, s[74:75]
	s_waitcnt vmcnt(10)
	s_barrier
	v_mfma_f32_16x16x32_bf16 v[52:55], v[208:211], v[144:147], v[52:55]
	v_mfma_f32_16x16x32_bf16 v[48:51], v[232:235], v[144:147], v[48:51]
	v_mfma_f32_16x16x32_bf16 v[36:39], v[208:211], v[152:155], v[36:39]
	v_mfma_f32_16x16x32_bf16 v[32:35], v[232:235], v[152:155], v[32:35]
	v_mfma_f32_16x16x32_bf16 v[20:23], v[208:211], v[190:193], v[20:23]
	v_mfma_f32_16x16x32_bf16 v[16:19], v[232:235], v[190:193], v[16:19]
	v_mfma_f32_16x16x32_bf16 v[4:7], v[208:211], v[198:201], v[4:7]
	v_mfma_f32_16x16x32_bf16 v[0:3], v[232:235], v[198:201], v[0:3]
	v_mfma_f32_16x16x32_bf16 v[52:55], v[226:229], v[148:151], v[52:55]
	v_mfma_f32_16x16x32_bf16 v[48:51], v[236:239], v[148:151], v[48:51]
	v_mfma_f32_16x16x32_bf16 v[36:39], v[226:229], v[186:189], v[36:39]
	v_mfma_f32_16x16x32_bf16 v[32:35], v[236:239], v[186:189], v[32:35]
	v_mfma_f32_16x16x32_bf16 v[20:23], v[226:229], v[194:197], v[20:23]
	v_mfma_f32_16x16x32_bf16 v[16:19], v[236:239], v[194:197], v[16:19]
	v_mfma_f32_16x16x32_bf16 v[4:7], v[226:229], v[204:207], v[4:7]
	v_mfma_f32_16x16x32_bf16 v[0:3], v[236:239], v[204:207], v[0:3]
	s_add_i32 s74, 0, 0x18000
	v_add_u32_e32 v140, s74, v202
	s_barrier
	ds_read_b128 v[128:131], v140
	ds_read_b128 v[132:135], v140 offset:1024
	ds_read_b128 v[136:139], v140 offset:2048
	ds_read_b128 v[140:143], v140 offset:3072
	s_add_u32 s48, s48, 0x40000
	s_addc_u32 s49, s49, 0
	s_mov_b32 m0, s63
	ds_read_b128 v[144:147], v203 offset:32768
	ds_read_b128 v[148:151], v203 offset:33792
	ds_read_b128 v[152:155], v203 offset:34816
	ds_read_b128 v[186:189], v203 offset:35840
	ds_read_b128 v[190:193], v203 offset:36864
	ds_read_b128 v[194:197], v203 offset:37888
	ds_read_b128 v[198:201], v203 offset:38912
	ds_read_b128 v[204:207], v203 offset:39936
	global_load_lds_dwordx4 v176, s[48:49]
	s_mov_b32 m0, s64
	s_nop 0
	global_load_lds_dwordx4 v158, s[48:49]
	s_waitcnt vmcnt(8)
	s_waitcnt lgkmcnt(8)
	s_barrier
; #define PG8_STAGE(bufoff, gbase, voff) do { _Pragma("unroll") for (int _i = 0; _i < 2; ++_i) \
;     __builtin_amdgcn_global_load_lds((const unsigned*)((const char*)(gbase) + (voff)[_i]), (LAS unsigned*)(lds + (bufoff) + ldsw + _i * 8192), 16, 0, 0); } while (0)
; #define PG8_LDA(dst, b, h) do { _Pragma("unroll") for (int m = 0; m < 4; ++m) _Pragma("unroll") for (int k = 0; k < 2; ++k) dst[m][k] = *(const LAS bf16x8*)(lds + PG8_SA(b, h) + aoff + m * 2048 + k * 1024); } while (0)
; #define PG8_LDB(dst, b, h) do { _Pragma("unroll") for (int n = 0; n < 2; ++n) _Pragma("unroll") for (int k = 0; k < 2; ++k) dst[n][k] = *(const LAS bf16x8*)(lds + PG8_SB(b, h) + boff + n * 2048 + k * 1024); } while (0)
; #define PG8_MMA(ai, bj, At, Bt) do { __builtin_amdgcn_s_setprio(1); _Pragma("unroll") for (int m = 0; m < 4; ++m) _Pragma("unroll") for (int n = 0; n < 2; ++n) _Pragma("unroll") for (int k = 0; k < 2; ++k) \
;     acc[ai][bj][m][n] = __builtin_amdgcn_mfma_f32_16x16x32_bf16(Bt[n][k], At[m][k], acc[ai][bj][m][n], 0, 0, 0); __builtin_amdgcn_s_setprio(0); } while (0)
; #define PG8_WAIT_V(n) asm volatile("s_waitcnt vmcnt(" #n ")" ::: "memory")
; #define PG8_WAIT_L(n) asm volatile("s_waitcnt lgkmcnt(" #n ")" ::: "memory")
; #define PG8_BAR __builtin_amdgcn_s_barrier()
; #define PG8_SCHED __builtin_amdgcn_sched_barrier(0)
; template <class Epi, class Sched>
; __device__ __forceinline__ void gemm_phase(LAS unsigned char* lds, const Gemm g, const Sched& S, const Epi& E) {
;     ...
;       PG8_WAIT_L(8); PG8_BAR; PG8_WAIT_L(0); PG8_MMA(0, 0, At, B0); PG8_BAR; PG8_SCHED;
;       PG8_LDB(B1, 1, 1); PG8_STAGE(PG8_SB(1, 0), b3, voffB);
;       PG8_BAR; PG8_WAIT_L(0); PG8_MMA(0, 1, At, B1); PG8_BAR;
;       PG8_LDA(At, 1, 1); PG8_STAGE(PG8_SA(1, 0), a3, voffA);
;       PG8_BAR; PG8_WAIT_L(0); PG8_MMA(1, 0, At, B0); PG8_BAR; PG8_SCHED;
;       PG8_STAGE(PG8_SB(1, 1), b3 + hstep, voffB);
;       PG8_WAIT_V(6); PG8_BAR; PG8_MMA(1, 1, At, B1); PG8_BAR;
;     }
	s_waitcnt lgkmcnt(0)
	s_waitcnt lgkmcnt(0)
	v_mfma_f32_16x16x32_bf16 v[124:127], v[128:131], v[144:147], v[124:127]
	v_mfma_f32_16x16x32_bf16 v[120:123], v[136:139], v[144:147], v[120:123]
	v_mfma_f32_16x16x32_bf16 v[108:111], v[128:131], v[152:155], v[108:111]
	v_mfma_f32_16x16x32_bf16 v[104:107], v[136:139], v[152:155], v[104:107]
	v_mfma_f32_16x16x32_bf16 v[92:95], v[128:131], v[190:193], v[92:95]
	v_mfma_f32_16x16x32_bf16 v[88:91], v[136:139], v[190:193], v[88:91]
	v_mfma_f32_16x16x32_bf16 v[76:79], v[128:131], v[198:201], v[76:79]
	v_mfma_f32_16x16x32_bf16 v[72:75], v[136:139], v[198:201], v[72:75]
	v_mfma_f32_16x16x32_bf16 v[124:127], v[132:135], v[148:151], v[124:127]
	v_mfma_f32_16x16x32_bf16 v[120:123], v[140:143], v[148:151], v[120:123]
	v_mfma_f32_16x16x32_bf16 v[108:111], v[132:135], v[186:189], v[108:111]
	v_mfma_f32_16x16x32_bf16 v[104:107], v[140:143], v[186:189], v[104:107]
	v_mfma_f32_16x16x32_bf16 v[92:95], v[132:135], v[194:197], v[92:95]
	v_mfma_f32_16x16x32_bf16 v[88:91], v[140:143], v[194:197], v[88:91]
	v_mfma_f32_16x16x32_bf16 v[76:79], v[132:135], v[204:207], v[76:79]
	v_mfma_f32_16x16x32_bf16 v[72:75], v[140:143], v[204:207], v[72:75]
	s_barrier
	s_add_i32 s75, 0, 0x1c000
	s_add_i32 s48, s74, s7
	v_add_u32_e32 v160, s75, v202
	s_add_u32 s60, vcc_lo, s80
	s_addc_u32 s61, vcc_hi, s81
	s_mov_b32 m0, s48
	ds_read_b128 v[208:211], v160
	ds_read_b128 v[226:229], v160 offset:1024
	ds_read_b128 v[232:235], v160 offset:2048
	ds_read_b128 v[236:239], v160 offset:3072
	global_load_lds_dwordx4 v174, s[60:61]
	v_lshl_add_u64 v[212:213], v[222:223], 0, s[80:81]
	s_add_i32 m0, s48, 0x2000
	s_nop 0
	global_load_lds_dwordx4 v156, s[60:61]
	s_barrier
	s_waitcnt lgkmcnt(0)
	s_waitcnt lgkmcnt(0)
	v_mfma_f32_16x16x32_bf16 v[116:119], v[208:211], v[144:147], v[116:119]
	v_mfma_f32_16x16x32_bf16 v[112:115], v[232:235], v[144:147], v[112:115]
	v_mfma_f32_16x16x32_bf16 v[100:103], v[208:211], v[152:155], v[100:103]
	v_mfma_f32_16x16x32_bf16 v[96:99], v[232:235], v[152:155], v[96:99]
	v_mfma_f32_16x16x32_bf16 v[84:87], v[208:211], v[190:193], v[84:87]
	v_mfma_f32_16x16x32_bf16 v[80:83], v[232:235], v[190:193], v[80:83]
	v_mfma_f32_16x16x32_bf16 v[68:71], v[208:211], v[198:201], v[68:71]
	v_mfma_f32_16x16x32_bf16 v[64:67], v[232:235], v[198:201], v[64:67]
	v_mfma_f32_16x16x32_bf16 v[116:119], v[226:229], v[148:151], v[116:119]
	v_mfma_f32_16x16x32_bf16 v[112:115], v[236:239], v[148:151], v[112:115]
	v_mfma_f32_16x16x32_bf16 v[100:103], v[226:229], v[186:189], v[100:103]
	v_mfma_f32_16x16x32_bf16 v[96:99], v[236:239], v[186:189], v[96:99]
	v_mfma_f32_16x16x32_bf16 v[84:87], v[226:229], v[194:197], v[84:87]
	v_mfma_f32_16x16x32_bf16 v[80:83], v[236:239], v[194:197], v[80:83]
	v_mfma_f32_16x16x32_bf16 v[68:71], v[226:229], v[204:207], v[68:71]
	v_mfma_f32_16x16x32_bf16 v[64:67], v[236:239], v[204:207], v[64:67]
	s_mov_b32 m0, s65
	v_lshl_add_u64 v[212:213], v[240:241], 0, s[80:81]
	s_barrier
	ds_read_b128 v[144:147], v203 offset:49152
	ds_read_b128 v[148:151], v203 offset:50176
	ds_read_b128 v[152:155], v203 offset:51200
	ds_read_b128 v[186:189], v203 offset:52224
	ds_read_b128 v[190:193], v203 offset:53248
	ds_read_b128 v[194:197], v203 offset:54272
	ds_read_b128 v[198:201], v203 offset:55296
	ds_read_b128 v[204:207], v203 offset:56320
	global_load_lds_dwordx4 v[212:213], off
	v_lshl_add_u64 v[212:213], v[242:243], 0, s[80:81]
	s_mov_b32 m0, s70
	s_nop 0
	global_load_lds_dwordx4 v[212:213], off
	s_barrier
	s_waitcnt lgkmcnt(0)
	s_waitcnt lgkmcnt(0)
	v_mfma_f32_16x16x32_bf16 v[60:63], v[128:131], v[144:147], v[60:63]
	v_mfma_f32_16x16x32_bf16 v[56:59], v[136:139], v[144:147], v[56:59]
	v_mfma_f32_16x16x32_bf16 v[44:47], v[128:131], v[152:155], v[44:47]
	v_mfma_f32_16x16x32_bf16 v[40:43], v[136:139], v[152:155], v[40:43]
	v_mfma_f32_16x16x32_bf16 v[28:31], v[128:131], v[190:193], v[28:31]
	v_mfma_f32_16x16x32_bf16 v[24:27], v[136:139], v[190:193], v[24:27]
	v_mfma_f32_16x16x32_bf16 v[12:15], v[128:131], v[198:201], v[12:15]
	v_mfma_f32_16x16x32_bf16 v[8:11], v[136:139], v[198:201], v[8:11]
	v_mfma_f32_16x16x32_bf16 v[60:63], v[132:135], v[148:151], v[60:63]
	v_mfma_f32_16x16x32_bf16 v[56:59], v[140:143], v[148:151], v[56:59]
	v_mfma_f32_16x16x32_bf16 v[44:47], v[132:135], v[186:189], v[44:47]
	v_mfma_f32_16x16x32_bf16 v[40:43], v[140:143], v[186:189], v[40:43]
	v_mfma_f32_16x16x32_bf16 v[28:31], v[132:135], v[194:197], v[28:31]
	v_mfma_f32_16x16x32_bf16 v[24:27], v[140:143], v[194:197], v[24:27]
	v_mfma_f32_16x16x32_bf16 v[12:15], v[132:135], v[204:207], v[12:15]
	v_mfma_f32_16x16x32_bf16 v[8:11], v[140:143], v[204:207], v[8:11]
	s_barrier
	s_add_u32 s48, vcc_lo, 0x40080
	s_addc_u32 s49, vcc_hi, 0
	s_add_i32 s74, s75, s7
	s_mov_b32 m0, s74
	s_nop 0
	global_load_lds_dwordx4 v174, s[48:49]
	s_add_i32 m0, s74, 0x2000
	s_nop 0
	global_load_lds_dwordx4 v156, s[48:49]
	s_waitcnt vmcnt(10)
	s_barrier
	v_mfma_f32_16x16x32_bf16 v[52:55], v[208:211], v[144:147], v[52:55]
	v_mfma_f32_16x16x32_bf16 v[48:51], v[232:235], v[144:147], v[48:51]
	v_mfma_f32_16x16x32_bf16 v[36:39], v[208:211], v[152:155], v[36:39]
	v_mfma_f32_16x16x32_bf16 v[32:35], v[232:235], v[152:155], v[32:35]
	v_mfma_f32_16x16x32_bf16 v[20:23], v[208:211], v[190:193], v[20:23]
	v_mfma_f32_16x16x32_bf16 v[16:19], v[232:235], v[190:193], v[16:19]
	v_mfma_f32_16x16x32_bf16 v[4:7], v[208:211], v[198:201], v[4:7]
	v_mfma_f32_16x16x32_bf16 v[0:3], v[232:235], v[198:201], v[0:3]
	v_mfma_f32_16x16x32_bf16 v[52:55], v[226:229], v[148:151], v[52:55]
	v_mfma_f32_16x16x32_bf16 v[48:51], v[236:239], v[148:151], v[48:51]
	v_mfma_f32_16x16x32_bf16 v[36:39], v[226:229], v[186:189], v[36:39]
	v_mfma_f32_16x16x32_bf16 v[32:35], v[236:239], v[186:189], v[32:35]
	v_mfma_f32_16x16x32_bf16 v[20:23], v[226:229], v[194:197], v[20:23]
	v_mfma_f32_16x16x32_bf16 v[16:19], v[236:239], v[194:197], v[16:19]
	v_mfma_f32_16x16x32_bf16 v[4:7], v[226:229], v[204:207], v[4:7]
	v_mfma_f32_16x16x32_bf16 v[0:3], v[236:239], v[204:207], v[0:3]
	s_add_i32 s73, s73, 2
	s_add_u32 s34, s34, 0x100
	s_addc_u32 s35, s35, 0
	s_add_u32 s52, s52, 0x100
	s_addc_u32 s72, s72, 0
	s_cmp_gt_u32 s73, 13
	s_barrier
	s_cbranch_scc0 .LBB0_1057
	s_cmp_lt_u32 s101, 0x100
	s_cbranch_scc0 .Lxa_9
	s_barrier

; #define PG8_STAGE(bufoff, gbase, voff) do { _Pragma("unroll") for (int _i = 0; _i < 2; ++_i) \
;     __builtin_amdgcn_global_load_lds((const unsigned*)((const char*)(gbase) + (voff)[_i]), (LAS unsigned*)(lds + (bufoff) + ldsw + _i * 8192), 16, 0, 0); } while (0)
; #define PG8_LDA(dst, b, h) do { _Pragma("unroll") for (int m = 0; m < 4; ++m) _Pragma("unroll") for (int k = 0; k < 2; ++k) dst[m][k] = *(const LAS bf16x8*)(lds + PG8_SA(b, h) + aoff + m * 2048 + k * 1024); } while (0)
; #define PG8_LDB(dst, b, h) do { _Pragma("unroll") for (int n = 0; n < 2; ++n) _Pragma("unroll") for (int k = 0; k < 2; ++k) dst[n][k] = *(const LAS bf16x8*)(lds + PG8_SB(b, h) + boff + n * 2048 + k * 1024); } while (0)
; #define PG8_MMA(ai, bj, At, Bt) do { __builtin_amdgcn_s_setprio(1); _Pragma("unroll") for (int m = 0; m < 4; ++m) _Pragma("unroll") for (int n = 0; n < 2; ++n) _Pragma("unroll") for (int k = 0; k < 2; ++k) \
;     acc[ai][bj][m][n] = __builtin_amdgcn_mfma_f32_16x16x32_bf16(Bt[n][k], At[m][k], acc[ai][bj][m][n], 0, 0, 0); __builtin_amdgcn_s_setprio(0); } while (0)
; #define PG8_WAIT_L(n) asm volatile("s_waitcnt lgkmcnt(" #n ")" ::: "memory")
; template <class Epi, class Sched>
; __device__ __forceinline__ void gemm_phase(LAS unsigned char* lds, const Gemm g, const Sched& S, const Epi& E) {
;     ...
;     const bool has_next = S.next(ui + 1, nxt);
;     const char* nA = has_next ? (const char*)g.A + (size_t)nxt.pm * tstep : cA; const char* nB = has_next ? (const char*)g.Bt + (size_t)nxt.pn * tstep : cB;
;     for (int t = 0; t < nt; t += 2) {
;       const bool last = (t == nt - 2);
;       const char* a1 = cA + (size_t)(t + 1) * kstep;
;       const char* a2 = last ? nA : cA + (size_t)(t + 2) * kstep; const char* b2 = last ? nB : cB + (size_t)(t + 2) * kstep;
;       const char* a3 = a2 + kstep; const char* b3 = b2 + kstep;
;       if (last && has_next) S.a_ready(nxt);
;       PG8_LDB(B0, 0, 0); PG8_SCHED; PG8_LDA(At, 0, 0); PG8_STAGE(PG8_SA(1, 1), a1 + hstep, voffA);
;       PG8_WAIT_L(8); PG8_BAR; PG8_WAIT_L(0); PG8_MMA(0, 0, At, B0); PG8_BAR; PG8_SCHED;
;     ...
; #pragma unroll
;     for (int a = 0; a < 2; ++a)
; #pragma unroll
;       for (int b = 0; b < 2; ++b)
; #pragma unroll
;         for (int m = 0; m < 4; ++m)
; #pragma unroll
;           for (int n = 0; n < 2; ++n) acc[a][b][m][n] = (f32x4){0.f, 0.f, 0.f, 0.f};
;     cur = nxt; cA = nA; cB = nB; ++ui;
.LBB0_1141:
	s_ashr_i32 s35, s34, 31
	v_cmp_lt_i64_e32 vcc, s[36:37], v[164:165]
	s_lshl_b64 s[36:37], s[34:35], 19
	s_add_u32 s36, s94, s36
	s_addc_u32 s37, s95, s37
	s_and_b64 s[40:41], vcc, exec
	s_cselect_b32 s35, s37, s43
	s_cselect_b32 s71, s36, s42
	s_ashr_i32 s23, s22, 31
	s_lshl_b64 s[40:41], s[22:23], 19
	v_readlane_b32 s48, v252, 57
	v_readlane_b32 s49, v252, 58
	s_add_u32 s40, s48, s40
	s_addc_u32 s41, s49, s41
	s_and_b64 s[48:49], vcc, exec
	s_cselect_b32 s23, s41, s45
	s_cselect_b32 vcc_lo, s40, s44
	s_add_u32 s42, s42, 0x40080
	s_addc_u32 s43, s43, 0
	s_add_u32 s52, s44, 0x100
	v_mov_b32_e32 v0, 0
	s_addc_u32 s72, s45, 0
	s_mov_b32 s73, -2
	v_mov_b32_e32 v1, v0
	v_mov_b64_e32 v[2:3], v[0:1]
	v_mov_b64_e32 v[4:5], v[0:1]
	v_mov_b64_e32 v[6:7], v[0:1]
	v_mov_b64_e32 v[8:9], v[0:1]
	v_mov_b64_e32 v[10:11], v[0:1]
	v_mov_b64_e32 v[12:13], v[0:1]
	v_mov_b64_e32 v[14:15], v[0:1]
	v_mov_b64_e32 v[16:17], v[0:1]
	v_mov_b64_e32 v[18:19], v[0:1]
	v_mov_b64_e32 v[20:21], v[0:1]
	v_mov_b64_e32 v[22:23], v[0:1]
	v_mov_b64_e32 v[24:25], v[0:1]
	v_mov_b64_e32 v[26:27], v[0:1]
	v_mov_b64_e32 v[28:29], v[0:1]
	v_mov_b64_e32 v[30:31], v[0:1]
	v_mov_b64_e32 v[32:33], v[0:1]
	v_mov_b64_e32 v[34:35], v[0:1]
	v_mov_b64_e32 v[36:37], v[0:1]
	v_mov_b64_e32 v[38:39], v[0:1]
	v_mov_b64_e32 v[40:41], v[0:1]
	v_mov_b64_e32 v[42:43], v[0:1]
	v_mov_b64_e32 v[44:45], v[0:1]
	v_mov_b64_e32 v[46:47], v[0:1]
	v_mov_b64_e32 v[48:49], v[0:1]
	v_mov_b64_e32 v[50:51], v[0:1]
	v_mov_b64_e32 v[52:53], v[0:1]
	v_mov_b64_e32 v[54:55], v[0:1]
	v_mov_b64_e32 v[56:57], v[0:1]
	v_mov_b64_e32 v[58:59], v[0:1]
	v_mov_b64_e32 v[60:61], v[0:1]
	v_mov_b64_e32 v[62:63], v[0:1]
	v_mov_b64_e32 v[64:65], v[0:1]
	v_mov_b64_e32 v[66:67], v[0:1]
	v_mov_b64_e32 v[68:69], v[0:1]
	v_mov_b64_e32 v[70:71], v[0:1]
	v_mov_b64_e32 v[72:73], v[0:1]
	v_mov_b64_e32 v[74:75], v[0:1]
	v_mov_b64_e32 v[76:77], v[0:1]
	v_mov_b64_e32 v[78:79], v[0:1]
	v_mov_b64_e32 v[80:81], v[0:1]
	v_mov_b64_e32 v[82:83], v[0:1]
	v_mov_b64_e32 v[84:85], v[0:1]
	v_mov_b64_e32 v[86:87], v[0:1]
	v_mov_b64_e32 v[88:89], v[0:1]
	v_mov_b64_e32 v[90:91], v[0:1]
	v_mov_b64_e32 v[92:93], v[0:1]
	v_mov_b64_e32 v[94:95], v[0:1]
	v_mov_b64_e32 v[96:97], v[0:1]
	v_mov_b64_e32 v[98:99], v[0:1]
	v_mov_b64_e32 v[100:101], v[0:1]
	v_mov_b64_e32 v[102:103], v[0:1]
	v_mov_b64_e32 v[104:105], v[0:1]
	v_mov_b64_e32 v[106:107], v[0:1]
	v_mov_b64_e32 v[108:109], v[0:1]
	v_mov_b64_e32 v[110:111], v[0:1]
	v_mov_b64_e32 v[112:113], v[0:1]
	v_mov_b64_e32 v[114:115], v[0:1]
	v_mov_b64_e32 v[116:117], v[0:1]
	v_mov_b64_e32 v[118:119], v[0:1]
	v_mov_b64_e32 v[120:121], v[0:1]
	v_mov_b64_e32 v[122:123], v[0:1]
	v_mov_b64_e32 v[124:125], v[0:1]
	v_mov_b64_e32 v[126:127], v[0:1]
	s_cmp_eq_u32 s100, 0
	s_cbranch_scc1 .Lxs_e10
	s_barrier
	s_mov_b32 s100, 0
.Lxs_e10:
.LBB0_1142:
	s_add_u32 s44, s42, 0xfffc0080
	s_addc_u32 s45, s43, -1
	s_add_i32 s74, 0, 0x10000
	v_add_u32_e32 v151, s74, v141
	ds_read_b128 v[152:155], v151
	ds_read_b128 v[156:159], v151 offset:1024
	ds_read_b128 v[174:177], v151 offset:2048
	ds_read_b128 v[178:181], v151 offset:3072
	s_cmp_eq_u32 s73, 12
	s_cselect_b32 s49, s35, s45
	s_cselect_b32 s48, s71, s44
	s_cselect_b32 s45, s23, s72
	s_cselect_b32 s44, vcc_lo, s52
	s_add_i32 m0, s12, 0xc000
	ds_read_b128 v[182:185], v150
	ds_read_b128 v[186:189], v150 offset:1024
	ds_read_b128 v[190:193], v150 offset:2048
	ds_read_b128 v[194:197], v150 offset:3072
	ds_read_b128 v[198:201], v150 offset:4096
	ds_read_b128 v[202:205], v150 offset:5120
	ds_read_b128 v[206:209], v150 offset:6144
	ds_read_b128 v[210:213], v150 offset:7168
	global_load_lds_dwordx4 v136, s[42:43]
	s_add_i32 m0, s12, 0xe000
	s_nop 0
	global_load_lds_dwordx4 v138, s[42:43]
	s_waitcnt vmcnt(8)
	s_waitcnt lgkmcnt(8)
	s_barrier
	s_waitcnt lgkmcnt(0)
	s_waitcnt lgkmcnt(0)
	v_mfma_f32_16x16x32_bf16 v[124:127], v[152:155], v[182:185], v[124:127]
	v_mfma_f32_16x16x32_bf16 v[116:119], v[174:177], v[182:185], v[116:119]
	v_mfma_f32_16x16x32_bf16 v[108:111], v[152:155], v[190:193], v[108:111]
	v_mfma_f32_16x16x32_bf16 v[100:103], v[174:177], v[190:193], v[100:103]
	v_mfma_f32_16x16x32_bf16 v[92:95], v[152:155], v[198:201], v[92:95]
	v_mfma_f32_16x16x32_bf16 v[84:87], v[174:177], v[198:201], v[84:87]
	v_mfma_f32_16x16x32_bf16 v[76:79], v[152:155], v[206:209], v[76:79]
	v_mfma_f32_16x16x32_bf16 v[68:71], v[174:177], v[206:209], v[68:71]
	v_mfma_f32_16x16x32_bf16 v[124:127], v[156:159], v[186:189], v[124:127]
	v_mfma_f32_16x16x32_bf16 v[116:119], v[178:181], v[186:189], v[116:119]
	v_mfma_f32_16x16x32_bf16 v[108:111], v[156:159], v[194:197], v[108:111]
	v_mfma_f32_16x16x32_bf16 v[100:103], v[178:181], v[194:197], v[100:103]
	v_mfma_f32_16x16x32_bf16 v[92:95], v[156:159], v[202:205], v[92:95]
	v_mfma_f32_16x16x32_bf16 v[84:87], v[178:181], v[202:205], v[84:87]
	v_mfma_f32_16x16x32_bf16 v[76:79], v[156:159], v[210:213], v[76:79]
	v_mfma_f32_16x16x32_bf16 v[68:71], v[178:181], v[210:213], v[68:71]
	s_barrier
	s_add_i32 s76, 0, 0x14000
	s_add_i32 s74, s74, s7
	v_add_u32_e32 v151, s76, v141
	s_mov_b32 m0, s74
	ds_read_b128 v[226:229], v151
	ds_read_b128 v[232:235], v151 offset:1024
	ds_read_b128 v[236:239], v151 offset:2048
	ds_read_b128 v[240:243], v151 offset:3072
	global_load_lds_dwordx4 v132, s[44:45]
	s_add_i32 m0, s74, 0x2000
	s_nop 0
	global_load_lds_dwordx4 v128, s[44:45]
	s_barrier
; #define PG8_STAGE(bufoff, gbase, voff) do { _Pragma("unroll") for (int _i = 0; _i < 2; ++_i) \
;     __builtin_amdgcn_global_load_lds((const unsigned*)((const char*)(gbase) + (voff)[_i]), (LAS unsigned*)(lds + (bufoff) + ldsw + _i * 8192), 16, 0, 0); } while (0)
; #define PG8_LDA(dst, b, h) do { _Pragma("unroll") for (int m = 0; m < 4; ++m) _Pragma("unroll") for (int k = 0; k < 2; ++k) dst[m][k] = *(const LAS bf16x8*)(lds + PG8_SA(b, h) + aoff + m * 2048 + k * 1024); } while (0)
; #define PG8_LDB(dst, b, h) do { _Pragma("unroll") for (int n = 0; n < 2; ++n) _Pragma("unroll") for (int k = 0; k < 2; ++k) dst[n][k] = *(const LAS bf16x8*)(lds + PG8_SB(b, h) + boff + n * 2048 + k * 1024); } while (0)
; #define PG8_MMA(ai, bj, At, Bt) do { __builtin_amdgcn_s_setprio(1); _Pragma("unroll") for (int m = 0; m < 4; ++m) _Pragma("unroll") for (int n = 0; n < 2; ++n) _Pragma("unroll") for (int k = 0; k < 2; ++k) \
;     acc[ai][bj][m][n] = __builtin_amdgcn_mfma_f32_16x16x32_bf16(Bt[n][k], At[m][k], acc[ai][bj][m][n], 0, 0, 0); __builtin_amdgcn_s_setprio(0); } while (0)
; #define PG8_WAIT_V(n) asm volatile("s_waitcnt vmcnt(" #n ")" ::: "memory")
; #define PG8_WAIT_L(n) asm volatile("s_waitcnt lgkmcnt(" #n ")" ::: "memory")
; #define PG8_BAR __builtin_amdgcn_s_barrier()
; #define PG8_SCHED __builtin_amdgcn_sched_barrier(0)
; template <class Epi, class Sched>
; __device__ __forceinline__ void gemm_phase(LAS unsigned char* lds, const Gemm g, const Sched& S, const Epi& E) {
;     ...
;       PG8_LDB(B1, 0, 1); PG8_STAGE(PG8_SB(0, 0), b2, voffB);
;       PG8_BAR; PG8_WAIT_L(0); PG8_MMA(0, 1, At, B1); PG8_BAR;
;       PG8_LDA(At, 0, 1); PG8_STAGE(PG8_SA(0, 0), a2, voffA);
;       PG8_BAR; PG8_WAIT_L(0); PG8_MMA(1, 0, At, B0); PG8_BAR; PG8_SCHED;
;       PG8_STAGE(PG8_SB(0, 1), b2 + hstep, voffB);
;       PG8_WAIT_V(6); PG8_BAR; PG8_MMA(1, 1, At, B1); PG8_BAR;
;       PG8_LDB(B0, 1, 0); PG8_SCHED; PG8_LDA(At, 1, 0); PG8_STAGE(PG8_SA(0, 1), a2 + hstep, voffA);
;       PG8_WAIT_L(8); PG8_BAR; PG8_WAIT_L(0); PG8_MMA(0, 0, At, B0); PG8_BAR; PG8_SCHED;
	s_waitcnt lgkmcnt(0)
	s_waitcnt lgkmcnt(0)
	v_mfma_f32_16x16x32_bf16 v[120:123], v[226:229], v[182:185], v[120:123]
	v_mfma_f32_16x16x32_bf16 v[112:115], v[236:239], v[182:185], v[112:115]
	v_mfma_f32_16x16x32_bf16 v[104:107], v[226:229], v[190:193], v[104:107]
	v_mfma_f32_16x16x32_bf16 v[96:99], v[236:239], v[190:193], v[96:99]
	v_mfma_f32_16x16x32_bf16 v[88:91], v[226:229], v[198:201], v[88:91]
	v_mfma_f32_16x16x32_bf16 v[80:83], v[236:239], v[198:201], v[80:83]
	v_mfma_f32_16x16x32_bf16 v[72:75], v[226:229], v[206:209], v[72:75]
	v_mfma_f32_16x16x32_bf16 v[64:67], v[236:239], v[206:209], v[64:67]
	v_mfma_f32_16x16x32_bf16 v[120:123], v[232:235], v[186:189], v[120:123]
	v_mfma_f32_16x16x32_bf16 v[112:115], v[240:243], v[186:189], v[112:115]
	v_mfma_f32_16x16x32_bf16 v[104:107], v[232:235], v[194:197], v[104:107]
	v_mfma_f32_16x16x32_bf16 v[96:99], v[240:243], v[194:197], v[96:99]
	v_mfma_f32_16x16x32_bf16 v[88:91], v[232:235], v[202:205], v[88:91]
	v_mfma_f32_16x16x32_bf16 v[80:83], v[240:243], v[202:205], v[80:83]
	v_mfma_f32_16x16x32_bf16 v[72:75], v[232:235], v[210:213], v[72:75]
	v_mfma_f32_16x16x32_bf16 v[64:67], v[240:243], v[210:213], v[64:67]
	s_mov_b32 m0, s12
	v_lshl_add_u64 v[246:247], s[48:49], 0, v[134:135]
	s_barrier
	ds_read_b128 v[182:185], v150 offset:16384
	ds_read_b128 v[186:189], v150 offset:17408
	ds_read_b128 v[190:193], v150 offset:18432
	ds_read_b128 v[194:197], v150 offset:19456
	ds_read_b128 v[198:201], v150 offset:20480
	ds_read_b128 v[202:205], v150 offset:21504
	ds_read_b128 v[206:209], v150 offset:22528
	ds_read_b128 v[210:213], v150 offset:23552
	global_load_lds_dwordx4 v134, s[48:49]
	v_lshl_add_u64 v[248:249], s[48:49], 0, v[130:131]
	s_mov_b32 m0, s13
	s_nop 0
	global_load_lds_dwordx4 v130, s[48:49]
	s_barrier
	s_waitcnt lgkmcnt(0)
	s_waitcnt lgkmcnt(0)
	v_mfma_f32_16x16x32_bf16 v[60:63], v[152:155], v[182:185], v[60:63]
	v_mfma_f32_16x16x32_bf16 v[52:55], v[174:177], v[182:185], v[52:55]
	v_mfma_f32_16x16x32_bf16 v[44:47], v[152:155], v[190:193], v[44:47]
	v_mfma_f32_16x16x32_bf16 v[36:39], v[174:177], v[190:193], v[36:39]
	v_mfma_f32_16x16x32_bf16 v[28:31], v[152:155], v[198:201], v[28:31]
	v_mfma_f32_16x16x32_bf16 v[20:23], v[174:177], v[198:201], v[20:23]
	v_mfma_f32_16x16x32_bf16 v[12:15], v[152:155], v[206:209], v[12:15]
	v_mfma_f32_16x16x32_bf16 v[4:7], v[174:177], v[206:209], v[4:7]
	v_mfma_f32_16x16x32_bf16 v[60:63], v[156:159], v[186:189], v[60:63]
	v_mfma_f32_16x16x32_bf16 v[52:55], v[178:181], v[186:189], v[52:55]
	v_mfma_f32_16x16x32_bf16 v[44:47], v[156:159], v[194:197], v[44:47]
	v_mfma_f32_16x16x32_bf16 v[36:39], v[178:181], v[194:197], v[36:39]
	v_mfma_f32_16x16x32_bf16 v[28:31], v[156:159], v[202:205], v[28:31]
	v_mfma_f32_16x16x32_bf16 v[20:23], v[178:181], v[202:205], v[20:23]
	v_mfma_f32_16x16x32_bf16 v[12:15], v[156:159], v[210:213], v[12:15]
	v_mfma_f32_16x16x32_bf16 v[4:7], v[178:181], v[210:213], v[4:7]
	s_barrier
	s_add_u32 s74, s44, 0x40000
	s_addc_u32 s75, s45, 0
	s_add_i32 s76, s76, s7
	s_mov_b32 m0, s76
	s_nop 0
	global_load_lds_dwordx4 v132, s[74:75]
	s_add_i32 m0, s76, 0x2000
	s_nop 0
	global_load_lds_dwordx4 v128, s[74:75]
	s_waitcnt vmcnt(10)
	s_barrier
	v_mfma_f32_16x16x32_bf16 v[56:59], v[226:229], v[182:185], v[56:59]
	v_mfma_f32_16x16x32_bf16 v[48:51], v[236:239], v[182:185], v[48:51]
	v_mfma_f32_16x16x32_bf16 v[40:43], v[226:229], v[190:193], v[40:43]
	v_mfma_f32_16x16x32_bf16 v[32:35], v[236:239], v[190:193], v[32:35]
	v_mfma_f32_16x16x32_bf16 v[24:27], v[226:229], v[198:201], v[24:27]
	v_mfma_f32_16x16x32_bf16 v[16:19], v[236:239], v[198:201], v[16:19]
	v_mfma_f32_16x16x32_bf16 v[8:11], v[226:229], v[206:209], v[8:11]
	v_mfma_f32_16x16x32_bf16 v[0:3], v[236:239], v[206:209], v[0:3]
	v_mfma_f32_16x16x32_bf16 v[56:59], v[232:235], v[186:189], v[56:59]
	v_mfma_f32_16x16x32_bf16 v[48:51], v[240:243], v[186:189], v[48:51]
	v_mfma_f32_16x16x32_bf16 v[40:43], v[232:235], v[194:197], v[40:43]
	v_mfma_f32_16x16x32_bf16 v[32:35], v[240:243], v[194:197], v[32:35]
	v_mfma_f32_16x16x32_bf16 v[24:27], v[232:235], v[202:205], v[24:27]
	v_mfma_f32_16x16x32_bf16 v[16:19], v[240:243], v[202:205], v[16:19]
	v_mfma_f32_16x16x32_bf16 v[8:11], v[232:235], v[210:213], v[8:11]
	v_mfma_f32_16x16x32_bf16 v[0:3], v[240:243], v[210:213], v[0:3]
	s_add_i32 s74, 0, 0x18000
	v_add_u32_e32 v151, s74, v141
	s_barrier
	ds_read_b128 v[152:155], v151
	ds_read_b128 v[156:159], v151 offset:1024
	ds_read_b128 v[174:177], v151 offset:2048
	ds_read_b128 v[178:181], v151 offset:3072
	s_add_u32 s48, s48, 0x40000
	s_addc_u32 s49, s49, 0
	s_mov_b32 m0, s51
	ds_read_b128 v[182:185], v150 offset:32768
	ds_read_b128 v[186:189], v150 offset:33792
	ds_read_b128 v[190:193], v150 offset:34816
	ds_read_b128 v[194:197], v150 offset:35840
	ds_read_b128 v[198:201], v150 offset:36864
	ds_read_b128 v[202:205], v150 offset:37888
	ds_read_b128 v[206:209], v150 offset:38912
	ds_read_b128 v[210:213], v150 offset:39936
	global_load_lds_dwordx4 v134, s[48:49]
	s_mov_b32 m0, s62
	s_nop 0
	global_load_lds_dwordx4 v130, s[48:49]
	s_waitcnt vmcnt(8)
	s_waitcnt lgkmcnt(8)
	s_barrier
; #define PG8_STAGE(bufoff, gbase, voff) do { _Pragma("unroll") for (int _i = 0; _i < 2; ++_i) \
;     __builtin_amdgcn_global_load_lds((const unsigned*)((const char*)(gbase) + (voff)[_i]), (LAS unsigned*)(lds + (bufoff) + ldsw + _i * 8192), 16, 0, 0); } while (0)
; #define PG8_LDA(dst, b, h) do { _Pragma("unroll") for (int m = 0; m < 4; ++m) _Pragma("unroll") for (int k = 0; k < 2; ++k) dst[m][k] = *(const LAS bf16x8*)(lds + PG8_SA(b, h) + aoff + m * 2048 + k * 1024); } while (0)
; #define PG8_LDB(dst, b, h) do { _Pragma("unroll") for (int n = 0; n < 2; ++n) _Pragma("unroll") for (int k = 0; k < 2; ++k) dst[n][k] = *(const LAS bf16x8*)(lds + PG8_SB(b, h) + boff + n * 2048 + k * 1024); } while (0)
; #define PG8_MMA(ai, bj, At, Bt) do { __builtin_amdgcn_s_setprio(1); _Pragma("unroll") for (int m = 0; m < 4; ++m) _Pragma("unroll") for (int n = 0; n < 2; ++n) _Pragma("unroll") for (int k = 0; k < 2; ++k) \
;     acc[ai][bj][m][n] = __builtin_amdgcn_mfma_f32_16x16x32_bf16(Bt[n][k], At[m][k], acc[ai][bj][m][n], 0, 0, 0); __builtin_amdgcn_s_setprio(0); } while (0)
; #define PG8_WAIT_V(n) asm volatile("s_waitcnt vmcnt(" #n ")" ::: "memory")
; #define PG8_WAIT_L(n) asm volatile("s_waitcnt lgkmcnt(" #n ")" ::: "memory")
; #define PG8_BAR __builtin_amdgcn_s_barrier()
; #define PG8_SCHED __builtin_amdgcn_sched_barrier(0)
; template <class Epi, class Sched>
; __device__ __forceinline__ void gemm_phase(LAS unsigned char* lds, const Gemm g, const Sched& S, const Epi& E) {
;     ...
;       PG8_WAIT_L(8); PG8_BAR; PG8_WAIT_L(0); PG8_MMA(0, 0, At, B0); PG8_BAR; PG8_SCHED;
;       PG8_LDB(B1, 1, 1); PG8_STAGE(PG8_SB(1, 0), b3, voffB);
;       PG8_BAR; PG8_WAIT_L(0); PG8_MMA(0, 1, At, B1); PG8_BAR;
;       PG8_LDA(At, 1, 1); PG8_STAGE(PG8_SA(1, 0), a3, voffA);
;       PG8_BAR; PG8_WAIT_L(0); PG8_MMA(1, 0, At, B0); PG8_BAR; PG8_SCHED;
;       PG8_STAGE(PG8_SB(1, 1), b3 + hstep, voffB);
;       PG8_WAIT_V(6); PG8_BAR; PG8_MMA(1, 1, At, B1); PG8_BAR;
;     }
	s_waitcnt lgkmcnt(0)
	s_waitcnt lgkmcnt(0)
	v_mfma_f32_16x16x32_bf16 v[124:127], v[152:155], v[182:185], v[124:127]
	v_mfma_f32_16x16x32_bf16 v[116:119], v[174:177], v[182:185], v[116:119]
	v_mfma_f32_16x16x32_bf16 v[108:111], v[152:155], v[190:193], v[108:111]
	v_mfma_f32_16x16x32_bf16 v[100:103], v[174:177], v[190:193], v[100:103]
	v_mfma_f32_16x16x32_bf16 v[92:95], v[152:155], v[198:201], v[92:95]
	v_mfma_f32_16x16x32_bf16 v[84:87], v[174:177], v[198:201], v[84:87]
	v_mfma_f32_16x16x32_bf16 v[76:79], v[152:155], v[206:209], v[76:79]
	v_mfma_f32_16x16x32_bf16 v[68:71], v[174:177], v[206:209], v[68:71]
	v_mfma_f32_16x16x32_bf16 v[124:127], v[156:159], v[186:189], v[124:127]
	v_mfma_f32_16x16x32_bf16 v[116:119], v[178:181], v[186:189], v[116:119]
	v_mfma_f32_16x16x32_bf16 v[108:111], v[156:159], v[194:197], v[108:111]
	v_mfma_f32_16x16x32_bf16 v[100:103], v[178:181], v[194:197], v[100:103]
	v_mfma_f32_16x16x32_bf16 v[92:95], v[156:159], v[202:205], v[92:95]
	v_mfma_f32_16x16x32_bf16 v[84:87], v[178:181], v[202:205], v[84:87]
	v_mfma_f32_16x16x32_bf16 v[76:79], v[156:159], v[210:213], v[76:79]
	v_mfma_f32_16x16x32_bf16 v[68:71], v[178:181], v[210:213], v[68:71]
	s_barrier
	s_add_i32 s48, 0, 0x1c000
	s_add_i32 s49, s74, s7
	v_add_u32_e32 v151, s48, v141
	s_add_u32 s60, s44, s80
	s_addc_u32 s61, s45, s81
	s_mov_b32 m0, s49
	ds_read_b128 v[226:229], v151
	ds_read_b128 v[232:235], v151 offset:1024
	ds_read_b128 v[236:239], v151 offset:2048
	ds_read_b128 v[240:243], v151 offset:3072
	global_load_lds_dwordx4 v132, s[60:61]
	v_lshl_add_u64 v[222:223], v[244:245], 0, s[80:81]
	s_add_i32 m0, s49, 0x2000
	s_nop 0
	global_load_lds_dwordx4 v128, s[60:61]
	s_barrier
	s_waitcnt lgkmcnt(0)
	s_waitcnt lgkmcnt(0)
	v_mfma_f32_16x16x32_bf16 v[120:123], v[226:229], v[182:185], v[120:123]
	v_mfma_f32_16x16x32_bf16 v[112:115], v[236:239], v[182:185], v[112:115]
	v_mfma_f32_16x16x32_bf16 v[104:107], v[226:229], v[190:193], v[104:107]
	v_mfma_f32_16x16x32_bf16 v[96:99], v[236:239], v[190:193], v[96:99]
	v_mfma_f32_16x16x32_bf16 v[88:91], v[226:229], v[198:201], v[88:91]
	v_mfma_f32_16x16x32_bf16 v[80:83], v[236:239], v[198:201], v[80:83]
	v_mfma_f32_16x16x32_bf16 v[72:75], v[226:229], v[206:209], v[72:75]
	v_mfma_f32_16x16x32_bf16 v[64:67], v[236:239], v[206:209], v[64:67]
	v_mfma_f32_16x16x32_bf16 v[120:123], v[232:235], v[186:189], v[120:123]
	v_mfma_f32_16x16x32_bf16 v[112:115], v[240:243], v[186:189], v[112:115]
	v_mfma_f32_16x16x32_bf16 v[104:107], v[232:235], v[194:197], v[104:107]
	v_mfma_f32_16x16x32_bf16 v[96:99], v[240:243], v[194:197], v[96:99]
	v_mfma_f32_16x16x32_bf16 v[88:91], v[232:235], v[202:205], v[88:91]
	v_mfma_f32_16x16x32_bf16 v[80:83], v[240:243], v[202:205], v[80:83]
	v_mfma_f32_16x16x32_bf16 v[72:75], v[232:235], v[210:213], v[72:75]
	v_mfma_f32_16x16x32_bf16 v[64:67], v[240:243], v[210:213], v[64:67]
	s_mov_b32 m0, s63
	v_lshl_add_u64 v[222:223], v[246:247], 0, s[80:81]
	s_barrier
	ds_read_b128 v[182:185], v150 offset:49152
	ds_read_b128 v[186:189], v150 offset:50176
	ds_read_b128 v[190:193], v150 offset:51200
	ds_read_b128 v[194:197], v150 offset:52224
	ds_read_b128 v[198:201], v150 offset:53248
	ds_read_b128 v[202:205], v150 offset:54272
	ds_read_b128 v[206:209], v150 offset:55296
	ds_read_b128 v[210:213], v150 offset:56320
	global_load_lds_dwordx4 v[222:223], off
	v_lshl_add_u64 v[222:223], v[248:249], 0, s[80:81]
	s_mov_b32 m0, s64
	s_nop 0
	global_load_lds_dwordx4 v[222:223], off
	s_barrier
	s_waitcnt lgkmcnt(0)
	s_waitcnt lgkmcnt(0)
	v_mfma_f32_16x16x32_bf16 v[60:63], v[152:155], v[182:185], v[60:63]
	v_mfma_f32_16x16x32_bf16 v[52:55], v[174:177], v[182:185], v[52:55]
	v_mfma_f32_16x16x32_bf16 v[44:47], v[152:155], v[190:193], v[44:47]
	v_mfma_f32_16x16x32_bf16 v[36:39], v[174:177], v[190:193], v[36:39]
	v_mfma_f32_16x16x32_bf16 v[28:31], v[152:155], v[198:201], v[28:31]
	v_mfma_f32_16x16x32_bf16 v[20:23], v[174:177], v[198:201], v[20:23]
	v_mfma_f32_16x16x32_bf16 v[12:15], v[152:155], v[206:209], v[12:15]
	v_mfma_f32_16x16x32_bf16 v[4:7], v[174:177], v[206:209], v[4:7]
	v_mfma_f32_16x16x32_bf16 v[60:63], v[156:159], v[186:189], v[60:63]
	v_mfma_f32_16x16x32_bf16 v[52:55], v[178:181], v[186:189], v[52:55]
	v_mfma_f32_16x16x32_bf16 v[44:47], v[156:159], v[194:197], v[44:47]
	v_mfma_f32_16x16x32_bf16 v[36:39], v[178:181], v[194:197], v[36:39]
	v_mfma_f32_16x16x32_bf16 v[28:31], v[156:159], v[202:205], v[28:31]
	v_mfma_f32_16x16x32_bf16 v[20:23], v[178:181], v[202:205], v[20:23]
	v_mfma_f32_16x16x32_bf16 v[12:15], v[156:159], v[210:213], v[12:15]
	v_mfma_f32_16x16x32_bf16 v[4:7], v[178:181], v[210:213], v[4:7]
	s_barrier
	s_add_u32 s44, s44, 0x40080
	s_addc_u32 s45, s45, 0
	s_add_i32 s48, s48, s7
	s_mov_b32 m0, s48
	s_nop 0
	global_load_lds_dwordx4 v132, s[44:45]
	s_add_i32 m0, s48, 0x2000
	s_nop 0
	global_load_lds_dwordx4 v128, s[44:45]
	s_waitcnt vmcnt(10)
	s_barrier
	v_mfma_f32_16x16x32_bf16 v[56:59], v[226:229], v[182:185], v[56:59]
	v_mfma_f32_16x16x32_bf16 v[48:51], v[236:239], v[182:185], v[48:51]
	v_mfma_f32_16x16x32_bf16 v[40:43], v[226:229], v[190:193], v[40:43]
	v_mfma_f32_16x16x32_bf16 v[32:35], v[236:239], v[190:193], v[32:35]
	v_mfma_f32_16x16x32_bf16 v[24:27], v[226:229], v[198:201], v[24:27]
	v_mfma_f32_16x16x32_bf16 v[16:19], v[236:239], v[198:201], v[16:19]
	v_mfma_f32_16x16x32_bf16 v[8:11], v[226:229], v[206:209], v[8:11]
	v_mfma_f32_16x16x32_bf16 v[0:3], v[236:239], v[206:209], v[0:3]
	v_mfma_f32_16x16x32_bf16 v[56:59], v[232:235], v[186:189], v[56:59]
	v_mfma_f32_16x16x32_bf16 v[48:51], v[240:243], v[186:189], v[48:51]
	v_mfma_f32_16x16x32_bf16 v[40:43], v[232:235], v[194:197], v[40:43]
	v_mfma_f32_16x16x32_bf16 v[32:35], v[240:243], v[194:197], v[32:35]
	v_mfma_f32_16x16x32_bf16 v[24:27], v[232:235], v[202:205], v[24:27]
	v_mfma_f32_16x16x32_bf16 v[16:19], v[240:243], v[202:205], v[16:19]
	v_mfma_f32_16x16x32_bf16 v[8:11], v[232:235], v[210:213], v[8:11]
	v_mfma_f32_16x16x32_bf16 v[0:3], v[240:243], v[210:213], v[0:3]
	s_add_i32 s73, s73, 2
	s_add_u32 s42, s42, 0x100
	s_addc_u32 s43, s43, 0
	s_add_u32 s52, s52, 0x100
	s_addc_u32 s72, s72, 0
	s_cmp_gt_u32 s73, 13
	s_barrier
	s_cbranch_scc0 .LBB0_1142
	s_cmp_lt_u32 s101, 0x100
	s_cbranch_scc0 .Lxa_10
	s_barrier

; #define PG8_STAGE(bufoff, gbase, voff) do { _Pragma("unroll") for (int _i = 0; _i < 2; ++_i) \
;     __builtin_amdgcn_global_load_lds((const unsigned*)((const char*)(gbase) + (voff)[_i]), (LAS unsigned*)(lds + (bufoff) + ldsw + _i * 8192), 16, 0, 0); } while (0)
; #define PG8_LDA(dst, b, h) do { _Pragma("unroll") for (int m = 0; m < 4; ++m) _Pragma("unroll") for (int k = 0; k < 2; ++k) dst[m][k] = *(const LAS bf16x8*)(lds + PG8_SA(b, h) + aoff + m * 2048 + k * 1024); } while (0)
; #define PG8_LDB(dst, b, h) do { _Pragma("unroll") for (int n = 0; n < 2; ++n) _Pragma("unroll") for (int k = 0; k < 2; ++k) dst[n][k] = *(const LAS bf16x8*)(lds + PG8_SB(b, h) + boff + n * 2048 + k * 1024); } while (0)
; #define PG8_WAIT_L(n) asm volatile("s_waitcnt lgkmcnt(" #n ")" ::: "memory")
; #define PG8_BAR __builtin_amdgcn_s_barrier()
; #define PG8_SCHED __builtin_amdgcn_sched_barrier(0)
; template <class Epi, class Sched>
; __device__ __forceinline__ void gemm_phase(LAS unsigned char* lds, const Gemm g, const Sched& S, const Epi& E) {
;     ...
;     const bool has_next = S.next(ui + 1, nxt);
;     const char* nA = has_next ? (const char*)g.A + (size_t)nxt.pm * tstep : cA; const char* nB = has_next ? (const char*)g.Bt + (size_t)nxt.pn * tstep : cB;
;     for (int t = 0; t < nt; t += 2) {
;       const bool last = (t == nt - 2);
;       const char* a1 = cA + (size_t)(t + 1) * kstep;
;       const char* a2 = last ? nA : cA + (size_t)(t + 2) * kstep; const char* b2 = last ? nB : cB + (size_t)(t + 2) * kstep;
;       const char* a3 = a2 + kstep; const char* b3 = b2 + kstep;
;       if (last && has_next) S.a_ready(nxt);
;       PG8_LDB(B0, 0, 0); PG8_SCHED; PG8_LDA(At, 0, 0); PG8_STAGE(PG8_SA(1, 1), a1 + hstep, voffA);
;       PG8_WAIT_L(8); PG8_BAR; PG8_WAIT_L(0); PG8_MMA(0, 0, At, B0); PG8_BAR; PG8_SCHED;
;       PG8_LDB(B1, 0, 1); PG8_STAGE(PG8_SB(0, 0), b2, voffB);
;       PG8_BAR; PG8_WAIT_L(0); PG8_MMA(0, 1, At, B1); PG8_BAR;
;     ...
; #pragma unroll
;     for (int a = 0; a < 2; ++a)
; #pragma unroll
;       for (int b = 0; b < 2; ++b)
; #pragma unroll
;         for (int m = 0; m < 4; ++m)
; #pragma unroll
;           for (int n = 0; n < 2; ++n) acc[a][b][m][n] = (f32x4){0.f, 0.f, 0.f, 0.f};
;     cur = nxt; cA = nA; cB = nB; ++ui;
.LBB0_1214:
	s_add_u32 s52, s44, 0x100
	v_mov_b32_e32 v0, 0
	s_addc_u32 s72, s45, 0
	s_mov_b32 s73, -2
	s_waitcnt lgkmcnt(0)
	v_mov_b32_e32 v1, v0
	v_mov_b64_e32 v[2:3], v[0:1]
	v_mov_b64_e32 v[4:5], v[0:1]
	v_mov_b64_e32 v[6:7], v[0:1]
	v_mov_b64_e32 v[8:9], v[0:1]
	v_mov_b64_e32 v[10:11], v[0:1]
	v_mov_b64_e32 v[12:13], v[0:1]
	v_mov_b64_e32 v[14:15], v[0:1]
	v_mov_b64_e32 v[16:17], v[0:1]
	v_mov_b64_e32 v[18:19], v[0:1]
	v_mov_b64_e32 v[20:21], v[0:1]
	v_mov_b64_e32 v[22:23], v[0:1]
	v_mov_b64_e32 v[24:25], v[0:1]
	v_mov_b64_e32 v[26:27], v[0:1]
	v_mov_b64_e32 v[28:29], v[0:1]
	v_mov_b64_e32 v[30:31], v[0:1]
	v_mov_b64_e32 v[32:33], v[0:1]
	v_mov_b64_e32 v[34:35], v[0:1]
	v_mov_b64_e32 v[36:37], v[0:1]
	v_mov_b64_e32 v[38:39], v[0:1]
	v_mov_b64_e32 v[40:41], v[0:1]
	v_mov_b64_e32 v[42:43], v[0:1]
	v_mov_b64_e32 v[44:45], v[0:1]
	v_mov_b64_e32 v[46:47], v[0:1]
	v_mov_b64_e32 v[48:49], v[0:1]
	v_mov_b64_e32 v[50:51], v[0:1]
	v_mov_b64_e32 v[52:53], v[0:1]
	v_mov_b64_e32 v[54:55], v[0:1]
	v_mov_b64_e32 v[56:57], v[0:1]
	v_mov_b64_e32 v[58:59], v[0:1]
	v_mov_b64_e32 v[60:61], v[0:1]
	v_mov_b64_e32 v[62:63], v[0:1]
	v_mov_b64_e32 v[64:65], v[0:1]
	v_mov_b64_e32 v[66:67], v[0:1]
	v_mov_b64_e32 v[68:69], v[0:1]
	v_mov_b64_e32 v[70:71], v[0:1]
	v_mov_b64_e32 v[72:73], v[0:1]
	v_mov_b64_e32 v[74:75], v[0:1]
	v_mov_b64_e32 v[76:77], v[0:1]
	v_mov_b64_e32 v[78:79], v[0:1]
	v_mov_b64_e32 v[80:81], v[0:1]
	v_mov_b64_e32 v[82:83], v[0:1]
	v_mov_b64_e32 v[84:85], v[0:1]
	v_mov_b64_e32 v[86:87], v[0:1]
	v_mov_b64_e32 v[88:89], v[0:1]
	v_mov_b64_e32 v[90:91], v[0:1]
	v_mov_b64_e32 v[92:93], v[0:1]
	v_mov_b64_e32 v[94:95], v[0:1]
	v_mov_b64_e32 v[96:97], v[0:1]
	v_mov_b64_e32 v[98:99], v[0:1]
	v_mov_b64_e32 v[100:101], v[0:1]
	v_mov_b64_e32 v[102:103], v[0:1]
	v_mov_b64_e32 v[104:105], v[0:1]
	v_mov_b64_e32 v[106:107], v[0:1]
	v_mov_b64_e32 v[108:109], v[0:1]
	v_mov_b64_e32 v[110:111], v[0:1]
	v_mov_b64_e32 v[112:113], v[0:1]
	v_mov_b64_e32 v[114:115], v[0:1]
	v_mov_b64_e32 v[116:117], v[0:1]
	v_mov_b64_e32 v[118:119], v[0:1]
	v_mov_b64_e32 v[120:121], v[0:1]
	v_mov_b64_e32 v[122:123], v[0:1]
	v_mov_b64_e32 v[124:125], v[0:1]
	v_mov_b64_e32 v[126:127], v[0:1]
	s_cmp_eq_u32 s100, 0
	s_cbranch_scc1 .Lxs_e11
	s_barrier
	s_mov_b32 s100, 0
.Lxs_e11:
.LBB0_1215:
	s_add_u32 s42, s34, 0x100
	s_addc_u32 s43, s35, 0
	s_add_i32 s74, 0, 0x10000
	v_add_u32_e32 v140, s74, v202
	ds_read_b128 v[128:131], v140
	ds_read_b128 v[132:135], v140 offset:1024
	ds_read_b128 v[136:139], v140 offset:2048
	ds_read_b128 v[140:143], v140 offset:3072
	s_cmp_eq_u32 s73, 40
	s_cselect_b32 s49, s23, s43
	s_cselect_b32 s48, s22, s42
	s_cselect_b32 s45, s41, s72
	s_cselect_b32 s44, s40, s52
	s_add_i32 m0, s51, 0xc000
	ds_read_b128 v[144:147], v203
	ds_read_b128 v[148:151], v203 offset:1024
	ds_read_b128 v[152:155], v203 offset:2048
	ds_read_b128 v[186:189], v203 offset:3072
	ds_read_b128 v[190:193], v203 offset:4096
	ds_read_b128 v[194:197], v203 offset:5120
	ds_read_b128 v[198:201], v203 offset:6144
	ds_read_b128 v[204:207], v203 offset:7168
	global_load_lds_dwordx4 v182, s[34:35]
	s_add_i32 m0, s51, 0xe000
	s_nop 0
	global_load_lds_dwordx4 v184, s[34:35]
	s_waitcnt vmcnt(8)
	s_waitcnt lgkmcnt(8)
	s_barrier
	s_waitcnt lgkmcnt(0)
	s_waitcnt lgkmcnt(0)
	v_mfma_f32_16x16x32_bf16 v[124:127], v[128:131], v[144:147], v[124:127]
	v_mfma_f32_16x16x32_bf16 v[120:123], v[136:139], v[144:147], v[120:123]
	v_mfma_f32_16x16x32_bf16 v[108:111], v[128:131], v[152:155], v[108:111]
	v_mfma_f32_16x16x32_bf16 v[104:107], v[136:139], v[152:155], v[104:107]
	v_mfma_f32_16x16x32_bf16 v[92:95], v[128:131], v[190:193], v[92:95]
	v_mfma_f32_16x16x32_bf16 v[88:91], v[136:139], v[190:193], v[88:91]
	v_mfma_f32_16x16x32_bf16 v[76:79], v[128:131], v[198:201], v[76:79]
	v_mfma_f32_16x16x32_bf16 v[72:75], v[136:139], v[198:201], v[72:75]
	v_mfma_f32_16x16x32_bf16 v[124:127], v[132:135], v[148:151], v[124:127]
	v_mfma_f32_16x16x32_bf16 v[120:123], v[140:143], v[148:151], v[120:123]
	v_mfma_f32_16x16x32_bf16 v[108:111], v[132:135], v[186:189], v[108:111]
	v_mfma_f32_16x16x32_bf16 v[104:107], v[140:143], v[186:189], v[104:107]
	v_mfma_f32_16x16x32_bf16 v[92:95], v[132:135], v[194:197], v[92:95]
	v_mfma_f32_16x16x32_bf16 v[88:91], v[140:143], v[194:197], v[88:91]
	v_mfma_f32_16x16x32_bf16 v[76:79], v[132:135], v[204:207], v[76:79]
	v_mfma_f32_16x16x32_bf16 v[72:75], v[140:143], v[204:207], v[72:75]
	s_barrier
	s_add_i32 s75, 0, 0x14000
	s_add_i32 s34, s74, s7
	v_add_u32_e32 v160, s75, v202
	s_mov_b32 m0, s34
	ds_read_b128 v[208:211], v160
	ds_read_b128 v[226:229], v160 offset:1024
	ds_read_b128 v[232:235], v160 offset:2048
	ds_read_b128 v[236:239], v160 offset:3072
	global_load_lds_dwordx4 v174, s[44:45]
	s_add_i32 m0, s34, 0x2000
	s_nop 0
	global_load_lds_dwordx4 v156, s[44:45]
	s_barrier
	s_waitcnt lgkmcnt(0)
	s_waitcnt lgkmcnt(0)
	v_mfma_f32_16x16x32_bf16 v[116:119], v[208:211], v[144:147], v[116:119]
	v_mfma_f32_16x16x32_bf16 v[112:115], v[232:235], v[144:147], v[112:115]
	v_mfma_f32_16x16x32_bf16 v[100:103], v[208:211], v[152:155], v[100:103]
	v_mfma_f32_16x16x32_bf16 v[96:99], v[232:235], v[152:155], v[96:99]
	v_mfma_f32_16x16x32_bf16 v[84:87], v[208:211], v[190:193], v[84:87]
	v_mfma_f32_16x16x32_bf16 v[80:83], v[232:235], v[190:193], v[80:83]
	v_mfma_f32_16x16x32_bf16 v[68:71], v[208:211], v[198:201], v[68:71]
	v_mfma_f32_16x16x32_bf16 v[64:67], v[232:235], v[198:201], v[64:67]
	v_mfma_f32_16x16x32_bf16 v[116:119], v[226:229], v[148:151], v[116:119]
	v_mfma_f32_16x16x32_bf16 v[112:115], v[236:239], v[148:151], v[112:115]
	v_mfma_f32_16x16x32_bf16 v[100:103], v[226:229], v[186:189], v[100:103]
	v_mfma_f32_16x16x32_bf16 v[96:99], v[236:239], v[186:189], v[96:99]
	v_mfma_f32_16x16x32_bf16 v[84:87], v[226:229], v[194:197], v[84:87]
	v_mfma_f32_16x16x32_bf16 v[80:83], v[236:239], v[194:197], v[80:83]
	v_mfma_f32_16x16x32_bf16 v[68:71], v[226:229], v[204:207], v[68:71]
	v_mfma_f32_16x16x32_bf16 v[64:67], v[236:239], v[204:207], v[64:67]
	s_mov_b32 m0, s51
	v_lshl_add_u64 v[240:241], s[48:49], 0, v[176:177]
	s_barrier
; #define PG8_STAGE(bufoff, gbase, voff) do { _Pragma("unroll") for (int _i = 0; _i < 2; ++_i) \
;     __builtin_amdgcn_global_load_lds((const unsigned*)((const char*)(gbase) + (voff)[_i]), (LAS unsigned*)(lds + (bufoff) + ldsw + _i * 8192), 16, 0, 0); } while (0)
; #define PG8_LDA(dst, b, h) do { _Pragma("unroll") for (int m = 0; m < 4; ++m) _Pragma("unroll") for (int k = 0; k < 2; ++k) dst[m][k] = *(const LAS bf16x8*)(lds + PG8_SA(b, h) + aoff + m * 2048 + k * 1024); } while (0)
; #define PG8_LDB(dst, b, h) do { _Pragma("unroll") for (int n = 0; n < 2; ++n) _Pragma("unroll") for (int k = 0; k < 2; ++k) dst[n][k] = *(const LAS bf16x8*)(lds + PG8_SB(b, h) + boff + n * 2048 + k * 1024); } while (0)
; #define PG8_MMA(ai, bj, At, Bt) do { __builtin_amdgcn_s_setprio(1); _Pragma("unroll") for (int m = 0; m < 4; ++m) _Pragma("unroll") for (int n = 0; n < 2; ++n) _Pragma("unroll") for (int k = 0; k < 2; ++k) \
;     acc[ai][bj][m][n] = __builtin_amdgcn_mfma_f32_16x16x32_bf16(Bt[n][k], At[m][k], acc[ai][bj][m][n], 0, 0, 0); __builtin_amdgcn_s_setprio(0); } while (0)
; #define PG8_WAIT_V(n) asm volatile("s_waitcnt vmcnt(" #n ")" ::: "memory")
; #define PG8_WAIT_L(n) asm volatile("s_waitcnt lgkmcnt(" #n ")" ::: "memory")
; #define PG8_BAR __builtin_amdgcn_s_barrier()
; #define PG8_SCHED __builtin_amdgcn_sched_barrier(0)
; template <class Epi, class Sched>
; __device__ __forceinline__ void gemm_phase(LAS unsigned char* lds, const Gemm g, const Sched& S, const Epi& E) {
;     ...
;       PG8_LDA(At, 0, 1); PG8_STAGE(PG8_SA(0, 0), a2, voffA);
;       PG8_BAR; PG8_WAIT_L(0); PG8_MMA(1, 0, At, B0); PG8_BAR; PG8_SCHED;
;       PG8_STAGE(PG8_SB(0, 1), b2 + hstep, voffB);
;       PG8_WAIT_V(6); PG8_BAR; PG8_MMA(1, 1, At, B1); PG8_BAR;
;       PG8_LDB(B0, 1, 0); PG8_SCHED; PG8_LDA(At, 1, 0); PG8_STAGE(PG8_SA(0, 1), a2 + hstep, voffA);
;       PG8_WAIT_L(8); PG8_BAR; PG8_WAIT_L(0); PG8_MMA(0, 0, At, B0); PG8_BAR; PG8_SCHED;
	ds_read_b128 v[144:147], v203 offset:16384
	ds_read_b128 v[148:151], v203 offset:17408
	ds_read_b128 v[152:155], v203 offset:18432
	ds_read_b128 v[186:189], v203 offset:19456
	ds_read_b128 v[190:193], v203 offset:20480
	ds_read_b128 v[194:197], v203 offset:21504
	ds_read_b128 v[198:201], v203 offset:22528
	ds_read_b128 v[204:207], v203 offset:23552
	global_load_lds_dwordx4 v176, s[48:49]
	v_lshl_add_u64 v[242:243], s[48:49], 0, v[158:159]
	s_mov_b32 m0, s62
	s_nop 0
	global_load_lds_dwordx4 v158, s[48:49]
	s_barrier
	s_waitcnt lgkmcnt(0)
	s_waitcnt lgkmcnt(0)
	v_mfma_f32_16x16x32_bf16 v[60:63], v[128:131], v[144:147], v[60:63]
	v_mfma_f32_16x16x32_bf16 v[56:59], v[136:139], v[144:147], v[56:59]
	v_mfma_f32_16x16x32_bf16 v[44:47], v[128:131], v[152:155], v[44:47]
	v_mfma_f32_16x16x32_bf16 v[40:43], v[136:139], v[152:155], v[40:43]
	v_mfma_f32_16x16x32_bf16 v[28:31], v[128:131], v[190:193], v[28:31]
	v_mfma_f32_16x16x32_bf16 v[24:27], v[136:139], v[190:193], v[24:27]
	v_mfma_f32_16x16x32_bf16 v[12:15], v[128:131], v[198:201], v[12:15]
	v_mfma_f32_16x16x32_bf16 v[8:11], v[136:139], v[198:201], v[8:11]
	v_mfma_f32_16x16x32_bf16 v[60:63], v[132:135], v[148:151], v[60:63]
	v_mfma_f32_16x16x32_bf16 v[56:59], v[140:143], v[148:151], v[56:59]
	v_mfma_f32_16x16x32_bf16 v[44:47], v[132:135], v[186:189], v[44:47]
	v_mfma_f32_16x16x32_bf16 v[40:43], v[140:143], v[186:189], v[40:43]
	v_mfma_f32_16x16x32_bf16 v[28:31], v[132:135], v[194:197], v[28:31]
	v_mfma_f32_16x16x32_bf16 v[24:27], v[140:143], v[194:197], v[24:27]
	v_mfma_f32_16x16x32_bf16 v[12:15], v[132:135], v[204:207], v[12:15]
	v_mfma_f32_16x16x32_bf16 v[8:11], v[140:143], v[204:207], v[8:11]
	s_barrier
	s_add_u32 s34, s44, 0xb0000
	s_addc_u32 s35, s45, 0
	s_add_i32 s74, s75, s7
	s_mov_b32 m0, s74
	s_nop 0
	global_load_lds_dwordx4 v174, s[34:35]
	s_add_i32 m0, s74, 0x2000
	s_nop 0
	global_load_lds_dwordx4 v156, s[34:35]
	s_waitcnt vmcnt(10)
	s_barrier
	v_mfma_f32_16x16x32_bf16 v[52:55], v[208:211], v[144:147], v[52:55]
	v_mfma_f32_16x16x32_bf16 v[48:51], v[232:235], v[144:147], v[48:51]
	v_mfma_f32_16x16x32_bf16 v[36:39], v[208:211], v[152:155], v[36:39]
	v_mfma_f32_16x16x32_bf16 v[32:35], v[232:235], v[152:155], v[32:35]
	v_mfma_f32_16x16x32_bf16 v[20:23], v[208:211], v[190:193], v[20:23]
	v_mfma_f32_16x16x32_bf16 v[16:19], v[232:235], v[190:193], v[16:19]
	v_mfma_f32_16x16x32_bf16 v[4:7], v[208:211], v[198:201], v[4:7]
	v_mfma_f32_16x16x32_bf16 v[0:3], v[232:235], v[198:201], v[0:3]
	v_mfma_f32_16x16x32_bf16 v[52:55], v[226:229], v[148:151], v[52:55]
	v_mfma_f32_16x16x32_bf16 v[48:51], v[236:239], v[148:151], v[48:51]
	v_mfma_f32_16x16x32_bf16 v[36:39], v[226:229], v[186:189], v[36:39]
	v_mfma_f32_16x16x32_bf16 v[32:35], v[236:239], v[186:189], v[32:35]
	v_mfma_f32_16x16x32_bf16 v[20:23], v[226:229], v[194:197], v[20:23]
	v_mfma_f32_16x16x32_bf16 v[16:19], v[236:239], v[194:197], v[16:19]
	v_mfma_f32_16x16x32_bf16 v[4:7], v[226:229], v[204:207], v[4:7]
	v_mfma_f32_16x16x32_bf16 v[0:3], v[236:239], v[204:207], v[0:3]
	s_add_i32 s74, 0, 0x18000
	v_add_u32_e32 v140, s74, v202
	s_barrier
	ds_read_b128 v[128:131], v140
	ds_read_b128 v[132:135], v140 offset:1024
	ds_read_b128 v[136:139], v140 offset:2048
	ds_read_b128 v[140:143], v140 offset:3072
	s_add_u32 s34, s48, 0xb0000
	s_addc_u32 s35, s49, 0
	s_mov_b32 m0, s63
	ds_read_b128 v[144:147], v203 offset:32768
	ds_read_b128 v[148:151], v203 offset:33792
	ds_read_b128 v[152:155], v203 offset:34816
	ds_read_b128 v[186:189], v203 offset:35840
	ds_read_b128 v[190:193], v203 offset:36864
	ds_read_b128 v[194:197], v203 offset:37888
	ds_read_b128 v[198:201], v203 offset:38912
	ds_read_b128 v[204:207], v203 offset:39936
	global_load_lds_dwordx4 v176, s[34:35]
	s_mov_b32 m0, s64
	s_nop 0
	global_load_lds_dwordx4 v158, s[34:35]
	s_waitcnt vmcnt(8)
	s_waitcnt lgkmcnt(8)
	s_barrier
	s_waitcnt lgkmcnt(0)
	s_waitcnt lgkmcnt(0)
	v_mfma_f32_16x16x32_bf16 v[124:127], v[128:131], v[144:147], v[124:127]
	v_mfma_f32_16x16x32_bf16 v[120:123], v[136:139], v[144:147], v[120:123]
	v_mfma_f32_16x16x32_bf16 v[108:111], v[128:131], v[152:155], v[108:111]
	v_mfma_f32_16x16x32_bf16 v[104:107], v[136:139], v[152:155], v[104:107]
	v_mfma_f32_16x16x32_bf16 v[92:95], v[128:131], v[190:193], v[92:95]
	v_mfma_f32_16x16x32_bf16 v[88:91], v[136:139], v[190:193], v[88:91]
	v_mfma_f32_16x16x32_bf16 v[76:79], v[128:131], v[198:201], v[76:79]
	v_mfma_f32_16x16x32_bf16 v[72:75], v[136:139], v[198:201], v[72:75]
	v_mfma_f32_16x16x32_bf16 v[124:127], v[132:135], v[148:151], v[124:127]
	v_mfma_f32_16x16x32_bf16 v[120:123], v[140:143], v[148:151], v[120:123]
	v_mfma_f32_16x16x32_bf16 v[108:111], v[132:135], v[186:189], v[108:111]
	v_mfma_f32_16x16x32_bf16 v[104:107], v[140:143], v[186:189], v[104:107]
	v_mfma_f32_16x16x32_bf16 v[92:95], v[132:135], v[194:197], v[92:95]
	v_mfma_f32_16x16x32_bf16 v[88:91], v[140:143], v[194:197], v[88:91]
	v_mfma_f32_16x16x32_bf16 v[76:79], v[132:135], v[204:207], v[76:79]
	v_mfma_f32_16x16x32_bf16 v[72:75], v[140:143], v[204:207], v[72:75]
	s_barrier
; #define PG8_STAGE(bufoff, gbase, voff) do { _Pragma("unroll") for (int _i = 0; _i < 2; ++_i) \
;     __builtin_amdgcn_global_load_lds((const unsigned*)((const char*)(gbase) + (voff)[_i]), (LAS unsigned*)(lds + (bufoff) + ldsw + _i * 8192), 16, 0, 0); } while (0)
; #define PG8_LDA(dst, b, h) do { _Pragma("unroll") for (int m = 0; m < 4; ++m) _Pragma("unroll") for (int k = 0; k < 2; ++k) dst[m][k] = *(const LAS bf16x8*)(lds + PG8_SA(b, h) + aoff + m * 2048 + k * 1024); } while (0)
; #define PG8_LDB(dst, b, h) do { _Pragma("unroll") for (int n = 0; n < 2; ++n) _Pragma("unroll") for (int k = 0; k < 2; ++k) dst[n][k] = *(const LAS bf16x8*)(lds + PG8_SB(b, h) + boff + n * 2048 + k * 1024); } while (0)
; #define PG8_MMA(ai, bj, At, Bt) do { __builtin_amdgcn_s_setprio(1); _Pragma("unroll") for (int m = 0; m < 4; ++m) _Pragma("unroll") for (int n = 0; n < 2; ++n) _Pragma("unroll") for (int k = 0; k < 2; ++k) \
;     acc[ai][bj][m][n] = __builtin_amdgcn_mfma_f32_16x16x32_bf16(Bt[n][k], At[m][k], acc[ai][bj][m][n], 0, 0, 0); __builtin_amdgcn_s_setprio(0); } while (0)
; #define PG8_WAIT_V(n) asm volatile("s_waitcnt vmcnt(" #n ")" ::: "memory")
; #define PG8_WAIT_L(n) asm volatile("s_waitcnt lgkmcnt(" #n ")" ::: "memory")
; #define PG8_BAR __builtin_amdgcn_s_barrier()
; #define PG8_SCHED __builtin_amdgcn_sched_barrier(0)
; template <class Epi, class Sched>
; __device__ __forceinline__ void gemm_phase(LAS unsigned char* lds, const Gemm g, const Sched& S, const Epi& E) {
;     ...
;       PG8_LDB(B1, 1, 1); PG8_STAGE(PG8_SB(1, 0), b3, voffB);
;       PG8_BAR; PG8_WAIT_L(0); PG8_MMA(0, 1, At, B1); PG8_BAR;
;       PG8_LDA(At, 1, 1); PG8_STAGE(PG8_SA(1, 0), a3, voffA);
;       PG8_BAR; PG8_WAIT_L(0); PG8_MMA(1, 0, At, B0); PG8_BAR; PG8_SCHED;
;       PG8_STAGE(PG8_SB(1, 1), b3 + hstep, voffB);
;       PG8_WAIT_V(6); PG8_BAR; PG8_MMA(1, 1, At, B1); PG8_BAR;
;     }
	s_add_i32 s48, 0, 0x1c000
	s_add_i32 s34, s74, s7
	v_add_u32_e32 v160, s48, v202
	s_add_u32 s60, s44, s80
	s_addc_u32 s61, s45, s81
	s_mov_b32 m0, s34
	ds_read_b128 v[208:211], v160
	ds_read_b128 v[226:229], v160 offset:1024
	ds_read_b128 v[232:235], v160 offset:2048
	ds_read_b128 v[236:239], v160 offset:3072
	global_load_lds_dwordx4 v174, s[60:61]
	v_lshl_add_u64 v[212:213], v[222:223], 0, s[80:81]
	s_add_i32 m0, s34, 0x2000
	s_nop 0
	global_load_lds_dwordx4 v156, s[60:61]
	s_barrier
	s_waitcnt lgkmcnt(0)
	s_waitcnt lgkmcnt(0)
	v_mfma_f32_16x16x32_bf16 v[116:119], v[208:211], v[144:147], v[116:119]
	v_mfma_f32_16x16x32_bf16 v[112:115], v[232:235], v[144:147], v[112:115]
	v_mfma_f32_16x16x32_bf16 v[100:103], v[208:211], v[152:155], v[100:103]
	v_mfma_f32_16x16x32_bf16 v[96:99], v[232:235], v[152:155], v[96:99]
	v_mfma_f32_16x16x32_bf16 v[84:87], v[208:211], v[190:193], v[84:87]
	v_mfma_f32_16x16x32_bf16 v[80:83], v[232:235], v[190:193], v[80:83]
	v_mfma_f32_16x16x32_bf16 v[68:71], v[208:211], v[198:201], v[68:71]
	v_mfma_f32_16x16x32_bf16 v[64:67], v[232:235], v[198:201], v[64:67]
	v_mfma_f32_16x16x32_bf16 v[116:119], v[226:229], v[148:151], v[116:119]
	v_mfma_f32_16x16x32_bf16 v[112:115], v[236:239], v[148:151], v[112:115]
	v_mfma_f32_16x16x32_bf16 v[100:103], v[226:229], v[186:189], v[100:103]
	v_mfma_f32_16x16x32_bf16 v[96:99], v[236:239], v[186:189], v[96:99]
	v_mfma_f32_16x16x32_bf16 v[84:87], v[226:229], v[194:197], v[84:87]
	v_mfma_f32_16x16x32_bf16 v[80:83], v[236:239], v[194:197], v[80:83]
	v_mfma_f32_16x16x32_bf16 v[68:71], v[226:229], v[204:207], v[68:71]
	v_mfma_f32_16x16x32_bf16 v[64:67], v[236:239], v[204:207], v[64:67]
	s_mov_b32 m0, s65
	v_lshl_add_u64 v[212:213], v[240:241], 0, s[80:81]
	s_barrier
	ds_read_b128 v[144:147], v203 offset:49152
	ds_read_b128 v[148:151], v203 offset:50176
	ds_read_b128 v[152:155], v203 offset:51200
	ds_read_b128 v[186:189], v203 offset:52224
	ds_read_b128 v[190:193], v203 offset:53248
	ds_read_b128 v[194:197], v203 offset:54272
	ds_read_b128 v[198:201], v203 offset:55296
	ds_read_b128 v[204:207], v203 offset:56320
	global_load_lds_dwordx4 v[212:213], off
	v_lshl_add_u64 v[212:213], v[242:243], 0, s[80:81]
	s_mov_b32 m0, s70
	s_nop 0
	global_load_lds_dwordx4 v[212:213], off
	s_barrier
	s_waitcnt lgkmcnt(0)
	s_waitcnt lgkmcnt(0)
	v_mfma_f32_16x16x32_bf16 v[60:63], v[128:131], v[144:147], v[60:63]
	v_mfma_f32_16x16x32_bf16 v[56:59], v[136:139], v[144:147], v[56:59]
	v_mfma_f32_16x16x32_bf16 v[44:47], v[128:131], v[152:155], v[44:47]
	v_mfma_f32_16x16x32_bf16 v[40:43], v[136:139], v[152:155], v[40:43]
	v_mfma_f32_16x16x32_bf16 v[28:31], v[128:131], v[190:193], v[28:31]
	v_mfma_f32_16x16x32_bf16 v[24:27], v[136:139], v[190:193], v[24:27]
	v_mfma_f32_16x16x32_bf16 v[12:15], v[128:131], v[198:201], v[12:15]
	v_mfma_f32_16x16x32_bf16 v[8:11], v[136:139], v[198:201], v[8:11]
	v_mfma_f32_16x16x32_bf16 v[60:63], v[132:135], v[148:151], v[60:63]
	v_mfma_f32_16x16x32_bf16 v[56:59], v[140:143], v[148:151], v[56:59]
	v_mfma_f32_16x16x32_bf16 v[44:47], v[132:135], v[186:189], v[44:47]
	v_mfma_f32_16x16x32_bf16 v[40:43], v[140:143], v[186:189], v[40:43]
	v_mfma_f32_16x16x32_bf16 v[28:31], v[132:135], v[194:197], v[28:31]
	v_mfma_f32_16x16x32_bf16 v[24:27], v[140:143], v[194:197], v[24:27]
	v_mfma_f32_16x16x32_bf16 v[12:15], v[132:135], v[204:207], v[12:15]
	v_mfma_f32_16x16x32_bf16 v[8:11], v[140:143], v[204:207], v[8:11]
	s_barrier
	s_add_u32 s34, s44, 0xb0080
	s_addc_u32 s35, s45, 0
	s_add_i32 s44, s48, s7
	s_mov_b32 m0, s44
	s_nop 0
	global_load_lds_dwordx4 v174, s[34:35]
	s_add_i32 m0, s44, 0x2000
	s_nop 0
	global_load_lds_dwordx4 v156, s[34:35]
	s_waitcnt vmcnt(10)
	s_barrier
	v_mfma_f32_16x16x32_bf16 v[52:55], v[208:211], v[144:147], v[52:55]
	v_mfma_f32_16x16x32_bf16 v[48:51], v[232:235], v[144:147], v[48:51]
	v_mfma_f32_16x16x32_bf16 v[36:39], v[208:211], v[152:155], v[36:39]
	v_mfma_f32_16x16x32_bf16 v[32:35], v[232:235], v[152:155], v[32:35]
	v_mfma_f32_16x16x32_bf16 v[20:23], v[208:211], v[190:193], v[20:23]
	v_mfma_f32_16x16x32_bf16 v[16:19], v[232:235], v[190:193], v[16:19]
	v_mfma_f32_16x16x32_bf16 v[4:7], v[208:211], v[198:201], v[4:7]
	v_mfma_f32_16x16x32_bf16 v[0:3], v[232:235], v[198:201], v[0:3]
	v_mfma_f32_16x16x32_bf16 v[52:55], v[226:229], v[148:151], v[52:55]
	v_mfma_f32_16x16x32_bf16 v[48:51], v[236:239], v[148:151], v[48:51]
	v_mfma_f32_16x16x32_bf16 v[36:39], v[226:229], v[186:189], v[36:39]
	v_mfma_f32_16x16x32_bf16 v[32:35], v[236:239], v[186:189], v[32:35]
	v_mfma_f32_16x16x32_bf16 v[20:23], v[226:229], v[194:197], v[20:23]
	v_mfma_f32_16x16x32_bf16 v[16:19], v[236:239], v[194:197], v[16:19]
	v_mfma_f32_16x16x32_bf16 v[4:7], v[226:229], v[204:207], v[4:7]
	v_mfma_f32_16x16x32_bf16 v[0:3], v[236:239], v[204:207], v[0:3]
	s_add_i32 s73, s73, 2
	s_add_u32 s52, s52, 0x100
	s_addc_u32 s72, s72, 0
	s_cmp_gt_u32 s73, 41
	s_mov_b64 s[34:35], s[42:43]
	s_barrier
	s_cbranch_scc0 .LBB0_1215
	s_cmp_lt_u32 s101, 0x100
	s_cbranch_scc0 .Lxa_11
	s_barrier
